# c21: c16 + loader priority experiment: each K-loop load segment issues its ds_reads and LDS-DMAs at s_setprio 3, back to 0 before its closing waits
# baseline (speedup 1.0000x reference)
.LBB0_343:
	s_ashr_i32 s11, s10, 31
	s_lshl_b64 s[12:13], s[10:11], 20
	s_add_u32 s12, s26, s12
	s_addc_u32 s13, s27, s13
	s_and_b64 s[14:15], s[2:3], exec
	s_cselect_b32 s11, s13, s21
	s_cselect_b32 s75, s12, s20
	s_ashr_i32 s9, s8, 31
	s_lshl_b64 s[14:15], s[8:9], 20
	s_add_u32 s14, s28, s14
	s_addc_u32 s15, s29, s15
	s_and_b64 s[22:23], s[2:3], exec
	s_cselect_b32 s9, s15, s19
	s_cselect_b32 s76, s14, s18
	s_add_u32 s77, s18, 0x100
	s_addc_u32 s78, s19, 0
	s_add_u32 s18, s20, 0x80080
	s_addc_u32 s19, s21, 0
	s_add_u32 s79, s20, 0x100
	s_addc_u32 s80, s21, 0
	s_mov_b32 s81, -2
	s_setprio 3
	ds_read_b128 v[148:151], v143
	ds_read_b128 v[152:155], v143 offset:1024
	ds_read_b128 v[156:159], v143 offset:2048
	ds_read_b128 v[160:163], v143 offset:3072
	ds_read_b128 v[164:167], v144
	ds_read_b128 v[168:171], v144 offset:1024
	ds_read_b128 v[172:175], v144 offset:2048
	ds_read_b128 v[176:179], v144 offset:3072
	s_cmp_eq_u32 s81, 28
	s_cselect_b32 s21, s9, s78
	s_cselect_b32 s20, s76, s77
	s_cselect_b32 s23, s11, s80
	s_cselect_b32 s22, s75, s79
	ds_read_b128 v[180:183], v145
	ds_read_b128 v[184:187], v145 offset:1024
	ds_read_b128 v[188:191], v145 offset:2048
	ds_read_b128 v[192:195], v145 offset:3072
	ds_read_b128 v[196:199], v145 offset:4096
	ds_read_b128 v[200:203], v145 offset:5120
	ds_read_b128 v[204:207], v145 offset:6144
	ds_read_b128 v[208:211], v145 offset:7168
	s_add_u32 s82, s18, 0xfff80000
	s_addc_u32 s83, s19, -1
	s_mov_b32 s86, m0
	s_mov_b32 m0, s64
	s_nop 0
	global_load_lds_dwordx4 v138, s[82:83]
	s_mov_b32 m0, s86
	s_nop 0
	s_mov_b32 s86, m0
	s_mov_b32 m0, s67
	s_nop 0
	global_load_lds_dwordx4 v140, s[82:83]
	s_mov_b32 m0, s86
	s_mov_b32 s82, m0
	s_mov_b32 m0, s65
	s_nop 0
	global_load_lds_dwordx4 v138, s[18:19]
	s_mov_b32 m0, s82
	s_nop 0
	s_mov_b32 s82, m0
	s_mov_b32 m0, s73
	s_nop 0
	global_load_lds_dwordx4 v140, s[18:19]
	s_mov_b32 m0, s82
	s_setprio 0
	s_waitcnt vmcnt(8)
	s_waitcnt lgkmcnt(0)
	s_barrier
	s_setprio 1
	s_waitcnt lgkmcnt(7)
	v_mfma_f32_16x16x32_bf16 v[126:129], v[148:151], v[180:183], 0
	v_mfma_f32_16x16x32_bf16 v[126:129], v[152:155], v[184:187], v[126:129]
	s_waitcnt lgkmcnt(5)
	v_mfma_f32_16x16x32_bf16 v[122:125], v[156:159], v[180:183], 0
	v_mfma_f32_16x16x32_bf16 v[122:125], v[160:163], v[184:187], v[122:125]
	s_waitcnt lgkmcnt(3)
	v_mfma_f32_16x16x32_bf16 v[106:109], v[156:159], v[188:191], 0
	v_mfma_f32_16x16x32_bf16 v[106:109], v[160:163], v[192:195], v[106:109]
	s_waitcnt lgkmcnt(1)
	v_mfma_f32_16x16x32_bf16 v[110:113], v[148:151], v[188:191], 0
	v_mfma_f32_16x16x32_bf16 v[110:113], v[152:155], v[192:195], v[110:113]
	v_mfma_f32_16x16x32_bf16 v[94:97], v[148:151], v[196:199], 0
	v_mfma_f32_16x16x32_bf16 v[94:97], v[152:155], v[200:203], v[94:97]
	v_mfma_f32_16x16x32_bf16 v[90:93], v[156:159], v[196:199], 0
	v_mfma_f32_16x16x32_bf16 v[90:93], v[160:163], v[200:203], v[90:93]
	v_mfma_f32_16x16x32_bf16 v[74:77], v[156:159], v[204:207], 0
	v_mfma_f32_16x16x32_bf16 v[74:77], v[160:163], v[208:211], v[74:77]
	s_waitcnt lgkmcnt(0)
	v_mfma_f32_16x16x32_bf16 v[78:81], v[148:151], v[204:207], 0
	v_mfma_f32_16x16x32_bf16 v[78:81], v[152:155], v[208:211], v[78:81]
	s_setprio 0
	s_setprio 1
	v_mfma_f32_16x16x32_bf16 v[118:121], v[164:167], v[180:183], 0
	v_mfma_f32_16x16x32_bf16 v[118:121], v[168:171], v[184:187], v[118:121]
	v_mfma_f32_16x16x32_bf16 v[114:117], v[172:175], v[180:183], 0
	v_mfma_f32_16x16x32_bf16 v[114:117], v[176:179], v[184:187], v[114:117]
	v_mfma_f32_16x16x32_bf16 v[98:101], v[172:175], v[188:191], 0
	v_mfma_f32_16x16x32_bf16 v[98:101], v[176:179], v[192:195], v[98:101]
	v_mfma_f32_16x16x32_bf16 v[102:105], v[164:167], v[188:191], 0
	v_mfma_f32_16x16x32_bf16 v[102:105], v[168:171], v[192:195], v[102:105]
	v_mfma_f32_16x16x32_bf16 v[86:89], v[164:167], v[196:199], 0
	v_mfma_f32_16x16x32_bf16 v[86:89], v[168:171], v[200:203], v[86:89]
	v_mfma_f32_16x16x32_bf16 v[82:85], v[172:175], v[196:199], 0
	v_mfma_f32_16x16x32_bf16 v[82:85], v[176:179], v[200:203], v[82:85]
	v_mfma_f32_16x16x32_bf16 v[66:69], v[172:175], v[204:207], 0
	v_mfma_f32_16x16x32_bf16 v[66:69], v[176:179], v[208:211], v[66:69]
	s_setprio 2
	s_barrier
	v_mfma_f32_16x16x32_bf16 v[70:73], v[164:167], v[204:207], 0
	v_mfma_f32_16x16x32_bf16 v[70:73], v[168:171], v[208:211], v[70:73]
	s_setprio 0
	s_setprio 3
	ds_read_b128 v[180:183], v145 offset:16384
	ds_read_b128 v[184:187], v145 offset:17408
	ds_read_b128 v[188:191], v145 offset:18432
	ds_read_b128 v[192:195], v145 offset:19456
	ds_read_b128 v[196:199], v145 offset:20480
	ds_read_b128 v[200:203], v145 offset:21504
	ds_read_b128 v[204:207], v145 offset:22528
	ds_read_b128 v[208:211], v145 offset:23552
	s_mov_b32 s82, m0
	s_mov_b32 m0, s35
	s_nop 0
	global_load_lds_dwordx4 v139, s[20:21]
	s_mov_b32 m0, s82
	s_nop 0
	s_mov_b32 s82, m0
	s_mov_b32 m0, s36
	s_nop 0
	global_load_lds_dwordx4 v141, s[20:21]
	s_mov_b32 m0, s82
	s_add_u32 s82, s20, 0x80000
	s_addc_u32 s83, s21, 0
	s_mov_b32 s86, m0
	s_mov_b32 m0, s37
	s_nop 0
	global_load_lds_dwordx4 v139, s[82:83]
	s_mov_b32 m0, s86
	s_nop 0
	s_mov_b32 s86, m0
	s_mov_b32 m0, s42
	s_nop 0
	global_load_lds_dwordx4 v141, s[82:83]
	s_mov_b32 m0, s86
	s_setprio 0
	s_waitcnt vmcnt(4)
	s_waitcnt lgkmcnt(0)
	s_barrier
	s_setprio 1
	s_waitcnt lgkmcnt(7)
	v_mfma_f32_16x16x32_bf16 v[62:65], v[148:151], v[180:183], 0
	v_mfma_f32_16x16x32_bf16 v[62:65], v[152:155], v[184:187], v[62:65]
	s_waitcnt lgkmcnt(5)
	v_mfma_f32_16x16x32_bf16 v[58:61], v[156:159], v[180:183], 0
	v_mfma_f32_16x16x32_bf16 v[58:61], v[160:163], v[184:187], v[58:61]
	s_waitcnt lgkmcnt(3)
	v_mfma_f32_16x16x32_bf16 v[42:45], v[156:159], v[188:191], 0
	v_mfma_f32_16x16x32_bf16 v[42:45], v[160:163], v[192:195], v[42:45]
	s_waitcnt lgkmcnt(1)
	v_mfma_f32_16x16x32_bf16 v[46:49], v[148:151], v[188:191], 0
	v_mfma_f32_16x16x32_bf16 v[46:49], v[152:155], v[192:195], v[46:49]
	v_mfma_f32_16x16x32_bf16 v[30:33], v[148:151], v[196:199], 0
	v_mfma_f32_16x16x32_bf16 v[30:33], v[152:155], v[200:203], v[30:33]
	v_mfma_f32_16x16x32_bf16 v[26:29], v[156:159], v[196:199], 0
	v_mfma_f32_16x16x32_bf16 v[26:29], v[160:163], v[200:203], v[26:29]
	v_mfma_f32_16x16x32_bf16 v[10:13], v[156:159], v[204:207], 0
	v_mfma_f32_16x16x32_bf16 v[10:13], v[160:163], v[208:211], v[10:13]
	s_waitcnt lgkmcnt(0)
	v_mfma_f32_16x16x32_bf16 v[14:17], v[148:151], v[204:207], 0
	v_mfma_f32_16x16x32_bf16 v[14:17], v[152:155], v[208:211], v[14:17]
	s_setprio 0
	s_setprio 1
	v_mfma_f32_16x16x32_bf16 v[54:57], v[164:167], v[180:183], 0
	v_mfma_f32_16x16x32_bf16 v[54:57], v[168:171], v[184:187], v[54:57]
	v_mfma_f32_16x16x32_bf16 v[50:53], v[172:175], v[180:183], 0
	v_mfma_f32_16x16x32_bf16 v[50:53], v[176:179], v[184:187], v[50:53]
	v_mfma_f32_16x16x32_bf16 v[34:37], v[172:175], v[188:191], 0
	v_mfma_f32_16x16x32_bf16 v[34:37], v[176:179], v[192:195], v[34:37]
	v_mfma_f32_16x16x32_bf16 v[38:41], v[164:167], v[188:191], 0
	v_mfma_f32_16x16x32_bf16 v[38:41], v[168:171], v[192:195], v[38:41]
	v_mfma_f32_16x16x32_bf16 v[22:25], v[164:167], v[196:199], 0
	v_mfma_f32_16x16x32_bf16 v[22:25], v[168:171], v[200:203], v[22:25]
	v_mfma_f32_16x16x32_bf16 v[18:21], v[172:175], v[196:199], 0
	v_mfma_f32_16x16x32_bf16 v[18:21], v[176:179], v[200:203], v[18:21]
	v_mfma_f32_16x16x32_bf16 v[2:5], v[172:175], v[204:207], 0
	v_mfma_f32_16x16x32_bf16 v[2:5], v[176:179], v[208:211], v[2:5]
	s_setprio 2
	s_barrier
	v_mfma_f32_16x16x32_bf16 v[6:9], v[164:167], v[204:207], 0
	v_mfma_f32_16x16x32_bf16 v[6:9], v[168:171], v[208:211], v[6:9]
	s_setprio 0
	s_setprio 3
	ds_read_b128 v[148:151], v146
	ds_read_b128 v[152:155], v146 offset:1024
	ds_read_b128 v[156:159], v146 offset:2048
	ds_read_b128 v[160:163], v146 offset:3072
	ds_read_b128 v[164:167], v147
	ds_read_b128 v[168:171], v147 offset:1024
	ds_read_b128 v[172:175], v147 offset:2048
	ds_read_b128 v[176:179], v147 offset:3072
	ds_read_b128 v[180:183], v145 offset:32768
	ds_read_b128 v[184:187], v145 offset:33792
	ds_read_b128 v[188:191], v145 offset:34816
	ds_read_b128 v[192:195], v145 offset:35840
	ds_read_b128 v[196:199], v145 offset:36864
	ds_read_b128 v[200:203], v145 offset:37888
	ds_read_b128 v[204:207], v145 offset:38912
	ds_read_b128 v[208:211], v145 offset:39936
	s_mov_b32 s82, m0
	s_mov_b32 m0, s31
	s_nop 0
	global_load_lds_dwordx4 v138, s[22:23]
	s_mov_b32 m0, s82
	s_nop 0
	s_mov_b32 s82, m0
	s_mov_b32 m0, s43
	s_nop 0
	global_load_lds_dwordx4 v140, s[22:23]
	s_mov_b32 m0, s82
	s_add_u32 s22, s22, 0x80000
	s_addc_u32 s23, s23, 0
	s_mov_b32 s82, m0
	s_mov_b32 m0, s46
	s_nop 0
	global_load_lds_dwordx4 v138, s[22:23]
	s_mov_b32 m0, s82
	s_nop 0
	s_mov_b32 s82, m0
	s_mov_b32 m0, s47
	s_nop 0
	global_load_lds_dwordx4 v140, s[22:23]
	s_mov_b32 m0, s82
	s_setprio 0
	s_waitcnt vmcnt(8)
	s_waitcnt lgkmcnt(0)
	s_barrier
	s_setprio 1
	s_waitcnt lgkmcnt(7)
	v_mfma_f32_16x16x32_bf16 v[126:129], v[148:151], v[180:183], v[126:129]
	v_mfma_f32_16x16x32_bf16 v[126:129], v[152:155], v[184:187], v[126:129]
	s_waitcnt lgkmcnt(5)
	v_mfma_f32_16x16x32_bf16 v[122:125], v[156:159], v[180:183], v[122:125]
	v_mfma_f32_16x16x32_bf16 v[122:125], v[160:163], v[184:187], v[122:125]
	s_waitcnt lgkmcnt(3)
	v_mfma_f32_16x16x32_bf16 v[106:109], v[156:159], v[188:191], v[106:109]
	v_mfma_f32_16x16x32_bf16 v[106:109], v[160:163], v[192:195], v[106:109]
	s_waitcnt lgkmcnt(1)
	v_mfma_f32_16x16x32_bf16 v[110:113], v[148:151], v[188:191], v[110:113]
	v_mfma_f32_16x16x32_bf16 v[110:113], v[152:155], v[192:195], v[110:113]
	v_mfma_f32_16x16x32_bf16 v[94:97], v[148:151], v[196:199], v[94:97]
	v_mfma_f32_16x16x32_bf16 v[94:97], v[152:155], v[200:203], v[94:97]
	v_mfma_f32_16x16x32_bf16 v[90:93], v[156:159], v[196:199], v[90:93]
	v_mfma_f32_16x16x32_bf16 v[90:93], v[160:163], v[200:203], v[90:93]
	v_mfma_f32_16x16x32_bf16 v[74:77], v[156:159], v[204:207], v[74:77]
	v_mfma_f32_16x16x32_bf16 v[74:77], v[160:163], v[208:211], v[74:77]
	s_waitcnt lgkmcnt(0)
	v_mfma_f32_16x16x32_bf16 v[78:81], v[148:151], v[204:207], v[78:81]
	v_mfma_f32_16x16x32_bf16 v[78:81], v[152:155], v[208:211], v[78:81]
	s_setprio 0
	s_setprio 1
	v_mfma_f32_16x16x32_bf16 v[118:121], v[164:167], v[180:183], v[118:121]
	v_mfma_f32_16x16x32_bf16 v[118:121], v[168:171], v[184:187], v[118:121]
	v_mfma_f32_16x16x32_bf16 v[114:117], v[172:175], v[180:183], v[114:117]
	v_mfma_f32_16x16x32_bf16 v[114:117], v[176:179], v[184:187], v[114:117]
	v_mfma_f32_16x16x32_bf16 v[98:101], v[172:175], v[188:191], v[98:101]
	v_mfma_f32_16x16x32_bf16 v[98:101], v[176:179], v[192:195], v[98:101]
	v_mfma_f32_16x16x32_bf16 v[102:105], v[164:167], v[188:191], v[102:105]
	v_mfma_f32_16x16x32_bf16 v[102:105], v[168:171], v[192:195], v[102:105]
	v_mfma_f32_16x16x32_bf16 v[86:89], v[164:167], v[196:199], v[86:89]
	v_mfma_f32_16x16x32_bf16 v[86:89], v[168:171], v[200:203], v[86:89]
	v_mfma_f32_16x16x32_bf16 v[82:85], v[172:175], v[196:199], v[82:85]
	v_mfma_f32_16x16x32_bf16 v[82:85], v[176:179], v[200:203], v[82:85]
	v_mfma_f32_16x16x32_bf16 v[66:69], v[172:175], v[204:207], v[66:69]
	v_mfma_f32_16x16x32_bf16 v[66:69], v[176:179], v[208:211], v[66:69]
	s_setprio 2
	s_barrier
	v_mfma_f32_16x16x32_bf16 v[70:73], v[164:167], v[204:207], v[70:73]
	v_mfma_f32_16x16x32_bf16 v[70:73], v[168:171], v[208:211], v[70:73]
	s_setprio 0
	s_setprio 3
	ds_read_b128 v[180:183], v145 offset:49152
	ds_read_b128 v[184:187], v145 offset:50176
	ds_read_b128 v[188:191], v145 offset:51200
	ds_read_b128 v[192:195], v145 offset:52224
	ds_read_b128 v[196:199], v145 offset:53248
	ds_read_b128 v[200:203], v145 offset:54272
	ds_read_b128 v[204:207], v145 offset:55296
	ds_read_b128 v[208:211], v145 offset:56320
	s_add_u32 s22, s20, 0x80
	s_addc_u32 s23, s21, 0
	s_mov_b32 s82, m0
	s_mov_b32 m0, s48
	s_nop 0
	global_load_lds_dwordx4 v139, s[22:23]
	s_mov_b32 m0, s82
	s_add_u32 s20, s20, 0x80080
	s_mov_b32 s82, m0
	s_mov_b32 m0, s49
	s_nop 0
	global_load_lds_dwordx4 v141, s[22:23]
	s_mov_b32 m0, s82
	s_addc_u32 s21, s21, 0
	s_mov_b32 s22, m0
	s_mov_b32 m0, s56
	s_nop 0
	global_load_lds_dwordx4 v139, s[20:21]
	s_mov_b32 m0, s22
	s_nop 0
	s_mov_b32 s22, m0
	s_mov_b32 m0, s57
	s_nop 0
	global_load_lds_dwordx4 v141, s[20:21]
	s_mov_b32 m0, s22
	s_setprio 0
	s_waitcnt vmcnt(4)
	s_waitcnt lgkmcnt(0)
	s_barrier
	s_setprio 1
	s_waitcnt lgkmcnt(7)
	v_mfma_f32_16x16x32_bf16 v[62:65], v[148:151], v[180:183], v[62:65]
	v_mfma_f32_16x16x32_bf16 v[62:65], v[152:155], v[184:187], v[62:65]
	s_waitcnt lgkmcnt(5)
	v_mfma_f32_16x16x32_bf16 v[58:61], v[156:159], v[180:183], v[58:61]
	v_mfma_f32_16x16x32_bf16 v[58:61], v[160:163], v[184:187], v[58:61]
	s_waitcnt lgkmcnt(3)
	v_mfma_f32_16x16x32_bf16 v[42:45], v[156:159], v[188:191], v[42:45]
	v_mfma_f32_16x16x32_bf16 v[42:45], v[160:163], v[192:195], v[42:45]
	s_waitcnt lgkmcnt(1)
	v_mfma_f32_16x16x32_bf16 v[46:49], v[148:151], v[188:191], v[46:49]
	v_mfma_f32_16x16x32_bf16 v[46:49], v[152:155], v[192:195], v[46:49]
	v_mfma_f32_16x16x32_bf16 v[30:33], v[148:151], v[196:199], v[30:33]
	v_mfma_f32_16x16x32_bf16 v[30:33], v[152:155], v[200:203], v[30:33]
	v_mfma_f32_16x16x32_bf16 v[26:29], v[156:159], v[196:199], v[26:29]
	v_mfma_f32_16x16x32_bf16 v[26:29], v[160:163], v[200:203], v[26:29]
	v_mfma_f32_16x16x32_bf16 v[10:13], v[156:159], v[204:207], v[10:13]
	v_mfma_f32_16x16x32_bf16 v[10:13], v[160:163], v[208:211], v[10:13]
	s_waitcnt lgkmcnt(0)
	v_mfma_f32_16x16x32_bf16 v[14:17], v[148:151], v[204:207], v[14:17]
	v_mfma_f32_16x16x32_bf16 v[14:17], v[152:155], v[208:211], v[14:17]
	s_setprio 0
	s_setprio 1
	v_mfma_f32_16x16x32_bf16 v[54:57], v[164:167], v[180:183], v[54:57]
	v_mfma_f32_16x16x32_bf16 v[54:57], v[168:171], v[184:187], v[54:57]
	v_mfma_f32_16x16x32_bf16 v[50:53], v[172:175], v[180:183], v[50:53]
	v_mfma_f32_16x16x32_bf16 v[50:53], v[176:179], v[184:187], v[50:53]
	v_mfma_f32_16x16x32_bf16 v[34:37], v[172:175], v[188:191], v[34:37]
	v_mfma_f32_16x16x32_bf16 v[34:37], v[176:179], v[192:195], v[34:37]
	v_mfma_f32_16x16x32_bf16 v[38:41], v[164:167], v[188:191], v[38:41]
	v_mfma_f32_16x16x32_bf16 v[38:41], v[168:171], v[192:195], v[38:41]
	v_mfma_f32_16x16x32_bf16 v[22:25], v[164:167], v[196:199], v[22:25]
	v_mfma_f32_16x16x32_bf16 v[22:25], v[168:171], v[200:203], v[22:25]
	v_mfma_f32_16x16x32_bf16 v[18:21], v[172:175], v[196:199], v[18:21]
	v_mfma_f32_16x16x32_bf16 v[18:21], v[176:179], v[200:203], v[18:21]
	v_mfma_f32_16x16x32_bf16 v[2:5], v[172:175], v[204:207], v[2:5]
	v_mfma_f32_16x16x32_bf16 v[2:5], v[176:179], v[208:211], v[2:5]
	s_setprio 2
	s_barrier
	v_mfma_f32_16x16x32_bf16 v[6:9], v[164:167], v[204:207], v[6:9]
	v_mfma_f32_16x16x32_bf16 v[6:9], v[168:171], v[208:211], v[6:9]
	s_setprio 0
	s_add_i32 s81, s81, 2
	s_add_u32 s77, s77, 0x100
	s_addc_u32 s78, s78, 0
	s_add_u32 s18, s18, 0x100
	s_addc_u32 s19, s19, 0
	s_add_u32 s79, s79, 0x100
	s_addc_u32 s80, s80, 0
	s_cmp_gt_u32 s81, 29
	.p2align 6
.LBB0_344:
	s_setprio 3
	ds_read_b128 v[148:151], v143
	ds_read_b128 v[152:155], v143 offset:1024
	ds_read_b128 v[156:159], v143 offset:2048
	ds_read_b128 v[160:163], v143 offset:3072
	ds_read_b128 v[164:167], v144
	ds_read_b128 v[168:171], v144 offset:1024
	ds_read_b128 v[172:175], v144 offset:2048
	ds_read_b128 v[176:179], v144 offset:3072
	s_cmp_eq_u32 s81, 28
	s_cselect_b32 s21, s9, s78
	s_cselect_b32 s20, s76, s77
	s_cselect_b32 s23, s11, s80
	s_cselect_b32 s22, s75, s79
	ds_read_b128 v[180:183], v145
	ds_read_b128 v[184:187], v145 offset:1024
	ds_read_b128 v[188:191], v145 offset:2048
	ds_read_b128 v[192:195], v145 offset:3072
	ds_read_b128 v[196:199], v145 offset:4096
	ds_read_b128 v[200:203], v145 offset:5120
	ds_read_b128 v[204:207], v145 offset:6144
	ds_read_b128 v[208:211], v145 offset:7168
	s_add_u32 s82, s18, 0xfff80000
	s_addc_u32 s83, s19, -1
	s_mov_b32 s86, m0
	s_mov_b32 m0, s64
	s_nop 0
	global_load_lds_dwordx4 v138, s[82:83]
	s_mov_b32 m0, s86
	s_nop 0
	s_mov_b32 s86, m0
	s_mov_b32 m0, s67
	s_nop 0
	global_load_lds_dwordx4 v140, s[82:83]
	s_mov_b32 m0, s86
	s_mov_b32 s82, m0
	s_mov_b32 m0, s65
	s_nop 0
	global_load_lds_dwordx4 v138, s[18:19]
	s_mov_b32 m0, s82
	s_nop 0
	s_mov_b32 s82, m0
	s_mov_b32 m0, s73
	s_nop 0
	global_load_lds_dwordx4 v140, s[18:19]
	s_mov_b32 m0, s82
	s_setprio 0
	s_waitcnt vmcnt(8)
	s_waitcnt lgkmcnt(0)
	s_barrier
	s_setprio 1
	s_waitcnt lgkmcnt(7)
	v_mfma_f32_16x16x32_bf16 v[126:129], v[148:151], v[180:183], v[126:129]
	v_mfma_f32_16x16x32_bf16 v[126:129], v[152:155], v[184:187], v[126:129]
	s_waitcnt lgkmcnt(5)
	v_mfma_f32_16x16x32_bf16 v[122:125], v[156:159], v[180:183], v[122:125]
	v_mfma_f32_16x16x32_bf16 v[122:125], v[160:163], v[184:187], v[122:125]
	s_waitcnt lgkmcnt(3)
	v_mfma_f32_16x16x32_bf16 v[106:109], v[156:159], v[188:191], v[106:109]
	v_mfma_f32_16x16x32_bf16 v[106:109], v[160:163], v[192:195], v[106:109]
	s_waitcnt lgkmcnt(1)
	v_mfma_f32_16x16x32_bf16 v[110:113], v[148:151], v[188:191], v[110:113]
	v_mfma_f32_16x16x32_bf16 v[110:113], v[152:155], v[192:195], v[110:113]
	v_mfma_f32_16x16x32_bf16 v[94:97], v[148:151], v[196:199], v[94:97]
	v_mfma_f32_16x16x32_bf16 v[94:97], v[152:155], v[200:203], v[94:97]
	v_mfma_f32_16x16x32_bf16 v[90:93], v[156:159], v[196:199], v[90:93]
	v_mfma_f32_16x16x32_bf16 v[90:93], v[160:163], v[200:203], v[90:93]
	v_mfma_f32_16x16x32_bf16 v[74:77], v[156:159], v[204:207], v[74:77]
	v_mfma_f32_16x16x32_bf16 v[74:77], v[160:163], v[208:211], v[74:77]
	s_waitcnt lgkmcnt(0)
	v_mfma_f32_16x16x32_bf16 v[78:81], v[148:151], v[204:207], v[78:81]
	v_mfma_f32_16x16x32_bf16 v[78:81], v[152:155], v[208:211], v[78:81]
	s_setprio 0
	s_setprio 1
	v_mfma_f32_16x16x32_bf16 v[118:121], v[164:167], v[180:183], v[118:121]
	v_mfma_f32_16x16x32_bf16 v[118:121], v[168:171], v[184:187], v[118:121]
	v_mfma_f32_16x16x32_bf16 v[114:117], v[172:175], v[180:183], v[114:117]
	v_mfma_f32_16x16x32_bf16 v[114:117], v[176:179], v[184:187], v[114:117]
	v_mfma_f32_16x16x32_bf16 v[98:101], v[172:175], v[188:191], v[98:101]
	v_mfma_f32_16x16x32_bf16 v[98:101], v[176:179], v[192:195], v[98:101]
	v_mfma_f32_16x16x32_bf16 v[102:105], v[164:167], v[188:191], v[102:105]
	v_mfma_f32_16x16x32_bf16 v[102:105], v[168:171], v[192:195], v[102:105]
	v_mfma_f32_16x16x32_bf16 v[86:89], v[164:167], v[196:199], v[86:89]
	v_mfma_f32_16x16x32_bf16 v[86:89], v[168:171], v[200:203], v[86:89]
	v_mfma_f32_16x16x32_bf16 v[82:85], v[172:175], v[196:199], v[82:85]
	v_mfma_f32_16x16x32_bf16 v[82:85], v[176:179], v[200:203], v[82:85]
	v_mfma_f32_16x16x32_bf16 v[66:69], v[172:175], v[204:207], v[66:69]
	v_mfma_f32_16x16x32_bf16 v[66:69], v[176:179], v[208:211], v[66:69]
	s_setprio 2
	s_barrier
	v_mfma_f32_16x16x32_bf16 v[70:73], v[164:167], v[204:207], v[70:73]
	v_mfma_f32_16x16x32_bf16 v[70:73], v[168:171], v[208:211], v[70:73]
	s_setprio 0
	s_setprio 3
	ds_read_b128 v[180:183], v145 offset:16384
	ds_read_b128 v[184:187], v145 offset:17408
	ds_read_b128 v[188:191], v145 offset:18432
	ds_read_b128 v[192:195], v145 offset:19456
	ds_read_b128 v[196:199], v145 offset:20480
	ds_read_b128 v[200:203], v145 offset:21504
	ds_read_b128 v[204:207], v145 offset:22528
	ds_read_b128 v[208:211], v145 offset:23552
	s_mov_b32 s82, m0
	s_mov_b32 m0, s35
	s_nop 0
	global_load_lds_dwordx4 v139, s[20:21]
	s_mov_b32 m0, s82
	s_nop 0
	s_mov_b32 s82, m0
	s_mov_b32 m0, s36
	s_nop 0
	global_load_lds_dwordx4 v141, s[20:21]
	s_mov_b32 m0, s82
	s_add_u32 s82, s20, 0x80000
	s_addc_u32 s83, s21, 0
	s_mov_b32 s86, m0
	s_mov_b32 m0, s37
	s_nop 0
	global_load_lds_dwordx4 v139, s[82:83]
	s_mov_b32 m0, s86
	s_nop 0
	s_mov_b32 s86, m0
	s_mov_b32 m0, s42
	s_nop 0
	global_load_lds_dwordx4 v141, s[82:83]
	s_mov_b32 m0, s86
	s_setprio 0
	s_waitcnt vmcnt(4)
	s_waitcnt lgkmcnt(0)
	s_barrier
	s_setprio 1
	s_waitcnt lgkmcnt(7)
	v_mfma_f32_16x16x32_bf16 v[62:65], v[148:151], v[180:183], v[62:65]
	v_mfma_f32_16x16x32_bf16 v[62:65], v[152:155], v[184:187], v[62:65]
	s_waitcnt lgkmcnt(5)
	v_mfma_f32_16x16x32_bf16 v[58:61], v[156:159], v[180:183], v[58:61]
	v_mfma_f32_16x16x32_bf16 v[58:61], v[160:163], v[184:187], v[58:61]
	s_waitcnt lgkmcnt(3)
	v_mfma_f32_16x16x32_bf16 v[42:45], v[156:159], v[188:191], v[42:45]
	v_mfma_f32_16x16x32_bf16 v[42:45], v[160:163], v[192:195], v[42:45]
	s_waitcnt lgkmcnt(1)
	v_mfma_f32_16x16x32_bf16 v[46:49], v[148:151], v[188:191], v[46:49]
	v_mfma_f32_16x16x32_bf16 v[46:49], v[152:155], v[192:195], v[46:49]
	v_mfma_f32_16x16x32_bf16 v[30:33], v[148:151], v[196:199], v[30:33]
	v_mfma_f32_16x16x32_bf16 v[30:33], v[152:155], v[200:203], v[30:33]
	v_mfma_f32_16x16x32_bf16 v[26:29], v[156:159], v[196:199], v[26:29]
	v_mfma_f32_16x16x32_bf16 v[26:29], v[160:163], v[200:203], v[26:29]
	v_mfma_f32_16x16x32_bf16 v[10:13], v[156:159], v[204:207], v[10:13]
	v_mfma_f32_16x16x32_bf16 v[10:13], v[160:163], v[208:211], v[10:13]
	s_waitcnt lgkmcnt(0)
	v_mfma_f32_16x16x32_bf16 v[14:17], v[148:151], v[204:207], v[14:17]
	v_mfma_f32_16x16x32_bf16 v[14:17], v[152:155], v[208:211], v[14:17]
	s_setprio 0
	s_setprio 1
	v_mfma_f32_16x16x32_bf16 v[54:57], v[164:167], v[180:183], v[54:57]
	v_mfma_f32_16x16x32_bf16 v[54:57], v[168:171], v[184:187], v[54:57]
	v_mfma_f32_16x16x32_bf16 v[50:53], v[172:175], v[180:183], v[50:53]
	v_mfma_f32_16x16x32_bf16 v[50:53], v[176:179], v[184:187], v[50:53]
	v_mfma_f32_16x16x32_bf16 v[34:37], v[172:175], v[188:191], v[34:37]
	v_mfma_f32_16x16x32_bf16 v[34:37], v[176:179], v[192:195], v[34:37]
	v_mfma_f32_16x16x32_bf16 v[38:41], v[164:167], v[188:191], v[38:41]
	v_mfma_f32_16x16x32_bf16 v[38:41], v[168:171], v[192:195], v[38:41]
	v_mfma_f32_16x16x32_bf16 v[22:25], v[164:167], v[196:199], v[22:25]
	v_mfma_f32_16x16x32_bf16 v[22:25], v[168:171], v[200:203], v[22:25]
	v_mfma_f32_16x16x32_bf16 v[18:21], v[172:175], v[196:199], v[18:21]
	v_mfma_f32_16x16x32_bf16 v[18:21], v[176:179], v[200:203], v[18:21]
	v_mfma_f32_16x16x32_bf16 v[2:5], v[172:175], v[204:207], v[2:5]
	v_mfma_f32_16x16x32_bf16 v[2:5], v[176:179], v[208:211], v[2:5]
	s_setprio 2
	s_barrier
	v_mfma_f32_16x16x32_bf16 v[6:9], v[164:167], v[204:207], v[6:9]
	v_mfma_f32_16x16x32_bf16 v[6:9], v[168:171], v[208:211], v[6:9]
	s_setprio 0
	s_setprio 3
	ds_read_b128 v[148:151], v146
	ds_read_b128 v[152:155], v146 offset:1024
	ds_read_b128 v[156:159], v146 offset:2048
	ds_read_b128 v[160:163], v146 offset:3072
	ds_read_b128 v[164:167], v147
	ds_read_b128 v[168:171], v147 offset:1024
	ds_read_b128 v[172:175], v147 offset:2048
	ds_read_b128 v[176:179], v147 offset:3072
	ds_read_b128 v[180:183], v145 offset:32768
	ds_read_b128 v[184:187], v145 offset:33792
	ds_read_b128 v[188:191], v145 offset:34816
	ds_read_b128 v[192:195], v145 offset:35840
	ds_read_b128 v[196:199], v145 offset:36864
	ds_read_b128 v[200:203], v145 offset:37888
	ds_read_b128 v[204:207], v145 offset:38912
	ds_read_b128 v[208:211], v145 offset:39936
	s_mov_b32 s82, m0
	s_mov_b32 m0, s31
	s_nop 0
	global_load_lds_dwordx4 v138, s[22:23]
	s_mov_b32 m0, s82
	s_nop 0
	s_mov_b32 s82, m0
	s_mov_b32 m0, s43
	s_nop 0
	global_load_lds_dwordx4 v140, s[22:23]
	s_mov_b32 m0, s82
	s_add_u32 s22, s22, 0x80000
	s_addc_u32 s23, s23, 0
	s_mov_b32 s82, m0
	s_mov_b32 m0, s46
	s_nop 0
	global_load_lds_dwordx4 v138, s[22:23]
	s_mov_b32 m0, s82
	s_nop 0
	s_mov_b32 s82, m0
	s_mov_b32 m0, s47
	s_nop 0
	global_load_lds_dwordx4 v140, s[22:23]
	s_mov_b32 m0, s82
	s_setprio 0
	s_waitcnt vmcnt(8)
	s_waitcnt lgkmcnt(0)
	s_barrier
	s_setprio 1
	s_waitcnt lgkmcnt(7)
	v_mfma_f32_16x16x32_bf16 v[126:129], v[148:151], v[180:183], v[126:129]
	v_mfma_f32_16x16x32_bf16 v[126:129], v[152:155], v[184:187], v[126:129]
	s_waitcnt lgkmcnt(5)
	v_mfma_f32_16x16x32_bf16 v[122:125], v[156:159], v[180:183], v[122:125]
	v_mfma_f32_16x16x32_bf16 v[122:125], v[160:163], v[184:187], v[122:125]
	s_waitcnt lgkmcnt(3)
	v_mfma_f32_16x16x32_bf16 v[106:109], v[156:159], v[188:191], v[106:109]
	v_mfma_f32_16x16x32_bf16 v[106:109], v[160:163], v[192:195], v[106:109]
	s_waitcnt lgkmcnt(1)
	v_mfma_f32_16x16x32_bf16 v[110:113], v[148:151], v[188:191], v[110:113]
	v_mfma_f32_16x16x32_bf16 v[110:113], v[152:155], v[192:195], v[110:113]
	v_mfma_f32_16x16x32_bf16 v[94:97], v[148:151], v[196:199], v[94:97]
	v_mfma_f32_16x16x32_bf16 v[94:97], v[152:155], v[200:203], v[94:97]
	v_mfma_f32_16x16x32_bf16 v[90:93], v[156:159], v[196:199], v[90:93]
	v_mfma_f32_16x16x32_bf16 v[90:93], v[160:163], v[200:203], v[90:93]
	v_mfma_f32_16x16x32_bf16 v[74:77], v[156:159], v[204:207], v[74:77]
	v_mfma_f32_16x16x32_bf16 v[74:77], v[160:163], v[208:211], v[74:77]
	s_waitcnt lgkmcnt(0)
	v_mfma_f32_16x16x32_bf16 v[78:81], v[148:151], v[204:207], v[78:81]
	v_mfma_f32_16x16x32_bf16 v[78:81], v[152:155], v[208:211], v[78:81]
	s_setprio 0
	s_setprio 1
	v_mfma_f32_16x16x32_bf16 v[118:121], v[164:167], v[180:183], v[118:121]
	v_mfma_f32_16x16x32_bf16 v[118:121], v[168:171], v[184:187], v[118:121]
	v_mfma_f32_16x16x32_bf16 v[114:117], v[172:175], v[180:183], v[114:117]
	v_mfma_f32_16x16x32_bf16 v[114:117], v[176:179], v[184:187], v[114:117]
	v_mfma_f32_16x16x32_bf16 v[98:101], v[172:175], v[188:191], v[98:101]
	v_mfma_f32_16x16x32_bf16 v[98:101], v[176:179], v[192:195], v[98:101]
	v_mfma_f32_16x16x32_bf16 v[102:105], v[164:167], v[188:191], v[102:105]
	v_mfma_f32_16x16x32_bf16 v[102:105], v[168:171], v[192:195], v[102:105]
	v_mfma_f32_16x16x32_bf16 v[86:89], v[164:167], v[196:199], v[86:89]
	v_mfma_f32_16x16x32_bf16 v[86:89], v[168:171], v[200:203], v[86:89]
	v_mfma_f32_16x16x32_bf16 v[82:85], v[172:175], v[196:199], v[82:85]
	v_mfma_f32_16x16x32_bf16 v[82:85], v[176:179], v[200:203], v[82:85]
	v_mfma_f32_16x16x32_bf16 v[66:69], v[172:175], v[204:207], v[66:69]
	v_mfma_f32_16x16x32_bf16 v[66:69], v[176:179], v[208:211], v[66:69]
	s_setprio 2
	s_barrier
	v_mfma_f32_16x16x32_bf16 v[70:73], v[164:167], v[204:207], v[70:73]
	v_mfma_f32_16x16x32_bf16 v[70:73], v[168:171], v[208:211], v[70:73]
	s_setprio 0
	s_setprio 3
	ds_read_b128 v[180:183], v145 offset:49152
	ds_read_b128 v[184:187], v145 offset:50176
	ds_read_b128 v[188:191], v145 offset:51200
	ds_read_b128 v[192:195], v145 offset:52224
	ds_read_b128 v[196:199], v145 offset:53248
	ds_read_b128 v[200:203], v145 offset:54272
	ds_read_b128 v[204:207], v145 offset:55296
	ds_read_b128 v[208:211], v145 offset:56320
	s_add_u32 s22, s20, 0x80
	s_addc_u32 s23, s21, 0
	s_mov_b32 s82, m0
	s_mov_b32 m0, s48
	s_nop 0
	global_load_lds_dwordx4 v139, s[22:23]
	s_mov_b32 m0, s82
	s_add_u32 s20, s20, 0x80080
	s_mov_b32 s82, m0
	s_mov_b32 m0, s49
	s_nop 0
	global_load_lds_dwordx4 v141, s[22:23]
	s_mov_b32 m0, s82
	s_addc_u32 s21, s21, 0
	s_mov_b32 s22, m0
	s_mov_b32 m0, s56
	s_nop 0
	global_load_lds_dwordx4 v139, s[20:21]
	s_mov_b32 m0, s22
	s_nop 0
	s_mov_b32 s22, m0
	s_mov_b32 m0, s57
	s_nop 0
	global_load_lds_dwordx4 v141, s[20:21]
	s_mov_b32 m0, s22
	s_setprio 0
	s_waitcnt vmcnt(4)
	s_waitcnt lgkmcnt(0)
	s_barrier
	s_setprio 1
	s_waitcnt lgkmcnt(7)
	v_mfma_f32_16x16x32_bf16 v[62:65], v[148:151], v[180:183], v[62:65]
	v_mfma_f32_16x16x32_bf16 v[62:65], v[152:155], v[184:187], v[62:65]
	s_waitcnt lgkmcnt(5)
	v_mfma_f32_16x16x32_bf16 v[58:61], v[156:159], v[180:183], v[58:61]
	v_mfma_f32_16x16x32_bf16 v[58:61], v[160:163], v[184:187], v[58:61]
	s_waitcnt lgkmcnt(3)
	v_mfma_f32_16x16x32_bf16 v[42:45], v[156:159], v[188:191], v[42:45]
	v_mfma_f32_16x16x32_bf16 v[42:45], v[160:163], v[192:195], v[42:45]
	s_waitcnt lgkmcnt(1)
	v_mfma_f32_16x16x32_bf16 v[46:49], v[148:151], v[188:191], v[46:49]
	v_mfma_f32_16x16x32_bf16 v[46:49], v[152:155], v[192:195], v[46:49]
	v_mfma_f32_16x16x32_bf16 v[30:33], v[148:151], v[196:199], v[30:33]
	v_mfma_f32_16x16x32_bf16 v[30:33], v[152:155], v[200:203], v[30:33]
	v_mfma_f32_16x16x32_bf16 v[26:29], v[156:159], v[196:199], v[26:29]
	v_mfma_f32_16x16x32_bf16 v[26:29], v[160:163], v[200:203], v[26:29]
	v_mfma_f32_16x16x32_bf16 v[10:13], v[156:159], v[204:207], v[10:13]
	v_mfma_f32_16x16x32_bf16 v[10:13], v[160:163], v[208:211], v[10:13]
	s_waitcnt lgkmcnt(0)
	v_mfma_f32_16x16x32_bf16 v[14:17], v[148:151], v[204:207], v[14:17]
	v_mfma_f32_16x16x32_bf16 v[14:17], v[152:155], v[208:211], v[14:17]
	s_setprio 0
	s_setprio 1
	v_mfma_f32_16x16x32_bf16 v[54:57], v[164:167], v[180:183], v[54:57]
	v_mfma_f32_16x16x32_bf16 v[54:57], v[168:171], v[184:187], v[54:57]
	v_mfma_f32_16x16x32_bf16 v[50:53], v[172:175], v[180:183], v[50:53]
	v_mfma_f32_16x16x32_bf16 v[50:53], v[176:179], v[184:187], v[50:53]
	v_mfma_f32_16x16x32_bf16 v[34:37], v[172:175], v[188:191], v[34:37]
	v_mfma_f32_16x16x32_bf16 v[34:37], v[176:179], v[192:195], v[34:37]
	v_mfma_f32_16x16x32_bf16 v[38:41], v[164:167], v[188:191], v[38:41]
	v_mfma_f32_16x16x32_bf16 v[38:41], v[168:171], v[192:195], v[38:41]
	v_mfma_f32_16x16x32_bf16 v[22:25], v[164:167], v[196:199], v[22:25]
	v_mfma_f32_16x16x32_bf16 v[22:25], v[168:171], v[200:203], v[22:25]
	v_mfma_f32_16x16x32_bf16 v[18:21], v[172:175], v[196:199], v[18:21]
	v_mfma_f32_16x16x32_bf16 v[18:21], v[176:179], v[200:203], v[18:21]
	v_mfma_f32_16x16x32_bf16 v[2:5], v[172:175], v[204:207], v[2:5]
	v_mfma_f32_16x16x32_bf16 v[2:5], v[176:179], v[208:211], v[2:5]
	s_setprio 2
	s_barrier
	v_mfma_f32_16x16x32_bf16 v[6:9], v[164:167], v[204:207], v[6:9]
	v_mfma_f32_16x16x32_bf16 v[6:9], v[168:171], v[208:211], v[6:9]
	s_setprio 0
	s_add_i32 s81, s81, 2
	s_add_u32 s77, s77, 0x100
	s_addc_u32 s78, s78, 0
	s_add_u32 s18, s18, 0x100
	s_addc_u32 s19, s19, 0
	s_add_u32 s79, s79, 0x100
	s_addc_u32 s80, s80, 0
	s_cmp_gt_u32 s81, 29
	s_cbranch_scc0 .LBB0_344
	s_and_b64 vcc, exec, s[6:7]
	s_cbranch_vccz .LBB0_347
	s_barrier

.LBB0_472:
	s_ashr_i32 s13, s12, 31
	s_lshl_b64 s[14:15], s[12:13], 15
	s_add_u32 s14, s28, s14
	s_addc_u32 s15, s29, s15
	s_and_b64 s[16:17], s[2:3], exec
	s_cselect_b32 s13, s15, s23
	s_cselect_b32 s76, s14, s22
	s_ashr_i32 s11, s10, 31
	s_lshl_b64 s[16:17], s[10:11], 15
	s_add_u32 s16, s30, s16
	s_addc_u32 s17, s31, s17
	s_and_b64 s[24:25], s[2:3], exec
	s_cselect_b32 s11, s17, s21
	s_cselect_b32 s77, s16, s20
	s_add_u32 s78, s20, 0x80000
	s_addc_u32 s79, s21, 0
	s_add_u32 s20, s22, 0x204000
	s_addc_u32 s21, s23, 0
	s_add_u32 s80, s22, 0x400000
	s_addc_u32 s81, s23, 0
	s_mov_b32 s82, -2
	s_waitcnt vmcnt(25)
	s_waitcnt vmcnt(24)
	s_waitcnt vmcnt(23)
	s_waitcnt vmcnt(22)
	s_waitcnt vmcnt(21)
	s_waitcnt vmcnt(20)
	s_waitcnt vmcnt(15)
	s_waitcnt vmcnt(14)
	s_waitcnt vmcnt(13)
	s_waitcnt vmcnt(12)
	s_waitcnt vmcnt(7)
	s_waitcnt vmcnt(6)
	s_waitcnt vmcnt(5)
	s_waitcnt vmcnt(4)
	s_waitcnt vmcnt(3)
	s_waitcnt vmcnt(2)
	s_waitcnt vmcnt(1)
	s_waitcnt vmcnt(0)
	s_setprio 3
	ds_read_b128 v[134:137], v161
	ds_read_b128 v[138:141], v161 offset:1024
	ds_read_b128 v[142:145], v161 offset:2048
	ds_read_b128 v[146:149], v161 offset:3072
	ds_read_b128 v[150:153], v162
	ds_read_b128 v[166:169], v162 offset:1024
	ds_read_b128 v[170:173], v162 offset:2048
	ds_read_b128 v[174:177], v162 offset:3072
	s_cmpk_eq_i32 s82, 0x52
	s_cselect_b32 s23, s11, s79
	s_cselect_b32 s22, s77, s78
	s_cselect_b32 s25, s13, s81
	s_cselect_b32 s24, s76, s80
	ds_read_b128 v[178:181], v163
	ds_read_b128 v[182:185], v163 offset:1024
	ds_read_b128 v[186:189], v163 offset:2048
	ds_read_b128 v[190:193], v163 offset:3072
	ds_read_b128 v[194:197], v163 offset:4096
	ds_read_b128 v[198:201], v163 offset:5120
	ds_read_b128 v[202:205], v163 offset:6144
	ds_read_b128 v[206:209], v163 offset:7168
	s_add_u32 s86, s20, 0xffffc000
	s_addc_u32 s87, s21, -1
	s_mov_b32 s83, m0
	s_mov_b32 m0, s65
	s_nop 0
	global_load_lds_dwordx4 v1, s[86:87]
	s_mov_b32 m0, s83
	s_nop 0
	s_mov_b32 s83, m0
	s_mov_b32 m0, s67
	s_nop 0
	global_load_lds_dwordx4 v157, s[86:87]
	s_mov_b32 m0, s83
	s_nop 0
	s_mov_b32 s83, m0
	s_mov_b32 m0, s66
	s_nop 0
	global_load_lds_dwordx4 v1, s[20:21]
	s_mov_b32 m0, s83
	s_nop 0
	s_mov_b32 s83, m0
	s_mov_b32 m0, s73
	s_nop 0
	global_load_lds_dwordx4 v157, s[20:21]
	s_mov_b32 m0, s83
	s_setprio 0
	s_waitcnt vmcnt(8)
	s_waitcnt lgkmcnt(0)
	s_barrier
	s_setprio 1
	s_waitcnt lgkmcnt(7)
	v_mfma_f32_16x16x32_bf16 v[126:129], v[134:137], v[178:181], 0
	v_mfma_f32_16x16x32_bf16 v[126:129], v[138:141], v[182:185], v[126:129]
	s_waitcnt lgkmcnt(5)
	v_mfma_f32_16x16x32_bf16 v[122:125], v[142:145], v[178:181], 0
	v_mfma_f32_16x16x32_bf16 v[122:125], v[146:149], v[182:185], v[122:125]
	s_waitcnt lgkmcnt(3)
	v_mfma_f32_16x16x32_bf16 v[114:117], v[142:145], v[186:189], 0
	v_mfma_f32_16x16x32_bf16 v[114:117], v[146:149], v[190:193], v[114:117]
	s_waitcnt lgkmcnt(1)
	v_mfma_f32_16x16x32_bf16 v[118:121], v[134:137], v[186:189], 0
	v_mfma_f32_16x16x32_bf16 v[118:121], v[138:141], v[190:193], v[118:121]
	v_mfma_f32_16x16x32_bf16 v[102:105], v[134:137], v[194:197], 0
	v_mfma_f32_16x16x32_bf16 v[102:105], v[138:141], v[198:201], v[102:105]
	v_mfma_f32_16x16x32_bf16 v[94:97], v[142:145], v[194:197], 0
	v_mfma_f32_16x16x32_bf16 v[94:97], v[146:149], v[198:201], v[94:97]
	v_mfma_f32_16x16x32_bf16 v[78:81], v[142:145], v[202:205], 0
	v_mfma_f32_16x16x32_bf16 v[78:81], v[146:149], v[206:209], v[78:81]
	s_waitcnt lgkmcnt(0)
	v_mfma_f32_16x16x32_bf16 v[86:89], v[134:137], v[202:205], 0
	v_mfma_f32_16x16x32_bf16 v[86:89], v[138:141], v[206:209], v[86:89]
	s_setprio 0
	s_setprio 1
	v_mfma_f32_16x16x32_bf16 v[110:113], v[150:153], v[178:181], 0
	v_mfma_f32_16x16x32_bf16 v[110:113], v[166:169], v[182:185], v[110:113]
	v_mfma_f32_16x16x32_bf16 v[106:109], v[170:173], v[178:181], 0
	v_mfma_f32_16x16x32_bf16 v[106:109], v[174:177], v[182:185], v[106:109]
	v_mfma_f32_16x16x32_bf16 v[90:93], v[170:173], v[186:189], 0
	v_mfma_f32_16x16x32_bf16 v[90:93], v[174:177], v[190:193], v[90:93]
	v_mfma_f32_16x16x32_bf16 v[98:101], v[150:153], v[186:189], 0
	v_mfma_f32_16x16x32_bf16 v[98:101], v[166:169], v[190:193], v[98:101]
	v_mfma_f32_16x16x32_bf16 v[82:85], v[150:153], v[194:197], 0
	v_mfma_f32_16x16x32_bf16 v[82:85], v[166:169], v[198:201], v[82:85]
	v_mfma_f32_16x16x32_bf16 v[74:77], v[170:173], v[194:197], 0
	v_mfma_f32_16x16x32_bf16 v[74:77], v[174:177], v[198:201], v[74:77]
	v_mfma_f32_16x16x32_bf16 v[66:69], v[170:173], v[202:205], 0
	v_mfma_f32_16x16x32_bf16 v[66:69], v[174:177], v[206:209], v[66:69]
	s_setprio 2
	s_barrier
	v_mfma_f32_16x16x32_bf16 v[70:73], v[150:153], v[202:205], 0
	v_mfma_f32_16x16x32_bf16 v[70:73], v[166:169], v[206:209], v[70:73]
	s_setprio 0
	s_setprio 3
	ds_read_b128 v[178:181], v163 offset:16384
	ds_read_b128 v[182:185], v163 offset:17408
	ds_read_b128 v[186:189], v163 offset:18432
	ds_read_b128 v[190:193], v163 offset:19456
	ds_read_b128 v[194:197], v163 offset:20480
	ds_read_b128 v[198:201], v163 offset:21504
	ds_read_b128 v[202:205], v163 offset:22528
	ds_read_b128 v[206:209], v163 offset:23552
	s_mov_b32 s83, m0
	s_mov_b32 m0, s19
	s_nop 0
	global_load_lds_dwordx4 v156, s[22:23]
	s_mov_b32 m0, s83
	s_add_u32 s86, s22, 0x4000
	s_mov_b32 s83, m0
	s_mov_b32 m0, s35
	s_nop 0
	global_load_lds_dwordx4 v158, s[22:23]
	s_mov_b32 m0, s83
	s_addc_u32 s87, s23, 0
	s_mov_b32 s83, m0
	s_mov_b32 m0, s36
	s_nop 0
	global_load_lds_dwordx4 v156, s[86:87]
	s_mov_b32 m0, s83
	s_nop 0
	s_mov_b32 s83, m0
	s_mov_b32 m0, s37
	s_nop 0
	global_load_lds_dwordx4 v158, s[86:87]
	s_mov_b32 m0, s83
	s_setprio 0
	s_waitcnt vmcnt(4)
	s_waitcnt lgkmcnt(0)
	s_barrier
	s_setprio 1
	s_waitcnt lgkmcnt(7)
	v_mfma_f32_16x16x32_bf16 v[62:65], v[134:137], v[178:181], 0
	v_mfma_f32_16x16x32_bf16 v[62:65], v[138:141], v[182:185], v[62:65]
	s_waitcnt lgkmcnt(5)
	v_mfma_f32_16x16x32_bf16 v[58:61], v[142:145], v[178:181], 0
	v_mfma_f32_16x16x32_bf16 v[58:61], v[146:149], v[182:185], v[58:61]
	s_waitcnt lgkmcnt(3)
	v_mfma_f32_16x16x32_bf16 v[46:49], v[142:145], v[186:189], 0
	v_mfma_f32_16x16x32_bf16 v[46:49], v[146:149], v[190:193], v[46:49]
	s_waitcnt lgkmcnt(1)
	v_mfma_f32_16x16x32_bf16 v[54:57], v[134:137], v[186:189], 0
	v_mfma_f32_16x16x32_bf16 v[54:57], v[138:141], v[190:193], v[54:57]
	v_mfma_f32_16x16x32_bf16 v[38:41], v[134:137], v[194:197], 0
	v_mfma_f32_16x16x32_bf16 v[38:41], v[138:141], v[198:201], v[38:41]
	v_mfma_f32_16x16x32_bf16 v[30:33], v[142:145], v[194:197], 0
	v_mfma_f32_16x16x32_bf16 v[30:33], v[146:149], v[198:201], v[30:33]
	v_mfma_f32_16x16x32_bf16 v[14:17], v[142:145], v[202:205], 0
	v_mfma_f32_16x16x32_bf16 v[14:17], v[146:149], v[206:209], v[14:17]
	s_waitcnt lgkmcnt(0)
	v_mfma_f32_16x16x32_bf16 v[22:25], v[134:137], v[202:205], 0
	v_mfma_f32_16x16x32_bf16 v[22:25], v[138:141], v[206:209], v[22:25]
	s_setprio 0
	s_setprio 1
	v_mfma_f32_16x16x32_bf16 v[50:53], v[150:153], v[178:181], 0
	v_mfma_f32_16x16x32_bf16 v[50:53], v[166:169], v[182:185], v[50:53]
	v_mfma_f32_16x16x32_bf16 v[42:45], v[170:173], v[178:181], 0
	v_mfma_f32_16x16x32_bf16 v[42:45], v[174:177], v[182:185], v[42:45]
	v_mfma_f32_16x16x32_bf16 v[26:29], v[170:173], v[186:189], 0
	v_mfma_f32_16x16x32_bf16 v[26:29], v[174:177], v[190:193], v[26:29]
	v_mfma_f32_16x16x32_bf16 v[34:37], v[150:153], v[186:189], 0
	v_mfma_f32_16x16x32_bf16 v[34:37], v[166:169], v[190:193], v[34:37]
	v_mfma_f32_16x16x32_bf16 v[18:21], v[150:153], v[194:197], 0
	v_mfma_f32_16x16x32_bf16 v[18:21], v[166:169], v[198:201], v[18:21]
	v_mfma_f32_16x16x32_bf16 v[10:13], v[170:173], v[194:197], 0
	v_mfma_f32_16x16x32_bf16 v[10:13], v[174:177], v[198:201], v[10:13]
	v_mfma_f32_16x16x32_bf16 v[2:5], v[170:173], v[202:205], 0
	v_mfma_f32_16x16x32_bf16 v[2:5], v[174:177], v[206:209], v[2:5]
	s_setprio 2
	s_barrier
	v_mfma_f32_16x16x32_bf16 v[6:9], v[150:153], v[202:205], 0
	v_mfma_f32_16x16x32_bf16 v[6:9], v[166:169], v[206:209], v[6:9]
	s_setprio 0
	s_setprio 3
	ds_read_b128 v[134:137], v164
	ds_read_b128 v[138:141], v164 offset:1024
	ds_read_b128 v[142:145], v164 offset:2048
	ds_read_b128 v[146:149], v164 offset:3072
	ds_read_b128 v[150:153], v165
	ds_read_b128 v[166:169], v165 offset:1024
	ds_read_b128 v[170:173], v165 offset:2048
	ds_read_b128 v[174:177], v165 offset:3072
	ds_read_b128 v[178:181], v163 offset:32768
	ds_read_b128 v[182:185], v163 offset:33792
	ds_read_b128 v[186:189], v163 offset:34816
	ds_read_b128 v[190:193], v163 offset:35840
	ds_read_b128 v[194:197], v163 offset:36864
	ds_read_b128 v[198:201], v163 offset:37888
	ds_read_b128 v[202:205], v163 offset:38912
	ds_read_b128 v[206:209], v163 offset:39936
	s_mov_b32 s83, m0
	s_mov_b32 m0, s34
	s_nop 0
	global_load_lds_dwordx4 v1, s[24:25]
	s_mov_b32 m0, s83
	s_nop 0
	s_mov_b32 s83, m0
	s_mov_b32 m0, s42
	s_nop 0
	global_load_lds_dwordx4 v157, s[24:25]
	s_mov_b32 m0, s83
	s_add_u32 s24, s24, 0x4000
	s_addc_u32 s25, s25, 0
	s_mov_b32 s83, m0
	s_mov_b32 m0, s43
	s_nop 0
	global_load_lds_dwordx4 v1, s[24:25]
	s_mov_b32 m0, s83
	s_nop 0
	s_mov_b32 s83, m0
	s_mov_b32 m0, s46
	s_nop 0
	global_load_lds_dwordx4 v157, s[24:25]
	s_mov_b32 m0, s83
	s_setprio 0
	s_waitcnt vmcnt(8)
	s_waitcnt lgkmcnt(0)
	s_barrier
	s_setprio 1
	s_waitcnt lgkmcnt(7)
	v_mfma_f32_16x16x32_bf16 v[126:129], v[134:137], v[178:181], v[126:129]
	v_mfma_f32_16x16x32_bf16 v[126:129], v[138:141], v[182:185], v[126:129]
	s_waitcnt lgkmcnt(5)
	v_mfma_f32_16x16x32_bf16 v[122:125], v[142:145], v[178:181], v[122:125]
	v_mfma_f32_16x16x32_bf16 v[122:125], v[146:149], v[182:185], v[122:125]
	s_waitcnt lgkmcnt(3)
	v_mfma_f32_16x16x32_bf16 v[114:117], v[142:145], v[186:189], v[114:117]
	v_mfma_f32_16x16x32_bf16 v[114:117], v[146:149], v[190:193], v[114:117]
	s_waitcnt lgkmcnt(1)
	v_mfma_f32_16x16x32_bf16 v[118:121], v[134:137], v[186:189], v[118:121]
	v_mfma_f32_16x16x32_bf16 v[118:121], v[138:141], v[190:193], v[118:121]
	v_mfma_f32_16x16x32_bf16 v[102:105], v[134:137], v[194:197], v[102:105]
	v_mfma_f32_16x16x32_bf16 v[102:105], v[138:141], v[198:201], v[102:105]
	v_mfma_f32_16x16x32_bf16 v[94:97], v[142:145], v[194:197], v[94:97]
	v_mfma_f32_16x16x32_bf16 v[94:97], v[146:149], v[198:201], v[94:97]
	v_mfma_f32_16x16x32_bf16 v[78:81], v[142:145], v[202:205], v[78:81]
	v_mfma_f32_16x16x32_bf16 v[78:81], v[146:149], v[206:209], v[78:81]
	s_waitcnt lgkmcnt(0)
	v_mfma_f32_16x16x32_bf16 v[86:89], v[134:137], v[202:205], v[86:89]
	v_mfma_f32_16x16x32_bf16 v[86:89], v[138:141], v[206:209], v[86:89]
	s_setprio 0
	s_setprio 1
	v_mfma_f32_16x16x32_bf16 v[110:113], v[150:153], v[178:181], v[110:113]
	v_mfma_f32_16x16x32_bf16 v[110:113], v[166:169], v[182:185], v[110:113]
	v_mfma_f32_16x16x32_bf16 v[106:109], v[170:173], v[178:181], v[106:109]
	v_mfma_f32_16x16x32_bf16 v[106:109], v[174:177], v[182:185], v[106:109]
	v_mfma_f32_16x16x32_bf16 v[90:93], v[170:173], v[186:189], v[90:93]
	v_mfma_f32_16x16x32_bf16 v[90:93], v[174:177], v[190:193], v[90:93]
	v_mfma_f32_16x16x32_bf16 v[98:101], v[150:153], v[186:189], v[98:101]
	v_mfma_f32_16x16x32_bf16 v[98:101], v[166:169], v[190:193], v[98:101]
	v_mfma_f32_16x16x32_bf16 v[82:85], v[150:153], v[194:197], v[82:85]
	v_mfma_f32_16x16x32_bf16 v[82:85], v[166:169], v[198:201], v[82:85]
	v_mfma_f32_16x16x32_bf16 v[74:77], v[170:173], v[194:197], v[74:77]
	v_mfma_f32_16x16x32_bf16 v[74:77], v[174:177], v[198:201], v[74:77]
	v_mfma_f32_16x16x32_bf16 v[66:69], v[170:173], v[202:205], v[66:69]
	v_mfma_f32_16x16x32_bf16 v[66:69], v[174:177], v[206:209], v[66:69]
	s_setprio 2
	s_barrier
	v_mfma_f32_16x16x32_bf16 v[70:73], v[150:153], v[202:205], v[70:73]
	v_mfma_f32_16x16x32_bf16 v[70:73], v[166:169], v[206:209], v[70:73]
	s_setprio 0
	s_setprio 3
	ds_read_b128 v[178:181], v163 offset:49152
	ds_read_b128 v[182:185], v163 offset:50176
	ds_read_b128 v[186:189], v163 offset:51200
	ds_read_b128 v[190:193], v163 offset:52224
	ds_read_b128 v[194:197], v163 offset:53248
	ds_read_b128 v[198:201], v163 offset:54272
	ds_read_b128 v[202:205], v163 offset:55296
	ds_read_b128 v[206:209], v163 offset:56320
	s_add_u32 s24, s22, 0x40000
	s_addc_u32 s25, s23, 0
	s_mov_b32 s83, m0
	s_mov_b32 m0, s47
	s_nop 0
	global_load_lds_dwordx4 v156, s[24:25]
	s_mov_b32 m0, s83
	s_add_u32 s22, s22, 0x44000
	s_mov_b32 s83, m0
	s_mov_b32 m0, s48
	s_nop 0
	global_load_lds_dwordx4 v158, s[24:25]
	s_mov_b32 m0, s83
	s_addc_u32 s23, s23, 0
	s_mov_b32 s24, m0
	s_mov_b32 m0, s49
	s_nop 0
	global_load_lds_dwordx4 v156, s[22:23]
	s_mov_b32 m0, s24
	s_nop 0
	s_mov_b32 s24, m0
	s_mov_b32 m0, s56
	s_nop 0
	global_load_lds_dwordx4 v158, s[22:23]
	s_mov_b32 m0, s24
	s_setprio 0
	s_waitcnt vmcnt(4)
	s_waitcnt lgkmcnt(0)
	s_barrier
	s_setprio 1
	s_waitcnt lgkmcnt(7)
	v_mfma_f32_16x16x32_bf16 v[62:65], v[134:137], v[178:181], v[62:65]
	v_mfma_f32_16x16x32_bf16 v[62:65], v[138:141], v[182:185], v[62:65]
	s_waitcnt lgkmcnt(5)
	v_mfma_f32_16x16x32_bf16 v[58:61], v[142:145], v[178:181], v[58:61]
	v_mfma_f32_16x16x32_bf16 v[58:61], v[146:149], v[182:185], v[58:61]
	s_waitcnt lgkmcnt(3)
	v_mfma_f32_16x16x32_bf16 v[46:49], v[142:145], v[186:189], v[46:49]
	v_mfma_f32_16x16x32_bf16 v[46:49], v[146:149], v[190:193], v[46:49]
	s_waitcnt lgkmcnt(1)
	v_mfma_f32_16x16x32_bf16 v[54:57], v[134:137], v[186:189], v[54:57]
	v_mfma_f32_16x16x32_bf16 v[54:57], v[138:141], v[190:193], v[54:57]
	v_mfma_f32_16x16x32_bf16 v[38:41], v[134:137], v[194:197], v[38:41]
	v_mfma_f32_16x16x32_bf16 v[38:41], v[138:141], v[198:201], v[38:41]
	v_mfma_f32_16x16x32_bf16 v[30:33], v[142:145], v[194:197], v[30:33]
	v_mfma_f32_16x16x32_bf16 v[30:33], v[146:149], v[198:201], v[30:33]
	v_mfma_f32_16x16x32_bf16 v[14:17], v[142:145], v[202:205], v[14:17]
	v_mfma_f32_16x16x32_bf16 v[14:17], v[146:149], v[206:209], v[14:17]
	s_waitcnt lgkmcnt(0)
	v_mfma_f32_16x16x32_bf16 v[22:25], v[134:137], v[202:205], v[22:25]
	v_mfma_f32_16x16x32_bf16 v[22:25], v[138:141], v[206:209], v[22:25]
	s_setprio 0
	s_setprio 1
	v_mfma_f32_16x16x32_bf16 v[50:53], v[150:153], v[178:181], v[50:53]
	v_mfma_f32_16x16x32_bf16 v[50:53], v[166:169], v[182:185], v[50:53]
	v_mfma_f32_16x16x32_bf16 v[42:45], v[170:173], v[178:181], v[42:45]
	v_mfma_f32_16x16x32_bf16 v[42:45], v[174:177], v[182:185], v[42:45]
	v_mfma_f32_16x16x32_bf16 v[26:29], v[170:173], v[186:189], v[26:29]
	v_mfma_f32_16x16x32_bf16 v[26:29], v[174:177], v[190:193], v[26:29]
	v_mfma_f32_16x16x32_bf16 v[34:37], v[150:153], v[186:189], v[34:37]
	v_mfma_f32_16x16x32_bf16 v[34:37], v[166:169], v[190:193], v[34:37]
	v_mfma_f32_16x16x32_bf16 v[18:21], v[150:153], v[194:197], v[18:21]
	v_mfma_f32_16x16x32_bf16 v[18:21], v[166:169], v[198:201], v[18:21]
	v_mfma_f32_16x16x32_bf16 v[10:13], v[170:173], v[194:197], v[10:13]
	v_mfma_f32_16x16x32_bf16 v[10:13], v[174:177], v[198:201], v[10:13]
	v_mfma_f32_16x16x32_bf16 v[2:5], v[170:173], v[202:205], v[2:5]
	v_mfma_f32_16x16x32_bf16 v[2:5], v[174:177], v[206:209], v[2:5]
	s_setprio 2
	s_barrier
	v_mfma_f32_16x16x32_bf16 v[6:9], v[150:153], v[202:205], v[6:9]
	v_mfma_f32_16x16x32_bf16 v[6:9], v[166:169], v[206:209], v[6:9]
	s_setprio 0
	s_add_i32 s82, s82, 2
	s_add_u32 s78, s78, 0x80000
	s_addc_u32 s79, s79, 0
	s_add_u32 s20, s20, 0x400000
	s_addc_u32 s21, s21, 0
	s_add_u32 s80, s80, 0x400000
	s_addc_u32 s81, s81, 0
	s_cmpk_gt_u32 s82, 0x53
	.p2align 6
.LBB0_473:
	s_setprio 3
	ds_read_b128 v[134:137], v161
	ds_read_b128 v[138:141], v161 offset:1024
	ds_read_b128 v[142:145], v161 offset:2048
	ds_read_b128 v[146:149], v161 offset:3072
	ds_read_b128 v[150:153], v162
	ds_read_b128 v[166:169], v162 offset:1024
	ds_read_b128 v[170:173], v162 offset:2048
	ds_read_b128 v[174:177], v162 offset:3072
	s_cmpk_eq_i32 s82, 0x52
	s_cselect_b32 s23, s11, s79
	s_cselect_b32 s22, s77, s78
	s_cselect_b32 s25, s13, s81
	s_cselect_b32 s24, s76, s80
	ds_read_b128 v[178:181], v163
	ds_read_b128 v[182:185], v163 offset:1024
	ds_read_b128 v[186:189], v163 offset:2048
	ds_read_b128 v[190:193], v163 offset:3072
	ds_read_b128 v[194:197], v163 offset:4096
	ds_read_b128 v[198:201], v163 offset:5120
	ds_read_b128 v[202:205], v163 offset:6144
	ds_read_b128 v[206:209], v163 offset:7168
	s_add_u32 s86, s20, 0xffffc000
	s_addc_u32 s87, s21, -1
	s_mov_b32 s83, m0
	s_mov_b32 m0, s65
	s_nop 0
	global_load_lds_dwordx4 v1, s[86:87]
	s_mov_b32 m0, s83
	s_nop 0
	s_mov_b32 s83, m0
	s_mov_b32 m0, s67
	s_nop 0
	global_load_lds_dwordx4 v157, s[86:87]
	s_mov_b32 m0, s83
	s_nop 0
	s_mov_b32 s83, m0
	s_mov_b32 m0, s66
	s_nop 0
	global_load_lds_dwordx4 v1, s[20:21]
	s_mov_b32 m0, s83
	s_nop 0
	s_mov_b32 s83, m0
	s_mov_b32 m0, s73
	s_nop 0
	global_load_lds_dwordx4 v157, s[20:21]
	s_mov_b32 m0, s83
	s_setprio 0
	s_waitcnt vmcnt(8)
	s_waitcnt lgkmcnt(0)
	s_barrier
	s_setprio 1
	s_waitcnt lgkmcnt(7)
	v_mfma_f32_16x16x32_bf16 v[126:129], v[134:137], v[178:181], v[126:129]
	v_mfma_f32_16x16x32_bf16 v[126:129], v[138:141], v[182:185], v[126:129]
	s_waitcnt lgkmcnt(5)
	v_mfma_f32_16x16x32_bf16 v[122:125], v[142:145], v[178:181], v[122:125]
	v_mfma_f32_16x16x32_bf16 v[122:125], v[146:149], v[182:185], v[122:125]
	s_waitcnt lgkmcnt(3)
	v_mfma_f32_16x16x32_bf16 v[114:117], v[142:145], v[186:189], v[114:117]
	v_mfma_f32_16x16x32_bf16 v[114:117], v[146:149], v[190:193], v[114:117]
	s_waitcnt lgkmcnt(1)
	v_mfma_f32_16x16x32_bf16 v[118:121], v[134:137], v[186:189], v[118:121]
	v_mfma_f32_16x16x32_bf16 v[118:121], v[138:141], v[190:193], v[118:121]
	v_mfma_f32_16x16x32_bf16 v[102:105], v[134:137], v[194:197], v[102:105]
	v_mfma_f32_16x16x32_bf16 v[102:105], v[138:141], v[198:201], v[102:105]
	v_mfma_f32_16x16x32_bf16 v[94:97], v[142:145], v[194:197], v[94:97]
	v_mfma_f32_16x16x32_bf16 v[94:97], v[146:149], v[198:201], v[94:97]
	v_mfma_f32_16x16x32_bf16 v[78:81], v[142:145], v[202:205], v[78:81]
	v_mfma_f32_16x16x32_bf16 v[78:81], v[146:149], v[206:209], v[78:81]
	s_waitcnt lgkmcnt(0)
	v_mfma_f32_16x16x32_bf16 v[86:89], v[134:137], v[202:205], v[86:89]
	v_mfma_f32_16x16x32_bf16 v[86:89], v[138:141], v[206:209], v[86:89]
	s_setprio 0
	s_setprio 1
	v_mfma_f32_16x16x32_bf16 v[110:113], v[150:153], v[178:181], v[110:113]
	v_mfma_f32_16x16x32_bf16 v[110:113], v[166:169], v[182:185], v[110:113]
	v_mfma_f32_16x16x32_bf16 v[106:109], v[170:173], v[178:181], v[106:109]
	v_mfma_f32_16x16x32_bf16 v[106:109], v[174:177], v[182:185], v[106:109]
	v_mfma_f32_16x16x32_bf16 v[90:93], v[170:173], v[186:189], v[90:93]
	v_mfma_f32_16x16x32_bf16 v[90:93], v[174:177], v[190:193], v[90:93]
	v_mfma_f32_16x16x32_bf16 v[98:101], v[150:153], v[186:189], v[98:101]
	v_mfma_f32_16x16x32_bf16 v[98:101], v[166:169], v[190:193], v[98:101]
	v_mfma_f32_16x16x32_bf16 v[82:85], v[150:153], v[194:197], v[82:85]
	v_mfma_f32_16x16x32_bf16 v[82:85], v[166:169], v[198:201], v[82:85]
	v_mfma_f32_16x16x32_bf16 v[74:77], v[170:173], v[194:197], v[74:77]
	v_mfma_f32_16x16x32_bf16 v[74:77], v[174:177], v[198:201], v[74:77]
	v_mfma_f32_16x16x32_bf16 v[66:69], v[170:173], v[202:205], v[66:69]
	v_mfma_f32_16x16x32_bf16 v[66:69], v[174:177], v[206:209], v[66:69]
	s_setprio 2
	s_barrier
	v_mfma_f32_16x16x32_bf16 v[70:73], v[150:153], v[202:205], v[70:73]
	v_mfma_f32_16x16x32_bf16 v[70:73], v[166:169], v[206:209], v[70:73]
	s_setprio 0
	s_setprio 3
	ds_read_b128 v[178:181], v163 offset:16384
	ds_read_b128 v[182:185], v163 offset:17408
	ds_read_b128 v[186:189], v163 offset:18432
	ds_read_b128 v[190:193], v163 offset:19456
	ds_read_b128 v[194:197], v163 offset:20480
	ds_read_b128 v[198:201], v163 offset:21504
	ds_read_b128 v[202:205], v163 offset:22528
	ds_read_b128 v[206:209], v163 offset:23552
	s_mov_b32 s83, m0
	s_mov_b32 m0, s19
	s_nop 0
	global_load_lds_dwordx4 v156, s[22:23]
	s_mov_b32 m0, s83
	s_add_u32 s86, s22, 0x4000
	s_mov_b32 s83, m0
	s_mov_b32 m0, s35
	s_nop 0
	global_load_lds_dwordx4 v158, s[22:23]
	s_mov_b32 m0, s83
	s_addc_u32 s87, s23, 0
	s_mov_b32 s83, m0
	s_mov_b32 m0, s36
	s_nop 0
	global_load_lds_dwordx4 v156, s[86:87]
	s_mov_b32 m0, s83
	s_nop 0
	s_mov_b32 s83, m0
	s_mov_b32 m0, s37
	s_nop 0
	global_load_lds_dwordx4 v158, s[86:87]
	s_mov_b32 m0, s83
	s_setprio 0
	s_waitcnt vmcnt(4)
	s_waitcnt lgkmcnt(0)
	s_barrier
	s_setprio 1
	s_waitcnt lgkmcnt(7)
	v_mfma_f32_16x16x32_bf16 v[62:65], v[134:137], v[178:181], v[62:65]
	v_mfma_f32_16x16x32_bf16 v[62:65], v[138:141], v[182:185], v[62:65]
	s_waitcnt lgkmcnt(5)
	v_mfma_f32_16x16x32_bf16 v[58:61], v[142:145], v[178:181], v[58:61]
	v_mfma_f32_16x16x32_bf16 v[58:61], v[146:149], v[182:185], v[58:61]
	s_waitcnt lgkmcnt(3)
	v_mfma_f32_16x16x32_bf16 v[46:49], v[142:145], v[186:189], v[46:49]
	v_mfma_f32_16x16x32_bf16 v[46:49], v[146:149], v[190:193], v[46:49]
	s_waitcnt lgkmcnt(1)
	v_mfma_f32_16x16x32_bf16 v[54:57], v[134:137], v[186:189], v[54:57]
	v_mfma_f32_16x16x32_bf16 v[54:57], v[138:141], v[190:193], v[54:57]
	v_mfma_f32_16x16x32_bf16 v[38:41], v[134:137], v[194:197], v[38:41]
	v_mfma_f32_16x16x32_bf16 v[38:41], v[138:141], v[198:201], v[38:41]
	v_mfma_f32_16x16x32_bf16 v[30:33], v[142:145], v[194:197], v[30:33]
	v_mfma_f32_16x16x32_bf16 v[30:33], v[146:149], v[198:201], v[30:33]
	v_mfma_f32_16x16x32_bf16 v[14:17], v[142:145], v[202:205], v[14:17]
	v_mfma_f32_16x16x32_bf16 v[14:17], v[146:149], v[206:209], v[14:17]
	s_waitcnt lgkmcnt(0)
	v_mfma_f32_16x16x32_bf16 v[22:25], v[134:137], v[202:205], v[22:25]
	v_mfma_f32_16x16x32_bf16 v[22:25], v[138:141], v[206:209], v[22:25]
	s_setprio 0
	s_setprio 1
	v_mfma_f32_16x16x32_bf16 v[50:53], v[150:153], v[178:181], v[50:53]
	v_mfma_f32_16x16x32_bf16 v[50:53], v[166:169], v[182:185], v[50:53]
	v_mfma_f32_16x16x32_bf16 v[42:45], v[170:173], v[178:181], v[42:45]
	v_mfma_f32_16x16x32_bf16 v[42:45], v[174:177], v[182:185], v[42:45]
	v_mfma_f32_16x16x32_bf16 v[26:29], v[170:173], v[186:189], v[26:29]
	v_mfma_f32_16x16x32_bf16 v[26:29], v[174:177], v[190:193], v[26:29]
	v_mfma_f32_16x16x32_bf16 v[34:37], v[150:153], v[186:189], v[34:37]
	v_mfma_f32_16x16x32_bf16 v[34:37], v[166:169], v[190:193], v[34:37]
	v_mfma_f32_16x16x32_bf16 v[18:21], v[150:153], v[194:197], v[18:21]
	v_mfma_f32_16x16x32_bf16 v[18:21], v[166:169], v[198:201], v[18:21]
	v_mfma_f32_16x16x32_bf16 v[10:13], v[170:173], v[194:197], v[10:13]
	v_mfma_f32_16x16x32_bf16 v[10:13], v[174:177], v[198:201], v[10:13]
	v_mfma_f32_16x16x32_bf16 v[2:5], v[170:173], v[202:205], v[2:5]
	v_mfma_f32_16x16x32_bf16 v[2:5], v[174:177], v[206:209], v[2:5]
	s_setprio 2
	s_barrier
	v_mfma_f32_16x16x32_bf16 v[6:9], v[150:153], v[202:205], v[6:9]
	v_mfma_f32_16x16x32_bf16 v[6:9], v[166:169], v[206:209], v[6:9]
	s_setprio 0
	s_setprio 3
	ds_read_b128 v[134:137], v164
	ds_read_b128 v[138:141], v164 offset:1024
	ds_read_b128 v[142:145], v164 offset:2048
	ds_read_b128 v[146:149], v164 offset:3072
	ds_read_b128 v[150:153], v165
	ds_read_b128 v[166:169], v165 offset:1024
	ds_read_b128 v[170:173], v165 offset:2048
	ds_read_b128 v[174:177], v165 offset:3072
	ds_read_b128 v[178:181], v163 offset:32768
	ds_read_b128 v[182:185], v163 offset:33792
	ds_read_b128 v[186:189], v163 offset:34816
	ds_read_b128 v[190:193], v163 offset:35840
	ds_read_b128 v[194:197], v163 offset:36864
	ds_read_b128 v[198:201], v163 offset:37888
	ds_read_b128 v[202:205], v163 offset:38912
	ds_read_b128 v[206:209], v163 offset:39936
	s_mov_b32 s83, m0
	s_mov_b32 m0, s34
	s_nop 0
	global_load_lds_dwordx4 v1, s[24:25]
	s_mov_b32 m0, s83
	s_nop 0
	s_mov_b32 s83, m0
	s_mov_b32 m0, s42
	s_nop 0
	global_load_lds_dwordx4 v157, s[24:25]
	s_mov_b32 m0, s83
	s_add_u32 s24, s24, 0x4000
	s_addc_u32 s25, s25, 0
	s_mov_b32 s83, m0
	s_mov_b32 m0, s43
	s_nop 0
	global_load_lds_dwordx4 v1, s[24:25]
	s_mov_b32 m0, s83
	s_nop 0
	s_mov_b32 s83, m0
	s_mov_b32 m0, s46
	s_nop 0
	global_load_lds_dwordx4 v157, s[24:25]
	s_mov_b32 m0, s83
	s_setprio 0
	s_waitcnt vmcnt(8)
	s_waitcnt lgkmcnt(0)
	s_barrier
	s_setprio 1
	s_waitcnt lgkmcnt(7)
	v_mfma_f32_16x16x32_bf16 v[126:129], v[134:137], v[178:181], v[126:129]
	v_mfma_f32_16x16x32_bf16 v[126:129], v[138:141], v[182:185], v[126:129]
	s_waitcnt lgkmcnt(5)
	v_mfma_f32_16x16x32_bf16 v[122:125], v[142:145], v[178:181], v[122:125]
	v_mfma_f32_16x16x32_bf16 v[122:125], v[146:149], v[182:185], v[122:125]
	s_waitcnt lgkmcnt(3)
	v_mfma_f32_16x16x32_bf16 v[114:117], v[142:145], v[186:189], v[114:117]
	v_mfma_f32_16x16x32_bf16 v[114:117], v[146:149], v[190:193], v[114:117]
	s_waitcnt lgkmcnt(1)
	v_mfma_f32_16x16x32_bf16 v[118:121], v[134:137], v[186:189], v[118:121]
	v_mfma_f32_16x16x32_bf16 v[118:121], v[138:141], v[190:193], v[118:121]
	v_mfma_f32_16x16x32_bf16 v[102:105], v[134:137], v[194:197], v[102:105]
	v_mfma_f32_16x16x32_bf16 v[102:105], v[138:141], v[198:201], v[102:105]
	v_mfma_f32_16x16x32_bf16 v[94:97], v[142:145], v[194:197], v[94:97]
	v_mfma_f32_16x16x32_bf16 v[94:97], v[146:149], v[198:201], v[94:97]
	v_mfma_f32_16x16x32_bf16 v[78:81], v[142:145], v[202:205], v[78:81]
	v_mfma_f32_16x16x32_bf16 v[78:81], v[146:149], v[206:209], v[78:81]
	s_waitcnt lgkmcnt(0)
	v_mfma_f32_16x16x32_bf16 v[86:89], v[134:137], v[202:205], v[86:89]
	v_mfma_f32_16x16x32_bf16 v[86:89], v[138:141], v[206:209], v[86:89]
	s_setprio 0
	s_setprio 1
	v_mfma_f32_16x16x32_bf16 v[110:113], v[150:153], v[178:181], v[110:113]
	v_mfma_f32_16x16x32_bf16 v[110:113], v[166:169], v[182:185], v[110:113]
	v_mfma_f32_16x16x32_bf16 v[106:109], v[170:173], v[178:181], v[106:109]
	v_mfma_f32_16x16x32_bf16 v[106:109], v[174:177], v[182:185], v[106:109]
	v_mfma_f32_16x16x32_bf16 v[90:93], v[170:173], v[186:189], v[90:93]
	v_mfma_f32_16x16x32_bf16 v[90:93], v[174:177], v[190:193], v[90:93]
	v_mfma_f32_16x16x32_bf16 v[98:101], v[150:153], v[186:189], v[98:101]
	v_mfma_f32_16x16x32_bf16 v[98:101], v[166:169], v[190:193], v[98:101]
	v_mfma_f32_16x16x32_bf16 v[82:85], v[150:153], v[194:197], v[82:85]
	v_mfma_f32_16x16x32_bf16 v[82:85], v[166:169], v[198:201], v[82:85]
	v_mfma_f32_16x16x32_bf16 v[74:77], v[170:173], v[194:197], v[74:77]
	v_mfma_f32_16x16x32_bf16 v[74:77], v[174:177], v[198:201], v[74:77]
	v_mfma_f32_16x16x32_bf16 v[66:69], v[170:173], v[202:205], v[66:69]
	v_mfma_f32_16x16x32_bf16 v[66:69], v[174:177], v[206:209], v[66:69]
	s_setprio 2
	s_barrier
	v_mfma_f32_16x16x32_bf16 v[70:73], v[150:153], v[202:205], v[70:73]
	v_mfma_f32_16x16x32_bf16 v[70:73], v[166:169], v[206:209], v[70:73]
	s_setprio 0
	s_setprio 3
	ds_read_b128 v[178:181], v163 offset:49152
	ds_read_b128 v[182:185], v163 offset:50176
	ds_read_b128 v[186:189], v163 offset:51200
	ds_read_b128 v[190:193], v163 offset:52224
	ds_read_b128 v[194:197], v163 offset:53248
	ds_read_b128 v[198:201], v163 offset:54272
	ds_read_b128 v[202:205], v163 offset:55296
	ds_read_b128 v[206:209], v163 offset:56320
	s_add_u32 s24, s22, 0x40000
	s_addc_u32 s25, s23, 0
	s_mov_b32 s83, m0
	s_mov_b32 m0, s47
	s_nop 0
	global_load_lds_dwordx4 v156, s[24:25]
	s_mov_b32 m0, s83
	s_add_u32 s22, s22, 0x44000
	s_mov_b32 s83, m0
	s_mov_b32 m0, s48
	s_nop 0
	global_load_lds_dwordx4 v158, s[24:25]
	s_mov_b32 m0, s83
	s_addc_u32 s23, s23, 0
	s_mov_b32 s24, m0
	s_mov_b32 m0, s49
	s_nop 0
	global_load_lds_dwordx4 v156, s[22:23]
	s_mov_b32 m0, s24
	s_nop 0
	s_mov_b32 s24, m0
	s_mov_b32 m0, s56
	s_nop 0
	global_load_lds_dwordx4 v158, s[22:23]
	s_mov_b32 m0, s24
	s_setprio 0
	s_waitcnt vmcnt(4)
	s_waitcnt lgkmcnt(0)
	s_barrier
	s_setprio 1
	s_waitcnt lgkmcnt(7)
	v_mfma_f32_16x16x32_bf16 v[62:65], v[134:137], v[178:181], v[62:65]
	v_mfma_f32_16x16x32_bf16 v[62:65], v[138:141], v[182:185], v[62:65]
	s_waitcnt lgkmcnt(5)
	v_mfma_f32_16x16x32_bf16 v[58:61], v[142:145], v[178:181], v[58:61]
	v_mfma_f32_16x16x32_bf16 v[58:61], v[146:149], v[182:185], v[58:61]
	s_waitcnt lgkmcnt(3)
	v_mfma_f32_16x16x32_bf16 v[46:49], v[142:145], v[186:189], v[46:49]
	v_mfma_f32_16x16x32_bf16 v[46:49], v[146:149], v[190:193], v[46:49]
	s_waitcnt lgkmcnt(1)
	v_mfma_f32_16x16x32_bf16 v[54:57], v[134:137], v[186:189], v[54:57]
	v_mfma_f32_16x16x32_bf16 v[54:57], v[138:141], v[190:193], v[54:57]
	v_mfma_f32_16x16x32_bf16 v[38:41], v[134:137], v[194:197], v[38:41]
	v_mfma_f32_16x16x32_bf16 v[38:41], v[138:141], v[198:201], v[38:41]
	v_mfma_f32_16x16x32_bf16 v[30:33], v[142:145], v[194:197], v[30:33]
	v_mfma_f32_16x16x32_bf16 v[30:33], v[146:149], v[198:201], v[30:33]
	v_mfma_f32_16x16x32_bf16 v[14:17], v[142:145], v[202:205], v[14:17]
	v_mfma_f32_16x16x32_bf16 v[14:17], v[146:149], v[206:209], v[14:17]
	s_waitcnt lgkmcnt(0)
	v_mfma_f32_16x16x32_bf16 v[22:25], v[134:137], v[202:205], v[22:25]
	v_mfma_f32_16x16x32_bf16 v[22:25], v[138:141], v[206:209], v[22:25]
	s_setprio 0
	s_setprio 1
	v_mfma_f32_16x16x32_bf16 v[50:53], v[150:153], v[178:181], v[50:53]
	v_mfma_f32_16x16x32_bf16 v[50:53], v[166:169], v[182:185], v[50:53]
	v_mfma_f32_16x16x32_bf16 v[42:45], v[170:173], v[178:181], v[42:45]
	v_mfma_f32_16x16x32_bf16 v[42:45], v[174:177], v[182:185], v[42:45]
	v_mfma_f32_16x16x32_bf16 v[26:29], v[170:173], v[186:189], v[26:29]
	v_mfma_f32_16x16x32_bf16 v[26:29], v[174:177], v[190:193], v[26:29]
	v_mfma_f32_16x16x32_bf16 v[34:37], v[150:153], v[186:189], v[34:37]
	v_mfma_f32_16x16x32_bf16 v[34:37], v[166:169], v[190:193], v[34:37]
	v_mfma_f32_16x16x32_bf16 v[18:21], v[150:153], v[194:197], v[18:21]
	v_mfma_f32_16x16x32_bf16 v[18:21], v[166:169], v[198:201], v[18:21]
	v_mfma_f32_16x16x32_bf16 v[10:13], v[170:173], v[194:197], v[10:13]
	v_mfma_f32_16x16x32_bf16 v[10:13], v[174:177], v[198:201], v[10:13]
	v_mfma_f32_16x16x32_bf16 v[2:5], v[170:173], v[202:205], v[2:5]
	v_mfma_f32_16x16x32_bf16 v[2:5], v[174:177], v[206:209], v[2:5]
	s_setprio 2
	s_barrier
	v_mfma_f32_16x16x32_bf16 v[6:9], v[150:153], v[202:205], v[6:9]
	v_mfma_f32_16x16x32_bf16 v[6:9], v[166:169], v[206:209], v[6:9]
	s_setprio 0
	s_add_i32 s82, s82, 2
	s_add_u32 s78, s78, 0x80000
	s_addc_u32 s79, s79, 0
	s_add_u32 s20, s20, 0x400000
	s_addc_u32 s21, s21, 0
	s_add_u32 s80, s80, 0x400000
	s_addc_u32 s81, s81, 0
	s_cmpk_gt_u32 s82, 0x53
	s_cbranch_scc0 .LBB0_473
	s_and_b64 vcc, exec, s[8:9]
	s_cbranch_vccz .LBB0_476
	s_barrier

.LBB0_653:
	s_ashr_i32 s23, s22, 31
	s_lshl_b64 s[24:25], s[22:23], 20
	s_add_u32 s24, s35, s24
	s_addc_u32 s25, s36, s25
	s_and_b64 s[26:27], s[2:3], exec
	s_cselect_b32 s7, s25, s11
	s_cselect_b32 s9, s24, s10
	s_ashr_i32 s21, s20, 31
	s_lshl_b64 s[26:27], s[20:21], 20
	s_add_u32 s26, s37, s26
	s_addc_u32 s27, s40, s27
	s_and_b64 s[28:29], s[2:3], exec
	s_cselect_b32 s21, s27, s5
	s_cselect_b32 s23, s26, s4
	s_add_u32 s30, s4, 0x100
	s_addc_u32 s31, s5, 0
	s_add_u32 s4, s10, 0x80080
	s_addc_u32 s5, s11, 0
	s_add_u32 s33, s10, 0x100
	s_addc_u32 s73, s11, 0
	s_mov_b32 s74, -2
	s_waitcnt vmcnt(25)
	s_waitcnt vmcnt(24)
	s_waitcnt vmcnt(15)
	s_waitcnt vmcnt(14)
	s_waitcnt vmcnt(13)
	s_waitcnt vmcnt(12)
	s_waitcnt vmcnt(11)
	s_waitcnt vmcnt(10)
	s_waitcnt vmcnt(9)
	s_waitcnt vmcnt(8)
	s_waitcnt vmcnt(7)
	s_waitcnt vmcnt(6)
	s_waitcnt vmcnt(5)
	s_waitcnt vmcnt(4)
	s_waitcnt vmcnt(3)
	s_waitcnt vmcnt(2)
	s_waitcnt vmcnt(1)
	s_waitcnt vmcnt(0)
	s_setprio 3
	ds_read_b128 v[130:133], v161
	ds_read_b128 v[138:141], v161 offset:1024
	ds_read_b128 v[142:145], v161 offset:2048
	ds_read_b128 v[146:149], v161 offset:3072
	ds_read_b128 v[150:153], v162
	ds_read_b128 v[168:171], v162 offset:1024
	ds_read_b128 v[172:175], v162 offset:2048
	ds_read_b128 v[176:179], v162 offset:3072
	s_cmp_eq_u32 s74, 28
	s_cselect_b32 s11, s21, s31
	s_cselect_b32 s10, s23, s30
	s_cselect_b32 s29, s7, s73
	s_cselect_b32 s28, s9, s33
	ds_read_b128 v[180:183], v163
	ds_read_b128 v[184:187], v163 offset:1024
	ds_read_b128 v[188:191], v163 offset:2048
	ds_read_b128 v[192:195], v163 offset:3072
	ds_read_b128 v[196:199], v163 offset:4096
	ds_read_b128 v[200:203], v163 offset:5120
	ds_read_b128 v[204:207], v163 offset:6144
	ds_read_b128 v[208:211], v163 offset:7168
	s_add_u32 s76, s4, 0xfff80000
	s_addc_u32 s77, s5, -1
	s_mov_b32 s75, m0
	s_mov_b32 m0, s80
	s_nop 0
	global_load_lds_dwordx4 v1, s[76:77]
	s_mov_b32 m0, s75
	s_nop 0
	s_mov_b32 s75, m0
	s_mov_b32 m0, s82
	s_nop 0
	global_load_lds_dwordx4 v157, s[76:77]
	s_mov_b32 m0, s75
	s_nop 0
	s_mov_b32 s75, m0
	s_mov_b32 m0, s81
	s_nop 0
	global_load_lds_dwordx4 v1, s[4:5]
	s_mov_b32 m0, s75
	s_nop 0
	s_mov_b32 s75, m0
	s_mov_b32 m0, s83
	s_nop 0
	global_load_lds_dwordx4 v157, s[4:5]
	s_mov_b32 m0, s75
	s_setprio 0
	s_waitcnt vmcnt(8)
	s_waitcnt lgkmcnt(0)
	s_barrier
	s_setprio 1
	s_waitcnt lgkmcnt(7)
	v_mfma_f32_16x16x32_bf16 v[126:129], v[130:133], v[180:183], 0
	v_mfma_f32_16x16x32_bf16 v[126:129], v[138:141], v[184:187], v[126:129]
	s_waitcnt lgkmcnt(5)
	v_mfma_f32_16x16x32_bf16 v[122:125], v[142:145], v[180:183], 0
	v_mfma_f32_16x16x32_bf16 v[122:125], v[146:149], v[184:187], v[122:125]
	s_waitcnt lgkmcnt(3)
	v_mfma_f32_16x16x32_bf16 v[106:109], v[142:145], v[188:191], 0
	v_mfma_f32_16x16x32_bf16 v[106:109], v[146:149], v[192:195], v[106:109]
	s_waitcnt lgkmcnt(1)
	v_mfma_f32_16x16x32_bf16 v[110:113], v[130:133], v[188:191], 0
	v_mfma_f32_16x16x32_bf16 v[110:113], v[138:141], v[192:195], v[110:113]
	v_mfma_f32_16x16x32_bf16 v[94:97], v[130:133], v[196:199], 0
	v_mfma_f32_16x16x32_bf16 v[94:97], v[138:141], v[200:203], v[94:97]
	v_mfma_f32_16x16x32_bf16 v[90:93], v[142:145], v[196:199], 0
	v_mfma_f32_16x16x32_bf16 v[90:93], v[146:149], v[200:203], v[90:93]
	v_mfma_f32_16x16x32_bf16 v[74:77], v[142:145], v[204:207], 0
	v_mfma_f32_16x16x32_bf16 v[74:77], v[146:149], v[208:211], v[74:77]
	s_waitcnt lgkmcnt(0)
	v_mfma_f32_16x16x32_bf16 v[78:81], v[130:133], v[204:207], 0
	v_mfma_f32_16x16x32_bf16 v[78:81], v[138:141], v[208:211], v[78:81]
	s_setprio 0
	s_setprio 1
	v_mfma_f32_16x16x32_bf16 v[118:121], v[150:153], v[180:183], 0
	v_mfma_f32_16x16x32_bf16 v[118:121], v[168:171], v[184:187], v[118:121]
	v_mfma_f32_16x16x32_bf16 v[114:117], v[172:175], v[180:183], 0
	v_mfma_f32_16x16x32_bf16 v[114:117], v[176:179], v[184:187], v[114:117]
	v_mfma_f32_16x16x32_bf16 v[98:101], v[172:175], v[188:191], 0
	v_mfma_f32_16x16x32_bf16 v[98:101], v[176:179], v[192:195], v[98:101]
	v_mfma_f32_16x16x32_bf16 v[102:105], v[150:153], v[188:191], 0
	v_mfma_f32_16x16x32_bf16 v[102:105], v[168:171], v[192:195], v[102:105]
	v_mfma_f32_16x16x32_bf16 v[86:89], v[150:153], v[196:199], 0
	v_mfma_f32_16x16x32_bf16 v[86:89], v[168:171], v[200:203], v[86:89]
	v_mfma_f32_16x16x32_bf16 v[82:85], v[172:175], v[196:199], 0
	v_mfma_f32_16x16x32_bf16 v[82:85], v[176:179], v[200:203], v[82:85]
	v_mfma_f32_16x16x32_bf16 v[66:69], v[172:175], v[204:207], 0
	v_mfma_f32_16x16x32_bf16 v[66:69], v[176:179], v[208:211], v[66:69]
	s_setprio 2
	s_barrier
	v_mfma_f32_16x16x32_bf16 v[70:73], v[150:153], v[204:207], 0
	v_mfma_f32_16x16x32_bf16 v[70:73], v[168:171], v[208:211], v[70:73]
	s_setprio 0
	s_setprio 3
	ds_read_b128 v[180:183], v163 offset:16384
	ds_read_b128 v[184:187], v163 offset:17408
	ds_read_b128 v[188:191], v163 offset:18432
	ds_read_b128 v[192:195], v163 offset:19456
	ds_read_b128 v[196:199], v163 offset:20480
	ds_read_b128 v[200:203], v163 offset:21504
	ds_read_b128 v[204:207], v163 offset:22528
	ds_read_b128 v[208:211], v163 offset:23552
	s_mov_b32 s75, m0
	s_mov_b32 m0, s43
	s_nop 0
	global_load_lds_dwordx4 v156, s[10:11]
	s_mov_b32 m0, s75
	s_add_u32 s76, s10, 0x80000
	s_mov_b32 s75, m0
	s_mov_b32 m0, s46
	s_nop 0
	global_load_lds_dwordx4 v158, s[10:11]
	s_mov_b32 m0, s75
	s_addc_u32 s77, s11, 0
	s_mov_b32 s75, m0
	s_mov_b32 m0, s47
	s_nop 0
	global_load_lds_dwordx4 v156, s[76:77]
	s_mov_b32 m0, s75
	s_nop 0
	s_mov_b32 s75, m0
	s_mov_b32 m0, s48
	s_nop 0
	global_load_lds_dwordx4 v158, s[76:77]
	s_mov_b32 m0, s75
	s_setprio 0
	s_waitcnt vmcnt(4)
	s_waitcnt lgkmcnt(0)
	s_barrier
	s_setprio 1
	s_waitcnt lgkmcnt(7)
	v_mfma_f32_16x16x32_bf16 v[62:65], v[130:133], v[180:183], 0
	v_mfma_f32_16x16x32_bf16 v[62:65], v[138:141], v[184:187], v[62:65]
	s_waitcnt lgkmcnt(5)
	v_mfma_f32_16x16x32_bf16 v[58:61], v[142:145], v[180:183], 0
	v_mfma_f32_16x16x32_bf16 v[58:61], v[146:149], v[184:187], v[58:61]
	s_waitcnt lgkmcnt(3)
	v_mfma_f32_16x16x32_bf16 v[42:45], v[142:145], v[188:191], 0
	v_mfma_f32_16x16x32_bf16 v[42:45], v[146:149], v[192:195], v[42:45]
	s_waitcnt lgkmcnt(1)
	v_mfma_f32_16x16x32_bf16 v[46:49], v[130:133], v[188:191], 0
	v_mfma_f32_16x16x32_bf16 v[46:49], v[138:141], v[192:195], v[46:49]
	v_mfma_f32_16x16x32_bf16 v[30:33], v[130:133], v[196:199], 0
	v_mfma_f32_16x16x32_bf16 v[30:33], v[138:141], v[200:203], v[30:33]
	v_mfma_f32_16x16x32_bf16 v[26:29], v[142:145], v[196:199], 0
	v_mfma_f32_16x16x32_bf16 v[26:29], v[146:149], v[200:203], v[26:29]
	v_mfma_f32_16x16x32_bf16 v[10:13], v[142:145], v[204:207], 0
	v_mfma_f32_16x16x32_bf16 v[10:13], v[146:149], v[208:211], v[10:13]
	s_waitcnt lgkmcnt(0)
	v_mfma_f32_16x16x32_bf16 v[14:17], v[130:133], v[204:207], 0
	v_mfma_f32_16x16x32_bf16 v[14:17], v[138:141], v[208:211], v[14:17]
	s_setprio 0
	s_setprio 1
	v_mfma_f32_16x16x32_bf16 v[54:57], v[150:153], v[180:183], 0
	v_mfma_f32_16x16x32_bf16 v[54:57], v[168:171], v[184:187], v[54:57]
	v_mfma_f32_16x16x32_bf16 v[50:53], v[172:175], v[180:183], 0
	v_mfma_f32_16x16x32_bf16 v[50:53], v[176:179], v[184:187], v[50:53]
	v_mfma_f32_16x16x32_bf16 v[34:37], v[172:175], v[188:191], 0
	v_mfma_f32_16x16x32_bf16 v[34:37], v[176:179], v[192:195], v[34:37]
	v_mfma_f32_16x16x32_bf16 v[38:41], v[150:153], v[188:191], 0
	v_mfma_f32_16x16x32_bf16 v[38:41], v[168:171], v[192:195], v[38:41]
	v_mfma_f32_16x16x32_bf16 v[22:25], v[150:153], v[196:199], 0
	v_mfma_f32_16x16x32_bf16 v[22:25], v[168:171], v[200:203], v[22:25]
	v_mfma_f32_16x16x32_bf16 v[18:21], v[172:175], v[196:199], 0
	v_mfma_f32_16x16x32_bf16 v[18:21], v[176:179], v[200:203], v[18:21]
	v_mfma_f32_16x16x32_bf16 v[2:5], v[172:175], v[204:207], 0
	v_mfma_f32_16x16x32_bf16 v[2:5], v[176:179], v[208:211], v[2:5]
	s_setprio 2
	s_barrier
	v_mfma_f32_16x16x32_bf16 v[6:9], v[150:153], v[204:207], 0
	v_mfma_f32_16x16x32_bf16 v[6:9], v[168:171], v[208:211], v[6:9]
	s_setprio 0
	s_setprio 3
	ds_read_b128 v[130:133], v164
	ds_read_b128 v[138:141], v164 offset:1024
	ds_read_b128 v[142:145], v164 offset:2048
	ds_read_b128 v[146:149], v164 offset:3072
	ds_read_b128 v[150:153], v165
	ds_read_b128 v[168:171], v165 offset:1024
	ds_read_b128 v[172:175], v165 offset:2048
	ds_read_b128 v[176:179], v165 offset:3072
	ds_read_b128 v[180:183], v163 offset:32768
	ds_read_b128 v[184:187], v163 offset:33792
	ds_read_b128 v[188:191], v163 offset:34816
	ds_read_b128 v[192:195], v163 offset:35840
	ds_read_b128 v[196:199], v163 offset:36864
	ds_read_b128 v[200:203], v163 offset:37888
	ds_read_b128 v[204:207], v163 offset:38912
	ds_read_b128 v[208:211], v163 offset:39936
	s_mov_b32 s75, m0
	s_mov_b32 m0, s42
	s_nop 0
	global_load_lds_dwordx4 v1, s[28:29]
	s_mov_b32 m0, s75
	s_nop 0
	s_mov_b32 s75, m0
	s_mov_b32 m0, s49
	s_nop 0
	global_load_lds_dwordx4 v157, s[28:29]
	s_mov_b32 m0, s75
	s_add_u32 s28, s28, 0x80000
	s_addc_u32 s29, s29, 0
	s_mov_b32 s75, m0
	s_mov_b32 m0, s56
	s_nop 0
	global_load_lds_dwordx4 v1, s[28:29]
	s_mov_b32 m0, s75
	s_nop 0
	s_mov_b32 s75, m0
	s_mov_b32 m0, s57
	s_nop 0
	global_load_lds_dwordx4 v157, s[28:29]
	s_mov_b32 m0, s75
	s_setprio 0
	s_waitcnt vmcnt(8)
	s_waitcnt lgkmcnt(0)
	s_barrier
	s_setprio 1
	s_waitcnt lgkmcnt(7)
	v_mfma_f32_16x16x32_bf16 v[126:129], v[130:133], v[180:183], v[126:129]
	v_mfma_f32_16x16x32_bf16 v[126:129], v[138:141], v[184:187], v[126:129]
	s_waitcnt lgkmcnt(5)
	v_mfma_f32_16x16x32_bf16 v[122:125], v[142:145], v[180:183], v[122:125]
	v_mfma_f32_16x16x32_bf16 v[122:125], v[146:149], v[184:187], v[122:125]
	s_waitcnt lgkmcnt(3)
	v_mfma_f32_16x16x32_bf16 v[106:109], v[142:145], v[188:191], v[106:109]
	v_mfma_f32_16x16x32_bf16 v[106:109], v[146:149], v[192:195], v[106:109]
	s_waitcnt lgkmcnt(1)
	v_mfma_f32_16x16x32_bf16 v[110:113], v[130:133], v[188:191], v[110:113]
	v_mfma_f32_16x16x32_bf16 v[110:113], v[138:141], v[192:195], v[110:113]
	v_mfma_f32_16x16x32_bf16 v[94:97], v[130:133], v[196:199], v[94:97]
	v_mfma_f32_16x16x32_bf16 v[94:97], v[138:141], v[200:203], v[94:97]
	v_mfma_f32_16x16x32_bf16 v[90:93], v[142:145], v[196:199], v[90:93]
	v_mfma_f32_16x16x32_bf16 v[90:93], v[146:149], v[200:203], v[90:93]
	v_mfma_f32_16x16x32_bf16 v[74:77], v[142:145], v[204:207], v[74:77]
	v_mfma_f32_16x16x32_bf16 v[74:77], v[146:149], v[208:211], v[74:77]
	s_waitcnt lgkmcnt(0)
	v_mfma_f32_16x16x32_bf16 v[78:81], v[130:133], v[204:207], v[78:81]
	v_mfma_f32_16x16x32_bf16 v[78:81], v[138:141], v[208:211], v[78:81]
	s_setprio 0
	s_setprio 1
	v_mfma_f32_16x16x32_bf16 v[118:121], v[150:153], v[180:183], v[118:121]
	v_mfma_f32_16x16x32_bf16 v[118:121], v[168:171], v[184:187], v[118:121]
	v_mfma_f32_16x16x32_bf16 v[114:117], v[172:175], v[180:183], v[114:117]
	v_mfma_f32_16x16x32_bf16 v[114:117], v[176:179], v[184:187], v[114:117]
	v_mfma_f32_16x16x32_bf16 v[98:101], v[172:175], v[188:191], v[98:101]
	v_mfma_f32_16x16x32_bf16 v[98:101], v[176:179], v[192:195], v[98:101]
	v_mfma_f32_16x16x32_bf16 v[102:105], v[150:153], v[188:191], v[102:105]
	v_mfma_f32_16x16x32_bf16 v[102:105], v[168:171], v[192:195], v[102:105]
	v_mfma_f32_16x16x32_bf16 v[86:89], v[150:153], v[196:199], v[86:89]
	v_mfma_f32_16x16x32_bf16 v[86:89], v[168:171], v[200:203], v[86:89]
	v_mfma_f32_16x16x32_bf16 v[82:85], v[172:175], v[196:199], v[82:85]
	v_mfma_f32_16x16x32_bf16 v[82:85], v[176:179], v[200:203], v[82:85]
	v_mfma_f32_16x16x32_bf16 v[66:69], v[172:175], v[204:207], v[66:69]
	v_mfma_f32_16x16x32_bf16 v[66:69], v[176:179], v[208:211], v[66:69]
	s_setprio 2
	s_barrier
	v_mfma_f32_16x16x32_bf16 v[70:73], v[150:153], v[204:207], v[70:73]
	v_mfma_f32_16x16x32_bf16 v[70:73], v[168:171], v[208:211], v[70:73]
	s_setprio 0
	s_setprio 3
	ds_read_b128 v[180:183], v163 offset:49152
	ds_read_b128 v[184:187], v163 offset:50176
	ds_read_b128 v[188:191], v163 offset:51200
	ds_read_b128 v[192:195], v163 offset:52224
	ds_read_b128 v[196:199], v163 offset:53248
	ds_read_b128 v[200:203], v163 offset:54272
	ds_read_b128 v[204:207], v163 offset:55296
	ds_read_b128 v[208:211], v163 offset:56320
	s_add_u32 s28, s10, 0x80
	s_addc_u32 s29, s11, 0
	s_mov_b32 s75, m0
	s_mov_b32 m0, s64
	s_nop 0
	global_load_lds_dwordx4 v156, s[28:29]
	s_mov_b32 m0, s75
	s_add_u32 s10, s10, 0x80080
	s_mov_b32 s75, m0
	s_mov_b32 m0, s65
	s_nop 0
	global_load_lds_dwordx4 v158, s[28:29]
	s_mov_b32 m0, s75
	s_addc_u32 s11, s11, 0
	s_mov_b32 s28, m0
	s_mov_b32 m0, s66
	s_nop 0
	global_load_lds_dwordx4 v156, s[10:11]
	s_mov_b32 m0, s28
	s_nop 0
	s_mov_b32 s28, m0
	s_mov_b32 m0, s67
	s_nop 0
	global_load_lds_dwordx4 v158, s[10:11]
	s_mov_b32 m0, s28
	s_setprio 0
	s_waitcnt vmcnt(4)
	s_waitcnt lgkmcnt(0)
	s_barrier
	s_setprio 1
	s_waitcnt lgkmcnt(7)
	v_mfma_f32_16x16x32_bf16 v[62:65], v[130:133], v[180:183], v[62:65]
	v_mfma_f32_16x16x32_bf16 v[62:65], v[138:141], v[184:187], v[62:65]
	s_waitcnt lgkmcnt(5)
	v_mfma_f32_16x16x32_bf16 v[58:61], v[142:145], v[180:183], v[58:61]
	v_mfma_f32_16x16x32_bf16 v[58:61], v[146:149], v[184:187], v[58:61]
	s_waitcnt lgkmcnt(3)
	v_mfma_f32_16x16x32_bf16 v[42:45], v[142:145], v[188:191], v[42:45]
	v_mfma_f32_16x16x32_bf16 v[42:45], v[146:149], v[192:195], v[42:45]
	s_waitcnt lgkmcnt(1)
	v_mfma_f32_16x16x32_bf16 v[46:49], v[130:133], v[188:191], v[46:49]
	v_mfma_f32_16x16x32_bf16 v[46:49], v[138:141], v[192:195], v[46:49]
	v_mfma_f32_16x16x32_bf16 v[30:33], v[130:133], v[196:199], v[30:33]
	v_mfma_f32_16x16x32_bf16 v[30:33], v[138:141], v[200:203], v[30:33]
	v_mfma_f32_16x16x32_bf16 v[26:29], v[142:145], v[196:199], v[26:29]
	v_mfma_f32_16x16x32_bf16 v[26:29], v[146:149], v[200:203], v[26:29]
	v_mfma_f32_16x16x32_bf16 v[10:13], v[142:145], v[204:207], v[10:13]
	v_mfma_f32_16x16x32_bf16 v[10:13], v[146:149], v[208:211], v[10:13]
	s_waitcnt lgkmcnt(0)
	v_mfma_f32_16x16x32_bf16 v[14:17], v[130:133], v[204:207], v[14:17]
	v_mfma_f32_16x16x32_bf16 v[14:17], v[138:141], v[208:211], v[14:17]
	s_setprio 0
	s_setprio 1
	v_mfma_f32_16x16x32_bf16 v[54:57], v[150:153], v[180:183], v[54:57]
	v_mfma_f32_16x16x32_bf16 v[54:57], v[168:171], v[184:187], v[54:57]
	v_mfma_f32_16x16x32_bf16 v[50:53], v[172:175], v[180:183], v[50:53]
	v_mfma_f32_16x16x32_bf16 v[50:53], v[176:179], v[184:187], v[50:53]
	v_mfma_f32_16x16x32_bf16 v[34:37], v[172:175], v[188:191], v[34:37]
	v_mfma_f32_16x16x32_bf16 v[34:37], v[176:179], v[192:195], v[34:37]
	v_mfma_f32_16x16x32_bf16 v[38:41], v[150:153], v[188:191], v[38:41]
	v_mfma_f32_16x16x32_bf16 v[38:41], v[168:171], v[192:195], v[38:41]
	v_mfma_f32_16x16x32_bf16 v[22:25], v[150:153], v[196:199], v[22:25]
	v_mfma_f32_16x16x32_bf16 v[22:25], v[168:171], v[200:203], v[22:25]
	v_mfma_f32_16x16x32_bf16 v[18:21], v[172:175], v[196:199], v[18:21]
	v_mfma_f32_16x16x32_bf16 v[18:21], v[176:179], v[200:203], v[18:21]
	v_mfma_f32_16x16x32_bf16 v[2:5], v[172:175], v[204:207], v[2:5]
	v_mfma_f32_16x16x32_bf16 v[2:5], v[176:179], v[208:211], v[2:5]
	s_setprio 2
	s_barrier
	v_mfma_f32_16x16x32_bf16 v[6:9], v[150:153], v[204:207], v[6:9]
	v_mfma_f32_16x16x32_bf16 v[6:9], v[168:171], v[208:211], v[6:9]
	s_setprio 0
	s_add_i32 s74, s74, 2
	s_add_u32 s30, s30, 0x100
	s_addc_u32 s31, s31, 0
	s_add_u32 s4, s4, 0x100
	s_addc_u32 s5, s5, 0
	s_add_u32 s33, s33, 0x100
	s_addc_u32 s73, s73, 0
	s_cmp_gt_u32 s74, 29
	.p2align 6
.LBB0_654:
	s_setprio 3
	ds_read_b128 v[130:133], v161
	ds_read_b128 v[138:141], v161 offset:1024
	ds_read_b128 v[142:145], v161 offset:2048
	ds_read_b128 v[146:149], v161 offset:3072
	ds_read_b128 v[150:153], v162
	ds_read_b128 v[168:171], v162 offset:1024
	ds_read_b128 v[172:175], v162 offset:2048
	ds_read_b128 v[176:179], v162 offset:3072
	s_cmp_eq_u32 s74, 28
	s_cselect_b32 s11, s21, s31
	s_cselect_b32 s10, s23, s30
	s_cselect_b32 s29, s7, s73
	s_cselect_b32 s28, s9, s33
	ds_read_b128 v[180:183], v163
	ds_read_b128 v[184:187], v163 offset:1024
	ds_read_b128 v[188:191], v163 offset:2048
	ds_read_b128 v[192:195], v163 offset:3072
	ds_read_b128 v[196:199], v163 offset:4096
	ds_read_b128 v[200:203], v163 offset:5120
	ds_read_b128 v[204:207], v163 offset:6144
	ds_read_b128 v[208:211], v163 offset:7168
	s_add_u32 s76, s4, 0xfff80000
	s_addc_u32 s77, s5, -1
	s_mov_b32 s75, m0
	s_mov_b32 m0, s80
	s_nop 0
	global_load_lds_dwordx4 v1, s[76:77]
	s_mov_b32 m0, s75
	s_nop 0
	s_mov_b32 s75, m0
	s_mov_b32 m0, s82
	s_nop 0
	global_load_lds_dwordx4 v157, s[76:77]
	s_mov_b32 m0, s75
	s_nop 0
	s_mov_b32 s75, m0
	s_mov_b32 m0, s81
	s_nop 0
	global_load_lds_dwordx4 v1, s[4:5]
	s_mov_b32 m0, s75
	s_nop 0
	s_mov_b32 s75, m0
	s_mov_b32 m0, s83
	s_nop 0
	global_load_lds_dwordx4 v157, s[4:5]
	s_mov_b32 m0, s75
	s_setprio 0
	s_waitcnt vmcnt(8)
	s_waitcnt lgkmcnt(0)
	s_barrier
	s_setprio 1
	s_waitcnt lgkmcnt(7)
	v_mfma_f32_16x16x32_bf16 v[126:129], v[130:133], v[180:183], v[126:129]
	v_mfma_f32_16x16x32_bf16 v[126:129], v[138:141], v[184:187], v[126:129]
	s_waitcnt lgkmcnt(5)
	v_mfma_f32_16x16x32_bf16 v[122:125], v[142:145], v[180:183], v[122:125]
	v_mfma_f32_16x16x32_bf16 v[122:125], v[146:149], v[184:187], v[122:125]
	s_waitcnt lgkmcnt(3)
	v_mfma_f32_16x16x32_bf16 v[106:109], v[142:145], v[188:191], v[106:109]
	v_mfma_f32_16x16x32_bf16 v[106:109], v[146:149], v[192:195], v[106:109]
	s_waitcnt lgkmcnt(1)
	v_mfma_f32_16x16x32_bf16 v[110:113], v[130:133], v[188:191], v[110:113]
	v_mfma_f32_16x16x32_bf16 v[110:113], v[138:141], v[192:195], v[110:113]
	v_mfma_f32_16x16x32_bf16 v[94:97], v[130:133], v[196:199], v[94:97]
	v_mfma_f32_16x16x32_bf16 v[94:97], v[138:141], v[200:203], v[94:97]
	v_mfma_f32_16x16x32_bf16 v[90:93], v[142:145], v[196:199], v[90:93]
	v_mfma_f32_16x16x32_bf16 v[90:93], v[146:149], v[200:203], v[90:93]
	v_mfma_f32_16x16x32_bf16 v[74:77], v[142:145], v[204:207], v[74:77]
	v_mfma_f32_16x16x32_bf16 v[74:77], v[146:149], v[208:211], v[74:77]
	s_waitcnt lgkmcnt(0)
	v_mfma_f32_16x16x32_bf16 v[78:81], v[130:133], v[204:207], v[78:81]
	v_mfma_f32_16x16x32_bf16 v[78:81], v[138:141], v[208:211], v[78:81]
	s_setprio 0
	s_setprio 1
	v_mfma_f32_16x16x32_bf16 v[118:121], v[150:153], v[180:183], v[118:121]
	v_mfma_f32_16x16x32_bf16 v[118:121], v[168:171], v[184:187], v[118:121]
	v_mfma_f32_16x16x32_bf16 v[114:117], v[172:175], v[180:183], v[114:117]
	v_mfma_f32_16x16x32_bf16 v[114:117], v[176:179], v[184:187], v[114:117]
	v_mfma_f32_16x16x32_bf16 v[98:101], v[172:175], v[188:191], v[98:101]
	v_mfma_f32_16x16x32_bf16 v[98:101], v[176:179], v[192:195], v[98:101]
	v_mfma_f32_16x16x32_bf16 v[102:105], v[150:153], v[188:191], v[102:105]
	v_mfma_f32_16x16x32_bf16 v[102:105], v[168:171], v[192:195], v[102:105]
	v_mfma_f32_16x16x32_bf16 v[86:89], v[150:153], v[196:199], v[86:89]
	v_mfma_f32_16x16x32_bf16 v[86:89], v[168:171], v[200:203], v[86:89]
	v_mfma_f32_16x16x32_bf16 v[82:85], v[172:175], v[196:199], v[82:85]
	v_mfma_f32_16x16x32_bf16 v[82:85], v[176:179], v[200:203], v[82:85]
	v_mfma_f32_16x16x32_bf16 v[66:69], v[172:175], v[204:207], v[66:69]
	v_mfma_f32_16x16x32_bf16 v[66:69], v[176:179], v[208:211], v[66:69]
	s_setprio 2
	s_barrier
	v_mfma_f32_16x16x32_bf16 v[70:73], v[150:153], v[204:207], v[70:73]
	v_mfma_f32_16x16x32_bf16 v[70:73], v[168:171], v[208:211], v[70:73]
	s_setprio 0
	s_setprio 3
	ds_read_b128 v[180:183], v163 offset:16384
	ds_read_b128 v[184:187], v163 offset:17408
	ds_read_b128 v[188:191], v163 offset:18432
	ds_read_b128 v[192:195], v163 offset:19456
	ds_read_b128 v[196:199], v163 offset:20480
	ds_read_b128 v[200:203], v163 offset:21504
	ds_read_b128 v[204:207], v163 offset:22528
	ds_read_b128 v[208:211], v163 offset:23552
	s_mov_b32 s75, m0
	s_mov_b32 m0, s43
	s_nop 0
	global_load_lds_dwordx4 v156, s[10:11]
	s_mov_b32 m0, s75
	s_add_u32 s76, s10, 0x80000
	s_mov_b32 s75, m0
	s_mov_b32 m0, s46
	s_nop 0
	global_load_lds_dwordx4 v158, s[10:11]
	s_mov_b32 m0, s75
	s_addc_u32 s77, s11, 0
	s_mov_b32 s75, m0
	s_mov_b32 m0, s47
	s_nop 0
	global_load_lds_dwordx4 v156, s[76:77]
	s_mov_b32 m0, s75
	s_nop 0
	s_mov_b32 s75, m0
	s_mov_b32 m0, s48
	s_nop 0
	global_load_lds_dwordx4 v158, s[76:77]
	s_mov_b32 m0, s75
	s_setprio 0
	s_waitcnt vmcnt(4)
	s_waitcnt lgkmcnt(0)
	s_barrier
	s_setprio 1
	s_waitcnt lgkmcnt(7)
	v_mfma_f32_16x16x32_bf16 v[62:65], v[130:133], v[180:183], v[62:65]
	v_mfma_f32_16x16x32_bf16 v[62:65], v[138:141], v[184:187], v[62:65]
	s_waitcnt lgkmcnt(5)
	v_mfma_f32_16x16x32_bf16 v[58:61], v[142:145], v[180:183], v[58:61]
	v_mfma_f32_16x16x32_bf16 v[58:61], v[146:149], v[184:187], v[58:61]
	s_waitcnt lgkmcnt(3)
	v_mfma_f32_16x16x32_bf16 v[42:45], v[142:145], v[188:191], v[42:45]
	v_mfma_f32_16x16x32_bf16 v[42:45], v[146:149], v[192:195], v[42:45]
	s_waitcnt lgkmcnt(1)
	v_mfma_f32_16x16x32_bf16 v[46:49], v[130:133], v[188:191], v[46:49]
	v_mfma_f32_16x16x32_bf16 v[46:49], v[138:141], v[192:195], v[46:49]
	v_mfma_f32_16x16x32_bf16 v[30:33], v[130:133], v[196:199], v[30:33]
	v_mfma_f32_16x16x32_bf16 v[30:33], v[138:141], v[200:203], v[30:33]
	v_mfma_f32_16x16x32_bf16 v[26:29], v[142:145], v[196:199], v[26:29]
	v_mfma_f32_16x16x32_bf16 v[26:29], v[146:149], v[200:203], v[26:29]
	v_mfma_f32_16x16x32_bf16 v[10:13], v[142:145], v[204:207], v[10:13]
	v_mfma_f32_16x16x32_bf16 v[10:13], v[146:149], v[208:211], v[10:13]
	s_waitcnt lgkmcnt(0)
	v_mfma_f32_16x16x32_bf16 v[14:17], v[130:133], v[204:207], v[14:17]
	v_mfma_f32_16x16x32_bf16 v[14:17], v[138:141], v[208:211], v[14:17]
	s_setprio 0
	s_setprio 1
	v_mfma_f32_16x16x32_bf16 v[54:57], v[150:153], v[180:183], v[54:57]
	v_mfma_f32_16x16x32_bf16 v[54:57], v[168:171], v[184:187], v[54:57]
	v_mfma_f32_16x16x32_bf16 v[50:53], v[172:175], v[180:183], v[50:53]
	v_mfma_f32_16x16x32_bf16 v[50:53], v[176:179], v[184:187], v[50:53]
	v_mfma_f32_16x16x32_bf16 v[34:37], v[172:175], v[188:191], v[34:37]
	v_mfma_f32_16x16x32_bf16 v[34:37], v[176:179], v[192:195], v[34:37]
	v_mfma_f32_16x16x32_bf16 v[38:41], v[150:153], v[188:191], v[38:41]
	v_mfma_f32_16x16x32_bf16 v[38:41], v[168:171], v[192:195], v[38:41]
	v_mfma_f32_16x16x32_bf16 v[22:25], v[150:153], v[196:199], v[22:25]
	v_mfma_f32_16x16x32_bf16 v[22:25], v[168:171], v[200:203], v[22:25]
	v_mfma_f32_16x16x32_bf16 v[18:21], v[172:175], v[196:199], v[18:21]
	v_mfma_f32_16x16x32_bf16 v[18:21], v[176:179], v[200:203], v[18:21]
	v_mfma_f32_16x16x32_bf16 v[2:5], v[172:175], v[204:207], v[2:5]
	v_mfma_f32_16x16x32_bf16 v[2:5], v[176:179], v[208:211], v[2:5]
	s_setprio 2
	s_barrier
	v_mfma_f32_16x16x32_bf16 v[6:9], v[150:153], v[204:207], v[6:9]
	v_mfma_f32_16x16x32_bf16 v[6:9], v[168:171], v[208:211], v[6:9]
	s_setprio 0
	s_setprio 3
	ds_read_b128 v[130:133], v164
	ds_read_b128 v[138:141], v164 offset:1024
	ds_read_b128 v[142:145], v164 offset:2048
	ds_read_b128 v[146:149], v164 offset:3072
	ds_read_b128 v[150:153], v165
	ds_read_b128 v[168:171], v165 offset:1024
	ds_read_b128 v[172:175], v165 offset:2048
	ds_read_b128 v[176:179], v165 offset:3072
	ds_read_b128 v[180:183], v163 offset:32768
	ds_read_b128 v[184:187], v163 offset:33792
	ds_read_b128 v[188:191], v163 offset:34816
	ds_read_b128 v[192:195], v163 offset:35840
	ds_read_b128 v[196:199], v163 offset:36864
	ds_read_b128 v[200:203], v163 offset:37888
	ds_read_b128 v[204:207], v163 offset:38912
	ds_read_b128 v[208:211], v163 offset:39936
	s_mov_b32 s75, m0
	s_mov_b32 m0, s42
	s_nop 0
	global_load_lds_dwordx4 v1, s[28:29]
	s_mov_b32 m0, s75
	s_nop 0
	s_mov_b32 s75, m0
	s_mov_b32 m0, s49
	s_nop 0
	global_load_lds_dwordx4 v157, s[28:29]
	s_mov_b32 m0, s75
	s_add_u32 s28, s28, 0x80000
	s_addc_u32 s29, s29, 0
	s_mov_b32 s75, m0
	s_mov_b32 m0, s56
	s_nop 0
	global_load_lds_dwordx4 v1, s[28:29]
	s_mov_b32 m0, s75
	s_nop 0
	s_mov_b32 s75, m0
	s_mov_b32 m0, s57
	s_nop 0
	global_load_lds_dwordx4 v157, s[28:29]
	s_mov_b32 m0, s75
	s_setprio 0
	s_waitcnt vmcnt(8)
	s_waitcnt lgkmcnt(0)
	s_barrier
	s_setprio 1
	s_waitcnt lgkmcnt(7)
	v_mfma_f32_16x16x32_bf16 v[126:129], v[130:133], v[180:183], v[126:129]
	v_mfma_f32_16x16x32_bf16 v[126:129], v[138:141], v[184:187], v[126:129]
	s_waitcnt lgkmcnt(5)
	v_mfma_f32_16x16x32_bf16 v[122:125], v[142:145], v[180:183], v[122:125]
	v_mfma_f32_16x16x32_bf16 v[122:125], v[146:149], v[184:187], v[122:125]
	s_waitcnt lgkmcnt(3)
	v_mfma_f32_16x16x32_bf16 v[106:109], v[142:145], v[188:191], v[106:109]
	v_mfma_f32_16x16x32_bf16 v[106:109], v[146:149], v[192:195], v[106:109]
	s_waitcnt lgkmcnt(1)
	v_mfma_f32_16x16x32_bf16 v[110:113], v[130:133], v[188:191], v[110:113]
	v_mfma_f32_16x16x32_bf16 v[110:113], v[138:141], v[192:195], v[110:113]
	v_mfma_f32_16x16x32_bf16 v[94:97], v[130:133], v[196:199], v[94:97]
	v_mfma_f32_16x16x32_bf16 v[94:97], v[138:141], v[200:203], v[94:97]
	v_mfma_f32_16x16x32_bf16 v[90:93], v[142:145], v[196:199], v[90:93]
	v_mfma_f32_16x16x32_bf16 v[90:93], v[146:149], v[200:203], v[90:93]
	v_mfma_f32_16x16x32_bf16 v[74:77], v[142:145], v[204:207], v[74:77]
	v_mfma_f32_16x16x32_bf16 v[74:77], v[146:149], v[208:211], v[74:77]
	s_waitcnt lgkmcnt(0)
	v_mfma_f32_16x16x32_bf16 v[78:81], v[130:133], v[204:207], v[78:81]
	v_mfma_f32_16x16x32_bf16 v[78:81], v[138:141], v[208:211], v[78:81]
	s_setprio 0
	s_setprio 1
	v_mfma_f32_16x16x32_bf16 v[118:121], v[150:153], v[180:183], v[118:121]
	v_mfma_f32_16x16x32_bf16 v[118:121], v[168:171], v[184:187], v[118:121]
	v_mfma_f32_16x16x32_bf16 v[114:117], v[172:175], v[180:183], v[114:117]
	v_mfma_f32_16x16x32_bf16 v[114:117], v[176:179], v[184:187], v[114:117]
	v_mfma_f32_16x16x32_bf16 v[98:101], v[172:175], v[188:191], v[98:101]
	v_mfma_f32_16x16x32_bf16 v[98:101], v[176:179], v[192:195], v[98:101]
	v_mfma_f32_16x16x32_bf16 v[102:105], v[150:153], v[188:191], v[102:105]
	v_mfma_f32_16x16x32_bf16 v[102:105], v[168:171], v[192:195], v[102:105]
	v_mfma_f32_16x16x32_bf16 v[86:89], v[150:153], v[196:199], v[86:89]
	v_mfma_f32_16x16x32_bf16 v[86:89], v[168:171], v[200:203], v[86:89]
	v_mfma_f32_16x16x32_bf16 v[82:85], v[172:175], v[196:199], v[82:85]
	v_mfma_f32_16x16x32_bf16 v[82:85], v[176:179], v[200:203], v[82:85]
	v_mfma_f32_16x16x32_bf16 v[66:69], v[172:175], v[204:207], v[66:69]
	v_mfma_f32_16x16x32_bf16 v[66:69], v[176:179], v[208:211], v[66:69]
	s_setprio 2
	s_barrier
	v_mfma_f32_16x16x32_bf16 v[70:73], v[150:153], v[204:207], v[70:73]
	v_mfma_f32_16x16x32_bf16 v[70:73], v[168:171], v[208:211], v[70:73]
	s_setprio 0
	s_setprio 3
	ds_read_b128 v[180:183], v163 offset:49152
	ds_read_b128 v[184:187], v163 offset:50176
	ds_read_b128 v[188:191], v163 offset:51200
	ds_read_b128 v[192:195], v163 offset:52224
	ds_read_b128 v[196:199], v163 offset:53248
	ds_read_b128 v[200:203], v163 offset:54272
	ds_read_b128 v[204:207], v163 offset:55296
	ds_read_b128 v[208:211], v163 offset:56320
	s_add_u32 s28, s10, 0x80
	s_addc_u32 s29, s11, 0
	s_mov_b32 s75, m0
	s_mov_b32 m0, s64
	s_nop 0
	global_load_lds_dwordx4 v156, s[28:29]
	s_mov_b32 m0, s75
	s_add_u32 s10, s10, 0x80080
	s_mov_b32 s75, m0
	s_mov_b32 m0, s65
	s_nop 0
	global_load_lds_dwordx4 v158, s[28:29]
	s_mov_b32 m0, s75
	s_addc_u32 s11, s11, 0
	s_mov_b32 s28, m0
	s_mov_b32 m0, s66
	s_nop 0
	global_load_lds_dwordx4 v156, s[10:11]
	s_mov_b32 m0, s28
	s_nop 0
	s_mov_b32 s28, m0
	s_mov_b32 m0, s67
	s_nop 0
	global_load_lds_dwordx4 v158, s[10:11]
	s_mov_b32 m0, s28
	s_setprio 0
	s_waitcnt vmcnt(4)
	s_waitcnt lgkmcnt(0)
	s_barrier
	s_setprio 1
	s_waitcnt lgkmcnt(7)
	v_mfma_f32_16x16x32_bf16 v[62:65], v[130:133], v[180:183], v[62:65]
	v_mfma_f32_16x16x32_bf16 v[62:65], v[138:141], v[184:187], v[62:65]
	s_waitcnt lgkmcnt(5)
	v_mfma_f32_16x16x32_bf16 v[58:61], v[142:145], v[180:183], v[58:61]
	v_mfma_f32_16x16x32_bf16 v[58:61], v[146:149], v[184:187], v[58:61]
	s_waitcnt lgkmcnt(3)
	v_mfma_f32_16x16x32_bf16 v[42:45], v[142:145], v[188:191], v[42:45]
	v_mfma_f32_16x16x32_bf16 v[42:45], v[146:149], v[192:195], v[42:45]
	s_waitcnt lgkmcnt(1)
	v_mfma_f32_16x16x32_bf16 v[46:49], v[130:133], v[188:191], v[46:49]
	v_mfma_f32_16x16x32_bf16 v[46:49], v[138:141], v[192:195], v[46:49]
	v_mfma_f32_16x16x32_bf16 v[30:33], v[130:133], v[196:199], v[30:33]
	v_mfma_f32_16x16x32_bf16 v[30:33], v[138:141], v[200:203], v[30:33]
	v_mfma_f32_16x16x32_bf16 v[26:29], v[142:145], v[196:199], v[26:29]
	v_mfma_f32_16x16x32_bf16 v[26:29], v[146:149], v[200:203], v[26:29]
	v_mfma_f32_16x16x32_bf16 v[10:13], v[142:145], v[204:207], v[10:13]
	v_mfma_f32_16x16x32_bf16 v[10:13], v[146:149], v[208:211], v[10:13]
	s_waitcnt lgkmcnt(0)
	v_mfma_f32_16x16x32_bf16 v[14:17], v[130:133], v[204:207], v[14:17]
	v_mfma_f32_16x16x32_bf16 v[14:17], v[138:141], v[208:211], v[14:17]
	s_setprio 0
	s_setprio 1
	v_mfma_f32_16x16x32_bf16 v[54:57], v[150:153], v[180:183], v[54:57]
	v_mfma_f32_16x16x32_bf16 v[54:57], v[168:171], v[184:187], v[54:57]
	v_mfma_f32_16x16x32_bf16 v[50:53], v[172:175], v[180:183], v[50:53]
	v_mfma_f32_16x16x32_bf16 v[50:53], v[176:179], v[184:187], v[50:53]
	v_mfma_f32_16x16x32_bf16 v[34:37], v[172:175], v[188:191], v[34:37]
	v_mfma_f32_16x16x32_bf16 v[34:37], v[176:179], v[192:195], v[34:37]
	v_mfma_f32_16x16x32_bf16 v[38:41], v[150:153], v[188:191], v[38:41]
	v_mfma_f32_16x16x32_bf16 v[38:41], v[168:171], v[192:195], v[38:41]
	v_mfma_f32_16x16x32_bf16 v[22:25], v[150:153], v[196:199], v[22:25]
	v_mfma_f32_16x16x32_bf16 v[22:25], v[168:171], v[200:203], v[22:25]
	v_mfma_f32_16x16x32_bf16 v[18:21], v[172:175], v[196:199], v[18:21]
	v_mfma_f32_16x16x32_bf16 v[18:21], v[176:179], v[200:203], v[18:21]
	v_mfma_f32_16x16x32_bf16 v[2:5], v[172:175], v[204:207], v[2:5]
	v_mfma_f32_16x16x32_bf16 v[2:5], v[176:179], v[208:211], v[2:5]
	s_setprio 2
	s_barrier
	v_mfma_f32_16x16x32_bf16 v[6:9], v[150:153], v[204:207], v[6:9]
	v_mfma_f32_16x16x32_bf16 v[6:9], v[168:171], v[208:211], v[6:9]
	s_setprio 0
	s_add_i32 s74, s74, 2
	s_add_u32 s30, s30, 0x100
	s_addc_u32 s31, s31, 0
	s_add_u32 s4, s4, 0x100
	s_addc_u32 s5, s5, 0
	s_add_u32 s33, s33, 0x100
	s_addc_u32 s73, s73, 0
	s_cmp_gt_u32 s74, 29
	s_cbranch_scc0 .LBB0_654
	s_and_b64 vcc, exec, s[18:19]
	s_cbranch_vccz .LBB0_657
	s_barrier

.LBB0_1052:
	s_ashr_i32 s13, s12, 31
	s_lshl_b64 s[14:15], s[12:13], 20
	s_add_u32 s14, s28, s14
	s_addc_u32 s15, s29, s15
	s_and_b64 s[16:17], s[2:3], exec
	s_cselect_b32 s13, s15, s23
	s_cselect_b32 s67, s14, s22
	s_ashr_i32 s11, s10, 31
	s_lshl_b64 s[16:17], s[10:11], 20
	s_add_u32 s16, s30, s16
	s_addc_u32 s17, s31, s17
	s_and_b64 s[24:25], s[2:3], exec
	s_cselect_b32 s11, s17, s21
	s_cselect_b32 s73, s16, s20
	s_add_u32 s74, s20, 0x100
	s_addc_u32 s75, s21, 0
	s_add_u32 s20, s22, 0x80080
	s_addc_u32 s21, s23, 0
	s_add_u32 s76, s22, 0x100
	s_addc_u32 s77, s23, 0
	s_mov_b32 s78, -2
	s_waitcnt vmcnt(25)
	s_waitcnt vmcnt(24)
	s_waitcnt vmcnt(15)
	s_waitcnt vmcnt(14)
	s_waitcnt vmcnt(13)
	s_waitcnt vmcnt(12)
	s_waitcnt vmcnt(11)
	s_waitcnt vmcnt(10)
	s_waitcnt vmcnt(9)
	s_waitcnt vmcnt(8)
	s_waitcnt vmcnt(7)
	s_waitcnt vmcnt(6)
	s_waitcnt vmcnt(5)
	s_waitcnt vmcnt(4)
	s_waitcnt vmcnt(3)
	s_waitcnt vmcnt(2)
	s_waitcnt vmcnt(1)
	s_waitcnt vmcnt(0)
	s_setprio 3
	ds_read_b128 v[130:133], v181
	ds_read_b128 v[134:137], v181 offset:1024
	ds_read_b128 v[138:141], v181 offset:2048
	ds_read_b128 v[142:145], v181 offset:3072
	ds_read_b128 v[146:149], v182
	ds_read_b128 v[150:153], v182 offset:1024
	ds_read_b128 v[154:157], v182 offset:2048
	ds_read_b128 v[158:161], v182 offset:3072
	s_cmp_eq_u32 s78, 28
	s_cselect_b32 s23, s11, s75
	s_cselect_b32 s22, s73, s74
	s_cselect_b32 s25, s13, s77
	s_cselect_b32 s24, s67, s76
	ds_read_b128 v[166:169], v183
	ds_read_b128 v[170:173], v183 offset:1024
	ds_read_b128 v[186:189], v183 offset:2048
	ds_read_b128 v[190:193], v183 offset:3072
	ds_read_b128 v[194:197], v183 offset:4096
	ds_read_b128 v[198:201], v183 offset:5120
	ds_read_b128 v[202:205], v183 offset:6144
	ds_read_b128 v[206:209], v183 offset:7168
	s_add_u32 s80, s20, 0xfff80000
	s_addc_u32 s81, s21, -1
	s_mov_b32 s79, m0
	s_mov_b32 m0, s58
	s_nop 0
	global_load_lds_dwordx4 v1, s[80:81]
	s_mov_b32 m0, s79
	s_nop 0
	s_mov_b32 s79, m0
	s_mov_b32 m0, s64
	s_nop 0
	global_load_lds_dwordx4 v177, s[80:81]
	s_mov_b32 m0, s79
	s_nop 0
	s_mov_b32 s79, m0
	s_mov_b32 m0, s59
	s_nop 0
	global_load_lds_dwordx4 v1, s[20:21]
	s_mov_b32 m0, s79
	s_nop 0
	s_mov_b32 s79, m0
	s_mov_b32 m0, s65
	s_nop 0
	global_load_lds_dwordx4 v177, s[20:21]
	s_mov_b32 m0, s79
	s_setprio 0
	s_waitcnt vmcnt(8)
	s_waitcnt lgkmcnt(0)
	s_barrier
	s_setprio 1
	s_waitcnt lgkmcnt(7)
	v_mfma_f32_16x16x32_bf16 v[126:129], v[130:133], v[166:169], 0
	v_mfma_f32_16x16x32_bf16 v[126:129], v[134:137], v[170:173], v[126:129]
	s_waitcnt lgkmcnt(5)
	v_mfma_f32_16x16x32_bf16 v[122:125], v[138:141], v[166:169], 0
	v_mfma_f32_16x16x32_bf16 v[122:125], v[142:145], v[170:173], v[122:125]
	s_waitcnt lgkmcnt(3)
	v_mfma_f32_16x16x32_bf16 v[114:117], v[138:141], v[186:189], 0
	v_mfma_f32_16x16x32_bf16 v[114:117], v[142:145], v[190:193], v[114:117]
	s_waitcnt lgkmcnt(1)
	v_mfma_f32_16x16x32_bf16 v[118:121], v[130:133], v[186:189], 0
	v_mfma_f32_16x16x32_bf16 v[118:121], v[134:137], v[190:193], v[118:121]
	v_mfma_f32_16x16x32_bf16 v[94:97], v[130:133], v[194:197], 0
	v_mfma_f32_16x16x32_bf16 v[94:97], v[134:137], v[198:201], v[94:97]
	v_mfma_f32_16x16x32_bf16 v[90:93], v[138:141], v[194:197], 0
	v_mfma_f32_16x16x32_bf16 v[90:93], v[142:145], v[198:201], v[90:93]
	v_mfma_f32_16x16x32_bf16 v[78:81], v[138:141], v[202:205], 0
	v_mfma_f32_16x16x32_bf16 v[78:81], v[142:145], v[206:209], v[78:81]
	s_waitcnt lgkmcnt(0)
	v_mfma_f32_16x16x32_bf16 v[86:89], v[130:133], v[202:205], 0
	v_mfma_f32_16x16x32_bf16 v[86:89], v[134:137], v[206:209], v[86:89]
	s_setprio 0
	s_setprio 1
	v_mfma_f32_16x16x32_bf16 v[110:113], v[146:149], v[166:169], 0
	v_mfma_f32_16x16x32_bf16 v[110:113], v[150:153], v[170:173], v[110:113]
	v_mfma_f32_16x16x32_bf16 v[106:109], v[154:157], v[166:169], 0
	v_mfma_f32_16x16x32_bf16 v[106:109], v[158:161], v[170:173], v[106:109]
	v_mfma_f32_16x16x32_bf16 v[98:101], v[154:157], v[186:189], 0
	v_mfma_f32_16x16x32_bf16 v[98:101], v[158:161], v[190:193], v[98:101]
	v_mfma_f32_16x16x32_bf16 v[102:105], v[146:149], v[186:189], 0
	v_mfma_f32_16x16x32_bf16 v[102:105], v[150:153], v[190:193], v[102:105]
	v_mfma_f32_16x16x32_bf16 v[82:85], v[146:149], v[194:197], 0
	v_mfma_f32_16x16x32_bf16 v[82:85], v[150:153], v[198:201], v[82:85]
	v_mfma_f32_16x16x32_bf16 v[74:77], v[154:157], v[194:197], 0
	v_mfma_f32_16x16x32_bf16 v[74:77], v[158:161], v[198:201], v[74:77]
	v_mfma_f32_16x16x32_bf16 v[66:69], v[154:157], v[202:205], 0
	v_mfma_f32_16x16x32_bf16 v[66:69], v[158:161], v[206:209], v[66:69]
	s_setprio 2
	s_barrier
	v_mfma_f32_16x16x32_bf16 v[70:73], v[146:149], v[202:205], 0
	v_mfma_f32_16x16x32_bf16 v[70:73], v[150:153], v[206:209], v[70:73]
	s_setprio 0
	s_setprio 3
	ds_read_b128 v[166:169], v183 offset:16384
	ds_read_b128 v[170:173], v183 offset:17408
	ds_read_b128 v[186:189], v183 offset:18432
	ds_read_b128 v[190:193], v183 offset:19456
	ds_read_b128 v[194:197], v183 offset:20480
	ds_read_b128 v[198:201], v183 offset:21504
	ds_read_b128 v[202:205], v183 offset:22528
	ds_read_b128 v[206:209], v183 offset:23552
	s_mov_b32 s79, m0
	s_mov_b32 m0, s35
	s_nop 0
	global_load_lds_dwordx4 v176, s[22:23]
	s_mov_b32 m0, s79
	s_add_u32 s80, s22, 0x80000
	s_mov_b32 s79, m0
	s_mov_b32 m0, s36
	s_nop 0
	global_load_lds_dwordx4 v178, s[22:23]
	s_mov_b32 m0, s79
	s_addc_u32 s81, s23, 0
	s_mov_b32 s79, m0
	s_mov_b32 m0, s37
	s_nop 0
	global_load_lds_dwordx4 v176, s[80:81]
	s_mov_b32 m0, s79
	s_nop 0
	s_mov_b32 s79, m0
	s_mov_b32 m0, s40
	s_nop 0
	global_load_lds_dwordx4 v178, s[80:81]
	s_mov_b32 m0, s79
	s_setprio 0
	s_waitcnt vmcnt(4)
	s_waitcnt lgkmcnt(0)
	s_barrier
	s_setprio 1
	s_waitcnt lgkmcnt(7)
	v_mfma_f32_16x16x32_bf16 v[62:65], v[130:133], v[166:169], 0
	v_mfma_f32_16x16x32_bf16 v[62:65], v[134:137], v[170:173], v[62:65]
	s_waitcnt lgkmcnt(5)
	v_mfma_f32_16x16x32_bf16 v[58:61], v[138:141], v[166:169], 0
	v_mfma_f32_16x16x32_bf16 v[58:61], v[142:145], v[170:173], v[58:61]
	s_waitcnt lgkmcnt(3)
	v_mfma_f32_16x16x32_bf16 v[42:45], v[138:141], v[186:189], 0
	v_mfma_f32_16x16x32_bf16 v[42:45], v[142:145], v[190:193], v[42:45]
	s_waitcnt lgkmcnt(1)
	v_mfma_f32_16x16x32_bf16 v[46:49], v[130:133], v[186:189], 0
	v_mfma_f32_16x16x32_bf16 v[46:49], v[134:137], v[190:193], v[46:49]
	v_mfma_f32_16x16x32_bf16 v[30:33], v[130:133], v[194:197], 0
	v_mfma_f32_16x16x32_bf16 v[30:33], v[134:137], v[198:201], v[30:33]
	v_mfma_f32_16x16x32_bf16 v[26:29], v[138:141], v[194:197], 0
	v_mfma_f32_16x16x32_bf16 v[26:29], v[142:145], v[198:201], v[26:29]
	v_mfma_f32_16x16x32_bf16 v[10:13], v[138:141], v[202:205], 0
	v_mfma_f32_16x16x32_bf16 v[10:13], v[142:145], v[206:209], v[10:13]
	s_waitcnt lgkmcnt(0)
	v_mfma_f32_16x16x32_bf16 v[14:17], v[130:133], v[202:205], 0
	v_mfma_f32_16x16x32_bf16 v[14:17], v[134:137], v[206:209], v[14:17]
	s_setprio 0
	s_setprio 1
	v_mfma_f32_16x16x32_bf16 v[54:57], v[146:149], v[166:169], 0
	v_mfma_f32_16x16x32_bf16 v[54:57], v[150:153], v[170:173], v[54:57]
	v_mfma_f32_16x16x32_bf16 v[50:53], v[154:157], v[166:169], 0
	v_mfma_f32_16x16x32_bf16 v[50:53], v[158:161], v[170:173], v[50:53]
	v_mfma_f32_16x16x32_bf16 v[34:37], v[154:157], v[186:189], 0
	v_mfma_f32_16x16x32_bf16 v[34:37], v[158:161], v[190:193], v[34:37]
	v_mfma_f32_16x16x32_bf16 v[38:41], v[146:149], v[186:189], 0
	v_mfma_f32_16x16x32_bf16 v[38:41], v[150:153], v[190:193], v[38:41]
	v_mfma_f32_16x16x32_bf16 v[22:25], v[146:149], v[194:197], 0
	v_mfma_f32_16x16x32_bf16 v[22:25], v[150:153], v[198:201], v[22:25]
	v_mfma_f32_16x16x32_bf16 v[18:21], v[154:157], v[194:197], 0
	v_mfma_f32_16x16x32_bf16 v[18:21], v[158:161], v[198:201], v[18:21]
	v_mfma_f32_16x16x32_bf16 v[2:5], v[154:157], v[202:205], 0
	v_mfma_f32_16x16x32_bf16 v[2:5], v[158:161], v[206:209], v[2:5]
	s_setprio 2
	s_barrier
	v_mfma_f32_16x16x32_bf16 v[6:9], v[146:149], v[202:205], 0
	v_mfma_f32_16x16x32_bf16 v[6:9], v[150:153], v[206:209], v[6:9]
	s_setprio 0
	s_setprio 3
	ds_read_b128 v[130:133], v184
	ds_read_b128 v[134:137], v184 offset:1024
	ds_read_b128 v[138:141], v184 offset:2048
	ds_read_b128 v[142:145], v184 offset:3072
	ds_read_b128 v[146:149], v185
	ds_read_b128 v[150:153], v185 offset:1024
	ds_read_b128 v[154:157], v185 offset:2048
	ds_read_b128 v[158:161], v185 offset:3072
	ds_read_b128 v[166:169], v183 offset:32768
	ds_read_b128 v[170:173], v183 offset:33792
	ds_read_b128 v[186:189], v183 offset:34816
	ds_read_b128 v[190:193], v183 offset:35840
	ds_read_b128 v[194:197], v183 offset:36864
	ds_read_b128 v[198:201], v183 offset:37888
	ds_read_b128 v[202:205], v183 offset:38912
	ds_read_b128 v[206:209], v183 offset:39936
	s_mov_b32 s79, m0
	s_mov_b32 m0, s34
	s_nop 0
	global_load_lds_dwordx4 v1, s[24:25]
	s_mov_b32 m0, s79
	s_nop 0
	s_mov_b32 s79, m0
	s_mov_b32 m0, s41
	s_nop 0
	global_load_lds_dwordx4 v177, s[24:25]
	s_mov_b32 m0, s79
	s_add_u32 s24, s24, 0x80000
	s_addc_u32 s25, s25, 0
	s_mov_b32 s79, m0
	s_mov_b32 m0, s42
	s_nop 0
	global_load_lds_dwordx4 v1, s[24:25]
	s_mov_b32 m0, s79
	s_nop 0
	s_mov_b32 s79, m0
	s_mov_b32 m0, s43
	s_nop 0
	global_load_lds_dwordx4 v177, s[24:25]
	s_mov_b32 m0, s79
	s_setprio 0
	s_waitcnt vmcnt(8)
	s_waitcnt lgkmcnt(0)
	s_barrier
	s_setprio 1
	s_waitcnt lgkmcnt(7)
	v_mfma_f32_16x16x32_bf16 v[126:129], v[130:133], v[166:169], v[126:129]
	v_mfma_f32_16x16x32_bf16 v[126:129], v[134:137], v[170:173], v[126:129]
	s_waitcnt lgkmcnt(5)
	v_mfma_f32_16x16x32_bf16 v[122:125], v[138:141], v[166:169], v[122:125]
	v_mfma_f32_16x16x32_bf16 v[122:125], v[142:145], v[170:173], v[122:125]
	s_waitcnt lgkmcnt(3)
	v_mfma_f32_16x16x32_bf16 v[114:117], v[138:141], v[186:189], v[114:117]
	v_mfma_f32_16x16x32_bf16 v[114:117], v[142:145], v[190:193], v[114:117]
	s_waitcnt lgkmcnt(1)
	v_mfma_f32_16x16x32_bf16 v[118:121], v[130:133], v[186:189], v[118:121]
	v_mfma_f32_16x16x32_bf16 v[118:121], v[134:137], v[190:193], v[118:121]
	v_mfma_f32_16x16x32_bf16 v[94:97], v[130:133], v[194:197], v[94:97]
	v_mfma_f32_16x16x32_bf16 v[94:97], v[134:137], v[198:201], v[94:97]
	v_mfma_f32_16x16x32_bf16 v[90:93], v[138:141], v[194:197], v[90:93]
	v_mfma_f32_16x16x32_bf16 v[90:93], v[142:145], v[198:201], v[90:93]
	v_mfma_f32_16x16x32_bf16 v[78:81], v[138:141], v[202:205], v[78:81]
	v_mfma_f32_16x16x32_bf16 v[78:81], v[142:145], v[206:209], v[78:81]
	s_waitcnt lgkmcnt(0)
	v_mfma_f32_16x16x32_bf16 v[86:89], v[130:133], v[202:205], v[86:89]
	v_mfma_f32_16x16x32_bf16 v[86:89], v[134:137], v[206:209], v[86:89]
	s_setprio 0
	s_setprio 1
	v_mfma_f32_16x16x32_bf16 v[110:113], v[146:149], v[166:169], v[110:113]
	v_mfma_f32_16x16x32_bf16 v[110:113], v[150:153], v[170:173], v[110:113]
	v_mfma_f32_16x16x32_bf16 v[106:109], v[154:157], v[166:169], v[106:109]
	v_mfma_f32_16x16x32_bf16 v[106:109], v[158:161], v[170:173], v[106:109]
	v_mfma_f32_16x16x32_bf16 v[98:101], v[154:157], v[186:189], v[98:101]
	v_mfma_f32_16x16x32_bf16 v[98:101], v[158:161], v[190:193], v[98:101]
	v_mfma_f32_16x16x32_bf16 v[102:105], v[146:149], v[186:189], v[102:105]
	v_mfma_f32_16x16x32_bf16 v[102:105], v[150:153], v[190:193], v[102:105]
	v_mfma_f32_16x16x32_bf16 v[82:85], v[146:149], v[194:197], v[82:85]
	v_mfma_f32_16x16x32_bf16 v[82:85], v[150:153], v[198:201], v[82:85]
	v_mfma_f32_16x16x32_bf16 v[74:77], v[154:157], v[194:197], v[74:77]
	v_mfma_f32_16x16x32_bf16 v[74:77], v[158:161], v[198:201], v[74:77]
	v_mfma_f32_16x16x32_bf16 v[66:69], v[154:157], v[202:205], v[66:69]
	v_mfma_f32_16x16x32_bf16 v[66:69], v[158:161], v[206:209], v[66:69]
	s_setprio 2
	s_barrier
	v_mfma_f32_16x16x32_bf16 v[70:73], v[146:149], v[202:205], v[70:73]
	v_mfma_f32_16x16x32_bf16 v[70:73], v[150:153], v[206:209], v[70:73]
	s_setprio 0
	s_setprio 3
	ds_read_b128 v[166:169], v183 offset:49152
	ds_read_b128 v[170:173], v183 offset:50176
	ds_read_b128 v[186:189], v183 offset:51200
	ds_read_b128 v[190:193], v183 offset:52224
	ds_read_b128 v[194:197], v183 offset:53248
	ds_read_b128 v[198:201], v183 offset:54272
	ds_read_b128 v[202:205], v183 offset:55296
	ds_read_b128 v[206:209], v183 offset:56320
	s_add_u32 s24, s22, 0x80
	s_addc_u32 s25, s23, 0
	s_mov_b32 s79, m0
	s_mov_b32 m0, s46
	s_nop 0
	global_load_lds_dwordx4 v176, s[24:25]
	s_mov_b32 m0, s79
	s_add_u32 s22, s22, 0x80080
	s_mov_b32 s79, m0
	s_mov_b32 m0, s47
	s_nop 0
	global_load_lds_dwordx4 v178, s[24:25]
	s_mov_b32 m0, s79
	s_addc_u32 s23, s23, 0
	s_mov_b32 s24, m0
	s_mov_b32 m0, s48
	s_nop 0
	global_load_lds_dwordx4 v176, s[22:23]
	s_mov_b32 m0, s24
	s_nop 0
	s_mov_b32 s24, m0
	s_mov_b32 m0, s49
	s_nop 0
	global_load_lds_dwordx4 v178, s[22:23]
	s_mov_b32 m0, s24
	s_setprio 0
	s_waitcnt vmcnt(4)
	s_waitcnt lgkmcnt(0)
	s_barrier
	s_setprio 1
	s_waitcnt lgkmcnt(7)
	v_mfma_f32_16x16x32_bf16 v[62:65], v[130:133], v[166:169], v[62:65]
	v_mfma_f32_16x16x32_bf16 v[62:65], v[134:137], v[170:173], v[62:65]
	s_waitcnt lgkmcnt(5)
	v_mfma_f32_16x16x32_bf16 v[58:61], v[138:141], v[166:169], v[58:61]
	v_mfma_f32_16x16x32_bf16 v[58:61], v[142:145], v[170:173], v[58:61]
	s_waitcnt lgkmcnt(3)
	v_mfma_f32_16x16x32_bf16 v[42:45], v[138:141], v[186:189], v[42:45]
	v_mfma_f32_16x16x32_bf16 v[42:45], v[142:145], v[190:193], v[42:45]
	s_waitcnt lgkmcnt(1)
	v_mfma_f32_16x16x32_bf16 v[46:49], v[130:133], v[186:189], v[46:49]
	v_mfma_f32_16x16x32_bf16 v[46:49], v[134:137], v[190:193], v[46:49]
	v_mfma_f32_16x16x32_bf16 v[30:33], v[130:133], v[194:197], v[30:33]
	v_mfma_f32_16x16x32_bf16 v[30:33], v[134:137], v[198:201], v[30:33]
	v_mfma_f32_16x16x32_bf16 v[26:29], v[138:141], v[194:197], v[26:29]
	v_mfma_f32_16x16x32_bf16 v[26:29], v[142:145], v[198:201], v[26:29]
	v_mfma_f32_16x16x32_bf16 v[10:13], v[138:141], v[202:205], v[10:13]
	v_mfma_f32_16x16x32_bf16 v[10:13], v[142:145], v[206:209], v[10:13]
	s_waitcnt lgkmcnt(0)
	v_mfma_f32_16x16x32_bf16 v[14:17], v[130:133], v[202:205], v[14:17]
	v_mfma_f32_16x16x32_bf16 v[14:17], v[134:137], v[206:209], v[14:17]
	s_setprio 0
	s_setprio 1
	v_mfma_f32_16x16x32_bf16 v[54:57], v[146:149], v[166:169], v[54:57]
	v_mfma_f32_16x16x32_bf16 v[54:57], v[150:153], v[170:173], v[54:57]
	v_mfma_f32_16x16x32_bf16 v[50:53], v[154:157], v[166:169], v[50:53]
	v_mfma_f32_16x16x32_bf16 v[50:53], v[158:161], v[170:173], v[50:53]
	v_mfma_f32_16x16x32_bf16 v[34:37], v[154:157], v[186:189], v[34:37]
	v_mfma_f32_16x16x32_bf16 v[34:37], v[158:161], v[190:193], v[34:37]
	v_mfma_f32_16x16x32_bf16 v[38:41], v[146:149], v[186:189], v[38:41]
	v_mfma_f32_16x16x32_bf16 v[38:41], v[150:153], v[190:193], v[38:41]
	v_mfma_f32_16x16x32_bf16 v[22:25], v[146:149], v[194:197], v[22:25]
	v_mfma_f32_16x16x32_bf16 v[22:25], v[150:153], v[198:201], v[22:25]
	v_mfma_f32_16x16x32_bf16 v[18:21], v[154:157], v[194:197], v[18:21]
	v_mfma_f32_16x16x32_bf16 v[18:21], v[158:161], v[198:201], v[18:21]
	v_mfma_f32_16x16x32_bf16 v[2:5], v[154:157], v[202:205], v[2:5]
	v_mfma_f32_16x16x32_bf16 v[2:5], v[158:161], v[206:209], v[2:5]
	s_setprio 2
	s_barrier
	v_mfma_f32_16x16x32_bf16 v[6:9], v[146:149], v[202:205], v[6:9]
	v_mfma_f32_16x16x32_bf16 v[6:9], v[150:153], v[206:209], v[6:9]
	s_setprio 0
	s_add_i32 s78, s78, 2
	s_add_u32 s74, s74, 0x100
	s_addc_u32 s75, s75, 0
	s_add_u32 s20, s20, 0x100
	s_addc_u32 s21, s21, 0
	s_add_u32 s76, s76, 0x100
	s_addc_u32 s77, s77, 0
	s_cmp_gt_u32 s78, 29
	.p2align 6
.LBB0_1053:
	s_setprio 3
	ds_read_b128 v[130:133], v181
	ds_read_b128 v[134:137], v181 offset:1024
	ds_read_b128 v[138:141], v181 offset:2048
	ds_read_b128 v[142:145], v181 offset:3072
	ds_read_b128 v[146:149], v182
	ds_read_b128 v[150:153], v182 offset:1024
	ds_read_b128 v[154:157], v182 offset:2048
	ds_read_b128 v[158:161], v182 offset:3072
	s_cmp_eq_u32 s78, 28
	s_cselect_b32 s23, s11, s75
	s_cselect_b32 s22, s73, s74
	s_cselect_b32 s25, s13, s77
	s_cselect_b32 s24, s67, s76
	ds_read_b128 v[166:169], v183
	ds_read_b128 v[170:173], v183 offset:1024
	ds_read_b128 v[186:189], v183 offset:2048
	ds_read_b128 v[190:193], v183 offset:3072
	ds_read_b128 v[194:197], v183 offset:4096
	ds_read_b128 v[198:201], v183 offset:5120
	ds_read_b128 v[202:205], v183 offset:6144
	ds_read_b128 v[206:209], v183 offset:7168
	s_add_u32 s80, s20, 0xfff80000
	s_addc_u32 s81, s21, -1
	s_mov_b32 s79, m0
	s_mov_b32 m0, s58
	s_nop 0
	global_load_lds_dwordx4 v1, s[80:81]
	s_mov_b32 m0, s79
	s_nop 0
	s_mov_b32 s79, m0
	s_mov_b32 m0, s64
	s_nop 0
	global_load_lds_dwordx4 v177, s[80:81]
	s_mov_b32 m0, s79
	s_nop 0
	s_mov_b32 s79, m0
	s_mov_b32 m0, s59
	s_nop 0
	global_load_lds_dwordx4 v1, s[20:21]
	s_mov_b32 m0, s79
	s_nop 0
	s_mov_b32 s79, m0
	s_mov_b32 m0, s65
	s_nop 0
	global_load_lds_dwordx4 v177, s[20:21]
	s_mov_b32 m0, s79
	s_setprio 0
	s_waitcnt vmcnt(8)
	s_waitcnt lgkmcnt(0)
	s_barrier
	s_setprio 1
	s_waitcnt lgkmcnt(7)
	v_mfma_f32_16x16x32_bf16 v[126:129], v[130:133], v[166:169], v[126:129]
	v_mfma_f32_16x16x32_bf16 v[126:129], v[134:137], v[170:173], v[126:129]
	s_waitcnt lgkmcnt(5)
	v_mfma_f32_16x16x32_bf16 v[122:125], v[138:141], v[166:169], v[122:125]
	v_mfma_f32_16x16x32_bf16 v[122:125], v[142:145], v[170:173], v[122:125]
	s_waitcnt lgkmcnt(3)
	v_mfma_f32_16x16x32_bf16 v[114:117], v[138:141], v[186:189], v[114:117]
	v_mfma_f32_16x16x32_bf16 v[114:117], v[142:145], v[190:193], v[114:117]
	s_waitcnt lgkmcnt(1)
	v_mfma_f32_16x16x32_bf16 v[118:121], v[130:133], v[186:189], v[118:121]
	v_mfma_f32_16x16x32_bf16 v[118:121], v[134:137], v[190:193], v[118:121]
	v_mfma_f32_16x16x32_bf16 v[94:97], v[130:133], v[194:197], v[94:97]
	v_mfma_f32_16x16x32_bf16 v[94:97], v[134:137], v[198:201], v[94:97]
	v_mfma_f32_16x16x32_bf16 v[90:93], v[138:141], v[194:197], v[90:93]
	v_mfma_f32_16x16x32_bf16 v[90:93], v[142:145], v[198:201], v[90:93]
	v_mfma_f32_16x16x32_bf16 v[78:81], v[138:141], v[202:205], v[78:81]
	v_mfma_f32_16x16x32_bf16 v[78:81], v[142:145], v[206:209], v[78:81]
	s_waitcnt lgkmcnt(0)
	v_mfma_f32_16x16x32_bf16 v[86:89], v[130:133], v[202:205], v[86:89]
	v_mfma_f32_16x16x32_bf16 v[86:89], v[134:137], v[206:209], v[86:89]
	s_setprio 0
	s_setprio 1
	v_mfma_f32_16x16x32_bf16 v[110:113], v[146:149], v[166:169], v[110:113]
	v_mfma_f32_16x16x32_bf16 v[110:113], v[150:153], v[170:173], v[110:113]
	v_mfma_f32_16x16x32_bf16 v[106:109], v[154:157], v[166:169], v[106:109]
	v_mfma_f32_16x16x32_bf16 v[106:109], v[158:161], v[170:173], v[106:109]
	v_mfma_f32_16x16x32_bf16 v[98:101], v[154:157], v[186:189], v[98:101]
	v_mfma_f32_16x16x32_bf16 v[98:101], v[158:161], v[190:193], v[98:101]
	v_mfma_f32_16x16x32_bf16 v[102:105], v[146:149], v[186:189], v[102:105]
	v_mfma_f32_16x16x32_bf16 v[102:105], v[150:153], v[190:193], v[102:105]
	v_mfma_f32_16x16x32_bf16 v[82:85], v[146:149], v[194:197], v[82:85]
	v_mfma_f32_16x16x32_bf16 v[82:85], v[150:153], v[198:201], v[82:85]
	v_mfma_f32_16x16x32_bf16 v[74:77], v[154:157], v[194:197], v[74:77]
	v_mfma_f32_16x16x32_bf16 v[74:77], v[158:161], v[198:201], v[74:77]
	v_mfma_f32_16x16x32_bf16 v[66:69], v[154:157], v[202:205], v[66:69]
	v_mfma_f32_16x16x32_bf16 v[66:69], v[158:161], v[206:209], v[66:69]
	s_setprio 2
	s_barrier
	v_mfma_f32_16x16x32_bf16 v[70:73], v[146:149], v[202:205], v[70:73]
	v_mfma_f32_16x16x32_bf16 v[70:73], v[150:153], v[206:209], v[70:73]
	s_setprio 0
	s_setprio 3
	ds_read_b128 v[166:169], v183 offset:16384
	ds_read_b128 v[170:173], v183 offset:17408
	ds_read_b128 v[186:189], v183 offset:18432
	ds_read_b128 v[190:193], v183 offset:19456
	ds_read_b128 v[194:197], v183 offset:20480
	ds_read_b128 v[198:201], v183 offset:21504
	ds_read_b128 v[202:205], v183 offset:22528
	ds_read_b128 v[206:209], v183 offset:23552
	s_mov_b32 s79, m0
	s_mov_b32 m0, s35
	s_nop 0
	global_load_lds_dwordx4 v176, s[22:23]
	s_mov_b32 m0, s79
	s_add_u32 s80, s22, 0x80000
	s_mov_b32 s79, m0
	s_mov_b32 m0, s36
	s_nop 0
	global_load_lds_dwordx4 v178, s[22:23]
	s_mov_b32 m0, s79
	s_addc_u32 s81, s23, 0
	s_mov_b32 s79, m0
	s_mov_b32 m0, s37
	s_nop 0
	global_load_lds_dwordx4 v176, s[80:81]
	s_mov_b32 m0, s79
	s_nop 0
	s_mov_b32 s79, m0
	s_mov_b32 m0, s40
	s_nop 0
	global_load_lds_dwordx4 v178, s[80:81]
	s_mov_b32 m0, s79
	s_setprio 0
	s_waitcnt vmcnt(4)
	s_waitcnt lgkmcnt(0)
	s_barrier
	s_setprio 1
	s_waitcnt lgkmcnt(7)
	v_mfma_f32_16x16x32_bf16 v[62:65], v[130:133], v[166:169], v[62:65]
	v_mfma_f32_16x16x32_bf16 v[62:65], v[134:137], v[170:173], v[62:65]
	s_waitcnt lgkmcnt(5)
	v_mfma_f32_16x16x32_bf16 v[58:61], v[138:141], v[166:169], v[58:61]
	v_mfma_f32_16x16x32_bf16 v[58:61], v[142:145], v[170:173], v[58:61]
	s_waitcnt lgkmcnt(3)
	v_mfma_f32_16x16x32_bf16 v[42:45], v[138:141], v[186:189], v[42:45]
	v_mfma_f32_16x16x32_bf16 v[42:45], v[142:145], v[190:193], v[42:45]
	s_waitcnt lgkmcnt(1)
	v_mfma_f32_16x16x32_bf16 v[46:49], v[130:133], v[186:189], v[46:49]
	v_mfma_f32_16x16x32_bf16 v[46:49], v[134:137], v[190:193], v[46:49]
	v_mfma_f32_16x16x32_bf16 v[30:33], v[130:133], v[194:197], v[30:33]
	v_mfma_f32_16x16x32_bf16 v[30:33], v[134:137], v[198:201], v[30:33]
	v_mfma_f32_16x16x32_bf16 v[26:29], v[138:141], v[194:197], v[26:29]
	v_mfma_f32_16x16x32_bf16 v[26:29], v[142:145], v[198:201], v[26:29]
	v_mfma_f32_16x16x32_bf16 v[10:13], v[138:141], v[202:205], v[10:13]
	v_mfma_f32_16x16x32_bf16 v[10:13], v[142:145], v[206:209], v[10:13]
	s_waitcnt lgkmcnt(0)
	v_mfma_f32_16x16x32_bf16 v[14:17], v[130:133], v[202:205], v[14:17]
	v_mfma_f32_16x16x32_bf16 v[14:17], v[134:137], v[206:209], v[14:17]
	s_setprio 0
	s_setprio 1
	v_mfma_f32_16x16x32_bf16 v[54:57], v[146:149], v[166:169], v[54:57]
	v_mfma_f32_16x16x32_bf16 v[54:57], v[150:153], v[170:173], v[54:57]
	v_mfma_f32_16x16x32_bf16 v[50:53], v[154:157], v[166:169], v[50:53]
	v_mfma_f32_16x16x32_bf16 v[50:53], v[158:161], v[170:173], v[50:53]
	v_mfma_f32_16x16x32_bf16 v[34:37], v[154:157], v[186:189], v[34:37]
	v_mfma_f32_16x16x32_bf16 v[34:37], v[158:161], v[190:193], v[34:37]
	v_mfma_f32_16x16x32_bf16 v[38:41], v[146:149], v[186:189], v[38:41]
	v_mfma_f32_16x16x32_bf16 v[38:41], v[150:153], v[190:193], v[38:41]
	v_mfma_f32_16x16x32_bf16 v[22:25], v[146:149], v[194:197], v[22:25]
	v_mfma_f32_16x16x32_bf16 v[22:25], v[150:153], v[198:201], v[22:25]
	v_mfma_f32_16x16x32_bf16 v[18:21], v[154:157], v[194:197], v[18:21]
	v_mfma_f32_16x16x32_bf16 v[18:21], v[158:161], v[198:201], v[18:21]
	v_mfma_f32_16x16x32_bf16 v[2:5], v[154:157], v[202:205], v[2:5]
	v_mfma_f32_16x16x32_bf16 v[2:5], v[158:161], v[206:209], v[2:5]
	s_setprio 2
	s_barrier
	v_mfma_f32_16x16x32_bf16 v[6:9], v[146:149], v[202:205], v[6:9]
	v_mfma_f32_16x16x32_bf16 v[6:9], v[150:153], v[206:209], v[6:9]
	s_setprio 0
	s_setprio 3
	ds_read_b128 v[130:133], v184
	ds_read_b128 v[134:137], v184 offset:1024
	ds_read_b128 v[138:141], v184 offset:2048
	ds_read_b128 v[142:145], v184 offset:3072
	ds_read_b128 v[146:149], v185
	ds_read_b128 v[150:153], v185 offset:1024
	ds_read_b128 v[154:157], v185 offset:2048
	ds_read_b128 v[158:161], v185 offset:3072
	ds_read_b128 v[166:169], v183 offset:32768
	ds_read_b128 v[170:173], v183 offset:33792
	ds_read_b128 v[186:189], v183 offset:34816
	ds_read_b128 v[190:193], v183 offset:35840
	ds_read_b128 v[194:197], v183 offset:36864
	ds_read_b128 v[198:201], v183 offset:37888
	ds_read_b128 v[202:205], v183 offset:38912
	ds_read_b128 v[206:209], v183 offset:39936
	s_mov_b32 s79, m0
	s_mov_b32 m0, s34
	s_nop 0
	global_load_lds_dwordx4 v1, s[24:25]
	s_mov_b32 m0, s79
	s_nop 0
	s_mov_b32 s79, m0
	s_mov_b32 m0, s41
	s_nop 0
	global_load_lds_dwordx4 v177, s[24:25]
	s_mov_b32 m0, s79
	s_add_u32 s24, s24, 0x80000
	s_addc_u32 s25, s25, 0
	s_mov_b32 s79, m0
	s_mov_b32 m0, s42
	s_nop 0
	global_load_lds_dwordx4 v1, s[24:25]
	s_mov_b32 m0, s79
	s_nop 0
	s_mov_b32 s79, m0
	s_mov_b32 m0, s43
	s_nop 0
	global_load_lds_dwordx4 v177, s[24:25]
	s_mov_b32 m0, s79
	s_setprio 0
	s_waitcnt vmcnt(8)
	s_waitcnt lgkmcnt(0)
	s_barrier
	s_setprio 1
	s_waitcnt lgkmcnt(7)
	v_mfma_f32_16x16x32_bf16 v[126:129], v[130:133], v[166:169], v[126:129]
	v_mfma_f32_16x16x32_bf16 v[126:129], v[134:137], v[170:173], v[126:129]
	s_waitcnt lgkmcnt(5)
	v_mfma_f32_16x16x32_bf16 v[122:125], v[138:141], v[166:169], v[122:125]
	v_mfma_f32_16x16x32_bf16 v[122:125], v[142:145], v[170:173], v[122:125]
	s_waitcnt lgkmcnt(3)
	v_mfma_f32_16x16x32_bf16 v[114:117], v[138:141], v[186:189], v[114:117]
	v_mfma_f32_16x16x32_bf16 v[114:117], v[142:145], v[190:193], v[114:117]
	s_waitcnt lgkmcnt(1)
	v_mfma_f32_16x16x32_bf16 v[118:121], v[130:133], v[186:189], v[118:121]
	v_mfma_f32_16x16x32_bf16 v[118:121], v[134:137], v[190:193], v[118:121]
	v_mfma_f32_16x16x32_bf16 v[94:97], v[130:133], v[194:197], v[94:97]
	v_mfma_f32_16x16x32_bf16 v[94:97], v[134:137], v[198:201], v[94:97]
	v_mfma_f32_16x16x32_bf16 v[90:93], v[138:141], v[194:197], v[90:93]
	v_mfma_f32_16x16x32_bf16 v[90:93], v[142:145], v[198:201], v[90:93]
	v_mfma_f32_16x16x32_bf16 v[78:81], v[138:141], v[202:205], v[78:81]
	v_mfma_f32_16x16x32_bf16 v[78:81], v[142:145], v[206:209], v[78:81]
	s_waitcnt lgkmcnt(0)
	v_mfma_f32_16x16x32_bf16 v[86:89], v[130:133], v[202:205], v[86:89]
	v_mfma_f32_16x16x32_bf16 v[86:89], v[134:137], v[206:209], v[86:89]
	s_setprio 0
	s_setprio 1
	v_mfma_f32_16x16x32_bf16 v[110:113], v[146:149], v[166:169], v[110:113]
	v_mfma_f32_16x16x32_bf16 v[110:113], v[150:153], v[170:173], v[110:113]
	v_mfma_f32_16x16x32_bf16 v[106:109], v[154:157], v[166:169], v[106:109]
	v_mfma_f32_16x16x32_bf16 v[106:109], v[158:161], v[170:173], v[106:109]
	v_mfma_f32_16x16x32_bf16 v[98:101], v[154:157], v[186:189], v[98:101]
	v_mfma_f32_16x16x32_bf16 v[98:101], v[158:161], v[190:193], v[98:101]
	v_mfma_f32_16x16x32_bf16 v[102:105], v[146:149], v[186:189], v[102:105]
	v_mfma_f32_16x16x32_bf16 v[102:105], v[150:153], v[190:193], v[102:105]
	v_mfma_f32_16x16x32_bf16 v[82:85], v[146:149], v[194:197], v[82:85]
	v_mfma_f32_16x16x32_bf16 v[82:85], v[150:153], v[198:201], v[82:85]
	v_mfma_f32_16x16x32_bf16 v[74:77], v[154:157], v[194:197], v[74:77]
	v_mfma_f32_16x16x32_bf16 v[74:77], v[158:161], v[198:201], v[74:77]
	v_mfma_f32_16x16x32_bf16 v[66:69], v[154:157], v[202:205], v[66:69]
	v_mfma_f32_16x16x32_bf16 v[66:69], v[158:161], v[206:209], v[66:69]
	s_setprio 2
	s_barrier
	v_mfma_f32_16x16x32_bf16 v[70:73], v[146:149], v[202:205], v[70:73]
	v_mfma_f32_16x16x32_bf16 v[70:73], v[150:153], v[206:209], v[70:73]
	s_setprio 0
	s_setprio 3
	ds_read_b128 v[166:169], v183 offset:49152
	ds_read_b128 v[170:173], v183 offset:50176
	ds_read_b128 v[186:189], v183 offset:51200
	ds_read_b128 v[190:193], v183 offset:52224
	ds_read_b128 v[194:197], v183 offset:53248
	ds_read_b128 v[198:201], v183 offset:54272
	ds_read_b128 v[202:205], v183 offset:55296
	ds_read_b128 v[206:209], v183 offset:56320
	s_add_u32 s24, s22, 0x80
	s_addc_u32 s25, s23, 0
	s_mov_b32 s79, m0
	s_mov_b32 m0, s46
	s_nop 0
	global_load_lds_dwordx4 v176, s[24:25]
	s_mov_b32 m0, s79
	s_add_u32 s22, s22, 0x80080
	s_mov_b32 s79, m0
	s_mov_b32 m0, s47
	s_nop 0
	global_load_lds_dwordx4 v178, s[24:25]
	s_mov_b32 m0, s79
	s_addc_u32 s23, s23, 0
	s_mov_b32 s24, m0
	s_mov_b32 m0, s48
	s_nop 0
	global_load_lds_dwordx4 v176, s[22:23]
	s_mov_b32 m0, s24
	s_nop 0
	s_mov_b32 s24, m0
	s_mov_b32 m0, s49
	s_nop 0
	global_load_lds_dwordx4 v178, s[22:23]
	s_mov_b32 m0, s24
	s_setprio 0
	s_waitcnt vmcnt(4)
	s_waitcnt lgkmcnt(0)
	s_barrier
	s_setprio 1
	s_waitcnt lgkmcnt(7)
	v_mfma_f32_16x16x32_bf16 v[62:65], v[130:133], v[166:169], v[62:65]
	v_mfma_f32_16x16x32_bf16 v[62:65], v[134:137], v[170:173], v[62:65]
	s_waitcnt lgkmcnt(5)
	v_mfma_f32_16x16x32_bf16 v[58:61], v[138:141], v[166:169], v[58:61]
	v_mfma_f32_16x16x32_bf16 v[58:61], v[142:145], v[170:173], v[58:61]
	s_waitcnt lgkmcnt(3)
	v_mfma_f32_16x16x32_bf16 v[42:45], v[138:141], v[186:189], v[42:45]
	v_mfma_f32_16x16x32_bf16 v[42:45], v[142:145], v[190:193], v[42:45]
	s_waitcnt lgkmcnt(1)
	v_mfma_f32_16x16x32_bf16 v[46:49], v[130:133], v[186:189], v[46:49]
	v_mfma_f32_16x16x32_bf16 v[46:49], v[134:137], v[190:193], v[46:49]
	v_mfma_f32_16x16x32_bf16 v[30:33], v[130:133], v[194:197], v[30:33]
	v_mfma_f32_16x16x32_bf16 v[30:33], v[134:137], v[198:201], v[30:33]
	v_mfma_f32_16x16x32_bf16 v[26:29], v[138:141], v[194:197], v[26:29]
	v_mfma_f32_16x16x32_bf16 v[26:29], v[142:145], v[198:201], v[26:29]
	v_mfma_f32_16x16x32_bf16 v[10:13], v[138:141], v[202:205], v[10:13]
	v_mfma_f32_16x16x32_bf16 v[10:13], v[142:145], v[206:209], v[10:13]
	s_waitcnt lgkmcnt(0)
	v_mfma_f32_16x16x32_bf16 v[14:17], v[130:133], v[202:205], v[14:17]
	v_mfma_f32_16x16x32_bf16 v[14:17], v[134:137], v[206:209], v[14:17]
	s_setprio 0
	s_setprio 1
	v_mfma_f32_16x16x32_bf16 v[54:57], v[146:149], v[166:169], v[54:57]
	v_mfma_f32_16x16x32_bf16 v[54:57], v[150:153], v[170:173], v[54:57]
	v_mfma_f32_16x16x32_bf16 v[50:53], v[154:157], v[166:169], v[50:53]
	v_mfma_f32_16x16x32_bf16 v[50:53], v[158:161], v[170:173], v[50:53]
	v_mfma_f32_16x16x32_bf16 v[34:37], v[154:157], v[186:189], v[34:37]
	v_mfma_f32_16x16x32_bf16 v[34:37], v[158:161], v[190:193], v[34:37]
	v_mfma_f32_16x16x32_bf16 v[38:41], v[146:149], v[186:189], v[38:41]
	v_mfma_f32_16x16x32_bf16 v[38:41], v[150:153], v[190:193], v[38:41]
	v_mfma_f32_16x16x32_bf16 v[22:25], v[146:149], v[194:197], v[22:25]
	v_mfma_f32_16x16x32_bf16 v[22:25], v[150:153], v[198:201], v[22:25]
	v_mfma_f32_16x16x32_bf16 v[18:21], v[154:157], v[194:197], v[18:21]
	v_mfma_f32_16x16x32_bf16 v[18:21], v[158:161], v[198:201], v[18:21]
	v_mfma_f32_16x16x32_bf16 v[2:5], v[154:157], v[202:205], v[2:5]
	v_mfma_f32_16x16x32_bf16 v[2:5], v[158:161], v[206:209], v[2:5]
	s_setprio 2
	s_barrier
	v_mfma_f32_16x16x32_bf16 v[6:9], v[146:149], v[202:205], v[6:9]
	v_mfma_f32_16x16x32_bf16 v[6:9], v[150:153], v[206:209], v[6:9]
	s_setprio 0
	s_add_i32 s78, s78, 2
	s_add_u32 s74, s74, 0x100
	s_addc_u32 s75, s75, 0
	s_add_u32 s20, s20, 0x100
	s_addc_u32 s21, s21, 0
	s_add_u32 s76, s76, 0x100
	s_addc_u32 s77, s77, 0
	s_cmp_gt_u32 s78, 29
	s_cbranch_scc0 .LBB0_1053
	s_and_b64 vcc, exec, s[8:9]
	s_cbranch_vccz .LBB0_1056
	s_barrier

.LBB0_1223:
	s_ashr_i32 s11, s10, 31
	s_lshl_b64 s[12:13], s[10:11], 20
	s_add_u32 s12, s26, s12
	s_addc_u32 s13, s27, s13
	s_and_b64 s[14:15], s[2:3], exec
	s_cselect_b32 s11, s13, s21
	s_cselect_b32 s66, s12, s20
	s_ashr_i32 s9, s8, 31
	s_lshl_b64 s[14:15], s[8:9], 20
	s_add_u32 s14, s28, s14
	s_addc_u32 s15, s29, s15
	s_and_b64 s[22:23], s[2:3], exec
	s_cselect_b32 s9, s15, s19
	s_cselect_b32 s67, s14, s18
	s_add_u32 s73, s18, 0x100
	s_addc_u32 s74, s19, 0
	s_add_u32 s18, s20, 0x80080
	s_addc_u32 s19, s21, 0
	s_add_u32 s75, s20, 0x100
	s_addc_u32 s76, s21, 0
	s_mov_b32 s77, -2
	s_setprio 3
	ds_read_b128 v[148:151], v143
	ds_read_b128 v[152:155], v143 offset:1024
	ds_read_b128 v[156:159], v143 offset:2048
	ds_read_b128 v[160:163], v143 offset:3072
	ds_read_b128 v[164:167], v144
	ds_read_b128 v[168:171], v144 offset:1024
	ds_read_b128 v[172:175], v144 offset:2048
	ds_read_b128 v[176:179], v144 offset:3072
	s_cmp_eq_u32 s77, 28
	s_cselect_b32 s21, s9, s74
	s_cselect_b32 s20, s67, s73
	s_cselect_b32 s23, s11, s76
	s_cselect_b32 s22, s66, s75
	ds_read_b128 v[180:183], v145
	ds_read_b128 v[184:187], v145 offset:1024
	ds_read_b128 v[188:191], v145 offset:2048
	ds_read_b128 v[192:195], v145 offset:3072
	ds_read_b128 v[196:199], v145 offset:4096
	ds_read_b128 v[200:203], v145 offset:5120
	ds_read_b128 v[204:207], v145 offset:6144
	ds_read_b128 v[208:211], v145 offset:7168
	s_add_u32 s78, s18, 0xfff80000
	s_addc_u32 s79, s19, -1
	s_mov_b32 s80, m0
	s_mov_b32 m0, s56
	s_nop 0
	global_load_lds_dwordx4 v138, s[78:79]
	s_mov_b32 m0, s80
	s_nop 0
	s_mov_b32 s80, m0
	s_mov_b32 m0, s59
	s_nop 0
	global_load_lds_dwordx4 v140, s[78:79]
	s_mov_b32 m0, s80
	s_mov_b32 s78, m0
	s_mov_b32 m0, s57
	s_nop 0
	global_load_lds_dwordx4 v138, s[18:19]
	s_mov_b32 m0, s78
	s_nop 0
	s_mov_b32 s78, m0
	s_mov_b32 m0, s64
	s_nop 0
	global_load_lds_dwordx4 v140, s[18:19]
	s_mov_b32 m0, s78
	s_setprio 0
	s_waitcnt vmcnt(8)
	s_waitcnt lgkmcnt(0)
	s_barrier
	s_setprio 1
	s_waitcnt lgkmcnt(7)
	v_mfma_f32_16x16x32_bf16 v[126:129], v[148:151], v[180:183], 0
	v_mfma_f32_16x16x32_bf16 v[126:129], v[152:155], v[184:187], v[126:129]
	s_waitcnt lgkmcnt(5)
	v_mfma_f32_16x16x32_bf16 v[122:125], v[156:159], v[180:183], 0
	v_mfma_f32_16x16x32_bf16 v[122:125], v[160:163], v[184:187], v[122:125]
	s_waitcnt lgkmcnt(3)
	v_mfma_f32_16x16x32_bf16 v[106:109], v[156:159], v[188:191], 0
	v_mfma_f32_16x16x32_bf16 v[106:109], v[160:163], v[192:195], v[106:109]
	s_waitcnt lgkmcnt(1)
	v_mfma_f32_16x16x32_bf16 v[110:113], v[148:151], v[188:191], 0
	v_mfma_f32_16x16x32_bf16 v[110:113], v[152:155], v[192:195], v[110:113]
	v_mfma_f32_16x16x32_bf16 v[94:97], v[148:151], v[196:199], 0
	v_mfma_f32_16x16x32_bf16 v[94:97], v[152:155], v[200:203], v[94:97]
	v_mfma_f32_16x16x32_bf16 v[90:93], v[156:159], v[196:199], 0
	v_mfma_f32_16x16x32_bf16 v[90:93], v[160:163], v[200:203], v[90:93]
	v_mfma_f32_16x16x32_bf16 v[74:77], v[156:159], v[204:207], 0
	v_mfma_f32_16x16x32_bf16 v[74:77], v[160:163], v[208:211], v[74:77]
	s_waitcnt lgkmcnt(0)
	v_mfma_f32_16x16x32_bf16 v[78:81], v[148:151], v[204:207], 0
	v_mfma_f32_16x16x32_bf16 v[78:81], v[152:155], v[208:211], v[78:81]
	s_setprio 0
	s_setprio 1
	v_mfma_f32_16x16x32_bf16 v[118:121], v[164:167], v[180:183], 0
	v_mfma_f32_16x16x32_bf16 v[118:121], v[168:171], v[184:187], v[118:121]
	v_mfma_f32_16x16x32_bf16 v[114:117], v[172:175], v[180:183], 0
	v_mfma_f32_16x16x32_bf16 v[114:117], v[176:179], v[184:187], v[114:117]
	v_mfma_f32_16x16x32_bf16 v[98:101], v[172:175], v[188:191], 0
	v_mfma_f32_16x16x32_bf16 v[98:101], v[176:179], v[192:195], v[98:101]
	v_mfma_f32_16x16x32_bf16 v[102:105], v[164:167], v[188:191], 0
	v_mfma_f32_16x16x32_bf16 v[102:105], v[168:171], v[192:195], v[102:105]
	v_mfma_f32_16x16x32_bf16 v[86:89], v[164:167], v[196:199], 0
	v_mfma_f32_16x16x32_bf16 v[86:89], v[168:171], v[200:203], v[86:89]
	v_mfma_f32_16x16x32_bf16 v[82:85], v[172:175], v[196:199], 0
	v_mfma_f32_16x16x32_bf16 v[82:85], v[176:179], v[200:203], v[82:85]
	v_mfma_f32_16x16x32_bf16 v[66:69], v[172:175], v[204:207], 0
	v_mfma_f32_16x16x32_bf16 v[66:69], v[176:179], v[208:211], v[66:69]
	s_setprio 2
	s_barrier
	v_mfma_f32_16x16x32_bf16 v[70:73], v[164:167], v[204:207], 0
	v_mfma_f32_16x16x32_bf16 v[70:73], v[168:171], v[208:211], v[70:73]
	s_setprio 0
	s_setprio 3
	ds_read_b128 v[180:183], v145 offset:16384
	ds_read_b128 v[184:187], v145 offset:17408
	ds_read_b128 v[188:191], v145 offset:18432
	ds_read_b128 v[192:195], v145 offset:19456
	ds_read_b128 v[196:199], v145 offset:20480
	ds_read_b128 v[200:203], v145 offset:21504
	ds_read_b128 v[204:207], v145 offset:22528
	ds_read_b128 v[208:211], v145 offset:23552
	s_mov_b32 s78, m0
	s_mov_b32 m0, s35
	s_nop 0
	global_load_lds_dwordx4 v139, s[20:21]
	s_mov_b32 m0, s78
	s_nop 0
	s_mov_b32 s78, m0
	s_mov_b32 m0, s36
	s_nop 0
	global_load_lds_dwordx4 v141, s[20:21]
	s_mov_b32 m0, s78
	s_add_u32 s78, s20, 0x80000
	s_addc_u32 s79, s21, 0
	s_mov_b32 s80, m0
	s_mov_b32 m0, s37
	s_nop 0
	global_load_lds_dwordx4 v139, s[78:79]
	s_mov_b32 m0, s80
	s_nop 0
	s_mov_b32 s80, m0
	s_mov_b32 m0, s40
	s_nop 0
	global_load_lds_dwordx4 v141, s[78:79]
	s_mov_b32 m0, s80
	s_setprio 0
	s_waitcnt vmcnt(4)
	s_waitcnt lgkmcnt(0)
	s_barrier
	s_setprio 1
	s_waitcnt lgkmcnt(7)
	v_mfma_f32_16x16x32_bf16 v[62:65], v[148:151], v[180:183], 0
	v_mfma_f32_16x16x32_bf16 v[62:65], v[152:155], v[184:187], v[62:65]
	s_waitcnt lgkmcnt(5)
	v_mfma_f32_16x16x32_bf16 v[58:61], v[156:159], v[180:183], 0
	v_mfma_f32_16x16x32_bf16 v[58:61], v[160:163], v[184:187], v[58:61]
	s_waitcnt lgkmcnt(3)
	v_mfma_f32_16x16x32_bf16 v[42:45], v[156:159], v[188:191], 0
	v_mfma_f32_16x16x32_bf16 v[42:45], v[160:163], v[192:195], v[42:45]
	s_waitcnt lgkmcnt(1)
	v_mfma_f32_16x16x32_bf16 v[46:49], v[148:151], v[188:191], 0
	v_mfma_f32_16x16x32_bf16 v[46:49], v[152:155], v[192:195], v[46:49]
	v_mfma_f32_16x16x32_bf16 v[30:33], v[148:151], v[196:199], 0
	v_mfma_f32_16x16x32_bf16 v[30:33], v[152:155], v[200:203], v[30:33]
	v_mfma_f32_16x16x32_bf16 v[26:29], v[156:159], v[196:199], 0
	v_mfma_f32_16x16x32_bf16 v[26:29], v[160:163], v[200:203], v[26:29]
	v_mfma_f32_16x16x32_bf16 v[10:13], v[156:159], v[204:207], 0
	v_mfma_f32_16x16x32_bf16 v[10:13], v[160:163], v[208:211], v[10:13]
	s_waitcnt lgkmcnt(0)
	v_mfma_f32_16x16x32_bf16 v[14:17], v[148:151], v[204:207], 0
	v_mfma_f32_16x16x32_bf16 v[14:17], v[152:155], v[208:211], v[14:17]
	s_setprio 0
	s_setprio 1
	v_mfma_f32_16x16x32_bf16 v[54:57], v[164:167], v[180:183], 0
	v_mfma_f32_16x16x32_bf16 v[54:57], v[168:171], v[184:187], v[54:57]
	v_mfma_f32_16x16x32_bf16 v[50:53], v[172:175], v[180:183], 0
	v_mfma_f32_16x16x32_bf16 v[50:53], v[176:179], v[184:187], v[50:53]
	v_mfma_f32_16x16x32_bf16 v[34:37], v[172:175], v[188:191], 0
	v_mfma_f32_16x16x32_bf16 v[34:37], v[176:179], v[192:195], v[34:37]
	v_mfma_f32_16x16x32_bf16 v[38:41], v[164:167], v[188:191], 0
	v_mfma_f32_16x16x32_bf16 v[38:41], v[168:171], v[192:195], v[38:41]
	v_mfma_f32_16x16x32_bf16 v[22:25], v[164:167], v[196:199], 0
	v_mfma_f32_16x16x32_bf16 v[22:25], v[168:171], v[200:203], v[22:25]
	v_mfma_f32_16x16x32_bf16 v[18:21], v[172:175], v[196:199], 0
	v_mfma_f32_16x16x32_bf16 v[18:21], v[176:179], v[200:203], v[18:21]
	v_mfma_f32_16x16x32_bf16 v[2:5], v[172:175], v[204:207], 0
	v_mfma_f32_16x16x32_bf16 v[2:5], v[176:179], v[208:211], v[2:5]
	s_setprio 2
	s_barrier
	v_mfma_f32_16x16x32_bf16 v[6:9], v[164:167], v[204:207], 0
	v_mfma_f32_16x16x32_bf16 v[6:9], v[168:171], v[208:211], v[6:9]
	s_setprio 0
	s_setprio 3
	ds_read_b128 v[148:151], v146
	ds_read_b128 v[152:155], v146 offset:1024
	ds_read_b128 v[156:159], v146 offset:2048
	ds_read_b128 v[160:163], v146 offset:3072
	ds_read_b128 v[164:167], v147
	ds_read_b128 v[168:171], v147 offset:1024
	ds_read_b128 v[172:175], v147 offset:2048
	ds_read_b128 v[176:179], v147 offset:3072
	ds_read_b128 v[180:183], v145 offset:32768
	ds_read_b128 v[184:187], v145 offset:33792
	ds_read_b128 v[188:191], v145 offset:34816
	ds_read_b128 v[192:195], v145 offset:35840
	ds_read_b128 v[196:199], v145 offset:36864
	ds_read_b128 v[200:203], v145 offset:37888
	ds_read_b128 v[204:207], v145 offset:38912
	ds_read_b128 v[208:211], v145 offset:39936
	s_mov_b32 s78, m0
	s_mov_b32 m0, s31
	s_nop 0
	global_load_lds_dwordx4 v138, s[22:23]
	s_mov_b32 m0, s78
	s_nop 0
	s_mov_b32 s78, m0
	s_mov_b32 m0, s41
	s_nop 0
	global_load_lds_dwordx4 v140, s[22:23]
	s_mov_b32 m0, s78
	s_add_u32 s22, s22, 0x80000
	s_addc_u32 s23, s23, 0
	s_mov_b32 s78, m0
	s_mov_b32 m0, s42
	s_nop 0
	global_load_lds_dwordx4 v138, s[22:23]
	s_mov_b32 m0, s78
	s_nop 0
	s_mov_b32 s78, m0
	s_mov_b32 m0, s43
	s_nop 0
	global_load_lds_dwordx4 v140, s[22:23]
	s_mov_b32 m0, s78
	s_setprio 0
	s_waitcnt vmcnt(8)
	s_waitcnt lgkmcnt(0)
	s_barrier
	s_setprio 1
	s_waitcnt lgkmcnt(7)
	v_mfma_f32_16x16x32_bf16 v[126:129], v[148:151], v[180:183], v[126:129]
	v_mfma_f32_16x16x32_bf16 v[126:129], v[152:155], v[184:187], v[126:129]
	s_waitcnt lgkmcnt(5)
	v_mfma_f32_16x16x32_bf16 v[122:125], v[156:159], v[180:183], v[122:125]
	v_mfma_f32_16x16x32_bf16 v[122:125], v[160:163], v[184:187], v[122:125]
	s_waitcnt lgkmcnt(3)
	v_mfma_f32_16x16x32_bf16 v[106:109], v[156:159], v[188:191], v[106:109]
	v_mfma_f32_16x16x32_bf16 v[106:109], v[160:163], v[192:195], v[106:109]
	s_waitcnt lgkmcnt(1)
	v_mfma_f32_16x16x32_bf16 v[110:113], v[148:151], v[188:191], v[110:113]
	v_mfma_f32_16x16x32_bf16 v[110:113], v[152:155], v[192:195], v[110:113]
	v_mfma_f32_16x16x32_bf16 v[94:97], v[148:151], v[196:199], v[94:97]
	v_mfma_f32_16x16x32_bf16 v[94:97], v[152:155], v[200:203], v[94:97]
	v_mfma_f32_16x16x32_bf16 v[90:93], v[156:159], v[196:199], v[90:93]
	v_mfma_f32_16x16x32_bf16 v[90:93], v[160:163], v[200:203], v[90:93]
	v_mfma_f32_16x16x32_bf16 v[74:77], v[156:159], v[204:207], v[74:77]
	v_mfma_f32_16x16x32_bf16 v[74:77], v[160:163], v[208:211], v[74:77]
	s_waitcnt lgkmcnt(0)
	v_mfma_f32_16x16x32_bf16 v[78:81], v[148:151], v[204:207], v[78:81]
	v_mfma_f32_16x16x32_bf16 v[78:81], v[152:155], v[208:211], v[78:81]
	s_setprio 0
	s_setprio 1
	v_mfma_f32_16x16x32_bf16 v[118:121], v[164:167], v[180:183], v[118:121]
	v_mfma_f32_16x16x32_bf16 v[118:121], v[168:171], v[184:187], v[118:121]
	v_mfma_f32_16x16x32_bf16 v[114:117], v[172:175], v[180:183], v[114:117]
	v_mfma_f32_16x16x32_bf16 v[114:117], v[176:179], v[184:187], v[114:117]
	v_mfma_f32_16x16x32_bf16 v[98:101], v[172:175], v[188:191], v[98:101]
	v_mfma_f32_16x16x32_bf16 v[98:101], v[176:179], v[192:195], v[98:101]
	v_mfma_f32_16x16x32_bf16 v[102:105], v[164:167], v[188:191], v[102:105]
	v_mfma_f32_16x16x32_bf16 v[102:105], v[168:171], v[192:195], v[102:105]
	v_mfma_f32_16x16x32_bf16 v[86:89], v[164:167], v[196:199], v[86:89]
	v_mfma_f32_16x16x32_bf16 v[86:89], v[168:171], v[200:203], v[86:89]
	v_mfma_f32_16x16x32_bf16 v[82:85], v[172:175], v[196:199], v[82:85]
	v_mfma_f32_16x16x32_bf16 v[82:85], v[176:179], v[200:203], v[82:85]
	v_mfma_f32_16x16x32_bf16 v[66:69], v[172:175], v[204:207], v[66:69]
	v_mfma_f32_16x16x32_bf16 v[66:69], v[176:179], v[208:211], v[66:69]
	s_setprio 2
	s_barrier
	v_mfma_f32_16x16x32_bf16 v[70:73], v[164:167], v[204:207], v[70:73]
	v_mfma_f32_16x16x32_bf16 v[70:73], v[168:171], v[208:211], v[70:73]
	s_setprio 0
	s_setprio 3
	ds_read_b128 v[180:183], v145 offset:49152
	ds_read_b128 v[184:187], v145 offset:50176
	ds_read_b128 v[188:191], v145 offset:51200
	ds_read_b128 v[192:195], v145 offset:52224
	ds_read_b128 v[196:199], v145 offset:53248
	ds_read_b128 v[200:203], v145 offset:54272
	ds_read_b128 v[204:207], v145 offset:55296
	ds_read_b128 v[208:211], v145 offset:56320
	s_add_u32 s22, s20, 0x80
	s_addc_u32 s23, s21, 0
	s_mov_b32 s78, m0
	s_mov_b32 m0, s46
	s_nop 0
	global_load_lds_dwordx4 v139, s[22:23]
	s_mov_b32 m0, s78
	s_add_u32 s20, s20, 0x80080
	s_mov_b32 s78, m0
	s_mov_b32 m0, s47
	s_nop 0
	global_load_lds_dwordx4 v141, s[22:23]
	s_mov_b32 m0, s78
	s_addc_u32 s21, s21, 0
	s_mov_b32 s22, m0
	s_mov_b32 m0, s48
	s_nop 0
	global_load_lds_dwordx4 v139, s[20:21]
	s_mov_b32 m0, s22
	s_nop 0
	s_mov_b32 s22, m0
	s_mov_b32 m0, s49
	s_nop 0
	global_load_lds_dwordx4 v141, s[20:21]
	s_mov_b32 m0, s22
	s_setprio 0
	s_waitcnt vmcnt(4)
	s_waitcnt lgkmcnt(0)
	s_barrier
	s_setprio 1
	s_waitcnt lgkmcnt(7)
	v_mfma_f32_16x16x32_bf16 v[62:65], v[148:151], v[180:183], v[62:65]
	v_mfma_f32_16x16x32_bf16 v[62:65], v[152:155], v[184:187], v[62:65]
	s_waitcnt lgkmcnt(5)
	v_mfma_f32_16x16x32_bf16 v[58:61], v[156:159], v[180:183], v[58:61]
	v_mfma_f32_16x16x32_bf16 v[58:61], v[160:163], v[184:187], v[58:61]
	s_waitcnt lgkmcnt(3)
	v_mfma_f32_16x16x32_bf16 v[42:45], v[156:159], v[188:191], v[42:45]
	v_mfma_f32_16x16x32_bf16 v[42:45], v[160:163], v[192:195], v[42:45]
	s_waitcnt lgkmcnt(1)
	v_mfma_f32_16x16x32_bf16 v[46:49], v[148:151], v[188:191], v[46:49]
	v_mfma_f32_16x16x32_bf16 v[46:49], v[152:155], v[192:195], v[46:49]
	v_mfma_f32_16x16x32_bf16 v[30:33], v[148:151], v[196:199], v[30:33]
	v_mfma_f32_16x16x32_bf16 v[30:33], v[152:155], v[200:203], v[30:33]
	v_mfma_f32_16x16x32_bf16 v[26:29], v[156:159], v[196:199], v[26:29]
	v_mfma_f32_16x16x32_bf16 v[26:29], v[160:163], v[200:203], v[26:29]
	v_mfma_f32_16x16x32_bf16 v[10:13], v[156:159], v[204:207], v[10:13]
	v_mfma_f32_16x16x32_bf16 v[10:13], v[160:163], v[208:211], v[10:13]
	s_waitcnt lgkmcnt(0)
	v_mfma_f32_16x16x32_bf16 v[14:17], v[148:151], v[204:207], v[14:17]
	v_mfma_f32_16x16x32_bf16 v[14:17], v[152:155], v[208:211], v[14:17]
	s_setprio 0
	s_setprio 1
	v_mfma_f32_16x16x32_bf16 v[54:57], v[164:167], v[180:183], v[54:57]
	v_mfma_f32_16x16x32_bf16 v[54:57], v[168:171], v[184:187], v[54:57]
	v_mfma_f32_16x16x32_bf16 v[50:53], v[172:175], v[180:183], v[50:53]
	v_mfma_f32_16x16x32_bf16 v[50:53], v[176:179], v[184:187], v[50:53]
	v_mfma_f32_16x16x32_bf16 v[34:37], v[172:175], v[188:191], v[34:37]
	v_mfma_f32_16x16x32_bf16 v[34:37], v[176:179], v[192:195], v[34:37]
	v_mfma_f32_16x16x32_bf16 v[38:41], v[164:167], v[188:191], v[38:41]
	v_mfma_f32_16x16x32_bf16 v[38:41], v[168:171], v[192:195], v[38:41]
	v_mfma_f32_16x16x32_bf16 v[22:25], v[164:167], v[196:199], v[22:25]
	v_mfma_f32_16x16x32_bf16 v[22:25], v[168:171], v[200:203], v[22:25]
	v_mfma_f32_16x16x32_bf16 v[18:21], v[172:175], v[196:199], v[18:21]
	v_mfma_f32_16x16x32_bf16 v[18:21], v[176:179], v[200:203], v[18:21]
	v_mfma_f32_16x16x32_bf16 v[2:5], v[172:175], v[204:207], v[2:5]
	v_mfma_f32_16x16x32_bf16 v[2:5], v[176:179], v[208:211], v[2:5]
	s_setprio 2
	s_barrier
	v_mfma_f32_16x16x32_bf16 v[6:9], v[164:167], v[204:207], v[6:9]
	v_mfma_f32_16x16x32_bf16 v[6:9], v[168:171], v[208:211], v[6:9]
	s_setprio 0
	s_add_i32 s77, s77, 2
	s_add_u32 s73, s73, 0x100
	s_addc_u32 s74, s74, 0
	s_add_u32 s18, s18, 0x100
	s_addc_u32 s19, s19, 0
	s_add_u32 s75, s75, 0x100
	s_addc_u32 s76, s76, 0
	s_cmp_gt_u32 s77, 29
	.p2align 6
.LBB0_1224:
	s_setprio 3
	ds_read_b128 v[148:151], v143
	ds_read_b128 v[152:155], v143 offset:1024
	ds_read_b128 v[156:159], v143 offset:2048
	ds_read_b128 v[160:163], v143 offset:3072
	ds_read_b128 v[164:167], v144
	ds_read_b128 v[168:171], v144 offset:1024
	ds_read_b128 v[172:175], v144 offset:2048
	ds_read_b128 v[176:179], v144 offset:3072
	s_cmp_eq_u32 s77, 28
	s_cselect_b32 s21, s9, s74
	s_cselect_b32 s20, s67, s73
	s_cselect_b32 s23, s11, s76
	s_cselect_b32 s22, s66, s75
	ds_read_b128 v[180:183], v145
	ds_read_b128 v[184:187], v145 offset:1024
	ds_read_b128 v[188:191], v145 offset:2048
	ds_read_b128 v[192:195], v145 offset:3072
	ds_read_b128 v[196:199], v145 offset:4096
	ds_read_b128 v[200:203], v145 offset:5120
	ds_read_b128 v[204:207], v145 offset:6144
	ds_read_b128 v[208:211], v145 offset:7168
	s_add_u32 s78, s18, 0xfff80000
	s_addc_u32 s79, s19, -1
	s_mov_b32 s80, m0
	s_mov_b32 m0, s56
	s_nop 0
	global_load_lds_dwordx4 v138, s[78:79]
	s_mov_b32 m0, s80
	s_nop 0
	s_mov_b32 s80, m0
	s_mov_b32 m0, s59
	s_nop 0
	global_load_lds_dwordx4 v140, s[78:79]
	s_mov_b32 m0, s80
	s_mov_b32 s78, m0
	s_mov_b32 m0, s57
	s_nop 0
	global_load_lds_dwordx4 v138, s[18:19]
	s_mov_b32 m0, s78
	s_nop 0
	s_mov_b32 s78, m0
	s_mov_b32 m0, s64
	s_nop 0
	global_load_lds_dwordx4 v140, s[18:19]
	s_mov_b32 m0, s78
	s_setprio 0
	s_waitcnt vmcnt(8)
	s_waitcnt lgkmcnt(0)
	s_barrier
	s_setprio 1
	s_waitcnt lgkmcnt(7)
	v_mfma_f32_16x16x32_bf16 v[126:129], v[148:151], v[180:183], v[126:129]
	v_mfma_f32_16x16x32_bf16 v[126:129], v[152:155], v[184:187], v[126:129]
	s_waitcnt lgkmcnt(5)
	v_mfma_f32_16x16x32_bf16 v[122:125], v[156:159], v[180:183], v[122:125]
	v_mfma_f32_16x16x32_bf16 v[122:125], v[160:163], v[184:187], v[122:125]
	s_waitcnt lgkmcnt(3)
	v_mfma_f32_16x16x32_bf16 v[106:109], v[156:159], v[188:191], v[106:109]
	v_mfma_f32_16x16x32_bf16 v[106:109], v[160:163], v[192:195], v[106:109]
	s_waitcnt lgkmcnt(1)
	v_mfma_f32_16x16x32_bf16 v[110:113], v[148:151], v[188:191], v[110:113]
	v_mfma_f32_16x16x32_bf16 v[110:113], v[152:155], v[192:195], v[110:113]
	v_mfma_f32_16x16x32_bf16 v[94:97], v[148:151], v[196:199], v[94:97]
	v_mfma_f32_16x16x32_bf16 v[94:97], v[152:155], v[200:203], v[94:97]
	v_mfma_f32_16x16x32_bf16 v[90:93], v[156:159], v[196:199], v[90:93]
	v_mfma_f32_16x16x32_bf16 v[90:93], v[160:163], v[200:203], v[90:93]
	v_mfma_f32_16x16x32_bf16 v[74:77], v[156:159], v[204:207], v[74:77]
	v_mfma_f32_16x16x32_bf16 v[74:77], v[160:163], v[208:211], v[74:77]
	s_waitcnt lgkmcnt(0)
	v_mfma_f32_16x16x32_bf16 v[78:81], v[148:151], v[204:207], v[78:81]
	v_mfma_f32_16x16x32_bf16 v[78:81], v[152:155], v[208:211], v[78:81]
	s_setprio 0
	s_setprio 1
	v_mfma_f32_16x16x32_bf16 v[118:121], v[164:167], v[180:183], v[118:121]
	v_mfma_f32_16x16x32_bf16 v[118:121], v[168:171], v[184:187], v[118:121]
	v_mfma_f32_16x16x32_bf16 v[114:117], v[172:175], v[180:183], v[114:117]
	v_mfma_f32_16x16x32_bf16 v[114:117], v[176:179], v[184:187], v[114:117]
	v_mfma_f32_16x16x32_bf16 v[98:101], v[172:175], v[188:191], v[98:101]
	v_mfma_f32_16x16x32_bf16 v[98:101], v[176:179], v[192:195], v[98:101]
	v_mfma_f32_16x16x32_bf16 v[102:105], v[164:167], v[188:191], v[102:105]
	v_mfma_f32_16x16x32_bf16 v[102:105], v[168:171], v[192:195], v[102:105]
	v_mfma_f32_16x16x32_bf16 v[86:89], v[164:167], v[196:199], v[86:89]
	v_mfma_f32_16x16x32_bf16 v[86:89], v[168:171], v[200:203], v[86:89]
	v_mfma_f32_16x16x32_bf16 v[82:85], v[172:175], v[196:199], v[82:85]
	v_mfma_f32_16x16x32_bf16 v[82:85], v[176:179], v[200:203], v[82:85]
	v_mfma_f32_16x16x32_bf16 v[66:69], v[172:175], v[204:207], v[66:69]
	v_mfma_f32_16x16x32_bf16 v[66:69], v[176:179], v[208:211], v[66:69]
	s_setprio 2
	s_barrier
	v_mfma_f32_16x16x32_bf16 v[70:73], v[164:167], v[204:207], v[70:73]
	v_mfma_f32_16x16x32_bf16 v[70:73], v[168:171], v[208:211], v[70:73]
	s_setprio 0
	s_setprio 3
	ds_read_b128 v[180:183], v145 offset:16384
	ds_read_b128 v[184:187], v145 offset:17408
	ds_read_b128 v[188:191], v145 offset:18432
	ds_read_b128 v[192:195], v145 offset:19456
	ds_read_b128 v[196:199], v145 offset:20480
	ds_read_b128 v[200:203], v145 offset:21504
	ds_read_b128 v[204:207], v145 offset:22528
	ds_read_b128 v[208:211], v145 offset:23552
	s_mov_b32 s78, m0
	s_mov_b32 m0, s35
	s_nop 0
	global_load_lds_dwordx4 v139, s[20:21]
	s_mov_b32 m0, s78
	s_nop 0
	s_mov_b32 s78, m0
	s_mov_b32 m0, s36
	s_nop 0
	global_load_lds_dwordx4 v141, s[20:21]
	s_mov_b32 m0, s78
	s_add_u32 s78, s20, 0x80000
	s_addc_u32 s79, s21, 0
	s_mov_b32 s80, m0
	s_mov_b32 m0, s37
	s_nop 0
	global_load_lds_dwordx4 v139, s[78:79]
	s_mov_b32 m0, s80
	s_nop 0
	s_mov_b32 s80, m0
	s_mov_b32 m0, s40
	s_nop 0
	global_load_lds_dwordx4 v141, s[78:79]
	s_mov_b32 m0, s80
	s_setprio 0
	s_waitcnt vmcnt(4)
	s_waitcnt lgkmcnt(0)
	s_barrier
	s_setprio 1
	s_waitcnt lgkmcnt(7)
	v_mfma_f32_16x16x32_bf16 v[62:65], v[148:151], v[180:183], v[62:65]
	v_mfma_f32_16x16x32_bf16 v[62:65], v[152:155], v[184:187], v[62:65]
	s_waitcnt lgkmcnt(5)
	v_mfma_f32_16x16x32_bf16 v[58:61], v[156:159], v[180:183], v[58:61]
	v_mfma_f32_16x16x32_bf16 v[58:61], v[160:163], v[184:187], v[58:61]
	s_waitcnt lgkmcnt(3)
	v_mfma_f32_16x16x32_bf16 v[42:45], v[156:159], v[188:191], v[42:45]
	v_mfma_f32_16x16x32_bf16 v[42:45], v[160:163], v[192:195], v[42:45]
	s_waitcnt lgkmcnt(1)
	v_mfma_f32_16x16x32_bf16 v[46:49], v[148:151], v[188:191], v[46:49]
	v_mfma_f32_16x16x32_bf16 v[46:49], v[152:155], v[192:195], v[46:49]
	v_mfma_f32_16x16x32_bf16 v[30:33], v[148:151], v[196:199], v[30:33]
	v_mfma_f32_16x16x32_bf16 v[30:33], v[152:155], v[200:203], v[30:33]
	v_mfma_f32_16x16x32_bf16 v[26:29], v[156:159], v[196:199], v[26:29]
	v_mfma_f32_16x16x32_bf16 v[26:29], v[160:163], v[200:203], v[26:29]
	v_mfma_f32_16x16x32_bf16 v[10:13], v[156:159], v[204:207], v[10:13]
	v_mfma_f32_16x16x32_bf16 v[10:13], v[160:163], v[208:211], v[10:13]
	s_waitcnt lgkmcnt(0)
	v_mfma_f32_16x16x32_bf16 v[14:17], v[148:151], v[204:207], v[14:17]
	v_mfma_f32_16x16x32_bf16 v[14:17], v[152:155], v[208:211], v[14:17]
	s_setprio 0
	s_setprio 1
	v_mfma_f32_16x16x32_bf16 v[54:57], v[164:167], v[180:183], v[54:57]
	v_mfma_f32_16x16x32_bf16 v[54:57], v[168:171], v[184:187], v[54:57]
	v_mfma_f32_16x16x32_bf16 v[50:53], v[172:175], v[180:183], v[50:53]
	v_mfma_f32_16x16x32_bf16 v[50:53], v[176:179], v[184:187], v[50:53]
	v_mfma_f32_16x16x32_bf16 v[34:37], v[172:175], v[188:191], v[34:37]
	v_mfma_f32_16x16x32_bf16 v[34:37], v[176:179], v[192:195], v[34:37]
	v_mfma_f32_16x16x32_bf16 v[38:41], v[164:167], v[188:191], v[38:41]
	v_mfma_f32_16x16x32_bf16 v[38:41], v[168:171], v[192:195], v[38:41]
	v_mfma_f32_16x16x32_bf16 v[22:25], v[164:167], v[196:199], v[22:25]
	v_mfma_f32_16x16x32_bf16 v[22:25], v[168:171], v[200:203], v[22:25]
	v_mfma_f32_16x16x32_bf16 v[18:21], v[172:175], v[196:199], v[18:21]
	v_mfma_f32_16x16x32_bf16 v[18:21], v[176:179], v[200:203], v[18:21]
	v_mfma_f32_16x16x32_bf16 v[2:5], v[172:175], v[204:207], v[2:5]
	v_mfma_f32_16x16x32_bf16 v[2:5], v[176:179], v[208:211], v[2:5]
	s_setprio 2
	s_barrier
	v_mfma_f32_16x16x32_bf16 v[6:9], v[164:167], v[204:207], v[6:9]
	v_mfma_f32_16x16x32_bf16 v[6:9], v[168:171], v[208:211], v[6:9]
	s_setprio 0
	s_setprio 3
	ds_read_b128 v[148:151], v146
	ds_read_b128 v[152:155], v146 offset:1024
	ds_read_b128 v[156:159], v146 offset:2048
	ds_read_b128 v[160:163], v146 offset:3072
	ds_read_b128 v[164:167], v147
	ds_read_b128 v[168:171], v147 offset:1024
	ds_read_b128 v[172:175], v147 offset:2048
	ds_read_b128 v[176:179], v147 offset:3072
	ds_read_b128 v[180:183], v145 offset:32768
	ds_read_b128 v[184:187], v145 offset:33792
	ds_read_b128 v[188:191], v145 offset:34816
	ds_read_b128 v[192:195], v145 offset:35840
	ds_read_b128 v[196:199], v145 offset:36864
	ds_read_b128 v[200:203], v145 offset:37888
	ds_read_b128 v[204:207], v145 offset:38912
	ds_read_b128 v[208:211], v145 offset:39936
	s_mov_b32 s78, m0
	s_mov_b32 m0, s31
	s_nop 0
	global_load_lds_dwordx4 v138, s[22:23]
	s_mov_b32 m0, s78
	s_nop 0
	s_mov_b32 s78, m0
	s_mov_b32 m0, s41
	s_nop 0
	global_load_lds_dwordx4 v140, s[22:23]
	s_mov_b32 m0, s78
	s_add_u32 s22, s22, 0x80000
	s_addc_u32 s23, s23, 0
	s_mov_b32 s78, m0
	s_mov_b32 m0, s42
	s_nop 0
	global_load_lds_dwordx4 v138, s[22:23]
	s_mov_b32 m0, s78
	s_nop 0
	s_mov_b32 s78, m0
	s_mov_b32 m0, s43
	s_nop 0
	global_load_lds_dwordx4 v140, s[22:23]
	s_mov_b32 m0, s78
	s_setprio 0
	s_waitcnt vmcnt(8)
	s_waitcnt lgkmcnt(0)
	s_barrier
	s_setprio 1
	s_waitcnt lgkmcnt(7)
	v_mfma_f32_16x16x32_bf16 v[126:129], v[148:151], v[180:183], v[126:129]
	v_mfma_f32_16x16x32_bf16 v[126:129], v[152:155], v[184:187], v[126:129]
	s_waitcnt lgkmcnt(5)
	v_mfma_f32_16x16x32_bf16 v[122:125], v[156:159], v[180:183], v[122:125]
	v_mfma_f32_16x16x32_bf16 v[122:125], v[160:163], v[184:187], v[122:125]
	s_waitcnt lgkmcnt(3)
	v_mfma_f32_16x16x32_bf16 v[106:109], v[156:159], v[188:191], v[106:109]
	v_mfma_f32_16x16x32_bf16 v[106:109], v[160:163], v[192:195], v[106:109]
	s_waitcnt lgkmcnt(1)
	v_mfma_f32_16x16x32_bf16 v[110:113], v[148:151], v[188:191], v[110:113]
	v_mfma_f32_16x16x32_bf16 v[110:113], v[152:155], v[192:195], v[110:113]
	v_mfma_f32_16x16x32_bf16 v[94:97], v[148:151], v[196:199], v[94:97]
	v_mfma_f32_16x16x32_bf16 v[94:97], v[152:155], v[200:203], v[94:97]
	v_mfma_f32_16x16x32_bf16 v[90:93], v[156:159], v[196:199], v[90:93]
	v_mfma_f32_16x16x32_bf16 v[90:93], v[160:163], v[200:203], v[90:93]
	v_mfma_f32_16x16x32_bf16 v[74:77], v[156:159], v[204:207], v[74:77]
	v_mfma_f32_16x16x32_bf16 v[74:77], v[160:163], v[208:211], v[74:77]
	s_waitcnt lgkmcnt(0)
	v_mfma_f32_16x16x32_bf16 v[78:81], v[148:151], v[204:207], v[78:81]
	v_mfma_f32_16x16x32_bf16 v[78:81], v[152:155], v[208:211], v[78:81]
	s_setprio 0
	s_setprio 1
	v_mfma_f32_16x16x32_bf16 v[118:121], v[164:167], v[180:183], v[118:121]
	v_mfma_f32_16x16x32_bf16 v[118:121], v[168:171], v[184:187], v[118:121]
	v_mfma_f32_16x16x32_bf16 v[114:117], v[172:175], v[180:183], v[114:117]
	v_mfma_f32_16x16x32_bf16 v[114:117], v[176:179], v[184:187], v[114:117]
	v_mfma_f32_16x16x32_bf16 v[98:101], v[172:175], v[188:191], v[98:101]
	v_mfma_f32_16x16x32_bf16 v[98:101], v[176:179], v[192:195], v[98:101]
	v_mfma_f32_16x16x32_bf16 v[102:105], v[164:167], v[188:191], v[102:105]
	v_mfma_f32_16x16x32_bf16 v[102:105], v[168:171], v[192:195], v[102:105]
	v_mfma_f32_16x16x32_bf16 v[86:89], v[164:167], v[196:199], v[86:89]
	v_mfma_f32_16x16x32_bf16 v[86:89], v[168:171], v[200:203], v[86:89]
	v_mfma_f32_16x16x32_bf16 v[82:85], v[172:175], v[196:199], v[82:85]
	v_mfma_f32_16x16x32_bf16 v[82:85], v[176:179], v[200:203], v[82:85]
	v_mfma_f32_16x16x32_bf16 v[66:69], v[172:175], v[204:207], v[66:69]
	v_mfma_f32_16x16x32_bf16 v[66:69], v[176:179], v[208:211], v[66:69]
	s_setprio 2
	s_barrier
	v_mfma_f32_16x16x32_bf16 v[70:73], v[164:167], v[204:207], v[70:73]
	v_mfma_f32_16x16x32_bf16 v[70:73], v[168:171], v[208:211], v[70:73]
	s_setprio 0
	s_setprio 3
	ds_read_b128 v[180:183], v145 offset:49152
	ds_read_b128 v[184:187], v145 offset:50176
	ds_read_b128 v[188:191], v145 offset:51200
	ds_read_b128 v[192:195], v145 offset:52224
	ds_read_b128 v[196:199], v145 offset:53248
	ds_read_b128 v[200:203], v145 offset:54272
	ds_read_b128 v[204:207], v145 offset:55296
	ds_read_b128 v[208:211], v145 offset:56320
	s_add_u32 s22, s20, 0x80
	s_addc_u32 s23, s21, 0
	s_mov_b32 s78, m0
	s_mov_b32 m0, s46
	s_nop 0
	global_load_lds_dwordx4 v139, s[22:23]
	s_mov_b32 m0, s78
	s_add_u32 s20, s20, 0x80080
	s_mov_b32 s78, m0
	s_mov_b32 m0, s47
	s_nop 0
	global_load_lds_dwordx4 v141, s[22:23]
	s_mov_b32 m0, s78
	s_addc_u32 s21, s21, 0
	s_mov_b32 s22, m0
	s_mov_b32 m0, s48
	s_nop 0
	global_load_lds_dwordx4 v139, s[20:21]
	s_mov_b32 m0, s22
	s_nop 0
	s_mov_b32 s22, m0
	s_mov_b32 m0, s49
	s_nop 0
	global_load_lds_dwordx4 v141, s[20:21]
	s_mov_b32 m0, s22
	s_setprio 0
	s_waitcnt vmcnt(4)
	s_waitcnt lgkmcnt(0)
	s_barrier
	s_setprio 1
	s_waitcnt lgkmcnt(7)
	v_mfma_f32_16x16x32_bf16 v[62:65], v[148:151], v[180:183], v[62:65]
	v_mfma_f32_16x16x32_bf16 v[62:65], v[152:155], v[184:187], v[62:65]
	s_waitcnt lgkmcnt(5)
	v_mfma_f32_16x16x32_bf16 v[58:61], v[156:159], v[180:183], v[58:61]
	v_mfma_f32_16x16x32_bf16 v[58:61], v[160:163], v[184:187], v[58:61]
	s_waitcnt lgkmcnt(3)
	v_mfma_f32_16x16x32_bf16 v[42:45], v[156:159], v[188:191], v[42:45]
	v_mfma_f32_16x16x32_bf16 v[42:45], v[160:163], v[192:195], v[42:45]
	s_waitcnt lgkmcnt(1)
	v_mfma_f32_16x16x32_bf16 v[46:49], v[148:151], v[188:191], v[46:49]
	v_mfma_f32_16x16x32_bf16 v[46:49], v[152:155], v[192:195], v[46:49]
	v_mfma_f32_16x16x32_bf16 v[30:33], v[148:151], v[196:199], v[30:33]
	v_mfma_f32_16x16x32_bf16 v[30:33], v[152:155], v[200:203], v[30:33]
	v_mfma_f32_16x16x32_bf16 v[26:29], v[156:159], v[196:199], v[26:29]
	v_mfma_f32_16x16x32_bf16 v[26:29], v[160:163], v[200:203], v[26:29]
	v_mfma_f32_16x16x32_bf16 v[10:13], v[156:159], v[204:207], v[10:13]
	v_mfma_f32_16x16x32_bf16 v[10:13], v[160:163], v[208:211], v[10:13]
	s_waitcnt lgkmcnt(0)
	v_mfma_f32_16x16x32_bf16 v[14:17], v[148:151], v[204:207], v[14:17]
	v_mfma_f32_16x16x32_bf16 v[14:17], v[152:155], v[208:211], v[14:17]
	s_setprio 0
	s_setprio 1
	v_mfma_f32_16x16x32_bf16 v[54:57], v[164:167], v[180:183], v[54:57]
	v_mfma_f32_16x16x32_bf16 v[54:57], v[168:171], v[184:187], v[54:57]
	v_mfma_f32_16x16x32_bf16 v[50:53], v[172:175], v[180:183], v[50:53]
	v_mfma_f32_16x16x32_bf16 v[50:53], v[176:179], v[184:187], v[50:53]
	v_mfma_f32_16x16x32_bf16 v[34:37], v[172:175], v[188:191], v[34:37]
	v_mfma_f32_16x16x32_bf16 v[34:37], v[176:179], v[192:195], v[34:37]
	v_mfma_f32_16x16x32_bf16 v[38:41], v[164:167], v[188:191], v[38:41]
	v_mfma_f32_16x16x32_bf16 v[38:41], v[168:171], v[192:195], v[38:41]
	v_mfma_f32_16x16x32_bf16 v[22:25], v[164:167], v[196:199], v[22:25]
	v_mfma_f32_16x16x32_bf16 v[22:25], v[168:171], v[200:203], v[22:25]
	v_mfma_f32_16x16x32_bf16 v[18:21], v[172:175], v[196:199], v[18:21]
	v_mfma_f32_16x16x32_bf16 v[18:21], v[176:179], v[200:203], v[18:21]
	v_mfma_f32_16x16x32_bf16 v[2:5], v[172:175], v[204:207], v[2:5]
	v_mfma_f32_16x16x32_bf16 v[2:5], v[176:179], v[208:211], v[2:5]
	s_setprio 2
	s_barrier
	v_mfma_f32_16x16x32_bf16 v[6:9], v[164:167], v[204:207], v[6:9]
	v_mfma_f32_16x16x32_bf16 v[6:9], v[168:171], v[208:211], v[6:9]
	s_setprio 0
	s_add_i32 s77, s77, 2
	s_add_u32 s73, s73, 0x100
	s_addc_u32 s74, s74, 0
	s_add_u32 s18, s18, 0x100
	s_addc_u32 s19, s19, 0
	s_add_u32 s75, s75, 0x100
	s_addc_u32 s76, s76, 0
	s_cmp_gt_u32 s77, 29
	s_cbranch_scc0 .LBB0_1224
	s_and_b64 vcc, exec, s[6:7]
	s_cbranch_vccz .LBB0_1227
	s_barrier

.LBB0_1356:
	s_ashr_i32 s13, s12, 31
	s_lshl_b64 s[14:15], s[12:13], 15
	s_add_u32 s14, s28, s14
	s_addc_u32 s15, s29, s15
	s_and_b64 s[16:17], s[2:3], exec
	s_cselect_b32 s13, s15, s23
	s_cselect_b32 s67, s14, s22
	s_ashr_i32 s11, s10, 31
	s_lshl_b64 s[16:17], s[10:11], 15
	s_add_u32 s16, s30, s16
	s_addc_u32 s17, s31, s17
	s_and_b64 s[24:25], s[2:3], exec
	s_cselect_b32 s11, s17, s21
	s_cselect_b32 s73, s16, s20
	s_add_u32 s74, s20, 0x80000
	s_addc_u32 s75, s21, 0
	s_add_u32 s20, s22, 0x204000
	s_addc_u32 s21, s23, 0
	s_add_u32 s76, s22, 0x400000
	s_addc_u32 s77, s23, 0
	s_mov_b32 s78, -2
	s_waitcnt vmcnt(25)
	s_waitcnt vmcnt(24)
	s_waitcnt vmcnt(15)
	s_waitcnt vmcnt(14)
	s_waitcnt vmcnt(13)
	s_waitcnt vmcnt(12)
	s_waitcnt vmcnt(11)
	s_waitcnt vmcnt(10)
	s_waitcnt vmcnt(9)
	s_waitcnt vmcnt(8)
	s_waitcnt vmcnt(7)
	s_waitcnt vmcnt(6)
	s_waitcnt vmcnt(5)
	s_waitcnt vmcnt(4)
	s_waitcnt vmcnt(3)
	s_waitcnt vmcnt(2)
	s_waitcnt vmcnt(1)
	s_waitcnt vmcnt(0)
	s_setprio 3
	ds_read_b128 v[130:133], v181
	ds_read_b128 v[134:137], v181 offset:1024
	ds_read_b128 v[138:141], v181 offset:2048
	ds_read_b128 v[142:145], v181 offset:3072
	ds_read_b128 v[150:153], v182
	ds_read_b128 v[154:157], v182 offset:1024
	ds_read_b128 v[158:161], v182 offset:2048
	ds_read_b128 v[162:165], v182 offset:3072
	s_cmpk_eq_i32 s78, 0x52
	s_cselect_b32 s23, s11, s75
	s_cselect_b32 s22, s73, s74
	s_cselect_b32 s25, s13, s77
	s_cselect_b32 s24, s67, s76
	ds_read_b128 v[166:169], v183
	ds_read_b128 v[170:173], v183 offset:1024
	ds_read_b128 v[186:189], v183 offset:2048
	ds_read_b128 v[190:193], v183 offset:3072
	ds_read_b128 v[194:197], v183 offset:4096
	ds_read_b128 v[198:201], v183 offset:5120
	ds_read_b128 v[202:205], v183 offset:6144
	ds_read_b128 v[206:209], v183 offset:7168
	s_add_u32 s80, s20, 0xffffc000
	s_addc_u32 s81, s21, -1
	s_mov_b32 s79, m0
	s_mov_b32 m0, s58
	s_nop 0
	global_load_lds_dwordx4 v1, s[80:81]
	s_mov_b32 m0, s79
	s_nop 0
	s_mov_b32 s79, m0
	s_mov_b32 m0, s64
	s_nop 0
	global_load_lds_dwordx4 v177, s[80:81]
	s_mov_b32 m0, s79
	s_nop 0
	s_mov_b32 s79, m0
	s_mov_b32 m0, s59
	s_nop 0
	global_load_lds_dwordx4 v1, s[20:21]
	s_mov_b32 m0, s79
	s_nop 0
	s_mov_b32 s79, m0
	s_mov_b32 m0, s65
	s_nop 0
	global_load_lds_dwordx4 v177, s[20:21]
	s_mov_b32 m0, s79
	s_setprio 0
	s_waitcnt vmcnt(8)
	s_waitcnt lgkmcnt(0)
	s_barrier
	s_setprio 1
	s_waitcnt lgkmcnt(7)
	v_mfma_f32_16x16x32_bf16 v[126:129], v[130:133], v[166:169], 0
	v_mfma_f32_16x16x32_bf16 v[126:129], v[134:137], v[170:173], v[126:129]
	s_waitcnt lgkmcnt(5)
	v_mfma_f32_16x16x32_bf16 v[122:125], v[138:141], v[166:169], 0
	v_mfma_f32_16x16x32_bf16 v[122:125], v[142:145], v[170:173], v[122:125]
	s_waitcnt lgkmcnt(3)
	v_mfma_f32_16x16x32_bf16 v[110:113], v[138:141], v[186:189], 0
	v_mfma_f32_16x16x32_bf16 v[110:113], v[142:145], v[190:193], v[110:113]
	s_waitcnt lgkmcnt(1)
	v_mfma_f32_16x16x32_bf16 v[118:121], v[130:133], v[186:189], 0
	v_mfma_f32_16x16x32_bf16 v[118:121], v[134:137], v[190:193], v[118:121]
	v_mfma_f32_16x16x32_bf16 v[94:97], v[130:133], v[194:197], 0
	v_mfma_f32_16x16x32_bf16 v[94:97], v[134:137], v[198:201], v[94:97]
	v_mfma_f32_16x16x32_bf16 v[90:93], v[138:141], v[194:197], 0
	v_mfma_f32_16x16x32_bf16 v[90:93], v[142:145], v[198:201], v[90:93]
	v_mfma_f32_16x16x32_bf16 v[78:81], v[138:141], v[202:205], 0
	v_mfma_f32_16x16x32_bf16 v[78:81], v[142:145], v[206:209], v[78:81]
	s_waitcnt lgkmcnt(0)
	v_mfma_f32_16x16x32_bf16 v[86:89], v[130:133], v[202:205], 0
	v_mfma_f32_16x16x32_bf16 v[86:89], v[134:137], v[206:209], v[86:89]
	s_setprio 0
	s_setprio 1
	v_mfma_f32_16x16x32_bf16 v[114:117], v[150:153], v[166:169], 0
	v_mfma_f32_16x16x32_bf16 v[114:117], v[154:157], v[170:173], v[114:117]
	v_mfma_f32_16x16x32_bf16 v[106:109], v[158:161], v[166:169], 0
	v_mfma_f32_16x16x32_bf16 v[106:109], v[162:165], v[170:173], v[106:109]
	v_mfma_f32_16x16x32_bf16 v[98:101], v[158:161], v[186:189], 0
	v_mfma_f32_16x16x32_bf16 v[98:101], v[162:165], v[190:193], v[98:101]
	v_mfma_f32_16x16x32_bf16 v[102:105], v[150:153], v[186:189], 0
	v_mfma_f32_16x16x32_bf16 v[102:105], v[154:157], v[190:193], v[102:105]
	v_mfma_f32_16x16x32_bf16 v[82:85], v[150:153], v[194:197], 0
	v_mfma_f32_16x16x32_bf16 v[82:85], v[154:157], v[198:201], v[82:85]
	v_mfma_f32_16x16x32_bf16 v[74:77], v[158:161], v[194:197], 0
	v_mfma_f32_16x16x32_bf16 v[74:77], v[162:165], v[198:201], v[74:77]
	v_mfma_f32_16x16x32_bf16 v[66:69], v[158:161], v[202:205], 0
	v_mfma_f32_16x16x32_bf16 v[66:69], v[162:165], v[206:209], v[66:69]
	s_setprio 2
	s_barrier
	v_mfma_f32_16x16x32_bf16 v[70:73], v[150:153], v[202:205], 0
	v_mfma_f32_16x16x32_bf16 v[70:73], v[154:157], v[206:209], v[70:73]
	s_setprio 0
	s_setprio 3
	ds_read_b128 v[166:169], v183 offset:16384
	ds_read_b128 v[170:173], v183 offset:17408
	ds_read_b128 v[186:189], v183 offset:18432
	ds_read_b128 v[190:193], v183 offset:19456
	ds_read_b128 v[194:197], v183 offset:20480
	ds_read_b128 v[198:201], v183 offset:21504
	ds_read_b128 v[202:205], v183 offset:22528
	ds_read_b128 v[206:209], v183 offset:23552
	s_mov_b32 s79, m0
	s_mov_b32 m0, s35
	s_nop 0
	global_load_lds_dwordx4 v176, s[22:23]
	s_mov_b32 m0, s79
	s_add_u32 s80, s22, 0x4000
	s_mov_b32 s79, m0
	s_mov_b32 m0, s36
	s_nop 0
	global_load_lds_dwordx4 v178, s[22:23]
	s_mov_b32 m0, s79
	s_addc_u32 s81, s23, 0
	s_mov_b32 s79, m0
	s_mov_b32 m0, s37
	s_nop 0
	global_load_lds_dwordx4 v176, s[80:81]
	s_mov_b32 m0, s79
	s_nop 0
	s_mov_b32 s79, m0
	s_mov_b32 m0, s40
	s_nop 0
	global_load_lds_dwordx4 v178, s[80:81]
	s_mov_b32 m0, s79
	s_setprio 0
	s_waitcnt vmcnt(4)
	s_waitcnt lgkmcnt(0)
	s_barrier
	s_setprio 1
	s_waitcnt lgkmcnt(7)
	v_mfma_f32_16x16x32_bf16 v[62:65], v[130:133], v[166:169], 0
	v_mfma_f32_16x16x32_bf16 v[62:65], v[134:137], v[170:173], v[62:65]
	s_waitcnt lgkmcnt(5)
	v_mfma_f32_16x16x32_bf16 v[58:61], v[138:141], v[166:169], 0
	v_mfma_f32_16x16x32_bf16 v[58:61], v[142:145], v[170:173], v[58:61]
	s_waitcnt lgkmcnt(3)
	v_mfma_f32_16x16x32_bf16 v[42:45], v[138:141], v[186:189], 0
	v_mfma_f32_16x16x32_bf16 v[42:45], v[142:145], v[190:193], v[42:45]
	s_waitcnt lgkmcnt(1)
	v_mfma_f32_16x16x32_bf16 v[46:49], v[130:133], v[186:189], 0
	v_mfma_f32_16x16x32_bf16 v[46:49], v[134:137], v[190:193], v[46:49]
	v_mfma_f32_16x16x32_bf16 v[30:33], v[130:133], v[194:197], 0
	v_mfma_f32_16x16x32_bf16 v[30:33], v[134:137], v[198:201], v[30:33]
	v_mfma_f32_16x16x32_bf16 v[26:29], v[138:141], v[194:197], 0
	v_mfma_f32_16x16x32_bf16 v[26:29], v[142:145], v[198:201], v[26:29]
	v_mfma_f32_16x16x32_bf16 v[10:13], v[138:141], v[202:205], 0
	v_mfma_f32_16x16x32_bf16 v[10:13], v[142:145], v[206:209], v[10:13]
	s_waitcnt lgkmcnt(0)
	v_mfma_f32_16x16x32_bf16 v[14:17], v[130:133], v[202:205], 0
	v_mfma_f32_16x16x32_bf16 v[14:17], v[134:137], v[206:209], v[14:17]
	s_setprio 0
	s_setprio 1
	v_mfma_f32_16x16x32_bf16 v[54:57], v[150:153], v[166:169], 0
	v_mfma_f32_16x16x32_bf16 v[54:57], v[154:157], v[170:173], v[54:57]
	v_mfma_f32_16x16x32_bf16 v[50:53], v[158:161], v[166:169], 0
	v_mfma_f32_16x16x32_bf16 v[50:53], v[162:165], v[170:173], v[50:53]
	v_mfma_f32_16x16x32_bf16 v[34:37], v[158:161], v[186:189], 0
	v_mfma_f32_16x16x32_bf16 v[34:37], v[162:165], v[190:193], v[34:37]
	v_mfma_f32_16x16x32_bf16 v[38:41], v[150:153], v[186:189], 0
	v_mfma_f32_16x16x32_bf16 v[38:41], v[154:157], v[190:193], v[38:41]
	v_mfma_f32_16x16x32_bf16 v[22:25], v[150:153], v[194:197], 0
	v_mfma_f32_16x16x32_bf16 v[22:25], v[154:157], v[198:201], v[22:25]
	v_mfma_f32_16x16x32_bf16 v[18:21], v[158:161], v[194:197], 0
	v_mfma_f32_16x16x32_bf16 v[18:21], v[162:165], v[198:201], v[18:21]
	v_mfma_f32_16x16x32_bf16 v[2:5], v[158:161], v[202:205], 0
	v_mfma_f32_16x16x32_bf16 v[2:5], v[162:165], v[206:209], v[2:5]
	s_setprio 2
	s_barrier
	v_mfma_f32_16x16x32_bf16 v[6:9], v[150:153], v[202:205], 0
	v_mfma_f32_16x16x32_bf16 v[6:9], v[154:157], v[206:209], v[6:9]
	s_setprio 0
	s_setprio 3
	ds_read_b128 v[130:133], v184
	ds_read_b128 v[134:137], v184 offset:1024
	ds_read_b128 v[138:141], v184 offset:2048
	ds_read_b128 v[142:145], v184 offset:3072
	ds_read_b128 v[150:153], v185
	ds_read_b128 v[154:157], v185 offset:1024
	ds_read_b128 v[158:161], v185 offset:2048
	ds_read_b128 v[162:165], v185 offset:3072
	ds_read_b128 v[166:169], v183 offset:32768
	ds_read_b128 v[170:173], v183 offset:33792
	ds_read_b128 v[186:189], v183 offset:34816
	ds_read_b128 v[190:193], v183 offset:35840
	ds_read_b128 v[194:197], v183 offset:36864
	ds_read_b128 v[198:201], v183 offset:37888
	ds_read_b128 v[202:205], v183 offset:38912
	ds_read_b128 v[206:209], v183 offset:39936
	s_mov_b32 s79, m0
	s_mov_b32 m0, s34
	s_nop 0
	global_load_lds_dwordx4 v1, s[24:25]
	s_mov_b32 m0, s79
	s_nop 0
	s_mov_b32 s79, m0
	s_mov_b32 m0, s41
	s_nop 0
	global_load_lds_dwordx4 v177, s[24:25]
	s_mov_b32 m0, s79
	s_add_u32 s24, s24, 0x4000
	s_addc_u32 s25, s25, 0
	s_mov_b32 s79, m0
	s_mov_b32 m0, s42
	s_nop 0
	global_load_lds_dwordx4 v1, s[24:25]
	s_mov_b32 m0, s79
	s_nop 0
	s_mov_b32 s79, m0
	s_mov_b32 m0, s43
	s_nop 0
	global_load_lds_dwordx4 v177, s[24:25]
	s_mov_b32 m0, s79
	s_setprio 0
	s_waitcnt vmcnt(8)
	s_waitcnt lgkmcnt(0)
	s_barrier
	s_setprio 1
	s_waitcnt lgkmcnt(7)
	v_mfma_f32_16x16x32_bf16 v[126:129], v[130:133], v[166:169], v[126:129]
	v_mfma_f32_16x16x32_bf16 v[126:129], v[134:137], v[170:173], v[126:129]
	s_waitcnt lgkmcnt(5)
	v_mfma_f32_16x16x32_bf16 v[122:125], v[138:141], v[166:169], v[122:125]
	v_mfma_f32_16x16x32_bf16 v[122:125], v[142:145], v[170:173], v[122:125]
	s_waitcnt lgkmcnt(3)
	v_mfma_f32_16x16x32_bf16 v[110:113], v[138:141], v[186:189], v[110:113]
	v_mfma_f32_16x16x32_bf16 v[110:113], v[142:145], v[190:193], v[110:113]
	s_waitcnt lgkmcnt(1)
	v_mfma_f32_16x16x32_bf16 v[118:121], v[130:133], v[186:189], v[118:121]
	v_mfma_f32_16x16x32_bf16 v[118:121], v[134:137], v[190:193], v[118:121]
	v_mfma_f32_16x16x32_bf16 v[94:97], v[130:133], v[194:197], v[94:97]
	v_mfma_f32_16x16x32_bf16 v[94:97], v[134:137], v[198:201], v[94:97]
	v_mfma_f32_16x16x32_bf16 v[90:93], v[138:141], v[194:197], v[90:93]
	v_mfma_f32_16x16x32_bf16 v[90:93], v[142:145], v[198:201], v[90:93]
	v_mfma_f32_16x16x32_bf16 v[78:81], v[138:141], v[202:205], v[78:81]
	v_mfma_f32_16x16x32_bf16 v[78:81], v[142:145], v[206:209], v[78:81]
	s_waitcnt lgkmcnt(0)
	v_mfma_f32_16x16x32_bf16 v[86:89], v[130:133], v[202:205], v[86:89]
	v_mfma_f32_16x16x32_bf16 v[86:89], v[134:137], v[206:209], v[86:89]
	s_setprio 0
	s_setprio 1
	v_mfma_f32_16x16x32_bf16 v[114:117], v[150:153], v[166:169], v[114:117]
	v_mfma_f32_16x16x32_bf16 v[114:117], v[154:157], v[170:173], v[114:117]
	v_mfma_f32_16x16x32_bf16 v[106:109], v[158:161], v[166:169], v[106:109]
	v_mfma_f32_16x16x32_bf16 v[106:109], v[162:165], v[170:173], v[106:109]
	v_mfma_f32_16x16x32_bf16 v[98:101], v[158:161], v[186:189], v[98:101]
	v_mfma_f32_16x16x32_bf16 v[98:101], v[162:165], v[190:193], v[98:101]
	v_mfma_f32_16x16x32_bf16 v[102:105], v[150:153], v[186:189], v[102:105]
	v_mfma_f32_16x16x32_bf16 v[102:105], v[154:157], v[190:193], v[102:105]
	v_mfma_f32_16x16x32_bf16 v[82:85], v[150:153], v[194:197], v[82:85]
	v_mfma_f32_16x16x32_bf16 v[82:85], v[154:157], v[198:201], v[82:85]
	v_mfma_f32_16x16x32_bf16 v[74:77], v[158:161], v[194:197], v[74:77]
	v_mfma_f32_16x16x32_bf16 v[74:77], v[162:165], v[198:201], v[74:77]
	v_mfma_f32_16x16x32_bf16 v[66:69], v[158:161], v[202:205], v[66:69]
	v_mfma_f32_16x16x32_bf16 v[66:69], v[162:165], v[206:209], v[66:69]
	s_setprio 2
	s_barrier
	v_mfma_f32_16x16x32_bf16 v[70:73], v[150:153], v[202:205], v[70:73]
	v_mfma_f32_16x16x32_bf16 v[70:73], v[154:157], v[206:209], v[70:73]
	s_setprio 0
	s_setprio 3
	ds_read_b128 v[166:169], v183 offset:49152
	ds_read_b128 v[170:173], v183 offset:50176
	ds_read_b128 v[186:189], v183 offset:51200
	ds_read_b128 v[190:193], v183 offset:52224
	ds_read_b128 v[194:197], v183 offset:53248
	ds_read_b128 v[198:201], v183 offset:54272
	ds_read_b128 v[202:205], v183 offset:55296
	ds_read_b128 v[206:209], v183 offset:56320
	s_add_u32 s24, s22, 0x40000
	s_addc_u32 s25, s23, 0
	s_mov_b32 s79, m0
	s_mov_b32 m0, s46
	s_nop 0
	global_load_lds_dwordx4 v176, s[24:25]
	s_mov_b32 m0, s79
	s_add_u32 s22, s22, 0x44000
	s_mov_b32 s79, m0
	s_mov_b32 m0, s47
	s_nop 0
	global_load_lds_dwordx4 v178, s[24:25]
	s_mov_b32 m0, s79
	s_addc_u32 s23, s23, 0
	s_mov_b32 s24, m0
	s_mov_b32 m0, s48
	s_nop 0
	global_load_lds_dwordx4 v176, s[22:23]
	s_mov_b32 m0, s24
	s_nop 0
	s_mov_b32 s24, m0
	s_mov_b32 m0, s49
	s_nop 0
	global_load_lds_dwordx4 v178, s[22:23]
	s_mov_b32 m0, s24
	s_setprio 0
	s_waitcnt vmcnt(4)
	s_waitcnt lgkmcnt(0)
	s_barrier
	s_setprio 1
	s_waitcnt lgkmcnt(7)
	v_mfma_f32_16x16x32_bf16 v[62:65], v[130:133], v[166:169], v[62:65]
	v_mfma_f32_16x16x32_bf16 v[62:65], v[134:137], v[170:173], v[62:65]
	s_waitcnt lgkmcnt(5)
	v_mfma_f32_16x16x32_bf16 v[58:61], v[138:141], v[166:169], v[58:61]
	v_mfma_f32_16x16x32_bf16 v[58:61], v[142:145], v[170:173], v[58:61]
	s_waitcnt lgkmcnt(3)
	v_mfma_f32_16x16x32_bf16 v[42:45], v[138:141], v[186:189], v[42:45]
	v_mfma_f32_16x16x32_bf16 v[42:45], v[142:145], v[190:193], v[42:45]
	s_waitcnt lgkmcnt(1)
	v_mfma_f32_16x16x32_bf16 v[46:49], v[130:133], v[186:189], v[46:49]
	v_mfma_f32_16x16x32_bf16 v[46:49], v[134:137], v[190:193], v[46:49]
	v_mfma_f32_16x16x32_bf16 v[30:33], v[130:133], v[194:197], v[30:33]
	v_mfma_f32_16x16x32_bf16 v[30:33], v[134:137], v[198:201], v[30:33]
	v_mfma_f32_16x16x32_bf16 v[26:29], v[138:141], v[194:197], v[26:29]
	v_mfma_f32_16x16x32_bf16 v[26:29], v[142:145], v[198:201], v[26:29]
	v_mfma_f32_16x16x32_bf16 v[10:13], v[138:141], v[202:205], v[10:13]
	v_mfma_f32_16x16x32_bf16 v[10:13], v[142:145], v[206:209], v[10:13]
	s_waitcnt lgkmcnt(0)
	v_mfma_f32_16x16x32_bf16 v[14:17], v[130:133], v[202:205], v[14:17]
	v_mfma_f32_16x16x32_bf16 v[14:17], v[134:137], v[206:209], v[14:17]
	s_setprio 0
	s_setprio 1
	v_mfma_f32_16x16x32_bf16 v[54:57], v[150:153], v[166:169], v[54:57]
	v_mfma_f32_16x16x32_bf16 v[54:57], v[154:157], v[170:173], v[54:57]
	v_mfma_f32_16x16x32_bf16 v[50:53], v[158:161], v[166:169], v[50:53]
	v_mfma_f32_16x16x32_bf16 v[50:53], v[162:165], v[170:173], v[50:53]
	v_mfma_f32_16x16x32_bf16 v[34:37], v[158:161], v[186:189], v[34:37]
	v_mfma_f32_16x16x32_bf16 v[34:37], v[162:165], v[190:193], v[34:37]
	v_mfma_f32_16x16x32_bf16 v[38:41], v[150:153], v[186:189], v[38:41]
	v_mfma_f32_16x16x32_bf16 v[38:41], v[154:157], v[190:193], v[38:41]
	v_mfma_f32_16x16x32_bf16 v[22:25], v[150:153], v[194:197], v[22:25]
	v_mfma_f32_16x16x32_bf16 v[22:25], v[154:157], v[198:201], v[22:25]
	v_mfma_f32_16x16x32_bf16 v[18:21], v[158:161], v[194:197], v[18:21]
	v_mfma_f32_16x16x32_bf16 v[18:21], v[162:165], v[198:201], v[18:21]
	v_mfma_f32_16x16x32_bf16 v[2:5], v[158:161], v[202:205], v[2:5]
	v_mfma_f32_16x16x32_bf16 v[2:5], v[162:165], v[206:209], v[2:5]
	s_setprio 2
	s_barrier
	v_mfma_f32_16x16x32_bf16 v[6:9], v[150:153], v[202:205], v[6:9]
	v_mfma_f32_16x16x32_bf16 v[6:9], v[154:157], v[206:209], v[6:9]
	s_setprio 0
	s_add_i32 s78, s78, 2
	s_add_u32 s74, s74, 0x80000
	s_addc_u32 s75, s75, 0
	s_add_u32 s20, s20, 0x400000
	s_addc_u32 s21, s21, 0
	s_add_u32 s76, s76, 0x400000
	s_addc_u32 s77, s77, 0
	s_cmpk_gt_u32 s78, 0x53
	.p2align 6
.LBB0_1357:
	s_setprio 3
	ds_read_b128 v[130:133], v181
	ds_read_b128 v[134:137], v181 offset:1024
	ds_read_b128 v[138:141], v181 offset:2048
	ds_read_b128 v[142:145], v181 offset:3072
	ds_read_b128 v[150:153], v182
	ds_read_b128 v[154:157], v182 offset:1024
	ds_read_b128 v[158:161], v182 offset:2048
	ds_read_b128 v[162:165], v182 offset:3072
	s_cmpk_eq_i32 s78, 0x52
	s_cselect_b32 s23, s11, s75
	s_cselect_b32 s22, s73, s74
	s_cselect_b32 s25, s13, s77
	s_cselect_b32 s24, s67, s76
	ds_read_b128 v[166:169], v183
	ds_read_b128 v[170:173], v183 offset:1024
	ds_read_b128 v[186:189], v183 offset:2048
	ds_read_b128 v[190:193], v183 offset:3072
	ds_read_b128 v[194:197], v183 offset:4096
	ds_read_b128 v[198:201], v183 offset:5120
	ds_read_b128 v[202:205], v183 offset:6144
	ds_read_b128 v[206:209], v183 offset:7168
	s_add_u32 s80, s20, 0xffffc000
	s_addc_u32 s81, s21, -1
	s_mov_b32 s79, m0
	s_mov_b32 m0, s58
	s_nop 0
	global_load_lds_dwordx4 v1, s[80:81]
	s_mov_b32 m0, s79
	s_nop 0
	s_mov_b32 s79, m0
	s_mov_b32 m0, s64
	s_nop 0
	global_load_lds_dwordx4 v177, s[80:81]
	s_mov_b32 m0, s79
	s_nop 0
	s_mov_b32 s79, m0
	s_mov_b32 m0, s59
	s_nop 0
	global_load_lds_dwordx4 v1, s[20:21]
	s_mov_b32 m0, s79
	s_nop 0
	s_mov_b32 s79, m0
	s_mov_b32 m0, s65
	s_nop 0
	global_load_lds_dwordx4 v177, s[20:21]
	s_mov_b32 m0, s79
	s_setprio 0
	s_waitcnt vmcnt(8)
	s_waitcnt lgkmcnt(0)
	s_barrier
	s_setprio 1
	s_waitcnt lgkmcnt(7)
	v_mfma_f32_16x16x32_bf16 v[126:129], v[130:133], v[166:169], v[126:129]
	v_mfma_f32_16x16x32_bf16 v[126:129], v[134:137], v[170:173], v[126:129]
	s_waitcnt lgkmcnt(5)
	v_mfma_f32_16x16x32_bf16 v[122:125], v[138:141], v[166:169], v[122:125]
	v_mfma_f32_16x16x32_bf16 v[122:125], v[142:145], v[170:173], v[122:125]
	s_waitcnt lgkmcnt(3)
	v_mfma_f32_16x16x32_bf16 v[110:113], v[138:141], v[186:189], v[110:113]
	v_mfma_f32_16x16x32_bf16 v[110:113], v[142:145], v[190:193], v[110:113]
	s_waitcnt lgkmcnt(1)
	v_mfma_f32_16x16x32_bf16 v[118:121], v[130:133], v[186:189], v[118:121]
	v_mfma_f32_16x16x32_bf16 v[118:121], v[134:137], v[190:193], v[118:121]
	v_mfma_f32_16x16x32_bf16 v[94:97], v[130:133], v[194:197], v[94:97]
	v_mfma_f32_16x16x32_bf16 v[94:97], v[134:137], v[198:201], v[94:97]
	v_mfma_f32_16x16x32_bf16 v[90:93], v[138:141], v[194:197], v[90:93]
	v_mfma_f32_16x16x32_bf16 v[90:93], v[142:145], v[198:201], v[90:93]
	v_mfma_f32_16x16x32_bf16 v[78:81], v[138:141], v[202:205], v[78:81]
	v_mfma_f32_16x16x32_bf16 v[78:81], v[142:145], v[206:209], v[78:81]
	s_waitcnt lgkmcnt(0)
	v_mfma_f32_16x16x32_bf16 v[86:89], v[130:133], v[202:205], v[86:89]
	v_mfma_f32_16x16x32_bf16 v[86:89], v[134:137], v[206:209], v[86:89]
	s_setprio 0
	s_setprio 1
	v_mfma_f32_16x16x32_bf16 v[114:117], v[150:153], v[166:169], v[114:117]
	v_mfma_f32_16x16x32_bf16 v[114:117], v[154:157], v[170:173], v[114:117]
	v_mfma_f32_16x16x32_bf16 v[106:109], v[158:161], v[166:169], v[106:109]
	v_mfma_f32_16x16x32_bf16 v[106:109], v[162:165], v[170:173], v[106:109]
	v_mfma_f32_16x16x32_bf16 v[98:101], v[158:161], v[186:189], v[98:101]
	v_mfma_f32_16x16x32_bf16 v[98:101], v[162:165], v[190:193], v[98:101]
	v_mfma_f32_16x16x32_bf16 v[102:105], v[150:153], v[186:189], v[102:105]
	v_mfma_f32_16x16x32_bf16 v[102:105], v[154:157], v[190:193], v[102:105]
	v_mfma_f32_16x16x32_bf16 v[82:85], v[150:153], v[194:197], v[82:85]
	v_mfma_f32_16x16x32_bf16 v[82:85], v[154:157], v[198:201], v[82:85]
	v_mfma_f32_16x16x32_bf16 v[74:77], v[158:161], v[194:197], v[74:77]
	v_mfma_f32_16x16x32_bf16 v[74:77], v[162:165], v[198:201], v[74:77]
	v_mfma_f32_16x16x32_bf16 v[66:69], v[158:161], v[202:205], v[66:69]
	v_mfma_f32_16x16x32_bf16 v[66:69], v[162:165], v[206:209], v[66:69]
	s_setprio 2
	s_barrier
	v_mfma_f32_16x16x32_bf16 v[70:73], v[150:153], v[202:205], v[70:73]
	v_mfma_f32_16x16x32_bf16 v[70:73], v[154:157], v[206:209], v[70:73]
	s_setprio 0
	s_setprio 3
	ds_read_b128 v[166:169], v183 offset:16384
	ds_read_b128 v[170:173], v183 offset:17408
	ds_read_b128 v[186:189], v183 offset:18432
	ds_read_b128 v[190:193], v183 offset:19456
	ds_read_b128 v[194:197], v183 offset:20480
	ds_read_b128 v[198:201], v183 offset:21504
	ds_read_b128 v[202:205], v183 offset:22528
	ds_read_b128 v[206:209], v183 offset:23552
	s_mov_b32 s79, m0
	s_mov_b32 m0, s35
	s_nop 0
	global_load_lds_dwordx4 v176, s[22:23]
	s_mov_b32 m0, s79
	s_add_u32 s80, s22, 0x4000
	s_mov_b32 s79, m0
	s_mov_b32 m0, s36
	s_nop 0
	global_load_lds_dwordx4 v178, s[22:23]
	s_mov_b32 m0, s79
	s_addc_u32 s81, s23, 0
	s_mov_b32 s79, m0
	s_mov_b32 m0, s37
	s_nop 0
	global_load_lds_dwordx4 v176, s[80:81]
	s_mov_b32 m0, s79
	s_nop 0
	s_mov_b32 s79, m0
	s_mov_b32 m0, s40
	s_nop 0
	global_load_lds_dwordx4 v178, s[80:81]
	s_mov_b32 m0, s79
	s_setprio 0
	s_waitcnt vmcnt(4)
	s_waitcnt lgkmcnt(0)
	s_barrier
	s_setprio 1
	s_waitcnt lgkmcnt(7)
	v_mfma_f32_16x16x32_bf16 v[62:65], v[130:133], v[166:169], v[62:65]
	v_mfma_f32_16x16x32_bf16 v[62:65], v[134:137], v[170:173], v[62:65]
	s_waitcnt lgkmcnt(5)
	v_mfma_f32_16x16x32_bf16 v[58:61], v[138:141], v[166:169], v[58:61]
	v_mfma_f32_16x16x32_bf16 v[58:61], v[142:145], v[170:173], v[58:61]
	s_waitcnt lgkmcnt(3)
	v_mfma_f32_16x16x32_bf16 v[42:45], v[138:141], v[186:189], v[42:45]
	v_mfma_f32_16x16x32_bf16 v[42:45], v[142:145], v[190:193], v[42:45]
	s_waitcnt lgkmcnt(1)
	v_mfma_f32_16x16x32_bf16 v[46:49], v[130:133], v[186:189], v[46:49]
	v_mfma_f32_16x16x32_bf16 v[46:49], v[134:137], v[190:193], v[46:49]
	v_mfma_f32_16x16x32_bf16 v[30:33], v[130:133], v[194:197], v[30:33]
	v_mfma_f32_16x16x32_bf16 v[30:33], v[134:137], v[198:201], v[30:33]
	v_mfma_f32_16x16x32_bf16 v[26:29], v[138:141], v[194:197], v[26:29]
	v_mfma_f32_16x16x32_bf16 v[26:29], v[142:145], v[198:201], v[26:29]
	v_mfma_f32_16x16x32_bf16 v[10:13], v[138:141], v[202:205], v[10:13]
	v_mfma_f32_16x16x32_bf16 v[10:13], v[142:145], v[206:209], v[10:13]
	s_waitcnt lgkmcnt(0)
	v_mfma_f32_16x16x32_bf16 v[14:17], v[130:133], v[202:205], v[14:17]
	v_mfma_f32_16x16x32_bf16 v[14:17], v[134:137], v[206:209], v[14:17]
	s_setprio 0
	s_setprio 1
	v_mfma_f32_16x16x32_bf16 v[54:57], v[150:153], v[166:169], v[54:57]
	v_mfma_f32_16x16x32_bf16 v[54:57], v[154:157], v[170:173], v[54:57]
	v_mfma_f32_16x16x32_bf16 v[50:53], v[158:161], v[166:169], v[50:53]
	v_mfma_f32_16x16x32_bf16 v[50:53], v[162:165], v[170:173], v[50:53]
	v_mfma_f32_16x16x32_bf16 v[34:37], v[158:161], v[186:189], v[34:37]
	v_mfma_f32_16x16x32_bf16 v[34:37], v[162:165], v[190:193], v[34:37]
	v_mfma_f32_16x16x32_bf16 v[38:41], v[150:153], v[186:189], v[38:41]
	v_mfma_f32_16x16x32_bf16 v[38:41], v[154:157], v[190:193], v[38:41]
	v_mfma_f32_16x16x32_bf16 v[22:25], v[150:153], v[194:197], v[22:25]
	v_mfma_f32_16x16x32_bf16 v[22:25], v[154:157], v[198:201], v[22:25]
	v_mfma_f32_16x16x32_bf16 v[18:21], v[158:161], v[194:197], v[18:21]
	v_mfma_f32_16x16x32_bf16 v[18:21], v[162:165], v[198:201], v[18:21]
	v_mfma_f32_16x16x32_bf16 v[2:5], v[158:161], v[202:205], v[2:5]
	v_mfma_f32_16x16x32_bf16 v[2:5], v[162:165], v[206:209], v[2:5]
	s_setprio 2
	s_barrier
	v_mfma_f32_16x16x32_bf16 v[6:9], v[150:153], v[202:205], v[6:9]
	v_mfma_f32_16x16x32_bf16 v[6:9], v[154:157], v[206:209], v[6:9]
	s_setprio 0
	s_setprio 3
	ds_read_b128 v[130:133], v184
	ds_read_b128 v[134:137], v184 offset:1024
	ds_read_b128 v[138:141], v184 offset:2048
	ds_read_b128 v[142:145], v184 offset:3072
	ds_read_b128 v[150:153], v185
	ds_read_b128 v[154:157], v185 offset:1024
	ds_read_b128 v[158:161], v185 offset:2048
	ds_read_b128 v[162:165], v185 offset:3072
	ds_read_b128 v[166:169], v183 offset:32768
	ds_read_b128 v[170:173], v183 offset:33792
	ds_read_b128 v[186:189], v183 offset:34816
	ds_read_b128 v[190:193], v183 offset:35840
	ds_read_b128 v[194:197], v183 offset:36864
	ds_read_b128 v[198:201], v183 offset:37888
	ds_read_b128 v[202:205], v183 offset:38912
	ds_read_b128 v[206:209], v183 offset:39936
	s_mov_b32 s79, m0
	s_mov_b32 m0, s34
	s_nop 0
	global_load_lds_dwordx4 v1, s[24:25]
	s_mov_b32 m0, s79
	s_nop 0
	s_mov_b32 s79, m0
	s_mov_b32 m0, s41
	s_nop 0
	global_load_lds_dwordx4 v177, s[24:25]
	s_mov_b32 m0, s79
	s_add_u32 s24, s24, 0x4000
	s_addc_u32 s25, s25, 0
	s_mov_b32 s79, m0
	s_mov_b32 m0, s42
	s_nop 0
	global_load_lds_dwordx4 v1, s[24:25]
	s_mov_b32 m0, s79
	s_nop 0
	s_mov_b32 s79, m0
	s_mov_b32 m0, s43
	s_nop 0
	global_load_lds_dwordx4 v177, s[24:25]
	s_mov_b32 m0, s79
	s_setprio 0
	s_waitcnt vmcnt(8)
	s_waitcnt lgkmcnt(0)
	s_barrier
	s_setprio 1
	s_waitcnt lgkmcnt(7)
	v_mfma_f32_16x16x32_bf16 v[126:129], v[130:133], v[166:169], v[126:129]
	v_mfma_f32_16x16x32_bf16 v[126:129], v[134:137], v[170:173], v[126:129]
	s_waitcnt lgkmcnt(5)
	v_mfma_f32_16x16x32_bf16 v[122:125], v[138:141], v[166:169], v[122:125]
	v_mfma_f32_16x16x32_bf16 v[122:125], v[142:145], v[170:173], v[122:125]
	s_waitcnt lgkmcnt(3)
	v_mfma_f32_16x16x32_bf16 v[110:113], v[138:141], v[186:189], v[110:113]
	v_mfma_f32_16x16x32_bf16 v[110:113], v[142:145], v[190:193], v[110:113]
	s_waitcnt lgkmcnt(1)
	v_mfma_f32_16x16x32_bf16 v[118:121], v[130:133], v[186:189], v[118:121]
	v_mfma_f32_16x16x32_bf16 v[118:121], v[134:137], v[190:193], v[118:121]
	v_mfma_f32_16x16x32_bf16 v[94:97], v[130:133], v[194:197], v[94:97]
	v_mfma_f32_16x16x32_bf16 v[94:97], v[134:137], v[198:201], v[94:97]
	v_mfma_f32_16x16x32_bf16 v[90:93], v[138:141], v[194:197], v[90:93]
	v_mfma_f32_16x16x32_bf16 v[90:93], v[142:145], v[198:201], v[90:93]
	v_mfma_f32_16x16x32_bf16 v[78:81], v[138:141], v[202:205], v[78:81]
	v_mfma_f32_16x16x32_bf16 v[78:81], v[142:145], v[206:209], v[78:81]
	s_waitcnt lgkmcnt(0)
	v_mfma_f32_16x16x32_bf16 v[86:89], v[130:133], v[202:205], v[86:89]
	v_mfma_f32_16x16x32_bf16 v[86:89], v[134:137], v[206:209], v[86:89]
	s_setprio 0
	s_setprio 1
	v_mfma_f32_16x16x32_bf16 v[114:117], v[150:153], v[166:169], v[114:117]
	v_mfma_f32_16x16x32_bf16 v[114:117], v[154:157], v[170:173], v[114:117]
	v_mfma_f32_16x16x32_bf16 v[106:109], v[158:161], v[166:169], v[106:109]
	v_mfma_f32_16x16x32_bf16 v[106:109], v[162:165], v[170:173], v[106:109]
	v_mfma_f32_16x16x32_bf16 v[98:101], v[158:161], v[186:189], v[98:101]
	v_mfma_f32_16x16x32_bf16 v[98:101], v[162:165], v[190:193], v[98:101]
	v_mfma_f32_16x16x32_bf16 v[102:105], v[150:153], v[186:189], v[102:105]
	v_mfma_f32_16x16x32_bf16 v[102:105], v[154:157], v[190:193], v[102:105]
	v_mfma_f32_16x16x32_bf16 v[82:85], v[150:153], v[194:197], v[82:85]
	v_mfma_f32_16x16x32_bf16 v[82:85], v[154:157], v[198:201], v[82:85]
	v_mfma_f32_16x16x32_bf16 v[74:77], v[158:161], v[194:197], v[74:77]
	v_mfma_f32_16x16x32_bf16 v[74:77], v[162:165], v[198:201], v[74:77]
	v_mfma_f32_16x16x32_bf16 v[66:69], v[158:161], v[202:205], v[66:69]
	v_mfma_f32_16x16x32_bf16 v[66:69], v[162:165], v[206:209], v[66:69]
	s_setprio 2
	s_barrier
	v_mfma_f32_16x16x32_bf16 v[70:73], v[150:153], v[202:205], v[70:73]
	v_mfma_f32_16x16x32_bf16 v[70:73], v[154:157], v[206:209], v[70:73]
	s_setprio 0
	s_setprio 3
	ds_read_b128 v[166:169], v183 offset:49152
	ds_read_b128 v[170:173], v183 offset:50176
	ds_read_b128 v[186:189], v183 offset:51200
	ds_read_b128 v[190:193], v183 offset:52224
	ds_read_b128 v[194:197], v183 offset:53248
	ds_read_b128 v[198:201], v183 offset:54272
	ds_read_b128 v[202:205], v183 offset:55296
	ds_read_b128 v[206:209], v183 offset:56320
	s_add_u32 s24, s22, 0x40000
	s_addc_u32 s25, s23, 0
	s_mov_b32 s79, m0
	s_mov_b32 m0, s46
	s_nop 0
	global_load_lds_dwordx4 v176, s[24:25]
	s_mov_b32 m0, s79
	s_add_u32 s22, s22, 0x44000
	s_mov_b32 s79, m0
	s_mov_b32 m0, s47
	s_nop 0
	global_load_lds_dwordx4 v178, s[24:25]
	s_mov_b32 m0, s79
	s_addc_u32 s23, s23, 0
	s_mov_b32 s24, m0
	s_mov_b32 m0, s48
	s_nop 0
	global_load_lds_dwordx4 v176, s[22:23]
	s_mov_b32 m0, s24
	s_nop 0
	s_mov_b32 s24, m0
	s_mov_b32 m0, s49
	s_nop 0
	global_load_lds_dwordx4 v178, s[22:23]
	s_mov_b32 m0, s24
	s_setprio 0
	s_waitcnt vmcnt(4)
	s_waitcnt lgkmcnt(0)
	s_barrier
	s_setprio 1
	s_waitcnt lgkmcnt(7)
	v_mfma_f32_16x16x32_bf16 v[62:65], v[130:133], v[166:169], v[62:65]
	v_mfma_f32_16x16x32_bf16 v[62:65], v[134:137], v[170:173], v[62:65]
	s_waitcnt lgkmcnt(5)
	v_mfma_f32_16x16x32_bf16 v[58:61], v[138:141], v[166:169], v[58:61]
	v_mfma_f32_16x16x32_bf16 v[58:61], v[142:145], v[170:173], v[58:61]
	s_waitcnt lgkmcnt(3)
	v_mfma_f32_16x16x32_bf16 v[42:45], v[138:141], v[186:189], v[42:45]
	v_mfma_f32_16x16x32_bf16 v[42:45], v[142:145], v[190:193], v[42:45]
	s_waitcnt lgkmcnt(1)
	v_mfma_f32_16x16x32_bf16 v[46:49], v[130:133], v[186:189], v[46:49]
	v_mfma_f32_16x16x32_bf16 v[46:49], v[134:137], v[190:193], v[46:49]
	v_mfma_f32_16x16x32_bf16 v[30:33], v[130:133], v[194:197], v[30:33]
	v_mfma_f32_16x16x32_bf16 v[30:33], v[134:137], v[198:201], v[30:33]
	v_mfma_f32_16x16x32_bf16 v[26:29], v[138:141], v[194:197], v[26:29]
	v_mfma_f32_16x16x32_bf16 v[26:29], v[142:145], v[198:201], v[26:29]
	v_mfma_f32_16x16x32_bf16 v[10:13], v[138:141], v[202:205], v[10:13]
	v_mfma_f32_16x16x32_bf16 v[10:13], v[142:145], v[206:209], v[10:13]
	s_waitcnt lgkmcnt(0)
	v_mfma_f32_16x16x32_bf16 v[14:17], v[130:133], v[202:205], v[14:17]
	v_mfma_f32_16x16x32_bf16 v[14:17], v[134:137], v[206:209], v[14:17]
	s_setprio 0
	s_setprio 1
	v_mfma_f32_16x16x32_bf16 v[54:57], v[150:153], v[166:169], v[54:57]
	v_mfma_f32_16x16x32_bf16 v[54:57], v[154:157], v[170:173], v[54:57]
	v_mfma_f32_16x16x32_bf16 v[50:53], v[158:161], v[166:169], v[50:53]
	v_mfma_f32_16x16x32_bf16 v[50:53], v[162:165], v[170:173], v[50:53]
	v_mfma_f32_16x16x32_bf16 v[34:37], v[158:161], v[186:189], v[34:37]
	v_mfma_f32_16x16x32_bf16 v[34:37], v[162:165], v[190:193], v[34:37]
	v_mfma_f32_16x16x32_bf16 v[38:41], v[150:153], v[186:189], v[38:41]
	v_mfma_f32_16x16x32_bf16 v[38:41], v[154:157], v[190:193], v[38:41]
	v_mfma_f32_16x16x32_bf16 v[22:25], v[150:153], v[194:197], v[22:25]
	v_mfma_f32_16x16x32_bf16 v[22:25], v[154:157], v[198:201], v[22:25]
	v_mfma_f32_16x16x32_bf16 v[18:21], v[158:161], v[194:197], v[18:21]
	v_mfma_f32_16x16x32_bf16 v[18:21], v[162:165], v[198:201], v[18:21]
	v_mfma_f32_16x16x32_bf16 v[2:5], v[158:161], v[202:205], v[2:5]
	v_mfma_f32_16x16x32_bf16 v[2:5], v[162:165], v[206:209], v[2:5]
	s_setprio 2
	s_barrier
	v_mfma_f32_16x16x32_bf16 v[6:9], v[150:153], v[202:205], v[6:9]
	v_mfma_f32_16x16x32_bf16 v[6:9], v[154:157], v[206:209], v[6:9]
	s_setprio 0
	s_add_i32 s78, s78, 2
	s_add_u32 s74, s74, 0x80000
	s_addc_u32 s75, s75, 0
	s_add_u32 s20, s20, 0x400000
	s_addc_u32 s21, s21, 0
	s_add_u32 s76, s76, 0x400000
	s_addc_u32 s77, s77, 0
	s_cmpk_gt_u32 s78, 0x53
	s_cbranch_scc0 .LBB0_1357
	s_and_b64 vcc, exec, s[8:9]
	s_cbranch_vccz .LBB0_1360
	s_barrier

.LBB0_1537:
	s_ashr_i32 s23, s22, 31
	s_lshl_b64 s[24:25], s[22:23], 20
	s_add_u32 s24, s41, s24
	s_addc_u32 s25, s42, s25
	s_and_b64 s[26:27], s[4:5], exec
	s_cselect_b32 s7, s25, s35
	s_cselect_b32 s23, s24, s34
	s_ashr_i32 s21, s20, 31
	s_lshl_b64 s[26:27], s[20:21], 20
	s_add_u32 s26, s43, s26
	s_addc_u32 s27, s46, s27
	s_and_b64 s[36:37], s[4:5], exec
	s_cselect_b32 s21, s27, s31
	s_cselect_b32 s29, s26, s30
	s_add_u32 s79, s30, 0x100
	s_addc_u32 s80, s31, 0
	s_add_u32 s30, s34, 0x80080
	s_addc_u32 s31, s35, 0
	s_add_u32 s81, s34, 0x100
	s_addc_u32 s82, s35, 0
	s_mov_b32 s83, -2
	s_waitcnt vmcnt(25)
	s_waitcnt vmcnt(24)
	s_waitcnt vmcnt(4)
	s_waitcnt vmcnt(14)
	s_waitcnt vmcnt(13)
	s_waitcnt vmcnt(12)
	s_waitcnt vmcnt(2)
	s_waitcnt vmcnt(10)
	s_waitcnt vmcnt(9)
	s_waitcnt vmcnt(8)
	s_waitcnt vmcnt(7)
	s_waitcnt vmcnt(6)
	s_waitcnt vmcnt(5)
	s_waitcnt vmcnt(4)
	s_waitcnt vmcnt(3)
	s_waitcnt vmcnt(2)
	s_waitcnt vmcnt(1)
	s_waitcnt vmcnt(0)
	s_setprio 3
	ds_read_b128 v[46:49], v182
	ds_read_b128 v[54:57], v182 offset:1024
	ds_read_b128 v[58:61], v182 offset:2048
	ds_read_b128 v[62:65], v182 offset:3072
	ds_read_b128 v[146:149], v183
	ds_read_b128 v[150:153], v183 offset:1024
	ds_read_b128 v[154:157], v183 offset:2048
	ds_read_b128 v[158:161], v183 offset:3072
	s_cmp_eq_u32 s83, 28
	s_cselect_b32 s35, s21, s80
	s_cselect_b32 s34, s29, s79
	s_cselect_b32 s37, s7, s82
	s_cselect_b32 s36, s23, s81
	ds_read_b128 v[170:173], v184
	ds_read_b128 v[188:191], v184 offset:1024
	ds_read_b128 v[192:195], v184 offset:2048
	ds_read_b128 v[196:199], v184 offset:3072
	ds_read_b128 v[200:203], v184 offset:4096
	ds_read_b128 v[204:207], v184 offset:5120
	ds_read_b128 v[208:211], v184 offset:6144
	ds_read_b128 v[212:215], v184 offset:7168
	s_add_u32 s86, s30, 0xfff80000
	s_addc_u32 s87, s31, -1
	s_mov_b32 s92, m0
	s_mov_b32 m0, s73
	s_nop 0
	global_load_lds_dwordx4 v176, s[86:87]
	s_mov_b32 m0, s92
	s_nop 0
	s_mov_b32 s92, m0
	s_mov_b32 m0, s75
	s_nop 0
	global_load_lds_dwordx4 v178, s[86:87]
	s_mov_b32 m0, s92
	s_mov_b32 s86, m0
	s_mov_b32 m0, s74
	s_nop 0
	global_load_lds_dwordx4 v176, s[30:31]
	s_mov_b32 m0, s86
	s_nop 0
	s_mov_b32 s86, m0
	s_mov_b32 m0, s76
	s_nop 0
	global_load_lds_dwordx4 v178, s[30:31]
	s_mov_b32 m0, s86
	s_setprio 0
	s_waitcnt vmcnt(8)
	s_waitcnt lgkmcnt(0)
	s_barrier
	s_setprio 1
	s_waitcnt lgkmcnt(7)
	v_mfma_f32_16x16x32_bf16 v[142:145], v[46:49], v[170:173], 0
	v_mfma_f32_16x16x32_bf16 v[142:145], v[54:57], v[188:191], v[142:145]
	s_waitcnt lgkmcnt(5)
	v_mfma_f32_16x16x32_bf16 v[138:141], v[58:61], v[170:173], 0
	v_mfma_f32_16x16x32_bf16 v[138:141], v[62:65], v[188:191], v[138:141]
	s_waitcnt lgkmcnt(3)
	v_mfma_f32_16x16x32_bf16 v[126:129], v[46:49], v[192:195], 0
	v_mfma_f32_16x16x32_bf16 v[126:129], v[54:57], v[196:199], v[126:129]
	s_waitcnt lgkmcnt(1)
	v_mfma_f32_16x16x32_bf16 v[122:125], v[58:61], v[192:195], 0
	v_mfma_f32_16x16x32_bf16 v[122:125], v[62:65], v[196:199], v[122:125]
	v_mfma_f32_16x16x32_bf16 v[110:113], v[46:49], v[200:203], 0
	v_mfma_f32_16x16x32_bf16 v[110:113], v[54:57], v[204:207], v[110:113]
	v_mfma_f32_16x16x32_bf16 v[106:109], v[58:61], v[200:203], 0
	v_mfma_f32_16x16x32_bf16 v[106:109], v[62:65], v[204:207], v[106:109]
	v_mfma_f32_16x16x32_bf16 v[94:97], v[46:49], v[208:211], 0
	v_mfma_f32_16x16x32_bf16 v[94:97], v[54:57], v[212:215], v[94:97]
	s_waitcnt lgkmcnt(0)
	v_mfma_f32_16x16x32_bf16 v[90:93], v[58:61], v[208:211], 0
	v_mfma_f32_16x16x32_bf16 v[90:93], v[62:65], v[212:215], v[90:93]
	s_setprio 0
	s_setprio 1
	v_mfma_f32_16x16x32_bf16 v[134:137], v[146:149], v[170:173], 0
	v_mfma_f32_16x16x32_bf16 v[134:137], v[150:153], v[188:191], v[134:137]
	v_mfma_f32_16x16x32_bf16 v[130:133], v[154:157], v[170:173], 0
	v_mfma_f32_16x16x32_bf16 v[130:133], v[158:161], v[188:191], v[130:133]
	v_mfma_f32_16x16x32_bf16 v[118:121], v[146:149], v[192:195], 0
	v_mfma_f32_16x16x32_bf16 v[118:121], v[150:153], v[196:199], v[118:121]
	v_mfma_f32_16x16x32_bf16 v[114:117], v[154:157], v[192:195], 0
	v_mfma_f32_16x16x32_bf16 v[114:117], v[158:161], v[196:199], v[114:117]
	v_mfma_f32_16x16x32_bf16 v[102:105], v[146:149], v[200:203], 0
	v_mfma_f32_16x16x32_bf16 v[102:105], v[150:153], v[204:207], v[102:105]
	v_mfma_f32_16x16x32_bf16 v[98:101], v[154:157], v[200:203], 0
	v_mfma_f32_16x16x32_bf16 v[98:101], v[158:161], v[204:207], v[98:101]
	v_mfma_f32_16x16x32_bf16 v[86:89], v[146:149], v[208:211], 0
	v_mfma_f32_16x16x32_bf16 v[86:89], v[150:153], v[212:215], v[86:89]
	s_setprio 2
	s_barrier
	v_mfma_f32_16x16x32_bf16 v[82:85], v[154:157], v[208:211], 0
	v_mfma_f32_16x16x32_bf16 v[82:85], v[158:161], v[212:215], v[82:85]
	s_setprio 0
	s_setprio 3
	ds_read_b128 v[170:173], v184 offset:16384
	ds_read_b128 v[188:191], v184 offset:17408
	ds_read_b128 v[192:195], v184 offset:18432
	ds_read_b128 v[196:199], v184 offset:19456
	ds_read_b128 v[200:203], v184 offset:20480
	ds_read_b128 v[204:207], v184 offset:21504
	ds_read_b128 v[208:211], v184 offset:22528
	ds_read_b128 v[212:215], v184 offset:23552
	s_mov_b32 s86, m0
	s_mov_b32 m0, s49
	s_nop 0
	global_load_lds_dwordx4 v177, s[34:35]
	s_mov_b32 m0, s86
	s_nop 0
	s_mov_b32 s86, m0
	s_mov_b32 m0, s56
	s_nop 0
	global_load_lds_dwordx4 v179, s[34:35]
	s_mov_b32 m0, s86
	s_add_u32 s86, s34, 0x80000
	s_addc_u32 s87, s35, 0
	s_mov_b32 s92, m0
	s_mov_b32 m0, s57
	s_nop 0
	global_load_lds_dwordx4 v177, s[86:87]
	s_mov_b32 m0, s92
	s_nop 0
	s_mov_b32 s92, m0
	s_mov_b32 m0, s58
	s_nop 0
	global_load_lds_dwordx4 v179, s[86:87]
	s_mov_b32 m0, s92
	s_setprio 0
	s_waitcnt vmcnt(4)
	s_waitcnt lgkmcnt(0)
	s_barrier
	s_setprio 1
	s_waitcnt lgkmcnt(7)
	v_mfma_f32_16x16x32_bf16 v[78:81], v[46:49], v[170:173], 0
	v_mfma_f32_16x16x32_bf16 v[78:81], v[54:57], v[188:191], v[78:81]
	s_waitcnt lgkmcnt(5)
	v_mfma_f32_16x16x32_bf16 v[74:77], v[58:61], v[170:173], 0
	v_mfma_f32_16x16x32_bf16 v[74:77], v[62:65], v[188:191], v[74:77]
	s_waitcnt lgkmcnt(3)
	v_mfma_f32_16x16x32_bf16 v[50:53], v[46:49], v[192:195], 0
	v_mfma_f32_16x16x32_bf16 v[50:53], v[54:57], v[196:199], v[50:53]
	s_waitcnt lgkmcnt(1)
	v_mfma_f32_16x16x32_bf16 v[42:45], v[58:61], v[192:195], 0
	v_mfma_f32_16x16x32_bf16 v[42:45], v[62:65], v[196:199], v[42:45]
	v_mfma_f32_16x16x32_bf16 v[30:33], v[46:49], v[200:203], 0
	v_mfma_f32_16x16x32_bf16 v[30:33], v[54:57], v[204:207], v[30:33]
	v_mfma_f32_16x16x32_bf16 v[26:29], v[58:61], v[200:203], 0
	v_mfma_f32_16x16x32_bf16 v[26:29], v[62:65], v[204:207], v[26:29]
	v_mfma_f32_16x16x32_bf16 v[14:17], v[46:49], v[208:211], 0
	v_mfma_f32_16x16x32_bf16 v[14:17], v[54:57], v[212:215], v[14:17]
	s_waitcnt lgkmcnt(0)
	v_mfma_f32_16x16x32_bf16 v[10:13], v[58:61], v[208:211], 0
	v_mfma_f32_16x16x32_bf16 v[10:13], v[62:65], v[212:215], v[10:13]
	s_setprio 0
	s_setprio 1
	v_mfma_f32_16x16x32_bf16 v[38:41], v[146:149], v[192:195], 0
	v_mfma_f32_16x16x32_bf16 v[38:41], v[150:153], v[196:199], v[38:41]
	v_mfma_f32_16x16x32_bf16 v[34:37], v[154:157], v[192:195], 0
	v_mfma_f32_16x16x32_bf16 v[34:37], v[158:161], v[196:199], v[34:37]
	v_mfma_f32_16x16x32_bf16 v[22:25], v[146:149], v[200:203], 0
	v_mfma_f32_16x16x32_bf16 v[22:25], v[150:153], v[204:207], v[22:25]
	v_mfma_f32_16x16x32_bf16 v[18:21], v[154:157], v[200:203], 0
	v_mfma_f32_16x16x32_bf16 v[18:21], v[158:161], v[204:207], v[18:21]
	v_mfma_f32_16x16x32_bf16 v[6:9], v[146:149], v[208:211], 0
	v_mfma_f32_16x16x32_bf16 v[6:9], v[150:153], v[212:215], v[6:9]
	v_mfma_f32_16x16x32_bf16 v[2:5], v[154:157], v[208:211], 0
	v_mfma_f32_16x16x32_bf16 v[2:5], v[158:161], v[212:215], v[2:5]
	v_mfma_f32_16x16x32_bf16 v[46:49], v[146:149], v[170:173], 0
	v_mfma_f32_16x16x32_bf16 v[46:49], v[150:153], v[188:191], v[46:49]
	s_setprio 2
	s_barrier
	v_mfma_f32_16x16x32_bf16 v[54:57], v[154:157], v[170:173], 0
	v_mfma_f32_16x16x32_bf16 v[54:57], v[158:161], v[188:191], v[54:57]
	s_setprio 0
	s_setprio 3
	ds_read_b128 v[58:61], v185
	ds_read_b128 v[62:65], v185 offset:1024
	ds_read_b128 v[66:69], v185 offset:2048
	ds_read_b128 v[70:73], v185 offset:3072
	ds_read_b128 v[146:149], v186
	ds_read_b128 v[150:153], v186 offset:1024
	ds_read_b128 v[154:157], v186 offset:2048
	ds_read_b128 v[158:161], v186 offset:3072
	ds_read_b128 v[170:173], v184 offset:32768
	ds_read_b128 v[188:191], v184 offset:33792
	ds_read_b128 v[192:195], v184 offset:34816
	ds_read_b128 v[196:199], v184 offset:35840
	ds_read_b128 v[200:203], v184 offset:36864
	ds_read_b128 v[204:207], v184 offset:37888
	ds_read_b128 v[208:211], v184 offset:38912
	ds_read_b128 v[212:215], v184 offset:39936
	s_mov_b32 s86, m0
	s_mov_b32 m0, s48
	s_nop 0
	global_load_lds_dwordx4 v176, s[36:37]
	s_mov_b32 m0, s86
	s_nop 0
	s_mov_b32 s86, m0
	s_mov_b32 m0, s59
	s_nop 0
	global_load_lds_dwordx4 v178, s[36:37]
	s_mov_b32 m0, s86
	s_add_u32 s36, s36, 0x80000
	s_addc_u32 s37, s37, 0
	s_mov_b32 s86, m0
	s_mov_b32 m0, s62
	s_nop 0
	global_load_lds_dwordx4 v176, s[36:37]
	s_mov_b32 m0, s86
	s_nop 0
	s_mov_b32 s86, m0
	s_mov_b32 m0, s63
	s_nop 0
	global_load_lds_dwordx4 v178, s[36:37]
	s_mov_b32 m0, s86
	s_setprio 0
	s_waitcnt vmcnt(8)
	s_waitcnt lgkmcnt(0)
	s_barrier
	s_setprio 1
	s_waitcnt lgkmcnt(7)
	v_mfma_f32_16x16x32_bf16 v[142:145], v[58:61], v[170:173], v[142:145]
	v_mfma_f32_16x16x32_bf16 v[142:145], v[62:65], v[188:191], v[142:145]
	s_waitcnt lgkmcnt(5)
	v_mfma_f32_16x16x32_bf16 v[138:141], v[66:69], v[170:173], v[138:141]
	v_mfma_f32_16x16x32_bf16 v[138:141], v[70:73], v[188:191], v[138:141]
	s_waitcnt lgkmcnt(3)
	v_mfma_f32_16x16x32_bf16 v[126:129], v[58:61], v[192:195], v[126:129]
	v_mfma_f32_16x16x32_bf16 v[126:129], v[62:65], v[196:199], v[126:129]
	s_waitcnt lgkmcnt(1)
	v_mfma_f32_16x16x32_bf16 v[122:125], v[66:69], v[192:195], v[122:125]
	v_mfma_f32_16x16x32_bf16 v[122:125], v[70:73], v[196:199], v[122:125]
	v_mfma_f32_16x16x32_bf16 v[110:113], v[58:61], v[200:203], v[110:113]
	v_mfma_f32_16x16x32_bf16 v[110:113], v[62:65], v[204:207], v[110:113]
	v_mfma_f32_16x16x32_bf16 v[106:109], v[66:69], v[200:203], v[106:109]
	v_mfma_f32_16x16x32_bf16 v[106:109], v[70:73], v[204:207], v[106:109]
	v_mfma_f32_16x16x32_bf16 v[94:97], v[58:61], v[208:211], v[94:97]
	v_mfma_f32_16x16x32_bf16 v[94:97], v[62:65], v[212:215], v[94:97]
	s_waitcnt lgkmcnt(0)
	v_mfma_f32_16x16x32_bf16 v[90:93], v[66:69], v[208:211], v[90:93]
	v_mfma_f32_16x16x32_bf16 v[90:93], v[70:73], v[212:215], v[90:93]
	s_setprio 0
	s_setprio 1
	v_mfma_f32_16x16x32_bf16 v[134:137], v[146:149], v[170:173], v[134:137]
	v_mfma_f32_16x16x32_bf16 v[134:137], v[150:153], v[188:191], v[134:137]
	v_mfma_f32_16x16x32_bf16 v[130:133], v[154:157], v[170:173], v[130:133]
	v_mfma_f32_16x16x32_bf16 v[130:133], v[158:161], v[188:191], v[130:133]
	v_mfma_f32_16x16x32_bf16 v[118:121], v[146:149], v[192:195], v[118:121]
	v_mfma_f32_16x16x32_bf16 v[118:121], v[150:153], v[196:199], v[118:121]
	v_mfma_f32_16x16x32_bf16 v[114:117], v[154:157], v[192:195], v[114:117]
	v_mfma_f32_16x16x32_bf16 v[114:117], v[158:161], v[196:199], v[114:117]
	v_mfma_f32_16x16x32_bf16 v[102:105], v[146:149], v[200:203], v[102:105]
	v_mfma_f32_16x16x32_bf16 v[102:105], v[150:153], v[204:207], v[102:105]
	v_mfma_f32_16x16x32_bf16 v[98:101], v[154:157], v[200:203], v[98:101]
	v_mfma_f32_16x16x32_bf16 v[98:101], v[158:161], v[204:207], v[98:101]
	v_mfma_f32_16x16x32_bf16 v[86:89], v[146:149], v[208:211], v[86:89]
	v_mfma_f32_16x16x32_bf16 v[86:89], v[150:153], v[212:215], v[86:89]
	s_setprio 2
	s_barrier
	v_mfma_f32_16x16x32_bf16 v[82:85], v[154:157], v[208:211], v[82:85]
	v_mfma_f32_16x16x32_bf16 v[82:85], v[158:161], v[212:215], v[82:85]
	s_setprio 0
	s_setprio 3
	ds_read_b128 v[170:173], v184 offset:49152
	ds_read_b128 v[188:191], v184 offset:50176
	ds_read_b128 v[192:195], v184 offset:51200
	ds_read_b128 v[196:199], v184 offset:52224
	ds_read_b128 v[200:203], v184 offset:53248
	ds_read_b128 v[204:207], v184 offset:54272
	ds_read_b128 v[208:211], v184 offset:55296
	ds_read_b128 v[212:215], v184 offset:56320
	s_add_u32 s36, s34, 0x80
	s_addc_u32 s37, s35, 0
	s_mov_b32 s86, m0
	s_mov_b32 m0, s64
	s_nop 0
	global_load_lds_dwordx4 v177, s[36:37]
	s_mov_b32 m0, s86
	s_add_u32 s34, s34, 0x80080
	s_mov_b32 s86, m0
	s_mov_b32 m0, s65
	s_nop 0
	global_load_lds_dwordx4 v179, s[36:37]
	s_mov_b32 m0, s86
	s_addc_u32 s35, s35, 0
	s_mov_b32 s36, m0
	s_mov_b32 m0, s66
	s_nop 0
	global_load_lds_dwordx4 v177, s[34:35]
	s_mov_b32 m0, s36
	s_nop 0
	s_mov_b32 s36, m0
	s_mov_b32 m0, s67
	s_nop 0
	global_load_lds_dwordx4 v179, s[34:35]
	s_mov_b32 m0, s36
	s_setprio 0
	s_waitcnt vmcnt(4)
	s_waitcnt lgkmcnt(0)
	s_barrier
	s_setprio 1
	s_waitcnt lgkmcnt(7)
	v_mfma_f32_16x16x32_bf16 v[78:81], v[58:61], v[170:173], v[78:81]
	v_mfma_f32_16x16x32_bf16 v[78:81], v[62:65], v[188:191], v[78:81]
	s_waitcnt lgkmcnt(5)
	v_mfma_f32_16x16x32_bf16 v[74:77], v[66:69], v[170:173], v[74:77]
	v_mfma_f32_16x16x32_bf16 v[74:77], v[70:73], v[188:191], v[74:77]
	s_waitcnt lgkmcnt(3)
	v_mfma_f32_16x16x32_bf16 v[50:53], v[58:61], v[192:195], v[50:53]
	v_mfma_f32_16x16x32_bf16 v[50:53], v[62:65], v[196:199], v[50:53]
	s_waitcnt lgkmcnt(1)
	v_mfma_f32_16x16x32_bf16 v[42:45], v[66:69], v[192:195], v[42:45]
	v_mfma_f32_16x16x32_bf16 v[42:45], v[70:73], v[196:199], v[42:45]
	v_mfma_f32_16x16x32_bf16 v[30:33], v[58:61], v[200:203], v[30:33]
	v_mfma_f32_16x16x32_bf16 v[30:33], v[62:65], v[204:207], v[30:33]
	v_mfma_f32_16x16x32_bf16 v[26:29], v[66:69], v[200:203], v[26:29]
	v_mfma_f32_16x16x32_bf16 v[26:29], v[70:73], v[204:207], v[26:29]
	v_mfma_f32_16x16x32_bf16 v[14:17], v[58:61], v[208:211], v[14:17]
	v_mfma_f32_16x16x32_bf16 v[14:17], v[62:65], v[212:215], v[14:17]
	s_waitcnt lgkmcnt(0)
	v_mfma_f32_16x16x32_bf16 v[10:13], v[66:69], v[208:211], v[10:13]
	v_mfma_f32_16x16x32_bf16 v[10:13], v[70:73], v[212:215], v[10:13]
	s_setprio 0
	s_setprio 1
	v_mfma_f32_16x16x32_bf16 v[46:49], v[146:149], v[170:173], v[46:49]
	v_mfma_f32_16x16x32_bf16 v[70:73], v[150:153], v[188:191], v[46:49]
	v_mfma_f32_16x16x32_bf16 v[46:49], v[154:157], v[170:173], v[54:57]
	v_mfma_f32_16x16x32_bf16 v[66:69], v[158:161], v[188:191], v[46:49]
	v_mfma_f32_16x16x32_bf16 v[38:41], v[146:149], v[192:195], v[38:41]
	v_mfma_f32_16x16x32_bf16 v[38:41], v[150:153], v[196:199], v[38:41]
	v_mfma_f32_16x16x32_bf16 v[34:37], v[154:157], v[192:195], v[34:37]
	v_mfma_f32_16x16x32_bf16 v[34:37], v[158:161], v[196:199], v[34:37]
	v_mfma_f32_16x16x32_bf16 v[22:25], v[146:149], v[200:203], v[22:25]
	v_mfma_f32_16x16x32_bf16 v[22:25], v[150:153], v[204:207], v[22:25]
	v_mfma_f32_16x16x32_bf16 v[18:21], v[154:157], v[200:203], v[18:21]
	v_mfma_f32_16x16x32_bf16 v[18:21], v[158:161], v[204:207], v[18:21]
	v_mfma_f32_16x16x32_bf16 v[6:9], v[146:149], v[208:211], v[6:9]
	v_mfma_f32_16x16x32_bf16 v[6:9], v[150:153], v[212:215], v[6:9]
	s_setprio 2
	s_barrier
	v_mfma_f32_16x16x32_bf16 v[2:5], v[154:157], v[208:211], v[2:5]
	v_mfma_f32_16x16x32_bf16 v[2:5], v[158:161], v[212:215], v[2:5]
	s_setprio 0
	s_add_i32 s83, s83, 2
	s_add_u32 s79, s79, 0x100
	s_addc_u32 s80, s80, 0
	s_add_u32 s30, s30, 0x100
	s_addc_u32 s31, s31, 0
	s_add_u32 s81, s81, 0x100
	s_addc_u32 s82, s82, 0
	s_cmp_gt_u32 s83, 29
	.p2align 6
.LBB0_1538:
	s_setprio 3
	ds_read_b128 v[46:49], v182
	ds_read_b128 v[54:57], v182 offset:1024
	ds_read_b128 v[58:61], v182 offset:2048
	ds_read_b128 v[62:65], v182 offset:3072
	ds_read_b128 v[146:149], v183
	ds_read_b128 v[150:153], v183 offset:1024
	ds_read_b128 v[154:157], v183 offset:2048
	ds_read_b128 v[158:161], v183 offset:3072
	s_cmp_eq_u32 s83, 28
	s_cselect_b32 s35, s21, s80
	s_cselect_b32 s34, s29, s79
	s_cselect_b32 s37, s7, s82
	s_cselect_b32 s36, s23, s81
	ds_read_b128 v[170:173], v184
	ds_read_b128 v[188:191], v184 offset:1024
	ds_read_b128 v[192:195], v184 offset:2048
	ds_read_b128 v[196:199], v184 offset:3072
	ds_read_b128 v[200:203], v184 offset:4096
	ds_read_b128 v[204:207], v184 offset:5120
	ds_read_b128 v[208:211], v184 offset:6144
	ds_read_b128 v[212:215], v184 offset:7168
	s_add_u32 s86, s30, 0xfff80000
	s_addc_u32 s87, s31, -1
	s_mov_b32 s92, m0
	s_mov_b32 m0, s73
	s_nop 0
	global_load_lds_dwordx4 v176, s[86:87]
	s_mov_b32 m0, s92
	s_nop 0
	s_mov_b32 s92, m0
	s_mov_b32 m0, s75
	s_nop 0
	global_load_lds_dwordx4 v178, s[86:87]
	s_mov_b32 m0, s92
	s_mov_b32 s86, m0
	s_mov_b32 m0, s74
	s_nop 0
	global_load_lds_dwordx4 v176, s[30:31]
	s_mov_b32 m0, s86
	s_nop 0
	s_mov_b32 s86, m0
	s_mov_b32 m0, s76
	s_nop 0
	global_load_lds_dwordx4 v178, s[30:31]
	s_mov_b32 m0, s86
	s_setprio 0
	s_waitcnt vmcnt(8)
	s_waitcnt lgkmcnt(0)
	s_barrier
	s_setprio 1
	s_waitcnt lgkmcnt(7)
	v_mfma_f32_16x16x32_bf16 v[142:145], v[46:49], v[170:173], v[142:145]
	v_mfma_f32_16x16x32_bf16 v[142:145], v[54:57], v[188:191], v[142:145]
	s_waitcnt lgkmcnt(5)
	v_mfma_f32_16x16x32_bf16 v[138:141], v[58:61], v[170:173], v[138:141]
	v_mfma_f32_16x16x32_bf16 v[138:141], v[62:65], v[188:191], v[138:141]
	s_waitcnt lgkmcnt(3)
	v_mfma_f32_16x16x32_bf16 v[126:129], v[46:49], v[192:195], v[126:129]
	v_mfma_f32_16x16x32_bf16 v[126:129], v[54:57], v[196:199], v[126:129]
	s_waitcnt lgkmcnt(1)
	v_mfma_f32_16x16x32_bf16 v[122:125], v[58:61], v[192:195], v[122:125]
	v_mfma_f32_16x16x32_bf16 v[122:125], v[62:65], v[196:199], v[122:125]
	v_mfma_f32_16x16x32_bf16 v[110:113], v[46:49], v[200:203], v[110:113]
	v_mfma_f32_16x16x32_bf16 v[110:113], v[54:57], v[204:207], v[110:113]
	v_mfma_f32_16x16x32_bf16 v[106:109], v[58:61], v[200:203], v[106:109]
	v_mfma_f32_16x16x32_bf16 v[106:109], v[62:65], v[204:207], v[106:109]
	v_mfma_f32_16x16x32_bf16 v[94:97], v[46:49], v[208:211], v[94:97]
	v_mfma_f32_16x16x32_bf16 v[94:97], v[54:57], v[212:215], v[94:97]
	s_waitcnt lgkmcnt(0)
	v_mfma_f32_16x16x32_bf16 v[90:93], v[58:61], v[208:211], v[90:93]
	v_mfma_f32_16x16x32_bf16 v[90:93], v[62:65], v[212:215], v[90:93]
	s_setprio 0
	s_setprio 1
	v_mfma_f32_16x16x32_bf16 v[134:137], v[146:149], v[170:173], v[134:137]
	v_mfma_f32_16x16x32_bf16 v[134:137], v[150:153], v[188:191], v[134:137]
	v_mfma_f32_16x16x32_bf16 v[130:133], v[154:157], v[170:173], v[130:133]
	v_mfma_f32_16x16x32_bf16 v[130:133], v[158:161], v[188:191], v[130:133]
	v_mfma_f32_16x16x32_bf16 v[118:121], v[146:149], v[192:195], v[118:121]
	v_mfma_f32_16x16x32_bf16 v[118:121], v[150:153], v[196:199], v[118:121]
	v_mfma_f32_16x16x32_bf16 v[114:117], v[154:157], v[192:195], v[114:117]
	v_mfma_f32_16x16x32_bf16 v[114:117], v[158:161], v[196:199], v[114:117]
	v_mfma_f32_16x16x32_bf16 v[102:105], v[146:149], v[200:203], v[102:105]
	v_mfma_f32_16x16x32_bf16 v[102:105], v[150:153], v[204:207], v[102:105]
	v_mfma_f32_16x16x32_bf16 v[98:101], v[154:157], v[200:203], v[98:101]
	v_mfma_f32_16x16x32_bf16 v[98:101], v[158:161], v[204:207], v[98:101]
	v_mfma_f32_16x16x32_bf16 v[86:89], v[146:149], v[208:211], v[86:89]
	v_mfma_f32_16x16x32_bf16 v[86:89], v[150:153], v[212:215], v[86:89]
	s_setprio 2
	s_barrier
	v_mfma_f32_16x16x32_bf16 v[82:85], v[154:157], v[208:211], v[82:85]
	v_mfma_f32_16x16x32_bf16 v[82:85], v[158:161], v[212:215], v[82:85]
	s_setprio 0
	s_setprio 3
	ds_read_b128 v[170:173], v184 offset:16384
	ds_read_b128 v[188:191], v184 offset:17408
	ds_read_b128 v[192:195], v184 offset:18432
	ds_read_b128 v[196:199], v184 offset:19456
	ds_read_b128 v[200:203], v184 offset:20480
	ds_read_b128 v[204:207], v184 offset:21504
	ds_read_b128 v[208:211], v184 offset:22528
	ds_read_b128 v[212:215], v184 offset:23552
	s_mov_b32 s86, m0
	s_mov_b32 m0, s49
	s_nop 0
	global_load_lds_dwordx4 v177, s[34:35]
	s_mov_b32 m0, s86
	s_nop 0
	s_mov_b32 s86, m0
	s_mov_b32 m0, s56
	s_nop 0
	global_load_lds_dwordx4 v179, s[34:35]
	s_mov_b32 m0, s86
	s_add_u32 s86, s34, 0x80000
	s_addc_u32 s87, s35, 0
	s_mov_b32 s92, m0
	s_mov_b32 m0, s57
	s_nop 0
	global_load_lds_dwordx4 v177, s[86:87]
	s_mov_b32 m0, s92
	s_nop 0
	s_mov_b32 s92, m0
	s_mov_b32 m0, s58
	s_nop 0
	global_load_lds_dwordx4 v179, s[86:87]
	s_mov_b32 m0, s92
	s_setprio 0
	s_waitcnt vmcnt(4)
	s_waitcnt lgkmcnt(0)
	s_barrier
	s_setprio 1
	s_waitcnt lgkmcnt(7)
	v_mfma_f32_16x16x32_bf16 v[78:81], v[46:49], v[170:173], v[78:81]
	v_mfma_f32_16x16x32_bf16 v[78:81], v[54:57], v[188:191], v[78:81]
	s_waitcnt lgkmcnt(5)
	v_mfma_f32_16x16x32_bf16 v[74:77], v[58:61], v[170:173], v[74:77]
	v_mfma_f32_16x16x32_bf16 v[74:77], v[62:65], v[188:191], v[74:77]
	s_waitcnt lgkmcnt(3)
	v_mfma_f32_16x16x32_bf16 v[50:53], v[46:49], v[192:195], v[50:53]
	v_mfma_f32_16x16x32_bf16 v[50:53], v[54:57], v[196:199], v[50:53]
	s_waitcnt lgkmcnt(1)
	v_mfma_f32_16x16x32_bf16 v[42:45], v[58:61], v[192:195], v[42:45]
	v_mfma_f32_16x16x32_bf16 v[42:45], v[62:65], v[196:199], v[42:45]
	v_mfma_f32_16x16x32_bf16 v[30:33], v[46:49], v[200:203], v[30:33]
	v_mfma_f32_16x16x32_bf16 v[30:33], v[54:57], v[204:207], v[30:33]
	v_mfma_f32_16x16x32_bf16 v[26:29], v[58:61], v[200:203], v[26:29]
	v_mfma_f32_16x16x32_bf16 v[26:29], v[62:65], v[204:207], v[26:29]
	v_mfma_f32_16x16x32_bf16 v[14:17], v[46:49], v[208:211], v[14:17]
	v_mfma_f32_16x16x32_bf16 v[14:17], v[54:57], v[212:215], v[14:17]
	s_waitcnt lgkmcnt(0)
	v_mfma_f32_16x16x32_bf16 v[10:13], v[58:61], v[208:211], v[10:13]
	v_mfma_f32_16x16x32_bf16 v[10:13], v[62:65], v[212:215], v[10:13]
	s_setprio 0
	s_setprio 1
	v_mfma_f32_16x16x32_bf16 v[38:41], v[146:149], v[192:195], v[38:41]
	v_mfma_f32_16x16x32_bf16 v[38:41], v[150:153], v[196:199], v[38:41]
	v_mfma_f32_16x16x32_bf16 v[34:37], v[154:157], v[192:195], v[34:37]
	v_mfma_f32_16x16x32_bf16 v[34:37], v[158:161], v[196:199], v[34:37]
	v_mfma_f32_16x16x32_bf16 v[22:25], v[146:149], v[200:203], v[22:25]
	v_mfma_f32_16x16x32_bf16 v[22:25], v[150:153], v[204:207], v[22:25]
	v_mfma_f32_16x16x32_bf16 v[18:21], v[154:157], v[200:203], v[18:21]
	v_mfma_f32_16x16x32_bf16 v[18:21], v[158:161], v[204:207], v[18:21]
	v_mfma_f32_16x16x32_bf16 v[6:9], v[146:149], v[208:211], v[6:9]
	v_mfma_f32_16x16x32_bf16 v[6:9], v[150:153], v[212:215], v[6:9]
	v_mfma_f32_16x16x32_bf16 v[2:5], v[154:157], v[208:211], v[2:5]
	v_mfma_f32_16x16x32_bf16 v[2:5], v[158:161], v[212:215], v[2:5]
	v_mfma_f32_16x16x32_bf16 v[46:49], v[146:149], v[170:173], v[70:73]
	v_mfma_f32_16x16x32_bf16 v[46:49], v[150:153], v[188:191], v[46:49]
	s_setprio 2
	s_barrier
	v_mfma_f32_16x16x32_bf16 v[54:57], v[154:157], v[170:173], v[66:69]
	v_mfma_f32_16x16x32_bf16 v[54:57], v[158:161], v[188:191], v[54:57]
	s_setprio 0
	s_setprio 3
	ds_read_b128 v[58:61], v185
	ds_read_b128 v[62:65], v185 offset:1024
	ds_read_b128 v[66:69], v185 offset:2048
	ds_read_b128 v[70:73], v185 offset:3072
	ds_read_b128 v[146:149], v186
	ds_read_b128 v[150:153], v186 offset:1024
	ds_read_b128 v[154:157], v186 offset:2048
	ds_read_b128 v[158:161], v186 offset:3072
	ds_read_b128 v[170:173], v184 offset:32768
	ds_read_b128 v[188:191], v184 offset:33792
	ds_read_b128 v[192:195], v184 offset:34816
	ds_read_b128 v[196:199], v184 offset:35840
	ds_read_b128 v[200:203], v184 offset:36864
	ds_read_b128 v[204:207], v184 offset:37888
	ds_read_b128 v[208:211], v184 offset:38912
	ds_read_b128 v[212:215], v184 offset:39936
	s_mov_b32 s86, m0
	s_mov_b32 m0, s48
	s_nop 0
	global_load_lds_dwordx4 v176, s[36:37]
	s_mov_b32 m0, s86
	s_nop 0
	s_mov_b32 s86, m0
	s_mov_b32 m0, s59
	s_nop 0
	global_load_lds_dwordx4 v178, s[36:37]
	s_mov_b32 m0, s86
	s_add_u32 s36, s36, 0x80000
	s_addc_u32 s37, s37, 0
	s_mov_b32 s86, m0
	s_mov_b32 m0, s62
	s_nop 0
	global_load_lds_dwordx4 v176, s[36:37]
	s_mov_b32 m0, s86
	s_nop 0
	s_mov_b32 s86, m0
	s_mov_b32 m0, s63
	s_nop 0
	global_load_lds_dwordx4 v178, s[36:37]
	s_mov_b32 m0, s86
	s_setprio 0
	s_waitcnt vmcnt(8)
	s_waitcnt lgkmcnt(0)
	s_barrier
	s_setprio 1
	s_waitcnt lgkmcnt(7)
	v_mfma_f32_16x16x32_bf16 v[142:145], v[58:61], v[170:173], v[142:145]
	v_mfma_f32_16x16x32_bf16 v[142:145], v[62:65], v[188:191], v[142:145]
	s_waitcnt lgkmcnt(5)
	v_mfma_f32_16x16x32_bf16 v[138:141], v[66:69], v[170:173], v[138:141]
	v_mfma_f32_16x16x32_bf16 v[138:141], v[70:73], v[188:191], v[138:141]
	s_waitcnt lgkmcnt(3)
	v_mfma_f32_16x16x32_bf16 v[126:129], v[58:61], v[192:195], v[126:129]
	v_mfma_f32_16x16x32_bf16 v[126:129], v[62:65], v[196:199], v[126:129]
	s_waitcnt lgkmcnt(1)
	v_mfma_f32_16x16x32_bf16 v[122:125], v[66:69], v[192:195], v[122:125]
	v_mfma_f32_16x16x32_bf16 v[122:125], v[70:73], v[196:199], v[122:125]
	v_mfma_f32_16x16x32_bf16 v[110:113], v[58:61], v[200:203], v[110:113]
	v_mfma_f32_16x16x32_bf16 v[110:113], v[62:65], v[204:207], v[110:113]
	v_mfma_f32_16x16x32_bf16 v[106:109], v[66:69], v[200:203], v[106:109]
	v_mfma_f32_16x16x32_bf16 v[106:109], v[70:73], v[204:207], v[106:109]
	v_mfma_f32_16x16x32_bf16 v[94:97], v[58:61], v[208:211], v[94:97]
	v_mfma_f32_16x16x32_bf16 v[94:97], v[62:65], v[212:215], v[94:97]
	s_waitcnt lgkmcnt(0)
	v_mfma_f32_16x16x32_bf16 v[90:93], v[66:69], v[208:211], v[90:93]
	v_mfma_f32_16x16x32_bf16 v[90:93], v[70:73], v[212:215], v[90:93]
	s_setprio 0
	s_setprio 1
	v_mfma_f32_16x16x32_bf16 v[134:137], v[146:149], v[170:173], v[134:137]
	v_mfma_f32_16x16x32_bf16 v[134:137], v[150:153], v[188:191], v[134:137]
	v_mfma_f32_16x16x32_bf16 v[130:133], v[154:157], v[170:173], v[130:133]
	v_mfma_f32_16x16x32_bf16 v[130:133], v[158:161], v[188:191], v[130:133]
	v_mfma_f32_16x16x32_bf16 v[118:121], v[146:149], v[192:195], v[118:121]
	v_mfma_f32_16x16x32_bf16 v[118:121], v[150:153], v[196:199], v[118:121]
	v_mfma_f32_16x16x32_bf16 v[114:117], v[154:157], v[192:195], v[114:117]
	v_mfma_f32_16x16x32_bf16 v[114:117], v[158:161], v[196:199], v[114:117]
	v_mfma_f32_16x16x32_bf16 v[102:105], v[146:149], v[200:203], v[102:105]
	v_mfma_f32_16x16x32_bf16 v[102:105], v[150:153], v[204:207], v[102:105]
	v_mfma_f32_16x16x32_bf16 v[98:101], v[154:157], v[200:203], v[98:101]
	v_mfma_f32_16x16x32_bf16 v[98:101], v[158:161], v[204:207], v[98:101]
	v_mfma_f32_16x16x32_bf16 v[86:89], v[146:149], v[208:211], v[86:89]
	v_mfma_f32_16x16x32_bf16 v[86:89], v[150:153], v[212:215], v[86:89]
	s_setprio 2
	s_barrier
	v_mfma_f32_16x16x32_bf16 v[82:85], v[154:157], v[208:211], v[82:85]
	v_mfma_f32_16x16x32_bf16 v[82:85], v[158:161], v[212:215], v[82:85]
	s_setprio 0
	s_setprio 3
	ds_read_b128 v[170:173], v184 offset:49152
	ds_read_b128 v[188:191], v184 offset:50176
	ds_read_b128 v[192:195], v184 offset:51200
	ds_read_b128 v[196:199], v184 offset:52224
	ds_read_b128 v[200:203], v184 offset:53248
	ds_read_b128 v[204:207], v184 offset:54272
	ds_read_b128 v[208:211], v184 offset:55296
	ds_read_b128 v[212:215], v184 offset:56320
	s_add_u32 s36, s34, 0x80
	s_addc_u32 s37, s35, 0
	s_mov_b32 s86, m0
	s_mov_b32 m0, s64
	s_nop 0
	global_load_lds_dwordx4 v177, s[36:37]
	s_mov_b32 m0, s86
	s_add_u32 s34, s34, 0x80080
	s_mov_b32 s86, m0
	s_mov_b32 m0, s65
	s_nop 0
	global_load_lds_dwordx4 v179, s[36:37]
	s_mov_b32 m0, s86
	s_addc_u32 s35, s35, 0
	s_mov_b32 s36, m0
	s_mov_b32 m0, s66
	s_nop 0
	global_load_lds_dwordx4 v177, s[34:35]
	s_mov_b32 m0, s36
	s_nop 0
	s_mov_b32 s36, m0
	s_mov_b32 m0, s67
	s_nop 0
	global_load_lds_dwordx4 v179, s[34:35]
	s_mov_b32 m0, s36
	s_setprio 0
	s_waitcnt vmcnt(4)
	s_waitcnt lgkmcnt(0)
	s_barrier
	s_setprio 1
	s_waitcnt lgkmcnt(7)
	v_mfma_f32_16x16x32_bf16 v[78:81], v[58:61], v[170:173], v[78:81]
	v_mfma_f32_16x16x32_bf16 v[78:81], v[62:65], v[188:191], v[78:81]
	s_waitcnt lgkmcnt(5)
	v_mfma_f32_16x16x32_bf16 v[74:77], v[66:69], v[170:173], v[74:77]
	v_mfma_f32_16x16x32_bf16 v[74:77], v[70:73], v[188:191], v[74:77]
	s_waitcnt lgkmcnt(3)
	v_mfma_f32_16x16x32_bf16 v[50:53], v[58:61], v[192:195], v[50:53]
	v_mfma_f32_16x16x32_bf16 v[50:53], v[62:65], v[196:199], v[50:53]
	s_waitcnt lgkmcnt(1)
	v_mfma_f32_16x16x32_bf16 v[42:45], v[66:69], v[192:195], v[42:45]
	v_mfma_f32_16x16x32_bf16 v[42:45], v[70:73], v[196:199], v[42:45]
	v_mfma_f32_16x16x32_bf16 v[30:33], v[58:61], v[200:203], v[30:33]
	v_mfma_f32_16x16x32_bf16 v[30:33], v[62:65], v[204:207], v[30:33]
	v_mfma_f32_16x16x32_bf16 v[26:29], v[66:69], v[200:203], v[26:29]
	v_mfma_f32_16x16x32_bf16 v[26:29], v[70:73], v[204:207], v[26:29]
	v_mfma_f32_16x16x32_bf16 v[14:17], v[58:61], v[208:211], v[14:17]
	v_mfma_f32_16x16x32_bf16 v[14:17], v[62:65], v[212:215], v[14:17]
	s_waitcnt lgkmcnt(0)
	v_mfma_f32_16x16x32_bf16 v[10:13], v[66:69], v[208:211], v[10:13]
	v_mfma_f32_16x16x32_bf16 v[10:13], v[70:73], v[212:215], v[10:13]
	s_setprio 0
	s_setprio 1
	v_mfma_f32_16x16x32_bf16 v[46:49], v[146:149], v[170:173], v[46:49]
	v_mfma_f32_16x16x32_bf16 v[70:73], v[150:153], v[188:191], v[46:49]
	v_mfma_f32_16x16x32_bf16 v[46:49], v[154:157], v[170:173], v[54:57]
	v_mfma_f32_16x16x32_bf16 v[66:69], v[158:161], v[188:191], v[46:49]
	v_mfma_f32_16x16x32_bf16 v[38:41], v[146:149], v[192:195], v[38:41]
	v_mfma_f32_16x16x32_bf16 v[38:41], v[150:153], v[196:199], v[38:41]
	v_mfma_f32_16x16x32_bf16 v[34:37], v[154:157], v[192:195], v[34:37]
	v_mfma_f32_16x16x32_bf16 v[34:37], v[158:161], v[196:199], v[34:37]
	v_mfma_f32_16x16x32_bf16 v[22:25], v[146:149], v[200:203], v[22:25]
	v_mfma_f32_16x16x32_bf16 v[22:25], v[150:153], v[204:207], v[22:25]
	v_mfma_f32_16x16x32_bf16 v[18:21], v[154:157], v[200:203], v[18:21]
	v_mfma_f32_16x16x32_bf16 v[18:21], v[158:161], v[204:207], v[18:21]
	v_mfma_f32_16x16x32_bf16 v[6:9], v[146:149], v[208:211], v[6:9]
	v_mfma_f32_16x16x32_bf16 v[6:9], v[150:153], v[212:215], v[6:9]
	s_setprio 2
	s_barrier
	v_mfma_f32_16x16x32_bf16 v[2:5], v[154:157], v[208:211], v[2:5]
	v_mfma_f32_16x16x32_bf16 v[2:5], v[158:161], v[212:215], v[2:5]
	s_setprio 0
	s_add_i32 s83, s83, 2
	s_add_u32 s79, s79, 0x100
	s_addc_u32 s80, s80, 0
	s_add_u32 s30, s30, 0x100
	s_addc_u32 s31, s31, 0
	s_add_u32 s81, s81, 0x100
	s_addc_u32 s82, s82, 0
	s_cmp_gt_u32 s83, 29
	s_cbranch_scc0 .LBB0_1538
	s_and_b64 vcc, exec, s[16:17]
	s_cbranch_vccz .LBB0_1541
	s_barrier

.LBB0_1784:
	s_ashr_i32 s11, s10, 31
	s_lshl_b64 s[12:13], s[10:11], 20
	s_add_u32 s12, s26, s12
	s_addc_u32 s13, s27, s13
	s_and_b64 s[14:15], s[2:3], exec
	s_cselect_b32 s11, s13, s21
	s_cselect_b32 s64, s12, s20
	s_ashr_i32 s9, s8, 31
	s_lshl_b64 s[14:15], s[8:9], 20
	s_add_u32 s14, s28, s14
	s_addc_u32 s15, s29, s15
	s_and_b64 s[22:23], s[2:3], exec
	s_cselect_b32 s9, s15, s19
	s_cselect_b32 s65, s14, s18
	s_add_u32 s66, s18, 0x100
	s_addc_u32 s67, s19, 0
	s_add_u32 s18, s20, 0x80080
	s_addc_u32 s19, s21, 0
	s_add_u32 s70, s20, 0x100
	s_addc_u32 s71, s21, 0
	s_mov_b32 s73, -2
	s_setprio 3
	ds_read_b128 v[148:151], v143
	ds_read_b128 v[152:155], v143 offset:1024
	ds_read_b128 v[156:159], v143 offset:2048
	ds_read_b128 v[160:163], v143 offset:3072
	ds_read_b128 v[164:167], v144
	ds_read_b128 v[168:171], v144 offset:1024
	ds_read_b128 v[172:175], v144 offset:2048
	ds_read_b128 v[176:179], v144 offset:3072
	s_cmp_eq_u32 s73, 28
	s_cselect_b32 s21, s9, s67
	s_cselect_b32 s20, s65, s66
	s_cselect_b32 s23, s11, s71
	s_cselect_b32 s22, s64, s70
	ds_read_b128 v[180:183], v145
	ds_read_b128 v[184:187], v145 offset:1024
	ds_read_b128 v[188:191], v145 offset:2048
	ds_read_b128 v[192:195], v145 offset:3072
	ds_read_b128 v[196:199], v145 offset:4096
	ds_read_b128 v[200:203], v145 offset:5120
	ds_read_b128 v[204:207], v145 offset:6144
	ds_read_b128 v[208:211], v145 offset:7168
	s_add_u32 s74, s18, 0xfff80000
	s_addc_u32 s75, s19, -1
	s_mov_b32 s76, m0
	s_mov_b32 m0, s56
	s_nop 0
	global_load_lds_dwordx4 v138, s[74:75]
	s_mov_b32 m0, s76
	s_nop 0
	s_mov_b32 s76, m0
	s_mov_b32 m0, s59
	s_nop 0
	global_load_lds_dwordx4 v140, s[74:75]
	s_mov_b32 m0, s76
	s_mov_b32 s74, m0
	s_mov_b32 m0, s57
	s_nop 0
	global_load_lds_dwordx4 v138, s[18:19]
	s_mov_b32 m0, s74
	s_nop 0
	s_mov_b32 s74, m0
	s_mov_b32 m0, s62
	s_nop 0
	global_load_lds_dwordx4 v140, s[18:19]
	s_mov_b32 m0, s74
	s_setprio 0
	s_waitcnt vmcnt(8)
	s_waitcnt lgkmcnt(0)
	s_barrier
	s_setprio 1
	s_waitcnt lgkmcnt(7)
	v_mfma_f32_16x16x32_bf16 v[126:129], v[148:151], v[180:183], 0
	v_mfma_f32_16x16x32_bf16 v[126:129], v[152:155], v[184:187], v[126:129]
	s_waitcnt lgkmcnt(5)
	v_mfma_f32_16x16x32_bf16 v[122:125], v[156:159], v[180:183], 0
	v_mfma_f32_16x16x32_bf16 v[122:125], v[160:163], v[184:187], v[122:125]
	s_waitcnt lgkmcnt(3)
	v_mfma_f32_16x16x32_bf16 v[106:109], v[156:159], v[188:191], 0
	v_mfma_f32_16x16x32_bf16 v[106:109], v[160:163], v[192:195], v[106:109]
	s_waitcnt lgkmcnt(1)
	v_mfma_f32_16x16x32_bf16 v[110:113], v[148:151], v[188:191], 0
	v_mfma_f32_16x16x32_bf16 v[110:113], v[152:155], v[192:195], v[110:113]
	v_mfma_f32_16x16x32_bf16 v[94:97], v[148:151], v[196:199], 0
	v_mfma_f32_16x16x32_bf16 v[94:97], v[152:155], v[200:203], v[94:97]
	v_mfma_f32_16x16x32_bf16 v[90:93], v[156:159], v[196:199], 0
	v_mfma_f32_16x16x32_bf16 v[90:93], v[160:163], v[200:203], v[90:93]
	v_mfma_f32_16x16x32_bf16 v[74:77], v[156:159], v[204:207], 0
	v_mfma_f32_16x16x32_bf16 v[74:77], v[160:163], v[208:211], v[74:77]
	s_waitcnt lgkmcnt(0)
	v_mfma_f32_16x16x32_bf16 v[78:81], v[148:151], v[204:207], 0
	v_mfma_f32_16x16x32_bf16 v[78:81], v[152:155], v[208:211], v[78:81]
	s_setprio 0
	s_setprio 1
	v_mfma_f32_16x16x32_bf16 v[118:121], v[164:167], v[180:183], 0
	v_mfma_f32_16x16x32_bf16 v[118:121], v[168:171], v[184:187], v[118:121]
	v_mfma_f32_16x16x32_bf16 v[114:117], v[172:175], v[180:183], 0
	v_mfma_f32_16x16x32_bf16 v[114:117], v[176:179], v[184:187], v[114:117]
	v_mfma_f32_16x16x32_bf16 v[98:101], v[172:175], v[188:191], 0
	v_mfma_f32_16x16x32_bf16 v[98:101], v[176:179], v[192:195], v[98:101]
	v_mfma_f32_16x16x32_bf16 v[102:105], v[164:167], v[188:191], 0
	v_mfma_f32_16x16x32_bf16 v[102:105], v[168:171], v[192:195], v[102:105]
	v_mfma_f32_16x16x32_bf16 v[86:89], v[164:167], v[196:199], 0
	v_mfma_f32_16x16x32_bf16 v[86:89], v[168:171], v[200:203], v[86:89]
	v_mfma_f32_16x16x32_bf16 v[82:85], v[172:175], v[196:199], 0
	v_mfma_f32_16x16x32_bf16 v[82:85], v[176:179], v[200:203], v[82:85]
	v_mfma_f32_16x16x32_bf16 v[66:69], v[172:175], v[204:207], 0
	v_mfma_f32_16x16x32_bf16 v[66:69], v[176:179], v[208:211], v[66:69]
	s_setprio 2
	s_barrier
	v_mfma_f32_16x16x32_bf16 v[70:73], v[164:167], v[204:207], 0
	v_mfma_f32_16x16x32_bf16 v[70:73], v[168:171], v[208:211], v[70:73]
	s_setprio 0
	s_setprio 3
	ds_read_b128 v[180:183], v145 offset:16384
	ds_read_b128 v[184:187], v145 offset:17408
	ds_read_b128 v[188:191], v145 offset:18432
	ds_read_b128 v[192:195], v145 offset:19456
	ds_read_b128 v[196:199], v145 offset:20480
	ds_read_b128 v[200:203], v145 offset:21504
	ds_read_b128 v[204:207], v145 offset:22528
	ds_read_b128 v[208:211], v145 offset:23552
	s_mov_b32 s74, m0
	s_mov_b32 m0, s35
	s_nop 0
	global_load_lds_dwordx4 v139, s[20:21]
	s_mov_b32 m0, s74
	s_nop 0
	s_mov_b32 s74, m0
	s_mov_b32 m0, s36
	s_nop 0
	global_load_lds_dwordx4 v141, s[20:21]
	s_mov_b32 m0, s74
	s_add_u32 s74, s20, 0x80000
	s_addc_u32 s75, s21, 0
	s_mov_b32 s76, m0
	s_mov_b32 m0, s37
	s_nop 0
	global_load_lds_dwordx4 v139, s[74:75]
	s_mov_b32 m0, s76
	s_nop 0
	s_mov_b32 s76, m0
	s_mov_b32 m0, s40
	s_nop 0
	global_load_lds_dwordx4 v141, s[74:75]
	s_mov_b32 m0, s76
	s_setprio 0
	s_waitcnt vmcnt(4)
	s_waitcnt lgkmcnt(0)
	s_barrier
	s_setprio 1
	s_waitcnt lgkmcnt(7)
	v_mfma_f32_16x16x32_bf16 v[62:65], v[148:151], v[180:183], 0
	v_mfma_f32_16x16x32_bf16 v[62:65], v[152:155], v[184:187], v[62:65]
	s_waitcnt lgkmcnt(5)
	v_mfma_f32_16x16x32_bf16 v[58:61], v[156:159], v[180:183], 0
	v_mfma_f32_16x16x32_bf16 v[58:61], v[160:163], v[184:187], v[58:61]
	s_waitcnt lgkmcnt(3)
	v_mfma_f32_16x16x32_bf16 v[42:45], v[156:159], v[188:191], 0
	v_mfma_f32_16x16x32_bf16 v[42:45], v[160:163], v[192:195], v[42:45]
	s_waitcnt lgkmcnt(1)
	v_mfma_f32_16x16x32_bf16 v[46:49], v[148:151], v[188:191], 0
	v_mfma_f32_16x16x32_bf16 v[46:49], v[152:155], v[192:195], v[46:49]
	v_mfma_f32_16x16x32_bf16 v[30:33], v[148:151], v[196:199], 0
	v_mfma_f32_16x16x32_bf16 v[30:33], v[152:155], v[200:203], v[30:33]
	v_mfma_f32_16x16x32_bf16 v[26:29], v[156:159], v[196:199], 0
	v_mfma_f32_16x16x32_bf16 v[26:29], v[160:163], v[200:203], v[26:29]
	v_mfma_f32_16x16x32_bf16 v[10:13], v[156:159], v[204:207], 0
	v_mfma_f32_16x16x32_bf16 v[10:13], v[160:163], v[208:211], v[10:13]
	s_waitcnt lgkmcnt(0)
	v_mfma_f32_16x16x32_bf16 v[14:17], v[148:151], v[204:207], 0
	v_mfma_f32_16x16x32_bf16 v[14:17], v[152:155], v[208:211], v[14:17]
	s_setprio 0
	s_setprio 1
	v_mfma_f32_16x16x32_bf16 v[54:57], v[164:167], v[180:183], 0
	v_mfma_f32_16x16x32_bf16 v[54:57], v[168:171], v[184:187], v[54:57]
	v_mfma_f32_16x16x32_bf16 v[50:53], v[172:175], v[180:183], 0
	v_mfma_f32_16x16x32_bf16 v[50:53], v[176:179], v[184:187], v[50:53]
	v_mfma_f32_16x16x32_bf16 v[34:37], v[172:175], v[188:191], 0
	v_mfma_f32_16x16x32_bf16 v[34:37], v[176:179], v[192:195], v[34:37]
	v_mfma_f32_16x16x32_bf16 v[38:41], v[164:167], v[188:191], 0
	v_mfma_f32_16x16x32_bf16 v[38:41], v[168:171], v[192:195], v[38:41]
	v_mfma_f32_16x16x32_bf16 v[22:25], v[164:167], v[196:199], 0
	v_mfma_f32_16x16x32_bf16 v[22:25], v[168:171], v[200:203], v[22:25]
	v_mfma_f32_16x16x32_bf16 v[18:21], v[172:175], v[196:199], 0
	v_mfma_f32_16x16x32_bf16 v[18:21], v[176:179], v[200:203], v[18:21]
	v_mfma_f32_16x16x32_bf16 v[2:5], v[172:175], v[204:207], 0
	v_mfma_f32_16x16x32_bf16 v[2:5], v[176:179], v[208:211], v[2:5]
	s_setprio 2
	s_barrier
	v_mfma_f32_16x16x32_bf16 v[6:9], v[164:167], v[204:207], 0
	v_mfma_f32_16x16x32_bf16 v[6:9], v[168:171], v[208:211], v[6:9]
	s_setprio 0
	s_setprio 3
	ds_read_b128 v[148:151], v146
	ds_read_b128 v[152:155], v146 offset:1024
	ds_read_b128 v[156:159], v146 offset:2048
	ds_read_b128 v[160:163], v146 offset:3072
	ds_read_b128 v[164:167], v147
	ds_read_b128 v[168:171], v147 offset:1024
	ds_read_b128 v[172:175], v147 offset:2048
	ds_read_b128 v[176:179], v147 offset:3072
	ds_read_b128 v[180:183], v145 offset:32768
	ds_read_b128 v[184:187], v145 offset:33792
	ds_read_b128 v[188:191], v145 offset:34816
	ds_read_b128 v[192:195], v145 offset:35840
	ds_read_b128 v[196:199], v145 offset:36864
	ds_read_b128 v[200:203], v145 offset:37888
	ds_read_b128 v[204:207], v145 offset:38912
	ds_read_b128 v[208:211], v145 offset:39936
	s_mov_b32 s74, m0
	s_mov_b32 m0, s31
	s_nop 0
	global_load_lds_dwordx4 v138, s[22:23]
	s_mov_b32 m0, s74
	s_nop 0
	s_mov_b32 s74, m0
	s_mov_b32 m0, s41
	s_nop 0
	global_load_lds_dwordx4 v140, s[22:23]
	s_mov_b32 m0, s74
	s_add_u32 s22, s22, 0x80000
	s_addc_u32 s23, s23, 0
	s_mov_b32 s74, m0
	s_mov_b32 m0, s42
	s_nop 0
	global_load_lds_dwordx4 v138, s[22:23]
	s_mov_b32 m0, s74
	s_nop 0
	s_mov_b32 s74, m0
	s_mov_b32 m0, s43
	s_nop 0
	global_load_lds_dwordx4 v140, s[22:23]
	s_mov_b32 m0, s74
	s_setprio 0
	s_waitcnt vmcnt(8)
	s_waitcnt lgkmcnt(0)
	s_barrier
	s_setprio 1
	s_waitcnt lgkmcnt(7)
	v_mfma_f32_16x16x32_bf16 v[126:129], v[148:151], v[180:183], v[126:129]
	v_mfma_f32_16x16x32_bf16 v[126:129], v[152:155], v[184:187], v[126:129]
	s_waitcnt lgkmcnt(5)
	v_mfma_f32_16x16x32_bf16 v[122:125], v[156:159], v[180:183], v[122:125]
	v_mfma_f32_16x16x32_bf16 v[122:125], v[160:163], v[184:187], v[122:125]
	s_waitcnt lgkmcnt(3)
	v_mfma_f32_16x16x32_bf16 v[106:109], v[156:159], v[188:191], v[106:109]
	v_mfma_f32_16x16x32_bf16 v[106:109], v[160:163], v[192:195], v[106:109]
	s_waitcnt lgkmcnt(1)
	v_mfma_f32_16x16x32_bf16 v[110:113], v[148:151], v[188:191], v[110:113]
	v_mfma_f32_16x16x32_bf16 v[110:113], v[152:155], v[192:195], v[110:113]
	v_mfma_f32_16x16x32_bf16 v[94:97], v[148:151], v[196:199], v[94:97]
	v_mfma_f32_16x16x32_bf16 v[94:97], v[152:155], v[200:203], v[94:97]
	v_mfma_f32_16x16x32_bf16 v[90:93], v[156:159], v[196:199], v[90:93]
	v_mfma_f32_16x16x32_bf16 v[90:93], v[160:163], v[200:203], v[90:93]
	v_mfma_f32_16x16x32_bf16 v[74:77], v[156:159], v[204:207], v[74:77]
	v_mfma_f32_16x16x32_bf16 v[74:77], v[160:163], v[208:211], v[74:77]
	s_waitcnt lgkmcnt(0)
	v_mfma_f32_16x16x32_bf16 v[78:81], v[148:151], v[204:207], v[78:81]
	v_mfma_f32_16x16x32_bf16 v[78:81], v[152:155], v[208:211], v[78:81]
	s_setprio 0
	s_setprio 1
	v_mfma_f32_16x16x32_bf16 v[118:121], v[164:167], v[180:183], v[118:121]
	v_mfma_f32_16x16x32_bf16 v[118:121], v[168:171], v[184:187], v[118:121]
	v_mfma_f32_16x16x32_bf16 v[114:117], v[172:175], v[180:183], v[114:117]
	v_mfma_f32_16x16x32_bf16 v[114:117], v[176:179], v[184:187], v[114:117]
	v_mfma_f32_16x16x32_bf16 v[98:101], v[172:175], v[188:191], v[98:101]
	v_mfma_f32_16x16x32_bf16 v[98:101], v[176:179], v[192:195], v[98:101]
	v_mfma_f32_16x16x32_bf16 v[102:105], v[164:167], v[188:191], v[102:105]
	v_mfma_f32_16x16x32_bf16 v[102:105], v[168:171], v[192:195], v[102:105]
	v_mfma_f32_16x16x32_bf16 v[86:89], v[164:167], v[196:199], v[86:89]
	v_mfma_f32_16x16x32_bf16 v[86:89], v[168:171], v[200:203], v[86:89]
	v_mfma_f32_16x16x32_bf16 v[82:85], v[172:175], v[196:199], v[82:85]
	v_mfma_f32_16x16x32_bf16 v[82:85], v[176:179], v[200:203], v[82:85]
	v_mfma_f32_16x16x32_bf16 v[66:69], v[172:175], v[204:207], v[66:69]
	v_mfma_f32_16x16x32_bf16 v[66:69], v[176:179], v[208:211], v[66:69]
	s_setprio 2
	s_barrier
	v_mfma_f32_16x16x32_bf16 v[70:73], v[164:167], v[204:207], v[70:73]
	v_mfma_f32_16x16x32_bf16 v[70:73], v[168:171], v[208:211], v[70:73]
	s_setprio 0
	s_setprio 3
	ds_read_b128 v[180:183], v145 offset:49152
	ds_read_b128 v[184:187], v145 offset:50176
	ds_read_b128 v[188:191], v145 offset:51200
	ds_read_b128 v[192:195], v145 offset:52224
	ds_read_b128 v[196:199], v145 offset:53248
	ds_read_b128 v[200:203], v145 offset:54272
	ds_read_b128 v[204:207], v145 offset:55296
	ds_read_b128 v[208:211], v145 offset:56320
	s_add_u32 s22, s20, 0x80
	s_addc_u32 s23, s21, 0
	s_mov_b32 s74, m0
	s_mov_b32 m0, s46
	s_nop 0
	global_load_lds_dwordx4 v139, s[22:23]
	s_mov_b32 m0, s74
	s_add_u32 s20, s20, 0x80080
	s_mov_b32 s74, m0
	s_mov_b32 m0, s47
	s_nop 0
	global_load_lds_dwordx4 v141, s[22:23]
	s_mov_b32 m0, s74
	s_addc_u32 s21, s21, 0
	s_mov_b32 s22, m0
	s_mov_b32 m0, s48
	s_nop 0
	global_load_lds_dwordx4 v139, s[20:21]
	s_mov_b32 m0, s22
	s_nop 0
	s_mov_b32 s22, m0
	s_mov_b32 m0, s49
	s_nop 0
	global_load_lds_dwordx4 v141, s[20:21]
	s_mov_b32 m0, s22
	s_setprio 0
	s_waitcnt vmcnt(4)
	s_waitcnt lgkmcnt(0)
	s_barrier
	s_setprio 1
	s_waitcnt lgkmcnt(7)
	v_mfma_f32_16x16x32_bf16 v[62:65], v[148:151], v[180:183], v[62:65]
	v_mfma_f32_16x16x32_bf16 v[62:65], v[152:155], v[184:187], v[62:65]
	s_waitcnt lgkmcnt(5)
	v_mfma_f32_16x16x32_bf16 v[58:61], v[156:159], v[180:183], v[58:61]
	v_mfma_f32_16x16x32_bf16 v[58:61], v[160:163], v[184:187], v[58:61]
	s_waitcnt lgkmcnt(3)
	v_mfma_f32_16x16x32_bf16 v[42:45], v[156:159], v[188:191], v[42:45]
	v_mfma_f32_16x16x32_bf16 v[42:45], v[160:163], v[192:195], v[42:45]
	s_waitcnt lgkmcnt(1)
	v_mfma_f32_16x16x32_bf16 v[46:49], v[148:151], v[188:191], v[46:49]
	v_mfma_f32_16x16x32_bf16 v[46:49], v[152:155], v[192:195], v[46:49]
	v_mfma_f32_16x16x32_bf16 v[30:33], v[148:151], v[196:199], v[30:33]
	v_mfma_f32_16x16x32_bf16 v[30:33], v[152:155], v[200:203], v[30:33]
	v_mfma_f32_16x16x32_bf16 v[26:29], v[156:159], v[196:199], v[26:29]
	v_mfma_f32_16x16x32_bf16 v[26:29], v[160:163], v[200:203], v[26:29]
	v_mfma_f32_16x16x32_bf16 v[10:13], v[156:159], v[204:207], v[10:13]
	v_mfma_f32_16x16x32_bf16 v[10:13], v[160:163], v[208:211], v[10:13]
	s_waitcnt lgkmcnt(0)
	v_mfma_f32_16x16x32_bf16 v[14:17], v[148:151], v[204:207], v[14:17]
	v_mfma_f32_16x16x32_bf16 v[14:17], v[152:155], v[208:211], v[14:17]
	s_setprio 0
	s_setprio 1
	v_mfma_f32_16x16x32_bf16 v[54:57], v[164:167], v[180:183], v[54:57]
	v_mfma_f32_16x16x32_bf16 v[54:57], v[168:171], v[184:187], v[54:57]
	v_mfma_f32_16x16x32_bf16 v[50:53], v[172:175], v[180:183], v[50:53]
	v_mfma_f32_16x16x32_bf16 v[50:53], v[176:179], v[184:187], v[50:53]
	v_mfma_f32_16x16x32_bf16 v[34:37], v[172:175], v[188:191], v[34:37]
	v_mfma_f32_16x16x32_bf16 v[34:37], v[176:179], v[192:195], v[34:37]
	v_mfma_f32_16x16x32_bf16 v[38:41], v[164:167], v[188:191], v[38:41]
	v_mfma_f32_16x16x32_bf16 v[38:41], v[168:171], v[192:195], v[38:41]
	v_mfma_f32_16x16x32_bf16 v[22:25], v[164:167], v[196:199], v[22:25]
	v_mfma_f32_16x16x32_bf16 v[22:25], v[168:171], v[200:203], v[22:25]
	v_mfma_f32_16x16x32_bf16 v[18:21], v[172:175], v[196:199], v[18:21]
	v_mfma_f32_16x16x32_bf16 v[18:21], v[176:179], v[200:203], v[18:21]
	v_mfma_f32_16x16x32_bf16 v[2:5], v[172:175], v[204:207], v[2:5]
	v_mfma_f32_16x16x32_bf16 v[2:5], v[176:179], v[208:211], v[2:5]
	s_setprio 2
	s_barrier
	v_mfma_f32_16x16x32_bf16 v[6:9], v[164:167], v[204:207], v[6:9]
	v_mfma_f32_16x16x32_bf16 v[6:9], v[168:171], v[208:211], v[6:9]
	s_setprio 0
	s_add_i32 s73, s73, 2
	s_add_u32 s66, s66, 0x100
	s_addc_u32 s67, s67, 0
	s_add_u32 s18, s18, 0x100
	s_addc_u32 s19, s19, 0
	s_add_u32 s70, s70, 0x100
	s_addc_u32 s71, s71, 0
	s_cmp_gt_u32 s73, 29
	.p2align 6
.LBB0_1785:
	s_setprio 3
	ds_read_b128 v[148:151], v143
	ds_read_b128 v[152:155], v143 offset:1024
	ds_read_b128 v[156:159], v143 offset:2048
	ds_read_b128 v[160:163], v143 offset:3072
	ds_read_b128 v[164:167], v144
	ds_read_b128 v[168:171], v144 offset:1024
	ds_read_b128 v[172:175], v144 offset:2048
	ds_read_b128 v[176:179], v144 offset:3072
	s_cmp_eq_u32 s73, 28
	s_cselect_b32 s21, s9, s67
	s_cselect_b32 s20, s65, s66
	s_cselect_b32 s23, s11, s71
	s_cselect_b32 s22, s64, s70
	ds_read_b128 v[180:183], v145
	ds_read_b128 v[184:187], v145 offset:1024
	ds_read_b128 v[188:191], v145 offset:2048
	ds_read_b128 v[192:195], v145 offset:3072
	ds_read_b128 v[196:199], v145 offset:4096
	ds_read_b128 v[200:203], v145 offset:5120
	ds_read_b128 v[204:207], v145 offset:6144
	ds_read_b128 v[208:211], v145 offset:7168
	s_add_u32 s74, s18, 0xfff80000
	s_addc_u32 s75, s19, -1
	s_mov_b32 s76, m0
	s_mov_b32 m0, s56
	s_nop 0
	global_load_lds_dwordx4 v138, s[74:75]
	s_mov_b32 m0, s76
	s_nop 0
	s_mov_b32 s76, m0
	s_mov_b32 m0, s59
	s_nop 0
	global_load_lds_dwordx4 v140, s[74:75]
	s_mov_b32 m0, s76
	s_mov_b32 s74, m0
	s_mov_b32 m0, s57
	s_nop 0
	global_load_lds_dwordx4 v138, s[18:19]
	s_mov_b32 m0, s74
	s_nop 0
	s_mov_b32 s74, m0
	s_mov_b32 m0, s62
	s_nop 0
	global_load_lds_dwordx4 v140, s[18:19]
	s_mov_b32 m0, s74
	s_setprio 0
	s_waitcnt vmcnt(8)
	s_waitcnt lgkmcnt(0)
	s_barrier
	s_setprio 1
	s_waitcnt lgkmcnt(7)
	v_mfma_f32_16x16x32_bf16 v[126:129], v[148:151], v[180:183], v[126:129]
	v_mfma_f32_16x16x32_bf16 v[126:129], v[152:155], v[184:187], v[126:129]
	s_waitcnt lgkmcnt(5)
	v_mfma_f32_16x16x32_bf16 v[122:125], v[156:159], v[180:183], v[122:125]
	v_mfma_f32_16x16x32_bf16 v[122:125], v[160:163], v[184:187], v[122:125]
	s_waitcnt lgkmcnt(3)
	v_mfma_f32_16x16x32_bf16 v[106:109], v[156:159], v[188:191], v[106:109]
	v_mfma_f32_16x16x32_bf16 v[106:109], v[160:163], v[192:195], v[106:109]
	s_waitcnt lgkmcnt(1)
	v_mfma_f32_16x16x32_bf16 v[110:113], v[148:151], v[188:191], v[110:113]
	v_mfma_f32_16x16x32_bf16 v[110:113], v[152:155], v[192:195], v[110:113]
	v_mfma_f32_16x16x32_bf16 v[94:97], v[148:151], v[196:199], v[94:97]
	v_mfma_f32_16x16x32_bf16 v[94:97], v[152:155], v[200:203], v[94:97]
	v_mfma_f32_16x16x32_bf16 v[90:93], v[156:159], v[196:199], v[90:93]
	v_mfma_f32_16x16x32_bf16 v[90:93], v[160:163], v[200:203], v[90:93]
	v_mfma_f32_16x16x32_bf16 v[74:77], v[156:159], v[204:207], v[74:77]
	v_mfma_f32_16x16x32_bf16 v[74:77], v[160:163], v[208:211], v[74:77]
	s_waitcnt lgkmcnt(0)
	v_mfma_f32_16x16x32_bf16 v[78:81], v[148:151], v[204:207], v[78:81]
	v_mfma_f32_16x16x32_bf16 v[78:81], v[152:155], v[208:211], v[78:81]
	s_setprio 0
	s_setprio 1
	v_mfma_f32_16x16x32_bf16 v[118:121], v[164:167], v[180:183], v[118:121]
	v_mfma_f32_16x16x32_bf16 v[118:121], v[168:171], v[184:187], v[118:121]
	v_mfma_f32_16x16x32_bf16 v[114:117], v[172:175], v[180:183], v[114:117]
	v_mfma_f32_16x16x32_bf16 v[114:117], v[176:179], v[184:187], v[114:117]
	v_mfma_f32_16x16x32_bf16 v[98:101], v[172:175], v[188:191], v[98:101]
	v_mfma_f32_16x16x32_bf16 v[98:101], v[176:179], v[192:195], v[98:101]
	v_mfma_f32_16x16x32_bf16 v[102:105], v[164:167], v[188:191], v[102:105]
	v_mfma_f32_16x16x32_bf16 v[102:105], v[168:171], v[192:195], v[102:105]
	v_mfma_f32_16x16x32_bf16 v[86:89], v[164:167], v[196:199], v[86:89]
	v_mfma_f32_16x16x32_bf16 v[86:89], v[168:171], v[200:203], v[86:89]
	v_mfma_f32_16x16x32_bf16 v[82:85], v[172:175], v[196:199], v[82:85]
	v_mfma_f32_16x16x32_bf16 v[82:85], v[176:179], v[200:203], v[82:85]
	v_mfma_f32_16x16x32_bf16 v[66:69], v[172:175], v[204:207], v[66:69]
	v_mfma_f32_16x16x32_bf16 v[66:69], v[176:179], v[208:211], v[66:69]
	s_setprio 2
	s_barrier
	v_mfma_f32_16x16x32_bf16 v[70:73], v[164:167], v[204:207], v[70:73]
	v_mfma_f32_16x16x32_bf16 v[70:73], v[168:171], v[208:211], v[70:73]
	s_setprio 0
	s_setprio 3
	ds_read_b128 v[180:183], v145 offset:16384
	ds_read_b128 v[184:187], v145 offset:17408
	ds_read_b128 v[188:191], v145 offset:18432
	ds_read_b128 v[192:195], v145 offset:19456
	ds_read_b128 v[196:199], v145 offset:20480
	ds_read_b128 v[200:203], v145 offset:21504
	ds_read_b128 v[204:207], v145 offset:22528
	ds_read_b128 v[208:211], v145 offset:23552
	s_mov_b32 s74, m0
	s_mov_b32 m0, s35
	s_nop 0
	global_load_lds_dwordx4 v139, s[20:21]
	s_mov_b32 m0, s74
	s_nop 0
	s_mov_b32 s74, m0
	s_mov_b32 m0, s36
	s_nop 0
	global_load_lds_dwordx4 v141, s[20:21]
	s_mov_b32 m0, s74
	s_add_u32 s74, s20, 0x80000
	s_addc_u32 s75, s21, 0
	s_mov_b32 s76, m0
	s_mov_b32 m0, s37
	s_nop 0
	global_load_lds_dwordx4 v139, s[74:75]
	s_mov_b32 m0, s76
	s_nop 0
	s_mov_b32 s76, m0
	s_mov_b32 m0, s40
	s_nop 0
	global_load_lds_dwordx4 v141, s[74:75]
	s_mov_b32 m0, s76
	s_setprio 0
	s_waitcnt vmcnt(4)
	s_waitcnt lgkmcnt(0)
	s_barrier
	s_setprio 1
	s_waitcnt lgkmcnt(7)
	v_mfma_f32_16x16x32_bf16 v[62:65], v[148:151], v[180:183], v[62:65]
	v_mfma_f32_16x16x32_bf16 v[62:65], v[152:155], v[184:187], v[62:65]
	s_waitcnt lgkmcnt(5)
	v_mfma_f32_16x16x32_bf16 v[58:61], v[156:159], v[180:183], v[58:61]
	v_mfma_f32_16x16x32_bf16 v[58:61], v[160:163], v[184:187], v[58:61]
	s_waitcnt lgkmcnt(3)
	v_mfma_f32_16x16x32_bf16 v[42:45], v[156:159], v[188:191], v[42:45]
	v_mfma_f32_16x16x32_bf16 v[42:45], v[160:163], v[192:195], v[42:45]
	s_waitcnt lgkmcnt(1)
	v_mfma_f32_16x16x32_bf16 v[46:49], v[148:151], v[188:191], v[46:49]
	v_mfma_f32_16x16x32_bf16 v[46:49], v[152:155], v[192:195], v[46:49]
	v_mfma_f32_16x16x32_bf16 v[30:33], v[148:151], v[196:199], v[30:33]
	v_mfma_f32_16x16x32_bf16 v[30:33], v[152:155], v[200:203], v[30:33]
	v_mfma_f32_16x16x32_bf16 v[26:29], v[156:159], v[196:199], v[26:29]
	v_mfma_f32_16x16x32_bf16 v[26:29], v[160:163], v[200:203], v[26:29]
	v_mfma_f32_16x16x32_bf16 v[10:13], v[156:159], v[204:207], v[10:13]
	v_mfma_f32_16x16x32_bf16 v[10:13], v[160:163], v[208:211], v[10:13]
	s_waitcnt lgkmcnt(0)
	v_mfma_f32_16x16x32_bf16 v[14:17], v[148:151], v[204:207], v[14:17]
	v_mfma_f32_16x16x32_bf16 v[14:17], v[152:155], v[208:211], v[14:17]
	s_setprio 0
	s_setprio 1
	v_mfma_f32_16x16x32_bf16 v[54:57], v[164:167], v[180:183], v[54:57]
	v_mfma_f32_16x16x32_bf16 v[54:57], v[168:171], v[184:187], v[54:57]
	v_mfma_f32_16x16x32_bf16 v[50:53], v[172:175], v[180:183], v[50:53]
	v_mfma_f32_16x16x32_bf16 v[50:53], v[176:179], v[184:187], v[50:53]
	v_mfma_f32_16x16x32_bf16 v[34:37], v[172:175], v[188:191], v[34:37]
	v_mfma_f32_16x16x32_bf16 v[34:37], v[176:179], v[192:195], v[34:37]
	v_mfma_f32_16x16x32_bf16 v[38:41], v[164:167], v[188:191], v[38:41]
	v_mfma_f32_16x16x32_bf16 v[38:41], v[168:171], v[192:195], v[38:41]
	v_mfma_f32_16x16x32_bf16 v[22:25], v[164:167], v[196:199], v[22:25]
	v_mfma_f32_16x16x32_bf16 v[22:25], v[168:171], v[200:203], v[22:25]
	v_mfma_f32_16x16x32_bf16 v[18:21], v[172:175], v[196:199], v[18:21]
	v_mfma_f32_16x16x32_bf16 v[18:21], v[176:179], v[200:203], v[18:21]
	v_mfma_f32_16x16x32_bf16 v[2:5], v[172:175], v[204:207], v[2:5]
	v_mfma_f32_16x16x32_bf16 v[2:5], v[176:179], v[208:211], v[2:5]
	s_setprio 2
	s_barrier
	v_mfma_f32_16x16x32_bf16 v[6:9], v[164:167], v[204:207], v[6:9]
	v_mfma_f32_16x16x32_bf16 v[6:9], v[168:171], v[208:211], v[6:9]
	s_setprio 0
	s_setprio 3
	ds_read_b128 v[148:151], v146
	ds_read_b128 v[152:155], v146 offset:1024
	ds_read_b128 v[156:159], v146 offset:2048
	ds_read_b128 v[160:163], v146 offset:3072
	ds_read_b128 v[164:167], v147
	ds_read_b128 v[168:171], v147 offset:1024
	ds_read_b128 v[172:175], v147 offset:2048
	ds_read_b128 v[176:179], v147 offset:3072
	ds_read_b128 v[180:183], v145 offset:32768
	ds_read_b128 v[184:187], v145 offset:33792
	ds_read_b128 v[188:191], v145 offset:34816
	ds_read_b128 v[192:195], v145 offset:35840
	ds_read_b128 v[196:199], v145 offset:36864
	ds_read_b128 v[200:203], v145 offset:37888
	ds_read_b128 v[204:207], v145 offset:38912
	ds_read_b128 v[208:211], v145 offset:39936
	s_mov_b32 s74, m0
	s_mov_b32 m0, s31
	s_nop 0
	global_load_lds_dwordx4 v138, s[22:23]
	s_mov_b32 m0, s74
	s_nop 0
	s_mov_b32 s74, m0
	s_mov_b32 m0, s41
	s_nop 0
	global_load_lds_dwordx4 v140, s[22:23]
	s_mov_b32 m0, s74
	s_add_u32 s22, s22, 0x80000
	s_addc_u32 s23, s23, 0
	s_mov_b32 s74, m0
	s_mov_b32 m0, s42
	s_nop 0
	global_load_lds_dwordx4 v138, s[22:23]
	s_mov_b32 m0, s74
	s_nop 0
	s_mov_b32 s74, m0
	s_mov_b32 m0, s43
	s_nop 0
	global_load_lds_dwordx4 v140, s[22:23]
	s_mov_b32 m0, s74
	s_setprio 0
	s_waitcnt vmcnt(8)
	s_waitcnt lgkmcnt(0)
	s_barrier
	s_setprio 1
	s_waitcnt lgkmcnt(7)
	v_mfma_f32_16x16x32_bf16 v[126:129], v[148:151], v[180:183], v[126:129]
	v_mfma_f32_16x16x32_bf16 v[126:129], v[152:155], v[184:187], v[126:129]
	s_waitcnt lgkmcnt(5)
	v_mfma_f32_16x16x32_bf16 v[122:125], v[156:159], v[180:183], v[122:125]
	v_mfma_f32_16x16x32_bf16 v[122:125], v[160:163], v[184:187], v[122:125]
	s_waitcnt lgkmcnt(3)
	v_mfma_f32_16x16x32_bf16 v[106:109], v[156:159], v[188:191], v[106:109]
	v_mfma_f32_16x16x32_bf16 v[106:109], v[160:163], v[192:195], v[106:109]
	s_waitcnt lgkmcnt(1)
	v_mfma_f32_16x16x32_bf16 v[110:113], v[148:151], v[188:191], v[110:113]
	v_mfma_f32_16x16x32_bf16 v[110:113], v[152:155], v[192:195], v[110:113]
	v_mfma_f32_16x16x32_bf16 v[94:97], v[148:151], v[196:199], v[94:97]
	v_mfma_f32_16x16x32_bf16 v[94:97], v[152:155], v[200:203], v[94:97]
	v_mfma_f32_16x16x32_bf16 v[90:93], v[156:159], v[196:199], v[90:93]
	v_mfma_f32_16x16x32_bf16 v[90:93], v[160:163], v[200:203], v[90:93]
	v_mfma_f32_16x16x32_bf16 v[74:77], v[156:159], v[204:207], v[74:77]
	v_mfma_f32_16x16x32_bf16 v[74:77], v[160:163], v[208:211], v[74:77]
	s_waitcnt lgkmcnt(0)
	v_mfma_f32_16x16x32_bf16 v[78:81], v[148:151], v[204:207], v[78:81]
	v_mfma_f32_16x16x32_bf16 v[78:81], v[152:155], v[208:211], v[78:81]
	s_setprio 0
	s_setprio 1
	v_mfma_f32_16x16x32_bf16 v[118:121], v[164:167], v[180:183], v[118:121]
	v_mfma_f32_16x16x32_bf16 v[118:121], v[168:171], v[184:187], v[118:121]
	v_mfma_f32_16x16x32_bf16 v[114:117], v[172:175], v[180:183], v[114:117]
	v_mfma_f32_16x16x32_bf16 v[114:117], v[176:179], v[184:187], v[114:117]
	v_mfma_f32_16x16x32_bf16 v[98:101], v[172:175], v[188:191], v[98:101]
	v_mfma_f32_16x16x32_bf16 v[98:101], v[176:179], v[192:195], v[98:101]
	v_mfma_f32_16x16x32_bf16 v[102:105], v[164:167], v[188:191], v[102:105]
	v_mfma_f32_16x16x32_bf16 v[102:105], v[168:171], v[192:195], v[102:105]
	v_mfma_f32_16x16x32_bf16 v[86:89], v[164:167], v[196:199], v[86:89]
	v_mfma_f32_16x16x32_bf16 v[86:89], v[168:171], v[200:203], v[86:89]
	v_mfma_f32_16x16x32_bf16 v[82:85], v[172:175], v[196:199], v[82:85]
	v_mfma_f32_16x16x32_bf16 v[82:85], v[176:179], v[200:203], v[82:85]
	v_mfma_f32_16x16x32_bf16 v[66:69], v[172:175], v[204:207], v[66:69]
	v_mfma_f32_16x16x32_bf16 v[66:69], v[176:179], v[208:211], v[66:69]
	s_setprio 2
	s_barrier
	v_mfma_f32_16x16x32_bf16 v[70:73], v[164:167], v[204:207], v[70:73]
	v_mfma_f32_16x16x32_bf16 v[70:73], v[168:171], v[208:211], v[70:73]
	s_setprio 0
	s_setprio 3
	ds_read_b128 v[180:183], v145 offset:49152
	ds_read_b128 v[184:187], v145 offset:50176
	ds_read_b128 v[188:191], v145 offset:51200
	ds_read_b128 v[192:195], v145 offset:52224
	ds_read_b128 v[196:199], v145 offset:53248
	ds_read_b128 v[200:203], v145 offset:54272
	ds_read_b128 v[204:207], v145 offset:55296
	ds_read_b128 v[208:211], v145 offset:56320
	s_add_u32 s22, s20, 0x80
	s_addc_u32 s23, s21, 0
	s_mov_b32 s74, m0
	s_mov_b32 m0, s46
	s_nop 0
	global_load_lds_dwordx4 v139, s[22:23]
	s_mov_b32 m0, s74
	s_add_u32 s20, s20, 0x80080
	s_mov_b32 s74, m0
	s_mov_b32 m0, s47
	s_nop 0
	global_load_lds_dwordx4 v141, s[22:23]
	s_mov_b32 m0, s74
	s_addc_u32 s21, s21, 0
	s_mov_b32 s22, m0
	s_mov_b32 m0, s48
	s_nop 0
	global_load_lds_dwordx4 v139, s[20:21]
	s_mov_b32 m0, s22
	s_nop 0
	s_mov_b32 s22, m0
	s_mov_b32 m0, s49
	s_nop 0
	global_load_lds_dwordx4 v141, s[20:21]
	s_mov_b32 m0, s22
	s_setprio 0
	s_waitcnt vmcnt(4)
	s_waitcnt lgkmcnt(0)
	s_barrier
	s_setprio 1
	s_waitcnt lgkmcnt(7)
	v_mfma_f32_16x16x32_bf16 v[62:65], v[148:151], v[180:183], v[62:65]
	v_mfma_f32_16x16x32_bf16 v[62:65], v[152:155], v[184:187], v[62:65]
	s_waitcnt lgkmcnt(5)
	v_mfma_f32_16x16x32_bf16 v[58:61], v[156:159], v[180:183], v[58:61]
	v_mfma_f32_16x16x32_bf16 v[58:61], v[160:163], v[184:187], v[58:61]
	s_waitcnt lgkmcnt(3)
	v_mfma_f32_16x16x32_bf16 v[42:45], v[156:159], v[188:191], v[42:45]
	v_mfma_f32_16x16x32_bf16 v[42:45], v[160:163], v[192:195], v[42:45]
	s_waitcnt lgkmcnt(1)
	v_mfma_f32_16x16x32_bf16 v[46:49], v[148:151], v[188:191], v[46:49]
	v_mfma_f32_16x16x32_bf16 v[46:49], v[152:155], v[192:195], v[46:49]
	v_mfma_f32_16x16x32_bf16 v[30:33], v[148:151], v[196:199], v[30:33]
	v_mfma_f32_16x16x32_bf16 v[30:33], v[152:155], v[200:203], v[30:33]
	v_mfma_f32_16x16x32_bf16 v[26:29], v[156:159], v[196:199], v[26:29]
	v_mfma_f32_16x16x32_bf16 v[26:29], v[160:163], v[200:203], v[26:29]
	v_mfma_f32_16x16x32_bf16 v[10:13], v[156:159], v[204:207], v[10:13]
	v_mfma_f32_16x16x32_bf16 v[10:13], v[160:163], v[208:211], v[10:13]
	s_waitcnt lgkmcnt(0)
	v_mfma_f32_16x16x32_bf16 v[14:17], v[148:151], v[204:207], v[14:17]
	v_mfma_f32_16x16x32_bf16 v[14:17], v[152:155], v[208:211], v[14:17]
	s_setprio 0
	s_setprio 1
	v_mfma_f32_16x16x32_bf16 v[54:57], v[164:167], v[180:183], v[54:57]
	v_mfma_f32_16x16x32_bf16 v[54:57], v[168:171], v[184:187], v[54:57]
	v_mfma_f32_16x16x32_bf16 v[50:53], v[172:175], v[180:183], v[50:53]
	v_mfma_f32_16x16x32_bf16 v[50:53], v[176:179], v[184:187], v[50:53]
	v_mfma_f32_16x16x32_bf16 v[34:37], v[172:175], v[188:191], v[34:37]
	v_mfma_f32_16x16x32_bf16 v[34:37], v[176:179], v[192:195], v[34:37]
	v_mfma_f32_16x16x32_bf16 v[38:41], v[164:167], v[188:191], v[38:41]
	v_mfma_f32_16x16x32_bf16 v[38:41], v[168:171], v[192:195], v[38:41]
	v_mfma_f32_16x16x32_bf16 v[22:25], v[164:167], v[196:199], v[22:25]
	v_mfma_f32_16x16x32_bf16 v[22:25], v[168:171], v[200:203], v[22:25]
	v_mfma_f32_16x16x32_bf16 v[18:21], v[172:175], v[196:199], v[18:21]
	v_mfma_f32_16x16x32_bf16 v[18:21], v[176:179], v[200:203], v[18:21]
	v_mfma_f32_16x16x32_bf16 v[2:5], v[172:175], v[204:207], v[2:5]
	v_mfma_f32_16x16x32_bf16 v[2:5], v[176:179], v[208:211], v[2:5]
	s_setprio 2
	s_barrier
	v_mfma_f32_16x16x32_bf16 v[6:9], v[164:167], v[204:207], v[6:9]
	v_mfma_f32_16x16x32_bf16 v[6:9], v[168:171], v[208:211], v[6:9]
	s_setprio 0
	s_add_i32 s73, s73, 2
	s_add_u32 s66, s66, 0x100
	s_addc_u32 s67, s67, 0
	s_add_u32 s18, s18, 0x100
	s_addc_u32 s19, s19, 0
	s_add_u32 s70, s70, 0x100
	s_addc_u32 s71, s71, 0
	s_cmp_gt_u32 s73, 29
	s_cbranch_scc0 .LBB0_1785
	s_and_b64 vcc, exec, s[6:7]
	s_cbranch_vccz .LBB0_1788
	s_barrier

.LBB0_1951:
	s_ashr_i32 s13, s12, 31
	s_lshl_b64 s[14:15], s[12:13], 15
	s_add_u32 s14, s28, s14
	s_addc_u32 s15, s29, s15
	s_and_b64 s[16:17], s[2:3], exec
	s_cselect_b32 s13, s15, s23
	s_cselect_b32 s65, s14, s22
	s_ashr_i32 s11, s10, 31
	s_lshl_b64 s[16:17], s[10:11], 15
	s_add_u32 s16, s30, s16
	s_addc_u32 s17, s31, s17
	s_and_b64 s[24:25], s[2:3], exec
	s_cselect_b32 s11, s17, s21
	s_cselect_b32 s66, s16, s20
	s_add_u32 s67, s20, 0x80000
	s_addc_u32 s70, s21, 0
	s_add_u32 s20, s22, 0x204000
	s_addc_u32 s21, s23, 0
	s_add_u32 s71, s22, 0x400000
	s_addc_u32 s73, s23, 0
	s_mov_b32 s74, -2
	s_waitcnt vmcnt(25)
	s_waitcnt vmcnt(24)
	s_waitcnt vmcnt(4)
	s_waitcnt vmcnt(2)
	s_waitcnt vmcnt(1)
	s_waitcnt vmcnt(0)
	s_setprio 3
	ds_read_b128 v[130:133], v181
	ds_read_b128 v[134:137], v181 offset:1024
	ds_read_b128 v[138:141], v181 offset:2048
	ds_read_b128 v[142:145], v181 offset:3072
	ds_read_b128 v[150:153], v182
	ds_read_b128 v[154:157], v182 offset:1024
	ds_read_b128 v[158:161], v182 offset:2048
	ds_read_b128 v[162:165], v182 offset:3072
	s_cmpk_eq_i32 s74, 0x52
	s_cselect_b32 s23, s11, s70
	s_cselect_b32 s22, s66, s67
	s_cselect_b32 s25, s13, s73
	s_cselect_b32 s24, s65, s71
	ds_read_b128 v[166:169], v183
	ds_read_b128 v[170:173], v183 offset:1024
	ds_read_b128 v[186:189], v183 offset:2048
	ds_read_b128 v[190:193], v183 offset:3072
	ds_read_b128 v[194:197], v183 offset:4096
	ds_read_b128 v[198:201], v183 offset:5120
	ds_read_b128 v[202:205], v183 offset:6144
	ds_read_b128 v[206:209], v183 offset:7168
	s_add_u32 s76, s20, 0xffffc000
	s_addc_u32 s77, s21, -1
	s_mov_b32 s75, m0
	s_mov_b32 m0, s58
	s_nop 0
	global_load_lds_dwordx4 v1, s[76:77]
	s_mov_b32 m0, s75
	s_nop 0
	s_mov_b32 s75, m0
	s_mov_b32 m0, s62
	s_nop 0
	global_load_lds_dwordx4 v177, s[76:77]
	s_mov_b32 m0, s75
	s_nop 0
	s_mov_b32 s75, m0
	s_mov_b32 m0, s59
	s_nop 0
	global_load_lds_dwordx4 v1, s[20:21]
	s_mov_b32 m0, s75
	s_nop 0
	s_mov_b32 s75, m0
	s_mov_b32 m0, s63
	s_nop 0
	global_load_lds_dwordx4 v177, s[20:21]
	s_mov_b32 m0, s75
	s_setprio 0
	s_waitcnt vmcnt(8)
	s_waitcnt lgkmcnt(0)
	s_barrier
	s_setprio 1
	s_waitcnt lgkmcnt(7)
	v_mfma_f32_16x16x32_bf16 v[126:129], v[130:133], v[166:169], 0
	v_mfma_f32_16x16x32_bf16 v[126:129], v[134:137], v[170:173], v[126:129]
	s_waitcnt lgkmcnt(5)
	v_mfma_f32_16x16x32_bf16 v[122:125], v[138:141], v[166:169], 0
	v_mfma_f32_16x16x32_bf16 v[122:125], v[142:145], v[170:173], v[122:125]
	s_waitcnt lgkmcnt(3)
	v_mfma_f32_16x16x32_bf16 v[110:113], v[138:141], v[186:189], 0
	v_mfma_f32_16x16x32_bf16 v[110:113], v[142:145], v[190:193], v[110:113]
	s_waitcnt lgkmcnt(1)
	v_mfma_f32_16x16x32_bf16 v[118:121], v[130:133], v[186:189], 0
	v_mfma_f32_16x16x32_bf16 v[118:121], v[134:137], v[190:193], v[118:121]
	v_mfma_f32_16x16x32_bf16 v[94:97], v[130:133], v[194:197], 0
	v_mfma_f32_16x16x32_bf16 v[94:97], v[134:137], v[198:201], v[94:97]
	v_mfma_f32_16x16x32_bf16 v[90:93], v[138:141], v[194:197], 0
	v_mfma_f32_16x16x32_bf16 v[90:93], v[142:145], v[198:201], v[90:93]
	v_mfma_f32_16x16x32_bf16 v[78:81], v[138:141], v[202:205], 0
	v_mfma_f32_16x16x32_bf16 v[78:81], v[142:145], v[206:209], v[78:81]
	s_waitcnt lgkmcnt(0)
	v_mfma_f32_16x16x32_bf16 v[86:89], v[130:133], v[202:205], 0
	v_mfma_f32_16x16x32_bf16 v[86:89], v[134:137], v[206:209], v[86:89]
	s_setprio 0
	s_setprio 1
	v_mfma_f32_16x16x32_bf16 v[114:117], v[150:153], v[166:169], 0
	v_mfma_f32_16x16x32_bf16 v[114:117], v[154:157], v[170:173], v[114:117]
	v_mfma_f32_16x16x32_bf16 v[106:109], v[158:161], v[166:169], 0
	v_mfma_f32_16x16x32_bf16 v[106:109], v[162:165], v[170:173], v[106:109]
	v_mfma_f32_16x16x32_bf16 v[98:101], v[158:161], v[186:189], 0
	v_mfma_f32_16x16x32_bf16 v[98:101], v[162:165], v[190:193], v[98:101]
	v_mfma_f32_16x16x32_bf16 v[102:105], v[150:153], v[186:189], 0
	v_mfma_f32_16x16x32_bf16 v[102:105], v[154:157], v[190:193], v[102:105]
	v_mfma_f32_16x16x32_bf16 v[82:85], v[150:153], v[194:197], 0
	v_mfma_f32_16x16x32_bf16 v[82:85], v[154:157], v[198:201], v[82:85]
	v_mfma_f32_16x16x32_bf16 v[74:77], v[158:161], v[194:197], 0
	v_mfma_f32_16x16x32_bf16 v[74:77], v[162:165], v[198:201], v[74:77]
	v_mfma_f32_16x16x32_bf16 v[66:69], v[158:161], v[202:205], 0
	v_mfma_f32_16x16x32_bf16 v[66:69], v[162:165], v[206:209], v[66:69]
	s_setprio 2
	s_barrier
	v_mfma_f32_16x16x32_bf16 v[70:73], v[150:153], v[202:205], 0
	v_mfma_f32_16x16x32_bf16 v[70:73], v[154:157], v[206:209], v[70:73]
	s_setprio 0
	s_setprio 3
	ds_read_b128 v[166:169], v183 offset:16384
	ds_read_b128 v[170:173], v183 offset:17408
	ds_read_b128 v[186:189], v183 offset:18432
	ds_read_b128 v[190:193], v183 offset:19456
	ds_read_b128 v[194:197], v183 offset:20480
	ds_read_b128 v[198:201], v183 offset:21504
	ds_read_b128 v[202:205], v183 offset:22528
	ds_read_b128 v[206:209], v183 offset:23552
	s_mov_b32 s75, m0
	s_mov_b32 m0, s35
	s_nop 0
	global_load_lds_dwordx4 v176, s[22:23]
	s_mov_b32 m0, s75
	s_add_u32 s76, s22, 0x4000
	s_mov_b32 s75, m0
	s_mov_b32 m0, s36
	s_nop 0
	global_load_lds_dwordx4 v178, s[22:23]
	s_mov_b32 m0, s75
	s_addc_u32 s77, s23, 0
	s_mov_b32 s75, m0
	s_mov_b32 m0, s37
	s_nop 0
	global_load_lds_dwordx4 v176, s[76:77]
	s_mov_b32 m0, s75
	s_nop 0
	s_mov_b32 s75, m0
	s_mov_b32 m0, s40
	s_nop 0
	global_load_lds_dwordx4 v178, s[76:77]
	s_mov_b32 m0, s75
	s_setprio 0
	s_waitcnt vmcnt(4)
	s_waitcnt lgkmcnt(0)
	s_barrier
	s_setprio 1
	s_waitcnt lgkmcnt(7)
	v_mfma_f32_16x16x32_bf16 v[62:65], v[130:133], v[166:169], 0
	v_mfma_f32_16x16x32_bf16 v[62:65], v[134:137], v[170:173], v[62:65]
	s_waitcnt lgkmcnt(5)
	v_mfma_f32_16x16x32_bf16 v[58:61], v[138:141], v[166:169], 0
	v_mfma_f32_16x16x32_bf16 v[58:61], v[142:145], v[170:173], v[58:61]
	s_waitcnt lgkmcnt(3)
	v_mfma_f32_16x16x32_bf16 v[42:45], v[138:141], v[186:189], 0
	v_mfma_f32_16x16x32_bf16 v[42:45], v[142:145], v[190:193], v[42:45]
	s_waitcnt lgkmcnt(1)
	v_mfma_f32_16x16x32_bf16 v[46:49], v[130:133], v[186:189], 0
	v_mfma_f32_16x16x32_bf16 v[46:49], v[134:137], v[190:193], v[46:49]
	v_mfma_f32_16x16x32_bf16 v[30:33], v[130:133], v[194:197], 0
	v_mfma_f32_16x16x32_bf16 v[30:33], v[134:137], v[198:201], v[30:33]
	v_mfma_f32_16x16x32_bf16 v[26:29], v[138:141], v[194:197], 0
	v_mfma_f32_16x16x32_bf16 v[26:29], v[142:145], v[198:201], v[26:29]
	v_mfma_f32_16x16x32_bf16 v[10:13], v[138:141], v[202:205], 0
	v_mfma_f32_16x16x32_bf16 v[10:13], v[142:145], v[206:209], v[10:13]
	s_waitcnt lgkmcnt(0)
	v_mfma_f32_16x16x32_bf16 v[14:17], v[130:133], v[202:205], 0
	v_mfma_f32_16x16x32_bf16 v[14:17], v[134:137], v[206:209], v[14:17]
	s_setprio 0
	s_setprio 1
	v_mfma_f32_16x16x32_bf16 v[54:57], v[150:153], v[166:169], 0
	v_mfma_f32_16x16x32_bf16 v[54:57], v[154:157], v[170:173], v[54:57]
	v_mfma_f32_16x16x32_bf16 v[50:53], v[158:161], v[166:169], 0
	v_mfma_f32_16x16x32_bf16 v[50:53], v[162:165], v[170:173], v[50:53]
	v_mfma_f32_16x16x32_bf16 v[34:37], v[158:161], v[186:189], 0
	v_mfma_f32_16x16x32_bf16 v[34:37], v[162:165], v[190:193], v[34:37]
	v_mfma_f32_16x16x32_bf16 v[38:41], v[150:153], v[186:189], 0
	v_mfma_f32_16x16x32_bf16 v[38:41], v[154:157], v[190:193], v[38:41]
	v_mfma_f32_16x16x32_bf16 v[22:25], v[150:153], v[194:197], 0
	v_mfma_f32_16x16x32_bf16 v[22:25], v[154:157], v[198:201], v[22:25]
	v_mfma_f32_16x16x32_bf16 v[18:21], v[158:161], v[194:197], 0
	v_mfma_f32_16x16x32_bf16 v[18:21], v[162:165], v[198:201], v[18:21]
	v_mfma_f32_16x16x32_bf16 v[2:5], v[158:161], v[202:205], 0
	v_mfma_f32_16x16x32_bf16 v[2:5], v[162:165], v[206:209], v[2:5]
	s_setprio 2
	s_barrier
	v_mfma_f32_16x16x32_bf16 v[6:9], v[150:153], v[202:205], 0
	v_mfma_f32_16x16x32_bf16 v[6:9], v[154:157], v[206:209], v[6:9]
	s_setprio 0
	s_setprio 3
	ds_read_b128 v[130:133], v184
	ds_read_b128 v[134:137], v184 offset:1024
	ds_read_b128 v[138:141], v184 offset:2048
	ds_read_b128 v[142:145], v184 offset:3072
	ds_read_b128 v[150:153], v185
	ds_read_b128 v[154:157], v185 offset:1024
	ds_read_b128 v[158:161], v185 offset:2048
	ds_read_b128 v[162:165], v185 offset:3072
	ds_read_b128 v[166:169], v183 offset:32768
	ds_read_b128 v[170:173], v183 offset:33792
	ds_read_b128 v[186:189], v183 offset:34816
	ds_read_b128 v[190:193], v183 offset:35840
	ds_read_b128 v[194:197], v183 offset:36864
	ds_read_b128 v[198:201], v183 offset:37888
	ds_read_b128 v[202:205], v183 offset:38912
	ds_read_b128 v[206:209], v183 offset:39936
	s_mov_b32 s75, m0
	s_mov_b32 m0, s34
	s_nop 0
	global_load_lds_dwordx4 v1, s[24:25]
	s_mov_b32 m0, s75
	s_nop 0
	s_mov_b32 s75, m0
	s_mov_b32 m0, s41
	s_nop 0
	global_load_lds_dwordx4 v177, s[24:25]
	s_mov_b32 m0, s75
	s_add_u32 s24, s24, 0x4000
	s_addc_u32 s25, s25, 0
	s_mov_b32 s75, m0
	s_mov_b32 m0, s42
	s_nop 0
	global_load_lds_dwordx4 v1, s[24:25]
	s_mov_b32 m0, s75
	s_nop 0
	s_mov_b32 s75, m0
	s_mov_b32 m0, s43
	s_nop 0
	global_load_lds_dwordx4 v177, s[24:25]
	s_mov_b32 m0, s75
	s_setprio 0
	s_waitcnt vmcnt(8)
	s_waitcnt lgkmcnt(0)
	s_barrier
	s_setprio 1
	s_waitcnt lgkmcnt(7)
	v_mfma_f32_16x16x32_bf16 v[126:129], v[130:133], v[166:169], v[126:129]
	v_mfma_f32_16x16x32_bf16 v[126:129], v[134:137], v[170:173], v[126:129]
	s_waitcnt lgkmcnt(5)
	v_mfma_f32_16x16x32_bf16 v[122:125], v[138:141], v[166:169], v[122:125]
	v_mfma_f32_16x16x32_bf16 v[122:125], v[142:145], v[170:173], v[122:125]
	s_waitcnt lgkmcnt(3)
	v_mfma_f32_16x16x32_bf16 v[110:113], v[138:141], v[186:189], v[110:113]
	v_mfma_f32_16x16x32_bf16 v[110:113], v[142:145], v[190:193], v[110:113]
	s_waitcnt lgkmcnt(1)
	v_mfma_f32_16x16x32_bf16 v[118:121], v[130:133], v[186:189], v[118:121]
	v_mfma_f32_16x16x32_bf16 v[118:121], v[134:137], v[190:193], v[118:121]
	v_mfma_f32_16x16x32_bf16 v[94:97], v[130:133], v[194:197], v[94:97]
	v_mfma_f32_16x16x32_bf16 v[94:97], v[134:137], v[198:201], v[94:97]
	v_mfma_f32_16x16x32_bf16 v[90:93], v[138:141], v[194:197], v[90:93]
	v_mfma_f32_16x16x32_bf16 v[90:93], v[142:145], v[198:201], v[90:93]
	v_mfma_f32_16x16x32_bf16 v[78:81], v[138:141], v[202:205], v[78:81]
	v_mfma_f32_16x16x32_bf16 v[78:81], v[142:145], v[206:209], v[78:81]
	s_waitcnt lgkmcnt(0)
	v_mfma_f32_16x16x32_bf16 v[86:89], v[130:133], v[202:205], v[86:89]
	v_mfma_f32_16x16x32_bf16 v[86:89], v[134:137], v[206:209], v[86:89]
	s_setprio 0
	s_setprio 1
	v_mfma_f32_16x16x32_bf16 v[114:117], v[150:153], v[166:169], v[114:117]
	v_mfma_f32_16x16x32_bf16 v[114:117], v[154:157], v[170:173], v[114:117]
	v_mfma_f32_16x16x32_bf16 v[106:109], v[158:161], v[166:169], v[106:109]
	v_mfma_f32_16x16x32_bf16 v[106:109], v[162:165], v[170:173], v[106:109]
	v_mfma_f32_16x16x32_bf16 v[98:101], v[158:161], v[186:189], v[98:101]
	v_mfma_f32_16x16x32_bf16 v[98:101], v[162:165], v[190:193], v[98:101]
	v_mfma_f32_16x16x32_bf16 v[102:105], v[150:153], v[186:189], v[102:105]
	v_mfma_f32_16x16x32_bf16 v[102:105], v[154:157], v[190:193], v[102:105]
	v_mfma_f32_16x16x32_bf16 v[82:85], v[150:153], v[194:197], v[82:85]
	v_mfma_f32_16x16x32_bf16 v[82:85], v[154:157], v[198:201], v[82:85]
	v_mfma_f32_16x16x32_bf16 v[74:77], v[158:161], v[194:197], v[74:77]
	v_mfma_f32_16x16x32_bf16 v[74:77], v[162:165], v[198:201], v[74:77]
	v_mfma_f32_16x16x32_bf16 v[66:69], v[158:161], v[202:205], v[66:69]
	v_mfma_f32_16x16x32_bf16 v[66:69], v[162:165], v[206:209], v[66:69]
	s_setprio 2
	s_barrier
	v_mfma_f32_16x16x32_bf16 v[70:73], v[150:153], v[202:205], v[70:73]
	v_mfma_f32_16x16x32_bf16 v[70:73], v[154:157], v[206:209], v[70:73]
	s_setprio 0
	s_setprio 3
	ds_read_b128 v[166:169], v183 offset:49152
	ds_read_b128 v[170:173], v183 offset:50176
	ds_read_b128 v[186:189], v183 offset:51200
	ds_read_b128 v[190:193], v183 offset:52224
	ds_read_b128 v[194:197], v183 offset:53248
	ds_read_b128 v[198:201], v183 offset:54272
	ds_read_b128 v[202:205], v183 offset:55296
	ds_read_b128 v[206:209], v183 offset:56320
	s_add_u32 s24, s22, 0x40000
	s_addc_u32 s25, s23, 0
	s_mov_b32 s75, m0
	s_mov_b32 m0, s46
	s_nop 0
	global_load_lds_dwordx4 v176, s[24:25]
	s_mov_b32 m0, s75
	s_add_u32 s22, s22, 0x44000
	s_mov_b32 s75, m0
	s_mov_b32 m0, s47
	s_nop 0
	global_load_lds_dwordx4 v178, s[24:25]
	s_mov_b32 m0, s75
	s_addc_u32 s23, s23, 0
	s_mov_b32 s24, m0
	s_mov_b32 m0, s48
	s_nop 0
	global_load_lds_dwordx4 v176, s[22:23]
	s_mov_b32 m0, s24
	s_nop 0
	s_mov_b32 s24, m0
	s_mov_b32 m0, s49
	s_nop 0
	global_load_lds_dwordx4 v178, s[22:23]
	s_mov_b32 m0, s24
	s_setprio 0
	s_waitcnt vmcnt(4)
	s_waitcnt lgkmcnt(0)
	s_barrier
	s_setprio 1
	s_waitcnt lgkmcnt(7)
	v_mfma_f32_16x16x32_bf16 v[62:65], v[130:133], v[166:169], v[62:65]
	v_mfma_f32_16x16x32_bf16 v[62:65], v[134:137], v[170:173], v[62:65]
	s_waitcnt lgkmcnt(5)
	v_mfma_f32_16x16x32_bf16 v[58:61], v[138:141], v[166:169], v[58:61]
	v_mfma_f32_16x16x32_bf16 v[58:61], v[142:145], v[170:173], v[58:61]
	s_waitcnt lgkmcnt(3)
	v_mfma_f32_16x16x32_bf16 v[42:45], v[138:141], v[186:189], v[42:45]
	v_mfma_f32_16x16x32_bf16 v[42:45], v[142:145], v[190:193], v[42:45]
	s_waitcnt lgkmcnt(1)
	v_mfma_f32_16x16x32_bf16 v[46:49], v[130:133], v[186:189], v[46:49]
	v_mfma_f32_16x16x32_bf16 v[46:49], v[134:137], v[190:193], v[46:49]
	v_mfma_f32_16x16x32_bf16 v[30:33], v[130:133], v[194:197], v[30:33]
	v_mfma_f32_16x16x32_bf16 v[30:33], v[134:137], v[198:201], v[30:33]
	v_mfma_f32_16x16x32_bf16 v[26:29], v[138:141], v[194:197], v[26:29]
	v_mfma_f32_16x16x32_bf16 v[26:29], v[142:145], v[198:201], v[26:29]
	v_mfma_f32_16x16x32_bf16 v[10:13], v[138:141], v[202:205], v[10:13]
	v_mfma_f32_16x16x32_bf16 v[10:13], v[142:145], v[206:209], v[10:13]
	s_waitcnt lgkmcnt(0)
	v_mfma_f32_16x16x32_bf16 v[14:17], v[130:133], v[202:205], v[14:17]
	v_mfma_f32_16x16x32_bf16 v[14:17], v[134:137], v[206:209], v[14:17]
	s_setprio 0
	s_setprio 1
	v_mfma_f32_16x16x32_bf16 v[54:57], v[150:153], v[166:169], v[54:57]
	v_mfma_f32_16x16x32_bf16 v[54:57], v[154:157], v[170:173], v[54:57]
	v_mfma_f32_16x16x32_bf16 v[50:53], v[158:161], v[166:169], v[50:53]
	v_mfma_f32_16x16x32_bf16 v[50:53], v[162:165], v[170:173], v[50:53]
	v_mfma_f32_16x16x32_bf16 v[34:37], v[158:161], v[186:189], v[34:37]
	v_mfma_f32_16x16x32_bf16 v[34:37], v[162:165], v[190:193], v[34:37]
	v_mfma_f32_16x16x32_bf16 v[38:41], v[150:153], v[186:189], v[38:41]
	v_mfma_f32_16x16x32_bf16 v[38:41], v[154:157], v[190:193], v[38:41]
	v_mfma_f32_16x16x32_bf16 v[22:25], v[150:153], v[194:197], v[22:25]
	v_mfma_f32_16x16x32_bf16 v[22:25], v[154:157], v[198:201], v[22:25]
	v_mfma_f32_16x16x32_bf16 v[18:21], v[158:161], v[194:197], v[18:21]
	v_mfma_f32_16x16x32_bf16 v[18:21], v[162:165], v[198:201], v[18:21]
	v_mfma_f32_16x16x32_bf16 v[2:5], v[158:161], v[202:205], v[2:5]
	v_mfma_f32_16x16x32_bf16 v[2:5], v[162:165], v[206:209], v[2:5]
	s_setprio 2
	s_barrier
	v_mfma_f32_16x16x32_bf16 v[6:9], v[150:153], v[202:205], v[6:9]
	v_mfma_f32_16x16x32_bf16 v[6:9], v[154:157], v[206:209], v[6:9]
	s_setprio 0
	s_add_i32 s74, s74, 2
	s_add_u32 s67, s67, 0x80000
	s_addc_u32 s70, s70, 0
	s_add_u32 s20, s20, 0x400000
	s_addc_u32 s21, s21, 0
	s_add_u32 s71, s71, 0x400000
	s_addc_u32 s73, s73, 0
	s_cmpk_gt_u32 s74, 0x53
	.p2align 6
.LBB0_1952:
	s_setprio 3
	ds_read_b128 v[130:133], v181
	ds_read_b128 v[134:137], v181 offset:1024
	ds_read_b128 v[138:141], v181 offset:2048
	ds_read_b128 v[142:145], v181 offset:3072
	ds_read_b128 v[150:153], v182
	ds_read_b128 v[154:157], v182 offset:1024
	ds_read_b128 v[158:161], v182 offset:2048
	ds_read_b128 v[162:165], v182 offset:3072
	s_cmpk_eq_i32 s74, 0x52
	s_cselect_b32 s23, s11, s70
	s_cselect_b32 s22, s66, s67
	s_cselect_b32 s25, s13, s73
	s_cselect_b32 s24, s65, s71
	ds_read_b128 v[166:169], v183
	ds_read_b128 v[170:173], v183 offset:1024
	ds_read_b128 v[186:189], v183 offset:2048
	ds_read_b128 v[190:193], v183 offset:3072
	ds_read_b128 v[194:197], v183 offset:4096
	ds_read_b128 v[198:201], v183 offset:5120
	ds_read_b128 v[202:205], v183 offset:6144
	ds_read_b128 v[206:209], v183 offset:7168
	s_add_u32 s76, s20, 0xffffc000
	s_addc_u32 s77, s21, -1
	s_mov_b32 s75, m0
	s_mov_b32 m0, s58
	s_nop 0
	global_load_lds_dwordx4 v1, s[76:77]
	s_mov_b32 m0, s75
	s_nop 0
	s_mov_b32 s75, m0
	s_mov_b32 m0, s62
	s_nop 0
	global_load_lds_dwordx4 v177, s[76:77]
	s_mov_b32 m0, s75
	s_nop 0
	s_mov_b32 s75, m0
	s_mov_b32 m0, s59
	s_nop 0
	global_load_lds_dwordx4 v1, s[20:21]
	s_mov_b32 m0, s75
	s_nop 0
	s_mov_b32 s75, m0
	s_mov_b32 m0, s63
	s_nop 0
	global_load_lds_dwordx4 v177, s[20:21]
	s_mov_b32 m0, s75
	s_setprio 0
	s_waitcnt vmcnt(8)
	s_waitcnt lgkmcnt(0)
	s_barrier
	s_setprio 1
	s_waitcnt lgkmcnt(7)
	v_mfma_f32_16x16x32_bf16 v[126:129], v[130:133], v[166:169], v[126:129]
	v_mfma_f32_16x16x32_bf16 v[126:129], v[134:137], v[170:173], v[126:129]
	s_waitcnt lgkmcnt(5)
	v_mfma_f32_16x16x32_bf16 v[122:125], v[138:141], v[166:169], v[122:125]
	v_mfma_f32_16x16x32_bf16 v[122:125], v[142:145], v[170:173], v[122:125]
	s_waitcnt lgkmcnt(3)
	v_mfma_f32_16x16x32_bf16 v[110:113], v[138:141], v[186:189], v[110:113]
	v_mfma_f32_16x16x32_bf16 v[110:113], v[142:145], v[190:193], v[110:113]
	s_waitcnt lgkmcnt(1)
	v_mfma_f32_16x16x32_bf16 v[118:121], v[130:133], v[186:189], v[118:121]
	v_mfma_f32_16x16x32_bf16 v[118:121], v[134:137], v[190:193], v[118:121]
	v_mfma_f32_16x16x32_bf16 v[94:97], v[130:133], v[194:197], v[94:97]
	v_mfma_f32_16x16x32_bf16 v[94:97], v[134:137], v[198:201], v[94:97]
	v_mfma_f32_16x16x32_bf16 v[90:93], v[138:141], v[194:197], v[90:93]
	v_mfma_f32_16x16x32_bf16 v[90:93], v[142:145], v[198:201], v[90:93]
	v_mfma_f32_16x16x32_bf16 v[78:81], v[138:141], v[202:205], v[78:81]
	v_mfma_f32_16x16x32_bf16 v[78:81], v[142:145], v[206:209], v[78:81]
	s_waitcnt lgkmcnt(0)
	v_mfma_f32_16x16x32_bf16 v[86:89], v[130:133], v[202:205], v[86:89]
	v_mfma_f32_16x16x32_bf16 v[86:89], v[134:137], v[206:209], v[86:89]
	s_setprio 0
	s_setprio 1
	v_mfma_f32_16x16x32_bf16 v[114:117], v[150:153], v[166:169], v[114:117]
	v_mfma_f32_16x16x32_bf16 v[114:117], v[154:157], v[170:173], v[114:117]
	v_mfma_f32_16x16x32_bf16 v[106:109], v[158:161], v[166:169], v[106:109]
	v_mfma_f32_16x16x32_bf16 v[106:109], v[162:165], v[170:173], v[106:109]
	v_mfma_f32_16x16x32_bf16 v[98:101], v[158:161], v[186:189], v[98:101]
	v_mfma_f32_16x16x32_bf16 v[98:101], v[162:165], v[190:193], v[98:101]
	v_mfma_f32_16x16x32_bf16 v[102:105], v[150:153], v[186:189], v[102:105]
	v_mfma_f32_16x16x32_bf16 v[102:105], v[154:157], v[190:193], v[102:105]
	v_mfma_f32_16x16x32_bf16 v[82:85], v[150:153], v[194:197], v[82:85]
	v_mfma_f32_16x16x32_bf16 v[82:85], v[154:157], v[198:201], v[82:85]
	v_mfma_f32_16x16x32_bf16 v[74:77], v[158:161], v[194:197], v[74:77]
	v_mfma_f32_16x16x32_bf16 v[74:77], v[162:165], v[198:201], v[74:77]
	v_mfma_f32_16x16x32_bf16 v[66:69], v[158:161], v[202:205], v[66:69]
	v_mfma_f32_16x16x32_bf16 v[66:69], v[162:165], v[206:209], v[66:69]
	s_setprio 2
	s_barrier
	v_mfma_f32_16x16x32_bf16 v[70:73], v[150:153], v[202:205], v[70:73]
	v_mfma_f32_16x16x32_bf16 v[70:73], v[154:157], v[206:209], v[70:73]
	s_setprio 0
	s_setprio 3
	ds_read_b128 v[166:169], v183 offset:16384
	ds_read_b128 v[170:173], v183 offset:17408
	ds_read_b128 v[186:189], v183 offset:18432
	ds_read_b128 v[190:193], v183 offset:19456
	ds_read_b128 v[194:197], v183 offset:20480
	ds_read_b128 v[198:201], v183 offset:21504
	ds_read_b128 v[202:205], v183 offset:22528
	ds_read_b128 v[206:209], v183 offset:23552
	s_mov_b32 s75, m0
	s_mov_b32 m0, s35
	s_nop 0
	global_load_lds_dwordx4 v176, s[22:23]
	s_mov_b32 m0, s75
	s_add_u32 s76, s22, 0x4000
	s_mov_b32 s75, m0
	s_mov_b32 m0, s36
	s_nop 0
	global_load_lds_dwordx4 v178, s[22:23]
	s_mov_b32 m0, s75
	s_addc_u32 s77, s23, 0
	s_mov_b32 s75, m0
	s_mov_b32 m0, s37
	s_nop 0
	global_load_lds_dwordx4 v176, s[76:77]
	s_mov_b32 m0, s75
	s_nop 0
	s_mov_b32 s75, m0
	s_mov_b32 m0, s40
	s_nop 0
	global_load_lds_dwordx4 v178, s[76:77]
	s_mov_b32 m0, s75
	s_setprio 0
	s_waitcnt vmcnt(4)
	s_waitcnt lgkmcnt(0)
	s_barrier
	s_setprio 1
	s_waitcnt lgkmcnt(7)
	v_mfma_f32_16x16x32_bf16 v[62:65], v[130:133], v[166:169], v[62:65]
	v_mfma_f32_16x16x32_bf16 v[62:65], v[134:137], v[170:173], v[62:65]
	s_waitcnt lgkmcnt(5)
	v_mfma_f32_16x16x32_bf16 v[58:61], v[138:141], v[166:169], v[58:61]
	v_mfma_f32_16x16x32_bf16 v[58:61], v[142:145], v[170:173], v[58:61]
	s_waitcnt lgkmcnt(3)
	v_mfma_f32_16x16x32_bf16 v[42:45], v[138:141], v[186:189], v[42:45]
	v_mfma_f32_16x16x32_bf16 v[42:45], v[142:145], v[190:193], v[42:45]
	s_waitcnt lgkmcnt(1)
	v_mfma_f32_16x16x32_bf16 v[46:49], v[130:133], v[186:189], v[46:49]
	v_mfma_f32_16x16x32_bf16 v[46:49], v[134:137], v[190:193], v[46:49]
	v_mfma_f32_16x16x32_bf16 v[30:33], v[130:133], v[194:197], v[30:33]
	v_mfma_f32_16x16x32_bf16 v[30:33], v[134:137], v[198:201], v[30:33]
	v_mfma_f32_16x16x32_bf16 v[26:29], v[138:141], v[194:197], v[26:29]
	v_mfma_f32_16x16x32_bf16 v[26:29], v[142:145], v[198:201], v[26:29]
	v_mfma_f32_16x16x32_bf16 v[10:13], v[138:141], v[202:205], v[10:13]
	v_mfma_f32_16x16x32_bf16 v[10:13], v[142:145], v[206:209], v[10:13]
	s_waitcnt lgkmcnt(0)
	v_mfma_f32_16x16x32_bf16 v[14:17], v[130:133], v[202:205], v[14:17]
	v_mfma_f32_16x16x32_bf16 v[14:17], v[134:137], v[206:209], v[14:17]
	s_setprio 0
	s_setprio 1
	v_mfma_f32_16x16x32_bf16 v[54:57], v[150:153], v[166:169], v[54:57]
	v_mfma_f32_16x16x32_bf16 v[54:57], v[154:157], v[170:173], v[54:57]
	v_mfma_f32_16x16x32_bf16 v[50:53], v[158:161], v[166:169], v[50:53]
	v_mfma_f32_16x16x32_bf16 v[50:53], v[162:165], v[170:173], v[50:53]
	v_mfma_f32_16x16x32_bf16 v[34:37], v[158:161], v[186:189], v[34:37]
	v_mfma_f32_16x16x32_bf16 v[34:37], v[162:165], v[190:193], v[34:37]
	v_mfma_f32_16x16x32_bf16 v[38:41], v[150:153], v[186:189], v[38:41]
	v_mfma_f32_16x16x32_bf16 v[38:41], v[154:157], v[190:193], v[38:41]
	v_mfma_f32_16x16x32_bf16 v[22:25], v[150:153], v[194:197], v[22:25]
	v_mfma_f32_16x16x32_bf16 v[22:25], v[154:157], v[198:201], v[22:25]
	v_mfma_f32_16x16x32_bf16 v[18:21], v[158:161], v[194:197], v[18:21]
	v_mfma_f32_16x16x32_bf16 v[18:21], v[162:165], v[198:201], v[18:21]
	v_mfma_f32_16x16x32_bf16 v[2:5], v[158:161], v[202:205], v[2:5]
	v_mfma_f32_16x16x32_bf16 v[2:5], v[162:165], v[206:209], v[2:5]
	s_setprio 2
	s_barrier
	v_mfma_f32_16x16x32_bf16 v[6:9], v[150:153], v[202:205], v[6:9]
	v_mfma_f32_16x16x32_bf16 v[6:9], v[154:157], v[206:209], v[6:9]
	s_setprio 0
	s_setprio 3
	ds_read_b128 v[130:133], v184
	ds_read_b128 v[134:137], v184 offset:1024
	ds_read_b128 v[138:141], v184 offset:2048
	ds_read_b128 v[142:145], v184 offset:3072
	ds_read_b128 v[150:153], v185
	ds_read_b128 v[154:157], v185 offset:1024
	ds_read_b128 v[158:161], v185 offset:2048
	ds_read_b128 v[162:165], v185 offset:3072
	ds_read_b128 v[166:169], v183 offset:32768
	ds_read_b128 v[170:173], v183 offset:33792
	ds_read_b128 v[186:189], v183 offset:34816
	ds_read_b128 v[190:193], v183 offset:35840
	ds_read_b128 v[194:197], v183 offset:36864
	ds_read_b128 v[198:201], v183 offset:37888
	ds_read_b128 v[202:205], v183 offset:38912
	ds_read_b128 v[206:209], v183 offset:39936
	s_mov_b32 s75, m0
	s_mov_b32 m0, s34
	s_nop 0
	global_load_lds_dwordx4 v1, s[24:25]
	s_mov_b32 m0, s75
	s_nop 0
	s_mov_b32 s75, m0
	s_mov_b32 m0, s41
	s_nop 0
	global_load_lds_dwordx4 v177, s[24:25]
	s_mov_b32 m0, s75
	s_add_u32 s24, s24, 0x4000
	s_addc_u32 s25, s25, 0
	s_mov_b32 s75, m0
	s_mov_b32 m0, s42
	s_nop 0
	global_load_lds_dwordx4 v1, s[24:25]
	s_mov_b32 m0, s75
	s_nop 0
	s_mov_b32 s75, m0
	s_mov_b32 m0, s43
	s_nop 0
	global_load_lds_dwordx4 v177, s[24:25]
	s_mov_b32 m0, s75
	s_setprio 0
	s_waitcnt vmcnt(8)
	s_waitcnt lgkmcnt(0)
	s_barrier
	s_setprio 1
	s_waitcnt lgkmcnt(7)
	v_mfma_f32_16x16x32_bf16 v[126:129], v[130:133], v[166:169], v[126:129]
	v_mfma_f32_16x16x32_bf16 v[126:129], v[134:137], v[170:173], v[126:129]
	s_waitcnt lgkmcnt(5)
	v_mfma_f32_16x16x32_bf16 v[122:125], v[138:141], v[166:169], v[122:125]
	v_mfma_f32_16x16x32_bf16 v[122:125], v[142:145], v[170:173], v[122:125]
	s_waitcnt lgkmcnt(3)
	v_mfma_f32_16x16x32_bf16 v[110:113], v[138:141], v[186:189], v[110:113]
	v_mfma_f32_16x16x32_bf16 v[110:113], v[142:145], v[190:193], v[110:113]
	s_waitcnt lgkmcnt(1)
	v_mfma_f32_16x16x32_bf16 v[118:121], v[130:133], v[186:189], v[118:121]
	v_mfma_f32_16x16x32_bf16 v[118:121], v[134:137], v[190:193], v[118:121]
	v_mfma_f32_16x16x32_bf16 v[94:97], v[130:133], v[194:197], v[94:97]
	v_mfma_f32_16x16x32_bf16 v[94:97], v[134:137], v[198:201], v[94:97]
	v_mfma_f32_16x16x32_bf16 v[90:93], v[138:141], v[194:197], v[90:93]
	v_mfma_f32_16x16x32_bf16 v[90:93], v[142:145], v[198:201], v[90:93]
	v_mfma_f32_16x16x32_bf16 v[78:81], v[138:141], v[202:205], v[78:81]
	v_mfma_f32_16x16x32_bf16 v[78:81], v[142:145], v[206:209], v[78:81]
	s_waitcnt lgkmcnt(0)
	v_mfma_f32_16x16x32_bf16 v[86:89], v[130:133], v[202:205], v[86:89]
	v_mfma_f32_16x16x32_bf16 v[86:89], v[134:137], v[206:209], v[86:89]
	s_setprio 0
	s_setprio 1
	v_mfma_f32_16x16x32_bf16 v[114:117], v[150:153], v[166:169], v[114:117]
	v_mfma_f32_16x16x32_bf16 v[114:117], v[154:157], v[170:173], v[114:117]
	v_mfma_f32_16x16x32_bf16 v[106:109], v[158:161], v[166:169], v[106:109]
	v_mfma_f32_16x16x32_bf16 v[106:109], v[162:165], v[170:173], v[106:109]
	v_mfma_f32_16x16x32_bf16 v[98:101], v[158:161], v[186:189], v[98:101]
	v_mfma_f32_16x16x32_bf16 v[98:101], v[162:165], v[190:193], v[98:101]
	v_mfma_f32_16x16x32_bf16 v[102:105], v[150:153], v[186:189], v[102:105]
	v_mfma_f32_16x16x32_bf16 v[102:105], v[154:157], v[190:193], v[102:105]
	v_mfma_f32_16x16x32_bf16 v[82:85], v[150:153], v[194:197], v[82:85]
	v_mfma_f32_16x16x32_bf16 v[82:85], v[154:157], v[198:201], v[82:85]
	v_mfma_f32_16x16x32_bf16 v[74:77], v[158:161], v[194:197], v[74:77]
	v_mfma_f32_16x16x32_bf16 v[74:77], v[162:165], v[198:201], v[74:77]
	v_mfma_f32_16x16x32_bf16 v[66:69], v[158:161], v[202:205], v[66:69]
	v_mfma_f32_16x16x32_bf16 v[66:69], v[162:165], v[206:209], v[66:69]
	s_setprio 2
	s_barrier
	v_mfma_f32_16x16x32_bf16 v[70:73], v[150:153], v[202:205], v[70:73]
	v_mfma_f32_16x16x32_bf16 v[70:73], v[154:157], v[206:209], v[70:73]
	s_setprio 0
	s_setprio 3
	ds_read_b128 v[166:169], v183 offset:49152
	ds_read_b128 v[170:173], v183 offset:50176
	ds_read_b128 v[186:189], v183 offset:51200
	ds_read_b128 v[190:193], v183 offset:52224
	ds_read_b128 v[194:197], v183 offset:53248
	ds_read_b128 v[198:201], v183 offset:54272
	ds_read_b128 v[202:205], v183 offset:55296
	ds_read_b128 v[206:209], v183 offset:56320
	s_add_u32 s24, s22, 0x40000
	s_addc_u32 s25, s23, 0
	s_mov_b32 s75, m0
	s_mov_b32 m0, s46
	s_nop 0
	global_load_lds_dwordx4 v176, s[24:25]
	s_mov_b32 m0, s75
	s_add_u32 s22, s22, 0x44000
	s_mov_b32 s75, m0
	s_mov_b32 m0, s47
	s_nop 0
	global_load_lds_dwordx4 v178, s[24:25]
	s_mov_b32 m0, s75
	s_addc_u32 s23, s23, 0
	s_mov_b32 s24, m0
	s_mov_b32 m0, s48
	s_nop 0
	global_load_lds_dwordx4 v176, s[22:23]
	s_mov_b32 m0, s24
	s_nop 0
	s_mov_b32 s24, m0
	s_mov_b32 m0, s49
	s_nop 0
	global_load_lds_dwordx4 v178, s[22:23]
	s_mov_b32 m0, s24
	s_setprio 0
	s_waitcnt vmcnt(4)
	s_waitcnt lgkmcnt(0)
	s_barrier
	s_setprio 1
	s_waitcnt lgkmcnt(7)
	v_mfma_f32_16x16x32_bf16 v[62:65], v[130:133], v[166:169], v[62:65]
	v_mfma_f32_16x16x32_bf16 v[62:65], v[134:137], v[170:173], v[62:65]
	s_waitcnt lgkmcnt(5)
	v_mfma_f32_16x16x32_bf16 v[58:61], v[138:141], v[166:169], v[58:61]
	v_mfma_f32_16x16x32_bf16 v[58:61], v[142:145], v[170:173], v[58:61]
	s_waitcnt lgkmcnt(3)
	v_mfma_f32_16x16x32_bf16 v[42:45], v[138:141], v[186:189], v[42:45]
	v_mfma_f32_16x16x32_bf16 v[42:45], v[142:145], v[190:193], v[42:45]
	s_waitcnt lgkmcnt(1)
	v_mfma_f32_16x16x32_bf16 v[46:49], v[130:133], v[186:189], v[46:49]
	v_mfma_f32_16x16x32_bf16 v[46:49], v[134:137], v[190:193], v[46:49]
	v_mfma_f32_16x16x32_bf16 v[30:33], v[130:133], v[194:197], v[30:33]
	v_mfma_f32_16x16x32_bf16 v[30:33], v[134:137], v[198:201], v[30:33]
	v_mfma_f32_16x16x32_bf16 v[26:29], v[138:141], v[194:197], v[26:29]
	v_mfma_f32_16x16x32_bf16 v[26:29], v[142:145], v[198:201], v[26:29]
	v_mfma_f32_16x16x32_bf16 v[10:13], v[138:141], v[202:205], v[10:13]
	v_mfma_f32_16x16x32_bf16 v[10:13], v[142:145], v[206:209], v[10:13]
	s_waitcnt lgkmcnt(0)
	v_mfma_f32_16x16x32_bf16 v[14:17], v[130:133], v[202:205], v[14:17]
	v_mfma_f32_16x16x32_bf16 v[14:17], v[134:137], v[206:209], v[14:17]
	s_setprio 0
	s_setprio 1
	v_mfma_f32_16x16x32_bf16 v[54:57], v[150:153], v[166:169], v[54:57]
	v_mfma_f32_16x16x32_bf16 v[54:57], v[154:157], v[170:173], v[54:57]
	v_mfma_f32_16x16x32_bf16 v[50:53], v[158:161], v[166:169], v[50:53]
	v_mfma_f32_16x16x32_bf16 v[50:53], v[162:165], v[170:173], v[50:53]
	v_mfma_f32_16x16x32_bf16 v[34:37], v[158:161], v[186:189], v[34:37]
	v_mfma_f32_16x16x32_bf16 v[34:37], v[162:165], v[190:193], v[34:37]
	v_mfma_f32_16x16x32_bf16 v[38:41], v[150:153], v[186:189], v[38:41]
	v_mfma_f32_16x16x32_bf16 v[38:41], v[154:157], v[190:193], v[38:41]
	v_mfma_f32_16x16x32_bf16 v[22:25], v[150:153], v[194:197], v[22:25]
	v_mfma_f32_16x16x32_bf16 v[22:25], v[154:157], v[198:201], v[22:25]
	v_mfma_f32_16x16x32_bf16 v[18:21], v[158:161], v[194:197], v[18:21]
	v_mfma_f32_16x16x32_bf16 v[18:21], v[162:165], v[198:201], v[18:21]
	v_mfma_f32_16x16x32_bf16 v[2:5], v[158:161], v[202:205], v[2:5]
	v_mfma_f32_16x16x32_bf16 v[2:5], v[162:165], v[206:209], v[2:5]
	s_setprio 2
	s_barrier
	v_mfma_f32_16x16x32_bf16 v[6:9], v[150:153], v[202:205], v[6:9]
	v_mfma_f32_16x16x32_bf16 v[6:9], v[154:157], v[206:209], v[6:9]
	s_setprio 0
	s_add_i32 s74, s74, 2
	s_add_u32 s67, s67, 0x80000
	s_addc_u32 s70, s70, 0
	s_add_u32 s20, s20, 0x400000
	s_addc_u32 s21, s21, 0
	s_add_u32 s71, s71, 0x400000
	s_addc_u32 s73, s73, 0
	s_cmpk_gt_u32 s74, 0x53
	s_cbranch_scc0 .LBB0_1952
	s_and_b64 vcc, exec, s[8:9]
	s_cbranch_vccz .LBB0_1955
	s_barrier

.LBB0_2145:
	s_ashr_i32 s25, s24, 31
	s_lshl_b64 s[26:27], s[24:25], 20
	s_add_u32 s26, s33, s26
	s_addc_u32 s27, s42, s27
	s_and_b64 s[28:29], s[2:3], exec
	s_cselect_b32 s5, s27, s37
	s_cselect_b32 s25, s26, s36
	s_ashr_i32 s23, s22, 31
	s_lshl_b64 s[28:29], s[22:23], 20
	s_add_u32 s28, s43, s28
	s_addc_u32 s29, s46, s29
	s_and_b64 s[40:41], s[2:3], exec
	s_cselect_b32 s23, s29, s35
	s_cselect_b32 s31, s28, s34
	s_add_u32 s77, s34, 0x100
	s_addc_u32 s78, s35, 0
	s_add_u32 s34, s36, 0x80080
	s_addc_u32 s35, s37, 0
	s_add_u32 s79, s36, 0x100
	s_addc_u32 s80, s37, 0
	s_mov_b32 s81, -2
	s_waitcnt vmcnt(25)
	s_waitcnt vmcnt(24)
	s_waitcnt vmcnt(4)
	s_waitcnt vmcnt(2)
	s_waitcnt vmcnt(1)
	s_waitcnt vmcnt(0)
	s_setprio 3
	ds_read_b128 v[42:45], v181
	ds_read_b128 v[46:49], v181 offset:1024
	ds_read_b128 v[58:61], v181 offset:2048
	ds_read_b128 v[62:65], v181 offset:3072
	ds_read_b128 v[146:149], v182
	ds_read_b128 v[150:153], v182 offset:1024
	ds_read_b128 v[154:157], v182 offset:2048
	ds_read_b128 v[158:161], v182 offset:3072
	s_cmp_eq_u32 s81, 28
	s_cselect_b32 s37, s23, s78
	s_cselect_b32 s36, s31, s77
	s_cselect_b32 s41, s5, s80
	s_cselect_b32 s40, s25, s79
	ds_read_b128 v[170:173], v183
	ds_read_b128 v[188:191], v183 offset:1024
	ds_read_b128 v[192:195], v183 offset:2048
	ds_read_b128 v[196:199], v183 offset:3072
	ds_read_b128 v[200:203], v183 offset:4096
	ds_read_b128 v[204:207], v183 offset:5120
	ds_read_b128 v[208:211], v183 offset:6144
	ds_read_b128 v[212:215], v183 offset:7168
	s_add_u32 s82, s34, 0xfff80000
	s_addc_u32 s83, s35, -1
	s_mov_b32 s86, m0
	s_mov_b32 m0, s70
	s_nop 0
	global_load_lds_dwordx4 v1, s[82:83]
	s_mov_b32 m0, s86
	s_nop 0
	s_mov_b32 s86, m0
	s_mov_b32 m0, s73
	s_nop 0
	global_load_lds_dwordx4 v177, s[82:83]
	s_mov_b32 m0, s86
	s_mov_b32 s82, m0
	s_mov_b32 m0, s71
	s_nop 0
	global_load_lds_dwordx4 v1, s[34:35]
	s_mov_b32 m0, s82
	s_nop 0
	s_mov_b32 s82, m0
	s_mov_b32 m0, s74
	s_nop 0
	global_load_lds_dwordx4 v177, s[34:35]
	s_mov_b32 m0, s82
	s_setprio 0
	s_waitcnt vmcnt(8)
	s_waitcnt lgkmcnt(0)
	s_barrier
	s_setprio 1
	s_waitcnt lgkmcnt(7)
	v_mfma_f32_16x16x32_bf16 v[142:145], v[42:45], v[170:173], 0
	v_mfma_f32_16x16x32_bf16 v[142:145], v[46:49], v[188:191], v[142:145]
	s_waitcnt lgkmcnt(5)
	v_mfma_f32_16x16x32_bf16 v[138:141], v[58:61], v[170:173], 0
	v_mfma_f32_16x16x32_bf16 v[138:141], v[62:65], v[188:191], v[138:141]
	s_waitcnt lgkmcnt(3)
	v_mfma_f32_16x16x32_bf16 v[126:129], v[42:45], v[192:195], 0
	v_mfma_f32_16x16x32_bf16 v[126:129], v[46:49], v[196:199], v[126:129]
	s_waitcnt lgkmcnt(1)
	v_mfma_f32_16x16x32_bf16 v[122:125], v[58:61], v[192:195], 0
	v_mfma_f32_16x16x32_bf16 v[122:125], v[62:65], v[196:199], v[122:125]
	v_mfma_f32_16x16x32_bf16 v[110:113], v[42:45], v[200:203], 0
	v_mfma_f32_16x16x32_bf16 v[110:113], v[46:49], v[204:207], v[110:113]
	v_mfma_f32_16x16x32_bf16 v[106:109], v[58:61], v[200:203], 0
	v_mfma_f32_16x16x32_bf16 v[106:109], v[62:65], v[204:207], v[106:109]
	v_mfma_f32_16x16x32_bf16 v[94:97], v[42:45], v[208:211], 0
	v_mfma_f32_16x16x32_bf16 v[94:97], v[46:49], v[212:215], v[94:97]
	s_waitcnt lgkmcnt(0)
	v_mfma_f32_16x16x32_bf16 v[90:93], v[58:61], v[208:211], 0
	v_mfma_f32_16x16x32_bf16 v[90:93], v[62:65], v[212:215], v[90:93]
	s_setprio 0
	s_setprio 1
	v_mfma_f32_16x16x32_bf16 v[134:137], v[146:149], v[170:173], 0
	v_mfma_f32_16x16x32_bf16 v[134:137], v[150:153], v[188:191], v[134:137]
	v_mfma_f32_16x16x32_bf16 v[130:133], v[154:157], v[170:173], 0
	v_mfma_f32_16x16x32_bf16 v[130:133], v[158:161], v[188:191], v[130:133]
	v_mfma_f32_16x16x32_bf16 v[118:121], v[146:149], v[192:195], 0
	v_mfma_f32_16x16x32_bf16 v[118:121], v[150:153], v[196:199], v[118:121]
	v_mfma_f32_16x16x32_bf16 v[114:117], v[154:157], v[192:195], 0
	v_mfma_f32_16x16x32_bf16 v[114:117], v[158:161], v[196:199], v[114:117]
	v_mfma_f32_16x16x32_bf16 v[102:105], v[146:149], v[200:203], 0
	v_mfma_f32_16x16x32_bf16 v[102:105], v[150:153], v[204:207], v[102:105]
	v_mfma_f32_16x16x32_bf16 v[98:101], v[154:157], v[200:203], 0
	v_mfma_f32_16x16x32_bf16 v[98:101], v[158:161], v[204:207], v[98:101]
	v_mfma_f32_16x16x32_bf16 v[86:89], v[146:149], v[208:211], 0
	v_mfma_f32_16x16x32_bf16 v[86:89], v[150:153], v[212:215], v[86:89]
	s_setprio 2
	s_barrier
	v_mfma_f32_16x16x32_bf16 v[82:85], v[154:157], v[208:211], 0
	v_mfma_f32_16x16x32_bf16 v[82:85], v[158:161], v[212:215], v[82:85]
	s_setprio 0
	s_setprio 3
	ds_read_b128 v[170:173], v183 offset:16384
	ds_read_b128 v[188:191], v183 offset:17408
	ds_read_b128 v[192:195], v183 offset:18432
	ds_read_b128 v[196:199], v183 offset:19456
	ds_read_b128 v[200:203], v183 offset:20480
	ds_read_b128 v[204:207], v183 offset:21504
	ds_read_b128 v[208:211], v183 offset:22528
	ds_read_b128 v[212:215], v183 offset:23552
	s_mov_b32 s82, m0
	s_mov_b32 m0, s49
	s_nop 0
	global_load_lds_dwordx4 v176, s[36:37]
	s_mov_b32 m0, s82
	s_nop 0
	s_mov_b32 s82, m0
	s_mov_b32 m0, s56
	s_nop 0
	global_load_lds_dwordx4 v178, s[36:37]
	s_mov_b32 m0, s82
	s_add_u32 s82, s36, 0x80000
	s_addc_u32 s83, s37, 0
	s_mov_b32 s86, m0
	s_mov_b32 m0, s57
	s_nop 0
	global_load_lds_dwordx4 v176, s[82:83]
	s_mov_b32 m0, s86
	s_nop 0
	s_mov_b32 s86, m0
	s_mov_b32 m0, s58
	s_nop 0
	global_load_lds_dwordx4 v178, s[82:83]
	s_mov_b32 m0, s86
	s_setprio 0
	s_waitcnt vmcnt(4)
	s_waitcnt lgkmcnt(0)
	s_barrier
	s_setprio 1
	s_waitcnt lgkmcnt(7)
	v_mfma_f32_16x16x32_bf16 v[78:81], v[42:45], v[170:173], 0
	v_mfma_f32_16x16x32_bf16 v[78:81], v[46:49], v[188:191], v[78:81]
	s_waitcnt lgkmcnt(5)
	v_mfma_f32_16x16x32_bf16 v[74:77], v[58:61], v[170:173], 0
	v_mfma_f32_16x16x32_bf16 v[74:77], v[62:65], v[188:191], v[74:77]
	s_waitcnt lgkmcnt(3)
	v_mfma_f32_16x16x32_bf16 v[54:57], v[42:45], v[192:195], 0
	v_mfma_f32_16x16x32_bf16 v[54:57], v[46:49], v[196:199], v[54:57]
	s_waitcnt lgkmcnt(1)
	v_mfma_f32_16x16x32_bf16 v[50:53], v[58:61], v[192:195], 0
	v_mfma_f32_16x16x32_bf16 v[50:53], v[62:65], v[196:199], v[50:53]
	v_mfma_f32_16x16x32_bf16 v[30:33], v[42:45], v[200:203], 0
	v_mfma_f32_16x16x32_bf16 v[30:33], v[46:49], v[204:207], v[30:33]
	v_mfma_f32_16x16x32_bf16 v[26:29], v[58:61], v[200:203], 0
	v_mfma_f32_16x16x32_bf16 v[26:29], v[62:65], v[204:207], v[26:29]
	v_mfma_f32_16x16x32_bf16 v[14:17], v[42:45], v[208:211], 0
	v_mfma_f32_16x16x32_bf16 v[14:17], v[46:49], v[212:215], v[14:17]
	s_waitcnt lgkmcnt(0)
	v_mfma_f32_16x16x32_bf16 v[10:13], v[58:61], v[208:211], 0
	v_mfma_f32_16x16x32_bf16 v[10:13], v[62:65], v[212:215], v[10:13]
	s_setprio 0
	s_setprio 1
	v_mfma_f32_16x16x32_bf16 v[38:41], v[146:149], v[192:195], 0
	v_mfma_f32_16x16x32_bf16 v[38:41], v[150:153], v[196:199], v[38:41]
	v_mfma_f32_16x16x32_bf16 v[34:37], v[154:157], v[192:195], 0
	v_mfma_f32_16x16x32_bf16 v[34:37], v[158:161], v[196:199], v[34:37]
	v_mfma_f32_16x16x32_bf16 v[22:25], v[146:149], v[200:203], 0
	v_mfma_f32_16x16x32_bf16 v[22:25], v[150:153], v[204:207], v[22:25]
	v_mfma_f32_16x16x32_bf16 v[18:21], v[154:157], v[200:203], 0
	v_mfma_f32_16x16x32_bf16 v[18:21], v[158:161], v[204:207], v[18:21]
	v_mfma_f32_16x16x32_bf16 v[6:9], v[146:149], v[208:211], 0
	v_mfma_f32_16x16x32_bf16 v[6:9], v[150:153], v[212:215], v[6:9]
	v_mfma_f32_16x16x32_bf16 v[2:5], v[154:157], v[208:211], 0
	v_mfma_f32_16x16x32_bf16 v[2:5], v[158:161], v[212:215], v[2:5]
	v_mfma_f32_16x16x32_bf16 v[42:45], v[146:149], v[170:173], 0
	v_mfma_f32_16x16x32_bf16 v[42:45], v[150:153], v[188:191], v[42:45]
	s_setprio 2
	s_barrier
	v_mfma_f32_16x16x32_bf16 v[46:49], v[154:157], v[170:173], 0
	v_mfma_f32_16x16x32_bf16 v[46:49], v[158:161], v[188:191], v[46:49]
	s_setprio 0
	s_setprio 3
	ds_read_b128 v[58:61], v184
	ds_read_b128 v[62:65], v184 offset:1024
	ds_read_b128 v[66:69], v184 offset:2048
	ds_read_b128 v[70:73], v184 offset:3072
	ds_read_b128 v[146:149], v185
	ds_read_b128 v[150:153], v185 offset:1024
	ds_read_b128 v[154:157], v185 offset:2048
	ds_read_b128 v[158:161], v185 offset:3072
	ds_read_b128 v[170:173], v183 offset:32768
	ds_read_b128 v[188:191], v183 offset:33792
	ds_read_b128 v[192:195], v183 offset:34816
	ds_read_b128 v[196:199], v183 offset:35840
	ds_read_b128 v[200:203], v183 offset:36864
	ds_read_b128 v[204:207], v183 offset:37888
	ds_read_b128 v[208:211], v183 offset:38912
	ds_read_b128 v[212:215], v183 offset:39936
	s_mov_b32 s82, m0
	s_mov_b32 m0, s48
	s_nop 0
	global_load_lds_dwordx4 v1, s[40:41]
	s_mov_b32 m0, s82
	s_nop 0
	s_mov_b32 s82, m0
	s_mov_b32 m0, s59
	s_nop 0
	global_load_lds_dwordx4 v177, s[40:41]
	s_mov_b32 m0, s82
	s_add_u32 s40, s40, 0x80000
	s_addc_u32 s41, s41, 0
	s_mov_b32 s82, m0
	s_mov_b32 m0, s62
	s_nop 0
	global_load_lds_dwordx4 v1, s[40:41]
	s_mov_b32 m0, s82
	s_nop 0
	s_mov_b32 s82, m0
	s_mov_b32 m0, s63
	s_nop 0
	global_load_lds_dwordx4 v177, s[40:41]
	s_mov_b32 m0, s82
	s_setprio 0
	s_waitcnt vmcnt(8)
	s_waitcnt lgkmcnt(0)
	s_barrier
	s_setprio 1
	s_waitcnt lgkmcnt(7)
	v_mfma_f32_16x16x32_bf16 v[142:145], v[58:61], v[170:173], v[142:145]
	v_mfma_f32_16x16x32_bf16 v[142:145], v[62:65], v[188:191], v[142:145]
	s_waitcnt lgkmcnt(5)
	v_mfma_f32_16x16x32_bf16 v[138:141], v[66:69], v[170:173], v[138:141]
	v_mfma_f32_16x16x32_bf16 v[138:141], v[70:73], v[188:191], v[138:141]
	s_waitcnt lgkmcnt(3)
	v_mfma_f32_16x16x32_bf16 v[126:129], v[58:61], v[192:195], v[126:129]
	v_mfma_f32_16x16x32_bf16 v[126:129], v[62:65], v[196:199], v[126:129]
	s_waitcnt lgkmcnt(1)
	v_mfma_f32_16x16x32_bf16 v[122:125], v[66:69], v[192:195], v[122:125]
	v_mfma_f32_16x16x32_bf16 v[122:125], v[70:73], v[196:199], v[122:125]
	v_mfma_f32_16x16x32_bf16 v[110:113], v[58:61], v[200:203], v[110:113]
	v_mfma_f32_16x16x32_bf16 v[110:113], v[62:65], v[204:207], v[110:113]
	v_mfma_f32_16x16x32_bf16 v[106:109], v[66:69], v[200:203], v[106:109]
	v_mfma_f32_16x16x32_bf16 v[106:109], v[70:73], v[204:207], v[106:109]
	v_mfma_f32_16x16x32_bf16 v[94:97], v[58:61], v[208:211], v[94:97]
	v_mfma_f32_16x16x32_bf16 v[94:97], v[62:65], v[212:215], v[94:97]
	s_waitcnt lgkmcnt(0)
	v_mfma_f32_16x16x32_bf16 v[90:93], v[66:69], v[208:211], v[90:93]
	v_mfma_f32_16x16x32_bf16 v[90:93], v[70:73], v[212:215], v[90:93]
	s_setprio 0
	s_setprio 1
	v_mfma_f32_16x16x32_bf16 v[134:137], v[146:149], v[170:173], v[134:137]
	v_mfma_f32_16x16x32_bf16 v[134:137], v[150:153], v[188:191], v[134:137]
	v_mfma_f32_16x16x32_bf16 v[130:133], v[154:157], v[170:173], v[130:133]
	v_mfma_f32_16x16x32_bf16 v[130:133], v[158:161], v[188:191], v[130:133]
	v_mfma_f32_16x16x32_bf16 v[118:121], v[146:149], v[192:195], v[118:121]
	v_mfma_f32_16x16x32_bf16 v[118:121], v[150:153], v[196:199], v[118:121]
	v_mfma_f32_16x16x32_bf16 v[114:117], v[154:157], v[192:195], v[114:117]
	v_mfma_f32_16x16x32_bf16 v[114:117], v[158:161], v[196:199], v[114:117]
	v_mfma_f32_16x16x32_bf16 v[102:105], v[146:149], v[200:203], v[102:105]
	v_mfma_f32_16x16x32_bf16 v[102:105], v[150:153], v[204:207], v[102:105]
	v_mfma_f32_16x16x32_bf16 v[98:101], v[154:157], v[200:203], v[98:101]
	v_mfma_f32_16x16x32_bf16 v[98:101], v[158:161], v[204:207], v[98:101]
	v_mfma_f32_16x16x32_bf16 v[86:89], v[146:149], v[208:211], v[86:89]
	v_mfma_f32_16x16x32_bf16 v[86:89], v[150:153], v[212:215], v[86:89]
	s_setprio 2
	s_barrier
	v_mfma_f32_16x16x32_bf16 v[82:85], v[154:157], v[208:211], v[82:85]
	v_mfma_f32_16x16x32_bf16 v[82:85], v[158:161], v[212:215], v[82:85]
	s_setprio 0
	s_setprio 3
	ds_read_b128 v[170:173], v183 offset:49152
	ds_read_b128 v[188:191], v183 offset:50176
	ds_read_b128 v[192:195], v183 offset:51200
	ds_read_b128 v[196:199], v183 offset:52224
	ds_read_b128 v[200:203], v183 offset:53248
	ds_read_b128 v[204:207], v183 offset:54272
	ds_read_b128 v[208:211], v183 offset:55296
	ds_read_b128 v[212:215], v183 offset:56320
	s_add_u32 s40, s36, 0x80
	s_addc_u32 s41, s37, 0
	s_mov_b32 s82, m0
	s_mov_b32 m0, s64
	s_nop 0
	global_load_lds_dwordx4 v176, s[40:41]
	s_mov_b32 m0, s82
	s_add_u32 s36, s36, 0x80080
	s_mov_b32 s82, m0
	s_mov_b32 m0, s65
	s_nop 0
	global_load_lds_dwordx4 v178, s[40:41]
	s_mov_b32 m0, s82
	s_addc_u32 s37, s37, 0
	s_mov_b32 s40, m0
	s_mov_b32 m0, s66
	s_nop 0
	global_load_lds_dwordx4 v176, s[36:37]
	s_mov_b32 m0, s40
	s_nop 0
	s_mov_b32 s40, m0
	s_mov_b32 m0, s67
	s_nop 0
	global_load_lds_dwordx4 v178, s[36:37]
	s_mov_b32 m0, s40
	s_setprio 0
	s_waitcnt vmcnt(4)
	s_waitcnt lgkmcnt(0)
	s_barrier
	s_setprio 1
	s_waitcnt lgkmcnt(7)
	v_mfma_f32_16x16x32_bf16 v[78:81], v[58:61], v[170:173], v[78:81]
	v_mfma_f32_16x16x32_bf16 v[78:81], v[62:65], v[188:191], v[78:81]
	s_waitcnt lgkmcnt(5)
	v_mfma_f32_16x16x32_bf16 v[74:77], v[66:69], v[170:173], v[74:77]
	v_mfma_f32_16x16x32_bf16 v[74:77], v[70:73], v[188:191], v[74:77]
	s_waitcnt lgkmcnt(3)
	v_mfma_f32_16x16x32_bf16 v[54:57], v[58:61], v[192:195], v[54:57]
	v_mfma_f32_16x16x32_bf16 v[54:57], v[62:65], v[196:199], v[54:57]
	s_waitcnt lgkmcnt(1)
	v_mfma_f32_16x16x32_bf16 v[50:53], v[66:69], v[192:195], v[50:53]
	v_mfma_f32_16x16x32_bf16 v[50:53], v[70:73], v[196:199], v[50:53]
	v_mfma_f32_16x16x32_bf16 v[30:33], v[58:61], v[200:203], v[30:33]
	v_mfma_f32_16x16x32_bf16 v[30:33], v[62:65], v[204:207], v[30:33]
	v_mfma_f32_16x16x32_bf16 v[26:29], v[66:69], v[200:203], v[26:29]
	v_mfma_f32_16x16x32_bf16 v[26:29], v[70:73], v[204:207], v[26:29]
	v_mfma_f32_16x16x32_bf16 v[14:17], v[58:61], v[208:211], v[14:17]
	v_mfma_f32_16x16x32_bf16 v[14:17], v[62:65], v[212:215], v[14:17]
	s_waitcnt lgkmcnt(0)
	v_mfma_f32_16x16x32_bf16 v[10:13], v[66:69], v[208:211], v[10:13]
	v_mfma_f32_16x16x32_bf16 v[10:13], v[70:73], v[212:215], v[10:13]
	s_setprio 0
	s_setprio 1
	v_mfma_f32_16x16x32_bf16 v[42:45], v[146:149], v[170:173], v[42:45]
	v_mfma_f32_16x16x32_bf16 v[70:73], v[150:153], v[188:191], v[42:45]
	v_mfma_f32_16x16x32_bf16 v[42:45], v[154:157], v[170:173], v[46:49]
	v_mfma_f32_16x16x32_bf16 v[66:69], v[158:161], v[188:191], v[42:45]
	v_mfma_f32_16x16x32_bf16 v[38:41], v[146:149], v[192:195], v[38:41]
	v_mfma_f32_16x16x32_bf16 v[38:41], v[150:153], v[196:199], v[38:41]
	v_mfma_f32_16x16x32_bf16 v[34:37], v[154:157], v[192:195], v[34:37]
	v_mfma_f32_16x16x32_bf16 v[34:37], v[158:161], v[196:199], v[34:37]
	v_mfma_f32_16x16x32_bf16 v[22:25], v[146:149], v[200:203], v[22:25]
	v_mfma_f32_16x16x32_bf16 v[22:25], v[150:153], v[204:207], v[22:25]
	v_mfma_f32_16x16x32_bf16 v[18:21], v[154:157], v[200:203], v[18:21]
	v_mfma_f32_16x16x32_bf16 v[18:21], v[158:161], v[204:207], v[18:21]
	v_mfma_f32_16x16x32_bf16 v[6:9], v[146:149], v[208:211], v[6:9]
	v_mfma_f32_16x16x32_bf16 v[6:9], v[150:153], v[212:215], v[6:9]
	s_setprio 2
	s_barrier
	v_mfma_f32_16x16x32_bf16 v[2:5], v[154:157], v[208:211], v[2:5]
	v_mfma_f32_16x16x32_bf16 v[2:5], v[158:161], v[212:215], v[2:5]
	s_setprio 0
	s_add_i32 s81, s81, 2
	s_add_u32 s77, s77, 0x100
	s_addc_u32 s78, s78, 0
	s_add_u32 s34, s34, 0x100
	s_addc_u32 s35, s35, 0
	s_add_u32 s79, s79, 0x100
	s_addc_u32 s80, s80, 0
	s_cmp_gt_u32 s81, 29
	.p2align 6
.LBB0_2146:
	s_setprio 3
	ds_read_b128 v[42:45], v181
	ds_read_b128 v[46:49], v181 offset:1024
	ds_read_b128 v[58:61], v181 offset:2048
	ds_read_b128 v[62:65], v181 offset:3072
	ds_read_b128 v[146:149], v182
	ds_read_b128 v[150:153], v182 offset:1024
	ds_read_b128 v[154:157], v182 offset:2048
	ds_read_b128 v[158:161], v182 offset:3072
	s_cmp_eq_u32 s81, 28
	s_cselect_b32 s37, s23, s78
	s_cselect_b32 s36, s31, s77
	s_cselect_b32 s41, s5, s80
	s_cselect_b32 s40, s25, s79
	ds_read_b128 v[170:173], v183
	ds_read_b128 v[188:191], v183 offset:1024
	ds_read_b128 v[192:195], v183 offset:2048
	ds_read_b128 v[196:199], v183 offset:3072
	ds_read_b128 v[200:203], v183 offset:4096
	ds_read_b128 v[204:207], v183 offset:5120
	ds_read_b128 v[208:211], v183 offset:6144
	ds_read_b128 v[212:215], v183 offset:7168
	s_add_u32 s82, s34, 0xfff80000
	s_addc_u32 s83, s35, -1
	s_mov_b32 s86, m0
	s_mov_b32 m0, s70
	s_nop 0
	global_load_lds_dwordx4 v1, s[82:83]
	s_mov_b32 m0, s86
	s_nop 0
	s_mov_b32 s86, m0
	s_mov_b32 m0, s73
	s_nop 0
	global_load_lds_dwordx4 v177, s[82:83]
	s_mov_b32 m0, s86
	s_mov_b32 s82, m0
	s_mov_b32 m0, s71
	s_nop 0
	global_load_lds_dwordx4 v1, s[34:35]
	s_mov_b32 m0, s82
	s_nop 0
	s_mov_b32 s82, m0
	s_mov_b32 m0, s74
	s_nop 0
	global_load_lds_dwordx4 v177, s[34:35]
	s_mov_b32 m0, s82
	s_setprio 0
	s_waitcnt vmcnt(8)
	s_waitcnt lgkmcnt(0)
	s_barrier
	s_setprio 1
	s_waitcnt lgkmcnt(7)
	v_mfma_f32_16x16x32_bf16 v[142:145], v[42:45], v[170:173], v[142:145]
	v_mfma_f32_16x16x32_bf16 v[142:145], v[46:49], v[188:191], v[142:145]
	s_waitcnt lgkmcnt(5)
	v_mfma_f32_16x16x32_bf16 v[138:141], v[58:61], v[170:173], v[138:141]
	v_mfma_f32_16x16x32_bf16 v[138:141], v[62:65], v[188:191], v[138:141]
	s_waitcnt lgkmcnt(3)
	v_mfma_f32_16x16x32_bf16 v[126:129], v[42:45], v[192:195], v[126:129]
	v_mfma_f32_16x16x32_bf16 v[126:129], v[46:49], v[196:199], v[126:129]
	s_waitcnt lgkmcnt(1)
	v_mfma_f32_16x16x32_bf16 v[122:125], v[58:61], v[192:195], v[122:125]
	v_mfma_f32_16x16x32_bf16 v[122:125], v[62:65], v[196:199], v[122:125]
	v_mfma_f32_16x16x32_bf16 v[110:113], v[42:45], v[200:203], v[110:113]
	v_mfma_f32_16x16x32_bf16 v[110:113], v[46:49], v[204:207], v[110:113]
	v_mfma_f32_16x16x32_bf16 v[106:109], v[58:61], v[200:203], v[106:109]
	v_mfma_f32_16x16x32_bf16 v[106:109], v[62:65], v[204:207], v[106:109]
	v_mfma_f32_16x16x32_bf16 v[94:97], v[42:45], v[208:211], v[94:97]
	v_mfma_f32_16x16x32_bf16 v[94:97], v[46:49], v[212:215], v[94:97]
	s_waitcnt lgkmcnt(0)
	v_mfma_f32_16x16x32_bf16 v[90:93], v[58:61], v[208:211], v[90:93]
	v_mfma_f32_16x16x32_bf16 v[90:93], v[62:65], v[212:215], v[90:93]
	s_setprio 0
	s_setprio 1
	v_mfma_f32_16x16x32_bf16 v[134:137], v[146:149], v[170:173], v[134:137]
	v_mfma_f32_16x16x32_bf16 v[134:137], v[150:153], v[188:191], v[134:137]
	v_mfma_f32_16x16x32_bf16 v[130:133], v[154:157], v[170:173], v[130:133]
	v_mfma_f32_16x16x32_bf16 v[130:133], v[158:161], v[188:191], v[130:133]
	v_mfma_f32_16x16x32_bf16 v[118:121], v[146:149], v[192:195], v[118:121]
	v_mfma_f32_16x16x32_bf16 v[118:121], v[150:153], v[196:199], v[118:121]
	v_mfma_f32_16x16x32_bf16 v[114:117], v[154:157], v[192:195], v[114:117]
	v_mfma_f32_16x16x32_bf16 v[114:117], v[158:161], v[196:199], v[114:117]
	v_mfma_f32_16x16x32_bf16 v[102:105], v[146:149], v[200:203], v[102:105]
	v_mfma_f32_16x16x32_bf16 v[102:105], v[150:153], v[204:207], v[102:105]
	v_mfma_f32_16x16x32_bf16 v[98:101], v[154:157], v[200:203], v[98:101]
	v_mfma_f32_16x16x32_bf16 v[98:101], v[158:161], v[204:207], v[98:101]
	v_mfma_f32_16x16x32_bf16 v[86:89], v[146:149], v[208:211], v[86:89]
	v_mfma_f32_16x16x32_bf16 v[86:89], v[150:153], v[212:215], v[86:89]
	s_setprio 2
	s_barrier
	v_mfma_f32_16x16x32_bf16 v[82:85], v[154:157], v[208:211], v[82:85]
	v_mfma_f32_16x16x32_bf16 v[82:85], v[158:161], v[212:215], v[82:85]
	s_setprio 0
	s_setprio 3
	ds_read_b128 v[170:173], v183 offset:16384
	ds_read_b128 v[188:191], v183 offset:17408
	ds_read_b128 v[192:195], v183 offset:18432
	ds_read_b128 v[196:199], v183 offset:19456
	ds_read_b128 v[200:203], v183 offset:20480
	ds_read_b128 v[204:207], v183 offset:21504
	ds_read_b128 v[208:211], v183 offset:22528
	ds_read_b128 v[212:215], v183 offset:23552
	s_mov_b32 s82, m0
	s_mov_b32 m0, s49
	s_nop 0
	global_load_lds_dwordx4 v176, s[36:37]
	s_mov_b32 m0, s82
	s_nop 0
	s_mov_b32 s82, m0
	s_mov_b32 m0, s56
	s_nop 0
	global_load_lds_dwordx4 v178, s[36:37]
	s_mov_b32 m0, s82
	s_add_u32 s82, s36, 0x80000
	s_addc_u32 s83, s37, 0
	s_mov_b32 s86, m0
	s_mov_b32 m0, s57
	s_nop 0
	global_load_lds_dwordx4 v176, s[82:83]
	s_mov_b32 m0, s86
	s_nop 0
	s_mov_b32 s86, m0
	s_mov_b32 m0, s58
	s_nop 0
	global_load_lds_dwordx4 v178, s[82:83]
	s_mov_b32 m0, s86
	s_setprio 0
	s_waitcnt vmcnt(4)
	s_waitcnt lgkmcnt(0)
	s_barrier
	s_setprio 1
	s_waitcnt lgkmcnt(7)
	v_mfma_f32_16x16x32_bf16 v[78:81], v[42:45], v[170:173], v[78:81]
	v_mfma_f32_16x16x32_bf16 v[78:81], v[46:49], v[188:191], v[78:81]
	s_waitcnt lgkmcnt(5)
	v_mfma_f32_16x16x32_bf16 v[74:77], v[58:61], v[170:173], v[74:77]
	v_mfma_f32_16x16x32_bf16 v[74:77], v[62:65], v[188:191], v[74:77]
	s_waitcnt lgkmcnt(3)
	v_mfma_f32_16x16x32_bf16 v[54:57], v[42:45], v[192:195], v[54:57]
	v_mfma_f32_16x16x32_bf16 v[54:57], v[46:49], v[196:199], v[54:57]
	s_waitcnt lgkmcnt(1)
	v_mfma_f32_16x16x32_bf16 v[50:53], v[58:61], v[192:195], v[50:53]
	v_mfma_f32_16x16x32_bf16 v[50:53], v[62:65], v[196:199], v[50:53]
	v_mfma_f32_16x16x32_bf16 v[30:33], v[42:45], v[200:203], v[30:33]
	v_mfma_f32_16x16x32_bf16 v[30:33], v[46:49], v[204:207], v[30:33]
	v_mfma_f32_16x16x32_bf16 v[26:29], v[58:61], v[200:203], v[26:29]
	v_mfma_f32_16x16x32_bf16 v[26:29], v[62:65], v[204:207], v[26:29]
	v_mfma_f32_16x16x32_bf16 v[14:17], v[42:45], v[208:211], v[14:17]
	v_mfma_f32_16x16x32_bf16 v[14:17], v[46:49], v[212:215], v[14:17]
	s_waitcnt lgkmcnt(0)
	v_mfma_f32_16x16x32_bf16 v[10:13], v[58:61], v[208:211], v[10:13]
	v_mfma_f32_16x16x32_bf16 v[10:13], v[62:65], v[212:215], v[10:13]
	s_setprio 0
	s_setprio 1
	v_mfma_f32_16x16x32_bf16 v[38:41], v[146:149], v[192:195], v[38:41]
	v_mfma_f32_16x16x32_bf16 v[38:41], v[150:153], v[196:199], v[38:41]
	v_mfma_f32_16x16x32_bf16 v[34:37], v[154:157], v[192:195], v[34:37]
	v_mfma_f32_16x16x32_bf16 v[34:37], v[158:161], v[196:199], v[34:37]
	v_mfma_f32_16x16x32_bf16 v[22:25], v[146:149], v[200:203], v[22:25]
	v_mfma_f32_16x16x32_bf16 v[22:25], v[150:153], v[204:207], v[22:25]
	v_mfma_f32_16x16x32_bf16 v[18:21], v[154:157], v[200:203], v[18:21]
	v_mfma_f32_16x16x32_bf16 v[18:21], v[158:161], v[204:207], v[18:21]
	v_mfma_f32_16x16x32_bf16 v[6:9], v[146:149], v[208:211], v[6:9]
	v_mfma_f32_16x16x32_bf16 v[6:9], v[150:153], v[212:215], v[6:9]
	v_mfma_f32_16x16x32_bf16 v[2:5], v[154:157], v[208:211], v[2:5]
	v_mfma_f32_16x16x32_bf16 v[2:5], v[158:161], v[212:215], v[2:5]
	v_mfma_f32_16x16x32_bf16 v[42:45], v[146:149], v[170:173], v[70:73]
	v_mfma_f32_16x16x32_bf16 v[42:45], v[150:153], v[188:191], v[42:45]
	s_setprio 2
	s_barrier
	v_mfma_f32_16x16x32_bf16 v[46:49], v[154:157], v[170:173], v[66:69]
	v_mfma_f32_16x16x32_bf16 v[46:49], v[158:161], v[188:191], v[46:49]
	s_setprio 0
	s_setprio 3
	ds_read_b128 v[58:61], v184
	ds_read_b128 v[62:65], v184 offset:1024
	ds_read_b128 v[66:69], v184 offset:2048
	ds_read_b128 v[70:73], v184 offset:3072
	ds_read_b128 v[146:149], v185
	ds_read_b128 v[150:153], v185 offset:1024
	ds_read_b128 v[154:157], v185 offset:2048
	ds_read_b128 v[158:161], v185 offset:3072
	ds_read_b128 v[170:173], v183 offset:32768
	ds_read_b128 v[188:191], v183 offset:33792
	ds_read_b128 v[192:195], v183 offset:34816
	ds_read_b128 v[196:199], v183 offset:35840
	ds_read_b128 v[200:203], v183 offset:36864
	ds_read_b128 v[204:207], v183 offset:37888
	ds_read_b128 v[208:211], v183 offset:38912
	ds_read_b128 v[212:215], v183 offset:39936
	s_mov_b32 s82, m0
	s_mov_b32 m0, s48
	s_nop 0
	global_load_lds_dwordx4 v1, s[40:41]
	s_mov_b32 m0, s82
	s_nop 0
	s_mov_b32 s82, m0
	s_mov_b32 m0, s59
	s_nop 0
	global_load_lds_dwordx4 v177, s[40:41]
	s_mov_b32 m0, s82
	s_add_u32 s40, s40, 0x80000
	s_addc_u32 s41, s41, 0
	s_mov_b32 s82, m0
	s_mov_b32 m0, s62
	s_nop 0
	global_load_lds_dwordx4 v1, s[40:41]
	s_mov_b32 m0, s82
	s_nop 0
	s_mov_b32 s82, m0
	s_mov_b32 m0, s63
	s_nop 0
	global_load_lds_dwordx4 v177, s[40:41]
	s_mov_b32 m0, s82
	s_setprio 0
	s_waitcnt vmcnt(8)
	s_waitcnt lgkmcnt(0)
	s_barrier
	s_setprio 1
	s_waitcnt lgkmcnt(7)
	v_mfma_f32_16x16x32_bf16 v[142:145], v[58:61], v[170:173], v[142:145]
	v_mfma_f32_16x16x32_bf16 v[142:145], v[62:65], v[188:191], v[142:145]
	s_waitcnt lgkmcnt(5)
	v_mfma_f32_16x16x32_bf16 v[138:141], v[66:69], v[170:173], v[138:141]
	v_mfma_f32_16x16x32_bf16 v[138:141], v[70:73], v[188:191], v[138:141]
	s_waitcnt lgkmcnt(3)
	v_mfma_f32_16x16x32_bf16 v[126:129], v[58:61], v[192:195], v[126:129]
	v_mfma_f32_16x16x32_bf16 v[126:129], v[62:65], v[196:199], v[126:129]
	s_waitcnt lgkmcnt(1)
	v_mfma_f32_16x16x32_bf16 v[122:125], v[66:69], v[192:195], v[122:125]
	v_mfma_f32_16x16x32_bf16 v[122:125], v[70:73], v[196:199], v[122:125]
	v_mfma_f32_16x16x32_bf16 v[110:113], v[58:61], v[200:203], v[110:113]
	v_mfma_f32_16x16x32_bf16 v[110:113], v[62:65], v[204:207], v[110:113]
	v_mfma_f32_16x16x32_bf16 v[106:109], v[66:69], v[200:203], v[106:109]
	v_mfma_f32_16x16x32_bf16 v[106:109], v[70:73], v[204:207], v[106:109]
	v_mfma_f32_16x16x32_bf16 v[94:97], v[58:61], v[208:211], v[94:97]
	v_mfma_f32_16x16x32_bf16 v[94:97], v[62:65], v[212:215], v[94:97]
	s_waitcnt lgkmcnt(0)
	v_mfma_f32_16x16x32_bf16 v[90:93], v[66:69], v[208:211], v[90:93]
	v_mfma_f32_16x16x32_bf16 v[90:93], v[70:73], v[212:215], v[90:93]
	s_setprio 0
	s_setprio 1
	v_mfma_f32_16x16x32_bf16 v[134:137], v[146:149], v[170:173], v[134:137]
	v_mfma_f32_16x16x32_bf16 v[134:137], v[150:153], v[188:191], v[134:137]
	v_mfma_f32_16x16x32_bf16 v[130:133], v[154:157], v[170:173], v[130:133]
	v_mfma_f32_16x16x32_bf16 v[130:133], v[158:161], v[188:191], v[130:133]
	v_mfma_f32_16x16x32_bf16 v[118:121], v[146:149], v[192:195], v[118:121]
	v_mfma_f32_16x16x32_bf16 v[118:121], v[150:153], v[196:199], v[118:121]
	v_mfma_f32_16x16x32_bf16 v[114:117], v[154:157], v[192:195], v[114:117]
	v_mfma_f32_16x16x32_bf16 v[114:117], v[158:161], v[196:199], v[114:117]
	v_mfma_f32_16x16x32_bf16 v[102:105], v[146:149], v[200:203], v[102:105]
	v_mfma_f32_16x16x32_bf16 v[102:105], v[150:153], v[204:207], v[102:105]
	v_mfma_f32_16x16x32_bf16 v[98:101], v[154:157], v[200:203], v[98:101]
	v_mfma_f32_16x16x32_bf16 v[98:101], v[158:161], v[204:207], v[98:101]
	v_mfma_f32_16x16x32_bf16 v[86:89], v[146:149], v[208:211], v[86:89]
	v_mfma_f32_16x16x32_bf16 v[86:89], v[150:153], v[212:215], v[86:89]
	s_setprio 2
	s_barrier
	v_mfma_f32_16x16x32_bf16 v[82:85], v[154:157], v[208:211], v[82:85]
	v_mfma_f32_16x16x32_bf16 v[82:85], v[158:161], v[212:215], v[82:85]
	s_setprio 0
	s_setprio 3
	ds_read_b128 v[170:173], v183 offset:49152
	ds_read_b128 v[188:191], v183 offset:50176
	ds_read_b128 v[192:195], v183 offset:51200
	ds_read_b128 v[196:199], v183 offset:52224
	ds_read_b128 v[200:203], v183 offset:53248
	ds_read_b128 v[204:207], v183 offset:54272
	ds_read_b128 v[208:211], v183 offset:55296
	ds_read_b128 v[212:215], v183 offset:56320
	s_add_u32 s40, s36, 0x80
	s_addc_u32 s41, s37, 0
	s_mov_b32 s82, m0
	s_mov_b32 m0, s64
	s_nop 0
	global_load_lds_dwordx4 v176, s[40:41]
	s_mov_b32 m0, s82
	s_add_u32 s36, s36, 0x80080
	s_mov_b32 s82, m0
	s_mov_b32 m0, s65
	s_nop 0
	global_load_lds_dwordx4 v178, s[40:41]
	s_mov_b32 m0, s82
	s_addc_u32 s37, s37, 0
	s_mov_b32 s40, m0
	s_mov_b32 m0, s66
	s_nop 0
	global_load_lds_dwordx4 v176, s[36:37]
	s_mov_b32 m0, s40
	s_nop 0
	s_mov_b32 s40, m0
	s_mov_b32 m0, s67
	s_nop 0
	global_load_lds_dwordx4 v178, s[36:37]
	s_mov_b32 m0, s40
	s_setprio 0
	s_waitcnt vmcnt(4)
	s_waitcnt lgkmcnt(0)
	s_barrier
	s_setprio 1
	s_waitcnt lgkmcnt(7)
	v_mfma_f32_16x16x32_bf16 v[78:81], v[58:61], v[170:173], v[78:81]
	v_mfma_f32_16x16x32_bf16 v[78:81], v[62:65], v[188:191], v[78:81]
	s_waitcnt lgkmcnt(5)
	v_mfma_f32_16x16x32_bf16 v[74:77], v[66:69], v[170:173], v[74:77]
	v_mfma_f32_16x16x32_bf16 v[74:77], v[70:73], v[188:191], v[74:77]
	s_waitcnt lgkmcnt(3)
	v_mfma_f32_16x16x32_bf16 v[54:57], v[58:61], v[192:195], v[54:57]
	v_mfma_f32_16x16x32_bf16 v[54:57], v[62:65], v[196:199], v[54:57]
	s_waitcnt lgkmcnt(1)
	v_mfma_f32_16x16x32_bf16 v[50:53], v[66:69], v[192:195], v[50:53]
	v_mfma_f32_16x16x32_bf16 v[50:53], v[70:73], v[196:199], v[50:53]
	v_mfma_f32_16x16x32_bf16 v[30:33], v[58:61], v[200:203], v[30:33]
	v_mfma_f32_16x16x32_bf16 v[30:33], v[62:65], v[204:207], v[30:33]
	v_mfma_f32_16x16x32_bf16 v[26:29], v[66:69], v[200:203], v[26:29]
	v_mfma_f32_16x16x32_bf16 v[26:29], v[70:73], v[204:207], v[26:29]
	v_mfma_f32_16x16x32_bf16 v[14:17], v[58:61], v[208:211], v[14:17]
	v_mfma_f32_16x16x32_bf16 v[14:17], v[62:65], v[212:215], v[14:17]
	s_waitcnt lgkmcnt(0)
	v_mfma_f32_16x16x32_bf16 v[10:13], v[66:69], v[208:211], v[10:13]
	v_mfma_f32_16x16x32_bf16 v[10:13], v[70:73], v[212:215], v[10:13]
	s_setprio 0
	s_setprio 1
	v_mfma_f32_16x16x32_bf16 v[42:45], v[146:149], v[170:173], v[42:45]
	v_mfma_f32_16x16x32_bf16 v[70:73], v[150:153], v[188:191], v[42:45]
	v_mfma_f32_16x16x32_bf16 v[42:45], v[154:157], v[170:173], v[46:49]
	v_mfma_f32_16x16x32_bf16 v[66:69], v[158:161], v[188:191], v[42:45]
	v_mfma_f32_16x16x32_bf16 v[38:41], v[146:149], v[192:195], v[38:41]
	v_mfma_f32_16x16x32_bf16 v[38:41], v[150:153], v[196:199], v[38:41]
	v_mfma_f32_16x16x32_bf16 v[34:37], v[154:157], v[192:195], v[34:37]
	v_mfma_f32_16x16x32_bf16 v[34:37], v[158:161], v[196:199], v[34:37]
	v_mfma_f32_16x16x32_bf16 v[22:25], v[146:149], v[200:203], v[22:25]
	v_mfma_f32_16x16x32_bf16 v[22:25], v[150:153], v[204:207], v[22:25]
	v_mfma_f32_16x16x32_bf16 v[18:21], v[154:157], v[200:203], v[18:21]
	v_mfma_f32_16x16x32_bf16 v[18:21], v[158:161], v[204:207], v[18:21]
	v_mfma_f32_16x16x32_bf16 v[6:9], v[146:149], v[208:211], v[6:9]
	v_mfma_f32_16x16x32_bf16 v[6:9], v[150:153], v[212:215], v[6:9]
	s_setprio 2
	s_barrier
	v_mfma_f32_16x16x32_bf16 v[2:5], v[154:157], v[208:211], v[2:5]
	v_mfma_f32_16x16x32_bf16 v[2:5], v[158:161], v[212:215], v[2:5]
	s_setprio 0
	s_add_i32 s81, s81, 2
	s_add_u32 s77, s77, 0x100
	s_addc_u32 s78, s78, 0
	s_add_u32 s34, s34, 0x100
	s_addc_u32 s35, s35, 0
	s_add_u32 s79, s79, 0x100
	s_addc_u32 s80, s80, 0
	s_cmp_gt_u32 s81, 29
	s_cbranch_scc0 .LBB0_2146
	s_and_b64 vcc, exec, s[14:15]
	s_cbranch_vccz .LBB0_2149
	s_barrier

.LBB0_2409:
	s_ashr_i32 s17, s16, 31
	s_lshl_b64 s[18:19], s[16:17], 20
	s_add_u32 s18, s33, s18
	s_addc_u32 s19, s34, s19
	s_and_b64 s[20:21], s[2:3], exec
	s_cselect_b32 s17, s19, s27
	s_cselect_b32 s71, s18, s26
	s_ashr_i32 s15, s14, 31
	s_lshl_b64 s[20:21], s[14:15], 20
	s_add_u32 s20, s35, s20
	s_addc_u32 s21, s36, s21
	s_and_b64 s[28:29], s[2:3], exec
	s_cselect_b32 s15, s21, s25
	s_cselect_b32 s73, s20, s24
	s_add_u32 s74, s24, 0x100
	s_addc_u32 s75, s25, 0
	s_add_u32 s24, s26, 0x80080
	s_addc_u32 s25, s27, 0
	s_add_u32 s76, s26, 0x100
	s_addc_u32 s77, s27, 0
	s_mov_b32 s78, -2
	s_waitcnt vmcnt(25)
	s_waitcnt vmcnt(24)
	s_waitcnt vmcnt(4)
	s_waitcnt vmcnt(2)
	s_waitcnt vmcnt(1)
	s_waitcnt vmcnt(0)
	s_setprio 3
	ds_read_b128 v[130:133], v181
	ds_read_b128 v[134:137], v181 offset:1024
	ds_read_b128 v[138:141], v181 offset:2048
	ds_read_b128 v[142:145], v181 offset:3072
	ds_read_b128 v[146:149], v182
	ds_read_b128 v[150:153], v182 offset:1024
	ds_read_b128 v[154:157], v182 offset:2048
	ds_read_b128 v[158:161], v182 offset:3072
	s_cmp_eq_u32 s78, 28
	s_cselect_b32 s27, s15, s75
	s_cselect_b32 s26, s73, s74
	s_cselect_b32 s29, s17, s77
	s_cselect_b32 s28, s71, s76
	ds_read_b128 v[166:169], v183
	ds_read_b128 v[170:173], v183 offset:1024
	ds_read_b128 v[186:189], v183 offset:2048
	ds_read_b128 v[190:193], v183 offset:3072
	ds_read_b128 v[194:197], v183 offset:4096
	ds_read_b128 v[198:201], v183 offset:5120
	ds_read_b128 v[202:205], v183 offset:6144
	ds_read_b128 v[206:209], v183 offset:7168
	s_add_u32 s80, s24, 0xfff80000
	s_addc_u32 s81, s25, -1
	s_mov_b32 s79, m0
	s_mov_b32 m0, s64
	s_nop 0
	global_load_lds_dwordx4 v1, s[80:81]
	s_mov_b32 m0, s79
	s_nop 0
	s_mov_b32 s79, m0
	s_mov_b32 m0, s66
	s_nop 0
	global_load_lds_dwordx4 v177, s[80:81]
	s_mov_b32 m0, s79
	s_nop 0
	s_mov_b32 s79, m0
	s_mov_b32 m0, s65
	s_nop 0
	global_load_lds_dwordx4 v1, s[24:25]
	s_mov_b32 m0, s79
	s_nop 0
	s_mov_b32 s79, m0
	s_mov_b32 m0, s67
	s_nop 0
	global_load_lds_dwordx4 v177, s[24:25]
	s_mov_b32 m0, s79
	s_setprio 0
	s_waitcnt vmcnt(8)
	s_waitcnt lgkmcnt(0)
	s_barrier
	s_setprio 1
	s_waitcnt lgkmcnt(7)
	v_mfma_f32_16x16x32_bf16 v[126:129], v[130:133], v[166:169], 0
	v_mfma_f32_16x16x32_bf16 v[126:129], v[134:137], v[170:173], v[126:129]
	s_waitcnt lgkmcnt(5)
	v_mfma_f32_16x16x32_bf16 v[122:125], v[138:141], v[166:169], 0
	v_mfma_f32_16x16x32_bf16 v[122:125], v[142:145], v[170:173], v[122:125]
	s_waitcnt lgkmcnt(3)
	v_mfma_f32_16x16x32_bf16 v[114:117], v[138:141], v[186:189], 0
	v_mfma_f32_16x16x32_bf16 v[114:117], v[142:145], v[190:193], v[114:117]
	s_waitcnt lgkmcnt(1)
	v_mfma_f32_16x16x32_bf16 v[118:121], v[130:133], v[186:189], 0
	v_mfma_f32_16x16x32_bf16 v[118:121], v[134:137], v[190:193], v[118:121]
	v_mfma_f32_16x16x32_bf16 v[94:97], v[130:133], v[194:197], 0
	v_mfma_f32_16x16x32_bf16 v[94:97], v[134:137], v[198:201], v[94:97]
	v_mfma_f32_16x16x32_bf16 v[90:93], v[138:141], v[194:197], 0
	v_mfma_f32_16x16x32_bf16 v[90:93], v[142:145], v[198:201], v[90:93]
	v_mfma_f32_16x16x32_bf16 v[78:81], v[138:141], v[202:205], 0
	v_mfma_f32_16x16x32_bf16 v[78:81], v[142:145], v[206:209], v[78:81]
	s_waitcnt lgkmcnt(0)
	v_mfma_f32_16x16x32_bf16 v[86:89], v[130:133], v[202:205], 0
	v_mfma_f32_16x16x32_bf16 v[86:89], v[134:137], v[206:209], v[86:89]
	s_setprio 0
	s_setprio 1
	v_mfma_f32_16x16x32_bf16 v[110:113], v[146:149], v[166:169], 0
	v_mfma_f32_16x16x32_bf16 v[110:113], v[150:153], v[170:173], v[110:113]
	v_mfma_f32_16x16x32_bf16 v[106:109], v[154:157], v[166:169], 0
	v_mfma_f32_16x16x32_bf16 v[106:109], v[158:161], v[170:173], v[106:109]
	v_mfma_f32_16x16x32_bf16 v[98:101], v[154:157], v[186:189], 0
	v_mfma_f32_16x16x32_bf16 v[98:101], v[158:161], v[190:193], v[98:101]
	v_mfma_f32_16x16x32_bf16 v[102:105], v[146:149], v[186:189], 0
	v_mfma_f32_16x16x32_bf16 v[102:105], v[150:153], v[190:193], v[102:105]
	v_mfma_f32_16x16x32_bf16 v[82:85], v[146:149], v[194:197], 0
	v_mfma_f32_16x16x32_bf16 v[82:85], v[150:153], v[198:201], v[82:85]
	v_mfma_f32_16x16x32_bf16 v[74:77], v[154:157], v[194:197], 0
	v_mfma_f32_16x16x32_bf16 v[74:77], v[158:161], v[198:201], v[74:77]
	v_mfma_f32_16x16x32_bf16 v[66:69], v[154:157], v[202:205], 0
	v_mfma_f32_16x16x32_bf16 v[66:69], v[158:161], v[206:209], v[66:69]
	s_setprio 2
	s_barrier
	v_mfma_f32_16x16x32_bf16 v[70:73], v[146:149], v[202:205], 0
	v_mfma_f32_16x16x32_bf16 v[70:73], v[150:153], v[206:209], v[70:73]
	s_setprio 0
	s_setprio 3
	ds_read_b128 v[166:169], v183 offset:16384
	ds_read_b128 v[170:173], v183 offset:17408
	ds_read_b128 v[186:189], v183 offset:18432
	ds_read_b128 v[190:193], v183 offset:19456
	ds_read_b128 v[194:197], v183 offset:20480
	ds_read_b128 v[198:201], v183 offset:21504
	ds_read_b128 v[202:205], v183 offset:22528
	ds_read_b128 v[206:209], v183 offset:23552
	s_mov_b32 s79, m0
	s_mov_b32 m0, s41
	s_nop 0
	global_load_lds_dwordx4 v176, s[26:27]
	s_mov_b32 m0, s79
	s_add_u32 s80, s26, 0x80000
	s_mov_b32 s79, m0
	s_mov_b32 m0, s42
	s_nop 0
	global_load_lds_dwordx4 v178, s[26:27]
	s_mov_b32 m0, s79
	s_addc_u32 s81, s27, 0
	s_mov_b32 s79, m0
	s_mov_b32 m0, s43
	s_nop 0
	global_load_lds_dwordx4 v176, s[80:81]
	s_mov_b32 m0, s79
	s_nop 0
	s_mov_b32 s79, m0
	s_mov_b32 m0, s46
	s_nop 0
	global_load_lds_dwordx4 v178, s[80:81]
	s_mov_b32 m0, s79
	s_setprio 0
	s_waitcnt vmcnt(4)
	s_waitcnt lgkmcnt(0)
	s_barrier
	s_setprio 1
	s_waitcnt lgkmcnt(7)
	v_mfma_f32_16x16x32_bf16 v[62:65], v[130:133], v[166:169], 0
	v_mfma_f32_16x16x32_bf16 v[62:65], v[134:137], v[170:173], v[62:65]
	s_waitcnt lgkmcnt(5)
	v_mfma_f32_16x16x32_bf16 v[58:61], v[138:141], v[166:169], 0
	v_mfma_f32_16x16x32_bf16 v[58:61], v[142:145], v[170:173], v[58:61]
	s_waitcnt lgkmcnt(3)
	v_mfma_f32_16x16x32_bf16 v[42:45], v[138:141], v[186:189], 0
	v_mfma_f32_16x16x32_bf16 v[42:45], v[142:145], v[190:193], v[42:45]
	s_waitcnt lgkmcnt(1)
	v_mfma_f32_16x16x32_bf16 v[46:49], v[130:133], v[186:189], 0
	v_mfma_f32_16x16x32_bf16 v[46:49], v[134:137], v[190:193], v[46:49]
	v_mfma_f32_16x16x32_bf16 v[30:33], v[130:133], v[194:197], 0
	v_mfma_f32_16x16x32_bf16 v[30:33], v[134:137], v[198:201], v[30:33]
	v_mfma_f32_16x16x32_bf16 v[26:29], v[138:141], v[194:197], 0
	v_mfma_f32_16x16x32_bf16 v[26:29], v[142:145], v[198:201], v[26:29]
	v_mfma_f32_16x16x32_bf16 v[10:13], v[138:141], v[202:205], 0
	v_mfma_f32_16x16x32_bf16 v[10:13], v[142:145], v[206:209], v[10:13]
	s_waitcnt lgkmcnt(0)
	v_mfma_f32_16x16x32_bf16 v[14:17], v[130:133], v[202:205], 0
	v_mfma_f32_16x16x32_bf16 v[14:17], v[134:137], v[206:209], v[14:17]
	s_setprio 0
	s_setprio 1
	v_mfma_f32_16x16x32_bf16 v[54:57], v[146:149], v[166:169], 0
	v_mfma_f32_16x16x32_bf16 v[54:57], v[150:153], v[170:173], v[54:57]
	v_mfma_f32_16x16x32_bf16 v[50:53], v[154:157], v[166:169], 0
	v_mfma_f32_16x16x32_bf16 v[50:53], v[158:161], v[170:173], v[50:53]
	v_mfma_f32_16x16x32_bf16 v[34:37], v[154:157], v[186:189], 0
	v_mfma_f32_16x16x32_bf16 v[34:37], v[158:161], v[190:193], v[34:37]
	v_mfma_f32_16x16x32_bf16 v[38:41], v[146:149], v[186:189], 0
	v_mfma_f32_16x16x32_bf16 v[38:41], v[150:153], v[190:193], v[38:41]
	v_mfma_f32_16x16x32_bf16 v[22:25], v[146:149], v[194:197], 0
	v_mfma_f32_16x16x32_bf16 v[22:25], v[150:153], v[198:201], v[22:25]
	v_mfma_f32_16x16x32_bf16 v[18:21], v[154:157], v[194:197], 0
	v_mfma_f32_16x16x32_bf16 v[18:21], v[158:161], v[198:201], v[18:21]
	v_mfma_f32_16x16x32_bf16 v[2:5], v[154:157], v[202:205], 0
	v_mfma_f32_16x16x32_bf16 v[2:5], v[158:161], v[206:209], v[2:5]
	s_setprio 2
	s_barrier
	v_mfma_f32_16x16x32_bf16 v[6:9], v[146:149], v[202:205], 0
	v_mfma_f32_16x16x32_bf16 v[6:9], v[150:153], v[206:209], v[6:9]
	s_setprio 0
	s_setprio 3
	ds_read_b128 v[130:133], v184
	ds_read_b128 v[134:137], v184 offset:1024
	ds_read_b128 v[138:141], v184 offset:2048
	ds_read_b128 v[142:145], v184 offset:3072
	ds_read_b128 v[146:149], v185
	ds_read_b128 v[150:153], v185 offset:1024
	ds_read_b128 v[154:157], v185 offset:2048
	ds_read_b128 v[158:161], v185 offset:3072
	ds_read_b128 v[166:169], v183 offset:32768
	ds_read_b128 v[170:173], v183 offset:33792
	ds_read_b128 v[186:189], v183 offset:34816
	ds_read_b128 v[190:193], v183 offset:35840
	ds_read_b128 v[194:197], v183 offset:36864
	ds_read_b128 v[198:201], v183 offset:37888
	ds_read_b128 v[202:205], v183 offset:38912
	ds_read_b128 v[206:209], v183 offset:39936
	s_mov_b32 s79, m0
	s_mov_b32 m0, s40
	s_nop 0
	global_load_lds_dwordx4 v1, s[28:29]
	s_mov_b32 m0, s79
	s_nop 0
	s_mov_b32 s79, m0
	s_mov_b32 m0, s47
	s_nop 0
	global_load_lds_dwordx4 v177, s[28:29]
	s_mov_b32 m0, s79
	s_add_u32 s28, s28, 0x80000
	s_addc_u32 s29, s29, 0
	s_mov_b32 s79, m0
	s_mov_b32 m0, s48
	s_nop 0
	global_load_lds_dwordx4 v1, s[28:29]
	s_mov_b32 m0, s79
	s_nop 0
	s_mov_b32 s79, m0
	s_mov_b32 m0, s49
	s_nop 0
	global_load_lds_dwordx4 v177, s[28:29]
	s_mov_b32 m0, s79
	s_setprio 0
	s_waitcnt vmcnt(8)
	s_waitcnt lgkmcnt(0)
	s_barrier
	s_setprio 1
	s_waitcnt lgkmcnt(7)
	v_mfma_f32_16x16x32_bf16 v[126:129], v[130:133], v[166:169], v[126:129]
	v_mfma_f32_16x16x32_bf16 v[126:129], v[134:137], v[170:173], v[126:129]
	s_waitcnt lgkmcnt(5)
	v_mfma_f32_16x16x32_bf16 v[122:125], v[138:141], v[166:169], v[122:125]
	v_mfma_f32_16x16x32_bf16 v[122:125], v[142:145], v[170:173], v[122:125]
	s_waitcnt lgkmcnt(3)
	v_mfma_f32_16x16x32_bf16 v[114:117], v[138:141], v[186:189], v[114:117]
	v_mfma_f32_16x16x32_bf16 v[114:117], v[142:145], v[190:193], v[114:117]
	s_waitcnt lgkmcnt(1)
	v_mfma_f32_16x16x32_bf16 v[118:121], v[130:133], v[186:189], v[118:121]
	v_mfma_f32_16x16x32_bf16 v[118:121], v[134:137], v[190:193], v[118:121]
	v_mfma_f32_16x16x32_bf16 v[94:97], v[130:133], v[194:197], v[94:97]
	v_mfma_f32_16x16x32_bf16 v[94:97], v[134:137], v[198:201], v[94:97]
	v_mfma_f32_16x16x32_bf16 v[90:93], v[138:141], v[194:197], v[90:93]
	v_mfma_f32_16x16x32_bf16 v[90:93], v[142:145], v[198:201], v[90:93]
	v_mfma_f32_16x16x32_bf16 v[78:81], v[138:141], v[202:205], v[78:81]
	v_mfma_f32_16x16x32_bf16 v[78:81], v[142:145], v[206:209], v[78:81]
	s_waitcnt lgkmcnt(0)
	v_mfma_f32_16x16x32_bf16 v[86:89], v[130:133], v[202:205], v[86:89]
	v_mfma_f32_16x16x32_bf16 v[86:89], v[134:137], v[206:209], v[86:89]
	s_setprio 0
	s_setprio 1
	v_mfma_f32_16x16x32_bf16 v[110:113], v[146:149], v[166:169], v[110:113]
	v_mfma_f32_16x16x32_bf16 v[110:113], v[150:153], v[170:173], v[110:113]
	v_mfma_f32_16x16x32_bf16 v[106:109], v[154:157], v[166:169], v[106:109]
	v_mfma_f32_16x16x32_bf16 v[106:109], v[158:161], v[170:173], v[106:109]
	v_mfma_f32_16x16x32_bf16 v[98:101], v[154:157], v[186:189], v[98:101]
	v_mfma_f32_16x16x32_bf16 v[98:101], v[158:161], v[190:193], v[98:101]
	v_mfma_f32_16x16x32_bf16 v[102:105], v[146:149], v[186:189], v[102:105]
	v_mfma_f32_16x16x32_bf16 v[102:105], v[150:153], v[190:193], v[102:105]
	v_mfma_f32_16x16x32_bf16 v[82:85], v[146:149], v[194:197], v[82:85]
	v_mfma_f32_16x16x32_bf16 v[82:85], v[150:153], v[198:201], v[82:85]
	v_mfma_f32_16x16x32_bf16 v[74:77], v[154:157], v[194:197], v[74:77]
	v_mfma_f32_16x16x32_bf16 v[74:77], v[158:161], v[198:201], v[74:77]
	v_mfma_f32_16x16x32_bf16 v[66:69], v[154:157], v[202:205], v[66:69]
	v_mfma_f32_16x16x32_bf16 v[66:69], v[158:161], v[206:209], v[66:69]
	s_setprio 2
	s_barrier
	v_mfma_f32_16x16x32_bf16 v[70:73], v[146:149], v[202:205], v[70:73]
	v_mfma_f32_16x16x32_bf16 v[70:73], v[150:153], v[206:209], v[70:73]
	s_setprio 0
	s_setprio 3
	ds_read_b128 v[166:169], v183 offset:49152
	ds_read_b128 v[170:173], v183 offset:50176
	ds_read_b128 v[186:189], v183 offset:51200
	ds_read_b128 v[190:193], v183 offset:52224
	ds_read_b128 v[194:197], v183 offset:53248
	ds_read_b128 v[198:201], v183 offset:54272
	ds_read_b128 v[202:205], v183 offset:55296
	ds_read_b128 v[206:209], v183 offset:56320
	s_add_u32 s28, s26, 0x80
	s_addc_u32 s29, s27, 0
	s_mov_b32 s79, m0
	s_mov_b32 m0, s56
	s_nop 0
	global_load_lds_dwordx4 v176, s[28:29]
	s_mov_b32 m0, s79
	s_add_u32 s26, s26, 0x80080
	s_mov_b32 s79, m0
	s_mov_b32 m0, s57
	s_nop 0
	global_load_lds_dwordx4 v178, s[28:29]
	s_mov_b32 m0, s79
	s_addc_u32 s27, s27, 0
	s_mov_b32 s28, m0
	s_mov_b32 m0, s58
	s_nop 0
	global_load_lds_dwordx4 v176, s[26:27]
	s_mov_b32 m0, s28
	s_nop 0
	s_mov_b32 s28, m0
	s_mov_b32 m0, s59
	s_nop 0
	global_load_lds_dwordx4 v178, s[26:27]
	s_mov_b32 m0, s28
	s_setprio 0
	s_waitcnt vmcnt(4)
	s_waitcnt lgkmcnt(0)
	s_barrier
	s_setprio 1
	s_waitcnt lgkmcnt(7)
	v_mfma_f32_16x16x32_bf16 v[62:65], v[130:133], v[166:169], v[62:65]
	v_mfma_f32_16x16x32_bf16 v[62:65], v[134:137], v[170:173], v[62:65]
	s_waitcnt lgkmcnt(5)
	v_mfma_f32_16x16x32_bf16 v[58:61], v[138:141], v[166:169], v[58:61]
	v_mfma_f32_16x16x32_bf16 v[58:61], v[142:145], v[170:173], v[58:61]
	s_waitcnt lgkmcnt(3)
	v_mfma_f32_16x16x32_bf16 v[42:45], v[138:141], v[186:189], v[42:45]
	v_mfma_f32_16x16x32_bf16 v[42:45], v[142:145], v[190:193], v[42:45]
	s_waitcnt lgkmcnt(1)
	v_mfma_f32_16x16x32_bf16 v[46:49], v[130:133], v[186:189], v[46:49]
	v_mfma_f32_16x16x32_bf16 v[46:49], v[134:137], v[190:193], v[46:49]
	v_mfma_f32_16x16x32_bf16 v[30:33], v[130:133], v[194:197], v[30:33]
	v_mfma_f32_16x16x32_bf16 v[30:33], v[134:137], v[198:201], v[30:33]
	v_mfma_f32_16x16x32_bf16 v[26:29], v[138:141], v[194:197], v[26:29]
	v_mfma_f32_16x16x32_bf16 v[26:29], v[142:145], v[198:201], v[26:29]
	v_mfma_f32_16x16x32_bf16 v[10:13], v[138:141], v[202:205], v[10:13]
	v_mfma_f32_16x16x32_bf16 v[10:13], v[142:145], v[206:209], v[10:13]
	s_waitcnt lgkmcnt(0)
	v_mfma_f32_16x16x32_bf16 v[14:17], v[130:133], v[202:205], v[14:17]
	v_mfma_f32_16x16x32_bf16 v[14:17], v[134:137], v[206:209], v[14:17]
	s_setprio 0
	s_setprio 1
	v_mfma_f32_16x16x32_bf16 v[54:57], v[146:149], v[166:169], v[54:57]
	v_mfma_f32_16x16x32_bf16 v[54:57], v[150:153], v[170:173], v[54:57]
	v_mfma_f32_16x16x32_bf16 v[50:53], v[154:157], v[166:169], v[50:53]
	v_mfma_f32_16x16x32_bf16 v[50:53], v[158:161], v[170:173], v[50:53]
	v_mfma_f32_16x16x32_bf16 v[34:37], v[154:157], v[186:189], v[34:37]
	v_mfma_f32_16x16x32_bf16 v[34:37], v[158:161], v[190:193], v[34:37]
	v_mfma_f32_16x16x32_bf16 v[38:41], v[146:149], v[186:189], v[38:41]
	v_mfma_f32_16x16x32_bf16 v[38:41], v[150:153], v[190:193], v[38:41]
	v_mfma_f32_16x16x32_bf16 v[22:25], v[146:149], v[194:197], v[22:25]
	v_mfma_f32_16x16x32_bf16 v[22:25], v[150:153], v[198:201], v[22:25]
	v_mfma_f32_16x16x32_bf16 v[18:21], v[154:157], v[194:197], v[18:21]
	v_mfma_f32_16x16x32_bf16 v[18:21], v[158:161], v[198:201], v[18:21]
	v_mfma_f32_16x16x32_bf16 v[2:5], v[154:157], v[202:205], v[2:5]
	v_mfma_f32_16x16x32_bf16 v[2:5], v[158:161], v[206:209], v[2:5]
	s_setprio 2
	s_barrier
	v_mfma_f32_16x16x32_bf16 v[6:9], v[146:149], v[202:205], v[6:9]
	v_mfma_f32_16x16x32_bf16 v[6:9], v[150:153], v[206:209], v[6:9]
	s_setprio 0
	s_add_i32 s78, s78, 2
	s_add_u32 s74, s74, 0x100
	s_addc_u32 s75, s75, 0
	s_add_u32 s24, s24, 0x100
	s_addc_u32 s25, s25, 0
	s_add_u32 s76, s76, 0x100
	s_addc_u32 s77, s77, 0
	s_cmp_gt_u32 s78, 29
	.p2align 6
.LBB0_2410:
	s_setprio 3
	ds_read_b128 v[130:133], v181
	ds_read_b128 v[134:137], v181 offset:1024
	ds_read_b128 v[138:141], v181 offset:2048
	ds_read_b128 v[142:145], v181 offset:3072
	ds_read_b128 v[146:149], v182
	ds_read_b128 v[150:153], v182 offset:1024
	ds_read_b128 v[154:157], v182 offset:2048
	ds_read_b128 v[158:161], v182 offset:3072
	s_cmp_eq_u32 s78, 28
	s_cselect_b32 s27, s15, s75
	s_cselect_b32 s26, s73, s74
	s_cselect_b32 s29, s17, s77
	s_cselect_b32 s28, s71, s76
	ds_read_b128 v[166:169], v183
	ds_read_b128 v[170:173], v183 offset:1024
	ds_read_b128 v[186:189], v183 offset:2048
	ds_read_b128 v[190:193], v183 offset:3072
	ds_read_b128 v[194:197], v183 offset:4096
	ds_read_b128 v[198:201], v183 offset:5120
	ds_read_b128 v[202:205], v183 offset:6144
	ds_read_b128 v[206:209], v183 offset:7168
	s_add_u32 s80, s24, 0xfff80000
	s_addc_u32 s81, s25, -1
	s_mov_b32 s79, m0
	s_mov_b32 m0, s64
	s_nop 0
	global_load_lds_dwordx4 v1, s[80:81]
	s_mov_b32 m0, s79
	s_nop 0
	s_mov_b32 s79, m0
	s_mov_b32 m0, s66
	s_nop 0
	global_load_lds_dwordx4 v177, s[80:81]
	s_mov_b32 m0, s79
	s_nop 0
	s_mov_b32 s79, m0
	s_mov_b32 m0, s65
	s_nop 0
	global_load_lds_dwordx4 v1, s[24:25]
	s_mov_b32 m0, s79
	s_nop 0
	s_mov_b32 s79, m0
	s_mov_b32 m0, s67
	s_nop 0
	global_load_lds_dwordx4 v177, s[24:25]
	s_mov_b32 m0, s79
	s_setprio 0
	s_waitcnt vmcnt(8)
	s_waitcnt lgkmcnt(0)
	s_barrier
	s_setprio 1
	s_waitcnt lgkmcnt(7)
	v_mfma_f32_16x16x32_bf16 v[126:129], v[130:133], v[166:169], v[126:129]
	v_mfma_f32_16x16x32_bf16 v[126:129], v[134:137], v[170:173], v[126:129]
	s_waitcnt lgkmcnt(5)
	v_mfma_f32_16x16x32_bf16 v[122:125], v[138:141], v[166:169], v[122:125]
	v_mfma_f32_16x16x32_bf16 v[122:125], v[142:145], v[170:173], v[122:125]
	s_waitcnt lgkmcnt(3)
	v_mfma_f32_16x16x32_bf16 v[114:117], v[138:141], v[186:189], v[114:117]
	v_mfma_f32_16x16x32_bf16 v[114:117], v[142:145], v[190:193], v[114:117]
	s_waitcnt lgkmcnt(1)
	v_mfma_f32_16x16x32_bf16 v[118:121], v[130:133], v[186:189], v[118:121]
	v_mfma_f32_16x16x32_bf16 v[118:121], v[134:137], v[190:193], v[118:121]
	v_mfma_f32_16x16x32_bf16 v[94:97], v[130:133], v[194:197], v[94:97]
	v_mfma_f32_16x16x32_bf16 v[94:97], v[134:137], v[198:201], v[94:97]
	v_mfma_f32_16x16x32_bf16 v[90:93], v[138:141], v[194:197], v[90:93]
	v_mfma_f32_16x16x32_bf16 v[90:93], v[142:145], v[198:201], v[90:93]
	v_mfma_f32_16x16x32_bf16 v[78:81], v[138:141], v[202:205], v[78:81]
	v_mfma_f32_16x16x32_bf16 v[78:81], v[142:145], v[206:209], v[78:81]
	s_waitcnt lgkmcnt(0)
	v_mfma_f32_16x16x32_bf16 v[86:89], v[130:133], v[202:205], v[86:89]
	v_mfma_f32_16x16x32_bf16 v[86:89], v[134:137], v[206:209], v[86:89]
	s_setprio 0
	s_setprio 1
	v_mfma_f32_16x16x32_bf16 v[110:113], v[146:149], v[166:169], v[110:113]
	v_mfma_f32_16x16x32_bf16 v[110:113], v[150:153], v[170:173], v[110:113]
	v_mfma_f32_16x16x32_bf16 v[106:109], v[154:157], v[166:169], v[106:109]
	v_mfma_f32_16x16x32_bf16 v[106:109], v[158:161], v[170:173], v[106:109]
	v_mfma_f32_16x16x32_bf16 v[98:101], v[154:157], v[186:189], v[98:101]
	v_mfma_f32_16x16x32_bf16 v[98:101], v[158:161], v[190:193], v[98:101]
	v_mfma_f32_16x16x32_bf16 v[102:105], v[146:149], v[186:189], v[102:105]
	v_mfma_f32_16x16x32_bf16 v[102:105], v[150:153], v[190:193], v[102:105]
	v_mfma_f32_16x16x32_bf16 v[82:85], v[146:149], v[194:197], v[82:85]
	v_mfma_f32_16x16x32_bf16 v[82:85], v[150:153], v[198:201], v[82:85]
	v_mfma_f32_16x16x32_bf16 v[74:77], v[154:157], v[194:197], v[74:77]
	v_mfma_f32_16x16x32_bf16 v[74:77], v[158:161], v[198:201], v[74:77]
	v_mfma_f32_16x16x32_bf16 v[66:69], v[154:157], v[202:205], v[66:69]
	v_mfma_f32_16x16x32_bf16 v[66:69], v[158:161], v[206:209], v[66:69]
	s_setprio 2
	s_barrier
	v_mfma_f32_16x16x32_bf16 v[70:73], v[146:149], v[202:205], v[70:73]
	v_mfma_f32_16x16x32_bf16 v[70:73], v[150:153], v[206:209], v[70:73]
	s_setprio 0
	s_setprio 3
	ds_read_b128 v[166:169], v183 offset:16384
	ds_read_b128 v[170:173], v183 offset:17408
	ds_read_b128 v[186:189], v183 offset:18432
	ds_read_b128 v[190:193], v183 offset:19456
	ds_read_b128 v[194:197], v183 offset:20480
	ds_read_b128 v[198:201], v183 offset:21504
	ds_read_b128 v[202:205], v183 offset:22528
	ds_read_b128 v[206:209], v183 offset:23552
	s_mov_b32 s79, m0
	s_mov_b32 m0, s41
	s_nop 0
	global_load_lds_dwordx4 v176, s[26:27]
	s_mov_b32 m0, s79
	s_add_u32 s80, s26, 0x80000
	s_mov_b32 s79, m0
	s_mov_b32 m0, s42
	s_nop 0
	global_load_lds_dwordx4 v178, s[26:27]
	s_mov_b32 m0, s79
	s_addc_u32 s81, s27, 0
	s_mov_b32 s79, m0
	s_mov_b32 m0, s43
	s_nop 0
	global_load_lds_dwordx4 v176, s[80:81]
	s_mov_b32 m0, s79
	s_nop 0
	s_mov_b32 s79, m0
	s_mov_b32 m0, s46
	s_nop 0
	global_load_lds_dwordx4 v178, s[80:81]
	s_mov_b32 m0, s79
	s_setprio 0
	s_waitcnt vmcnt(4)
	s_waitcnt lgkmcnt(0)
	s_barrier
	s_setprio 1
	s_waitcnt lgkmcnt(7)
	v_mfma_f32_16x16x32_bf16 v[62:65], v[130:133], v[166:169], v[62:65]
	v_mfma_f32_16x16x32_bf16 v[62:65], v[134:137], v[170:173], v[62:65]
	s_waitcnt lgkmcnt(5)
	v_mfma_f32_16x16x32_bf16 v[58:61], v[138:141], v[166:169], v[58:61]
	v_mfma_f32_16x16x32_bf16 v[58:61], v[142:145], v[170:173], v[58:61]
	s_waitcnt lgkmcnt(3)
	v_mfma_f32_16x16x32_bf16 v[42:45], v[138:141], v[186:189], v[42:45]
	v_mfma_f32_16x16x32_bf16 v[42:45], v[142:145], v[190:193], v[42:45]
	s_waitcnt lgkmcnt(1)
	v_mfma_f32_16x16x32_bf16 v[46:49], v[130:133], v[186:189], v[46:49]
	v_mfma_f32_16x16x32_bf16 v[46:49], v[134:137], v[190:193], v[46:49]
	v_mfma_f32_16x16x32_bf16 v[30:33], v[130:133], v[194:197], v[30:33]
	v_mfma_f32_16x16x32_bf16 v[30:33], v[134:137], v[198:201], v[30:33]
	v_mfma_f32_16x16x32_bf16 v[26:29], v[138:141], v[194:197], v[26:29]
	v_mfma_f32_16x16x32_bf16 v[26:29], v[142:145], v[198:201], v[26:29]
	v_mfma_f32_16x16x32_bf16 v[10:13], v[138:141], v[202:205], v[10:13]
	v_mfma_f32_16x16x32_bf16 v[10:13], v[142:145], v[206:209], v[10:13]
	s_waitcnt lgkmcnt(0)
	v_mfma_f32_16x16x32_bf16 v[14:17], v[130:133], v[202:205], v[14:17]
	v_mfma_f32_16x16x32_bf16 v[14:17], v[134:137], v[206:209], v[14:17]
	s_setprio 0
	s_setprio 1
	v_mfma_f32_16x16x32_bf16 v[54:57], v[146:149], v[166:169], v[54:57]
	v_mfma_f32_16x16x32_bf16 v[54:57], v[150:153], v[170:173], v[54:57]
	v_mfma_f32_16x16x32_bf16 v[50:53], v[154:157], v[166:169], v[50:53]
	v_mfma_f32_16x16x32_bf16 v[50:53], v[158:161], v[170:173], v[50:53]
	v_mfma_f32_16x16x32_bf16 v[34:37], v[154:157], v[186:189], v[34:37]
	v_mfma_f32_16x16x32_bf16 v[34:37], v[158:161], v[190:193], v[34:37]
	v_mfma_f32_16x16x32_bf16 v[38:41], v[146:149], v[186:189], v[38:41]
	v_mfma_f32_16x16x32_bf16 v[38:41], v[150:153], v[190:193], v[38:41]
	v_mfma_f32_16x16x32_bf16 v[22:25], v[146:149], v[194:197], v[22:25]
	v_mfma_f32_16x16x32_bf16 v[22:25], v[150:153], v[198:201], v[22:25]
	v_mfma_f32_16x16x32_bf16 v[18:21], v[154:157], v[194:197], v[18:21]
	v_mfma_f32_16x16x32_bf16 v[18:21], v[158:161], v[198:201], v[18:21]
	v_mfma_f32_16x16x32_bf16 v[2:5], v[154:157], v[202:205], v[2:5]
	v_mfma_f32_16x16x32_bf16 v[2:5], v[158:161], v[206:209], v[2:5]
	s_setprio 2
	s_barrier
	v_mfma_f32_16x16x32_bf16 v[6:9], v[146:149], v[202:205], v[6:9]
	v_mfma_f32_16x16x32_bf16 v[6:9], v[150:153], v[206:209], v[6:9]
	s_setprio 0
	s_setprio 3
	ds_read_b128 v[130:133], v184
	ds_read_b128 v[134:137], v184 offset:1024
	ds_read_b128 v[138:141], v184 offset:2048
	ds_read_b128 v[142:145], v184 offset:3072
	ds_read_b128 v[146:149], v185
	ds_read_b128 v[150:153], v185 offset:1024
	ds_read_b128 v[154:157], v185 offset:2048
	ds_read_b128 v[158:161], v185 offset:3072
	ds_read_b128 v[166:169], v183 offset:32768
	ds_read_b128 v[170:173], v183 offset:33792
	ds_read_b128 v[186:189], v183 offset:34816
	ds_read_b128 v[190:193], v183 offset:35840
	ds_read_b128 v[194:197], v183 offset:36864
	ds_read_b128 v[198:201], v183 offset:37888
	ds_read_b128 v[202:205], v183 offset:38912
	ds_read_b128 v[206:209], v183 offset:39936
	s_mov_b32 s79, m0
	s_mov_b32 m0, s40
	s_nop 0
	global_load_lds_dwordx4 v1, s[28:29]
	s_mov_b32 m0, s79
	s_nop 0
	s_mov_b32 s79, m0
	s_mov_b32 m0, s47
	s_nop 0
	global_load_lds_dwordx4 v177, s[28:29]
	s_mov_b32 m0, s79
	s_add_u32 s28, s28, 0x80000
	s_addc_u32 s29, s29, 0
	s_mov_b32 s79, m0
	s_mov_b32 m0, s48
	s_nop 0
	global_load_lds_dwordx4 v1, s[28:29]
	s_mov_b32 m0, s79
	s_nop 0
	s_mov_b32 s79, m0
	s_mov_b32 m0, s49
	s_nop 0
	global_load_lds_dwordx4 v177, s[28:29]
	s_mov_b32 m0, s79
	s_setprio 0
	s_waitcnt vmcnt(8)
	s_waitcnt lgkmcnt(0)
	s_barrier
	s_setprio 1
	s_waitcnt lgkmcnt(7)
	v_mfma_f32_16x16x32_bf16 v[126:129], v[130:133], v[166:169], v[126:129]
	v_mfma_f32_16x16x32_bf16 v[126:129], v[134:137], v[170:173], v[126:129]
	s_waitcnt lgkmcnt(5)
	v_mfma_f32_16x16x32_bf16 v[122:125], v[138:141], v[166:169], v[122:125]
	v_mfma_f32_16x16x32_bf16 v[122:125], v[142:145], v[170:173], v[122:125]
	s_waitcnt lgkmcnt(3)
	v_mfma_f32_16x16x32_bf16 v[114:117], v[138:141], v[186:189], v[114:117]
	v_mfma_f32_16x16x32_bf16 v[114:117], v[142:145], v[190:193], v[114:117]
	s_waitcnt lgkmcnt(1)
	v_mfma_f32_16x16x32_bf16 v[118:121], v[130:133], v[186:189], v[118:121]
	v_mfma_f32_16x16x32_bf16 v[118:121], v[134:137], v[190:193], v[118:121]
	v_mfma_f32_16x16x32_bf16 v[94:97], v[130:133], v[194:197], v[94:97]
	v_mfma_f32_16x16x32_bf16 v[94:97], v[134:137], v[198:201], v[94:97]
	v_mfma_f32_16x16x32_bf16 v[90:93], v[138:141], v[194:197], v[90:93]
	v_mfma_f32_16x16x32_bf16 v[90:93], v[142:145], v[198:201], v[90:93]
	v_mfma_f32_16x16x32_bf16 v[78:81], v[138:141], v[202:205], v[78:81]
	v_mfma_f32_16x16x32_bf16 v[78:81], v[142:145], v[206:209], v[78:81]
	s_waitcnt lgkmcnt(0)
	v_mfma_f32_16x16x32_bf16 v[86:89], v[130:133], v[202:205], v[86:89]
	v_mfma_f32_16x16x32_bf16 v[86:89], v[134:137], v[206:209], v[86:89]
	s_setprio 0
	s_setprio 1
	v_mfma_f32_16x16x32_bf16 v[110:113], v[146:149], v[166:169], v[110:113]
	v_mfma_f32_16x16x32_bf16 v[110:113], v[150:153], v[170:173], v[110:113]
	v_mfma_f32_16x16x32_bf16 v[106:109], v[154:157], v[166:169], v[106:109]
	v_mfma_f32_16x16x32_bf16 v[106:109], v[158:161], v[170:173], v[106:109]
	v_mfma_f32_16x16x32_bf16 v[98:101], v[154:157], v[186:189], v[98:101]
	v_mfma_f32_16x16x32_bf16 v[98:101], v[158:161], v[190:193], v[98:101]
	v_mfma_f32_16x16x32_bf16 v[102:105], v[146:149], v[186:189], v[102:105]
	v_mfma_f32_16x16x32_bf16 v[102:105], v[150:153], v[190:193], v[102:105]
	v_mfma_f32_16x16x32_bf16 v[82:85], v[146:149], v[194:197], v[82:85]
	v_mfma_f32_16x16x32_bf16 v[82:85], v[150:153], v[198:201], v[82:85]
	v_mfma_f32_16x16x32_bf16 v[74:77], v[154:157], v[194:197], v[74:77]
	v_mfma_f32_16x16x32_bf16 v[74:77], v[158:161], v[198:201], v[74:77]
	v_mfma_f32_16x16x32_bf16 v[66:69], v[154:157], v[202:205], v[66:69]
	v_mfma_f32_16x16x32_bf16 v[66:69], v[158:161], v[206:209], v[66:69]
	s_setprio 2
	s_barrier
	v_mfma_f32_16x16x32_bf16 v[70:73], v[146:149], v[202:205], v[70:73]
	v_mfma_f32_16x16x32_bf16 v[70:73], v[150:153], v[206:209], v[70:73]
	s_setprio 0
	s_setprio 3
	ds_read_b128 v[166:169], v183 offset:49152
	ds_read_b128 v[170:173], v183 offset:50176
	ds_read_b128 v[186:189], v183 offset:51200
	ds_read_b128 v[190:193], v183 offset:52224
	ds_read_b128 v[194:197], v183 offset:53248
	ds_read_b128 v[198:201], v183 offset:54272
	ds_read_b128 v[202:205], v183 offset:55296
	ds_read_b128 v[206:209], v183 offset:56320
	s_add_u32 s28, s26, 0x80
	s_addc_u32 s29, s27, 0
	s_mov_b32 s79, m0
	s_mov_b32 m0, s56
	s_nop 0
	global_load_lds_dwordx4 v176, s[28:29]
	s_mov_b32 m0, s79
	s_add_u32 s26, s26, 0x80080
	s_mov_b32 s79, m0
	s_mov_b32 m0, s57
	s_nop 0
	global_load_lds_dwordx4 v178, s[28:29]
	s_mov_b32 m0, s79
	s_addc_u32 s27, s27, 0
	s_mov_b32 s28, m0
	s_mov_b32 m0, s58
	s_nop 0
	global_load_lds_dwordx4 v176, s[26:27]
	s_mov_b32 m0, s28
	s_nop 0
	s_mov_b32 s28, m0
	s_mov_b32 m0, s59
	s_nop 0
	global_load_lds_dwordx4 v178, s[26:27]
	s_mov_b32 m0, s28
	s_setprio 0
	s_waitcnt vmcnt(4)
	s_waitcnt lgkmcnt(0)
	s_barrier
	s_setprio 1
	s_waitcnt lgkmcnt(7)
	v_mfma_f32_16x16x32_bf16 v[62:65], v[130:133], v[166:169], v[62:65]
	v_mfma_f32_16x16x32_bf16 v[62:65], v[134:137], v[170:173], v[62:65]
	s_waitcnt lgkmcnt(5)
	v_mfma_f32_16x16x32_bf16 v[58:61], v[138:141], v[166:169], v[58:61]
	v_mfma_f32_16x16x32_bf16 v[58:61], v[142:145], v[170:173], v[58:61]
	s_waitcnt lgkmcnt(3)
	v_mfma_f32_16x16x32_bf16 v[42:45], v[138:141], v[186:189], v[42:45]
	v_mfma_f32_16x16x32_bf16 v[42:45], v[142:145], v[190:193], v[42:45]
	s_waitcnt lgkmcnt(1)
	v_mfma_f32_16x16x32_bf16 v[46:49], v[130:133], v[186:189], v[46:49]
	v_mfma_f32_16x16x32_bf16 v[46:49], v[134:137], v[190:193], v[46:49]
	v_mfma_f32_16x16x32_bf16 v[30:33], v[130:133], v[194:197], v[30:33]
	v_mfma_f32_16x16x32_bf16 v[30:33], v[134:137], v[198:201], v[30:33]
	v_mfma_f32_16x16x32_bf16 v[26:29], v[138:141], v[194:197], v[26:29]
	v_mfma_f32_16x16x32_bf16 v[26:29], v[142:145], v[198:201], v[26:29]
	v_mfma_f32_16x16x32_bf16 v[10:13], v[138:141], v[202:205], v[10:13]
	v_mfma_f32_16x16x32_bf16 v[10:13], v[142:145], v[206:209], v[10:13]
	s_waitcnt lgkmcnt(0)
	v_mfma_f32_16x16x32_bf16 v[14:17], v[130:133], v[202:205], v[14:17]
	v_mfma_f32_16x16x32_bf16 v[14:17], v[134:137], v[206:209], v[14:17]
	s_setprio 0
	s_setprio 1
	v_mfma_f32_16x16x32_bf16 v[54:57], v[146:149], v[166:169], v[54:57]
	v_mfma_f32_16x16x32_bf16 v[54:57], v[150:153], v[170:173], v[54:57]
	v_mfma_f32_16x16x32_bf16 v[50:53], v[154:157], v[166:169], v[50:53]
	v_mfma_f32_16x16x32_bf16 v[50:53], v[158:161], v[170:173], v[50:53]
	v_mfma_f32_16x16x32_bf16 v[34:37], v[154:157], v[186:189], v[34:37]
	v_mfma_f32_16x16x32_bf16 v[34:37], v[158:161], v[190:193], v[34:37]
	v_mfma_f32_16x16x32_bf16 v[38:41], v[146:149], v[186:189], v[38:41]
	v_mfma_f32_16x16x32_bf16 v[38:41], v[150:153], v[190:193], v[38:41]
	v_mfma_f32_16x16x32_bf16 v[22:25], v[146:149], v[194:197], v[22:25]
	v_mfma_f32_16x16x32_bf16 v[22:25], v[150:153], v[198:201], v[22:25]
	v_mfma_f32_16x16x32_bf16 v[18:21], v[154:157], v[194:197], v[18:21]
	v_mfma_f32_16x16x32_bf16 v[18:21], v[158:161], v[198:201], v[18:21]
	v_mfma_f32_16x16x32_bf16 v[2:5], v[154:157], v[202:205], v[2:5]
	v_mfma_f32_16x16x32_bf16 v[2:5], v[158:161], v[206:209], v[2:5]
	s_setprio 2
	s_barrier
	v_mfma_f32_16x16x32_bf16 v[6:9], v[146:149], v[202:205], v[6:9]
	v_mfma_f32_16x16x32_bf16 v[6:9], v[150:153], v[206:209], v[6:9]
	s_setprio 0
	s_add_i32 s78, s78, 2
	s_add_u32 s74, s74, 0x100
	s_addc_u32 s75, s75, 0
	s_add_u32 s24, s24, 0x100
	s_addc_u32 s25, s25, 0
	s_add_u32 s76, s76, 0x100
	s_addc_u32 s77, s77, 0
	s_cmp_gt_u32 s78, 29
	s_cbranch_scc0 .LBB0_2410
	s_and_b64 vcc, exec, s[8:9]
	s_cbranch_vccz .LBB0_2413
	s_barrier

.LBB0_2593:
	s_ashr_i32 s11, s10, 31
	s_lshl_b64 s[12:13], s[10:11], 20
	s_add_u32 s12, s26, s12
	s_addc_u32 s13, s27, s13
	s_and_b64 s[14:15], s[2:3], exec
	s_cselect_b32 s11, s13, s21
	s_cselect_b32 s62, s12, s20
	s_ashr_i32 s9, s8, 31
	s_lshl_b64 s[14:15], s[8:9], 20
	s_add_u32 s14, s28, s14
	s_addc_u32 s15, s29, s15
	s_and_b64 s[22:23], s[2:3], exec
	s_cselect_b32 s9, s15, s19
	s_cselect_b32 s63, s14, s18
	s_add_u32 s64, s18, 0x100
	s_addc_u32 s65, s19, 0
	s_add_u32 s18, s20, 0x80080
	s_addc_u32 s19, s21, 0
	s_add_u32 s66, s20, 0x100
	s_addc_u32 s67, s21, 0
	s_mov_b32 s70, -2
	s_setprio 3
	ds_read_b128 v[148:151], v143
	ds_read_b128 v[152:155], v143 offset:1024
	ds_read_b128 v[156:159], v143 offset:2048
	ds_read_b128 v[160:163], v143 offset:3072
	ds_read_b128 v[164:167], v144
	ds_read_b128 v[168:171], v144 offset:1024
	ds_read_b128 v[172:175], v144 offset:2048
	ds_read_b128 v[176:179], v144 offset:3072
	s_cmp_eq_u32 s70, 28
	s_cselect_b32 s21, s9, s65
	s_cselect_b32 s20, s63, s64
	s_cselect_b32 s23, s11, s67
	s_cselect_b32 s22, s62, s66
	ds_read_b128 v[180:183], v145
	ds_read_b128 v[184:187], v145 offset:1024
	ds_read_b128 v[188:191], v145 offset:2048
	ds_read_b128 v[192:195], v145 offset:3072
	ds_read_b128 v[196:199], v145 offset:4096
	ds_read_b128 v[200:203], v145 offset:5120
	ds_read_b128 v[204:207], v145 offset:6144
	ds_read_b128 v[208:211], v145 offset:7168
	s_add_u32 s74, s18, 0xfff80000
	s_addc_u32 s75, s19, -1
	s_mov_b32 s71, m0
	s_mov_b32 m0, s48
	s_nop 0
	global_load_lds_dwordx4 v138, s[74:75]
	s_mov_b32 m0, s71
	s_nop 0
	s_mov_b32 s71, m0
	s_mov_b32 m0, s57
	s_nop 0
	global_load_lds_dwordx4 v140, s[74:75]
	s_mov_b32 m0, s71
	s_nop 0
	s_mov_b32 s71, m0
	s_mov_b32 m0, s49
	s_nop 0
	global_load_lds_dwordx4 v138, s[18:19]
	s_mov_b32 m0, s71
	s_nop 0
	s_mov_b32 s71, m0
	s_mov_b32 m0, s58
	s_nop 0
	global_load_lds_dwordx4 v140, s[18:19]
	s_mov_b32 m0, s71
	s_setprio 0
	s_waitcnt vmcnt(8)
	s_waitcnt lgkmcnt(0)
	s_barrier
	s_setprio 1
	s_waitcnt lgkmcnt(7)
	v_mfma_f32_16x16x32_bf16 v[126:129], v[148:151], v[180:183], 0
	v_mfma_f32_16x16x32_bf16 v[126:129], v[152:155], v[184:187], v[126:129]
	s_waitcnt lgkmcnt(5)
	v_mfma_f32_16x16x32_bf16 v[122:125], v[156:159], v[180:183], 0
	v_mfma_f32_16x16x32_bf16 v[122:125], v[160:163], v[184:187], v[122:125]
	s_waitcnt lgkmcnt(3)
	v_mfma_f32_16x16x32_bf16 v[106:109], v[156:159], v[188:191], 0
	v_mfma_f32_16x16x32_bf16 v[106:109], v[160:163], v[192:195], v[106:109]
	s_waitcnt lgkmcnt(1)
	v_mfma_f32_16x16x32_bf16 v[110:113], v[148:151], v[188:191], 0
	v_mfma_f32_16x16x32_bf16 v[110:113], v[152:155], v[192:195], v[110:113]
	v_mfma_f32_16x16x32_bf16 v[94:97], v[148:151], v[196:199], 0
	v_mfma_f32_16x16x32_bf16 v[94:97], v[152:155], v[200:203], v[94:97]
	v_mfma_f32_16x16x32_bf16 v[90:93], v[156:159], v[196:199], 0
	v_mfma_f32_16x16x32_bf16 v[90:93], v[160:163], v[200:203], v[90:93]
	v_mfma_f32_16x16x32_bf16 v[74:77], v[156:159], v[204:207], 0
	v_mfma_f32_16x16x32_bf16 v[74:77], v[160:163], v[208:211], v[74:77]
	s_waitcnt lgkmcnt(0)
	v_mfma_f32_16x16x32_bf16 v[78:81], v[148:151], v[204:207], 0
	v_mfma_f32_16x16x32_bf16 v[78:81], v[152:155], v[208:211], v[78:81]
	s_setprio 0
	s_setprio 1
	v_mfma_f32_16x16x32_bf16 v[118:121], v[164:167], v[180:183], 0
	v_mfma_f32_16x16x32_bf16 v[118:121], v[168:171], v[184:187], v[118:121]
	v_mfma_f32_16x16x32_bf16 v[114:117], v[172:175], v[180:183], 0
	v_mfma_f32_16x16x32_bf16 v[114:117], v[176:179], v[184:187], v[114:117]
	v_mfma_f32_16x16x32_bf16 v[98:101], v[172:175], v[188:191], 0
	v_mfma_f32_16x16x32_bf16 v[98:101], v[176:179], v[192:195], v[98:101]
	v_mfma_f32_16x16x32_bf16 v[102:105], v[164:167], v[188:191], 0
	v_mfma_f32_16x16x32_bf16 v[102:105], v[168:171], v[192:195], v[102:105]
	v_mfma_f32_16x16x32_bf16 v[86:89], v[164:167], v[196:199], 0
	v_mfma_f32_16x16x32_bf16 v[86:89], v[168:171], v[200:203], v[86:89]
	v_mfma_f32_16x16x32_bf16 v[82:85], v[172:175], v[196:199], 0
	v_mfma_f32_16x16x32_bf16 v[82:85], v[176:179], v[200:203], v[82:85]
	v_mfma_f32_16x16x32_bf16 v[66:69], v[172:175], v[204:207], 0
	v_mfma_f32_16x16x32_bf16 v[66:69], v[176:179], v[208:211], v[66:69]
	s_setprio 2
	s_barrier
	v_mfma_f32_16x16x32_bf16 v[70:73], v[164:167], v[204:207], 0
	v_mfma_f32_16x16x32_bf16 v[70:73], v[168:171], v[208:211], v[70:73]
	s_setprio 0
	s_setprio 3
	ds_read_b128 v[180:183], v145 offset:16384
	ds_read_b128 v[184:187], v145 offset:17408
	ds_read_b128 v[188:191], v145 offset:18432
	ds_read_b128 v[192:195], v145 offset:19456
	ds_read_b128 v[196:199], v145 offset:20480
	ds_read_b128 v[200:203], v145 offset:21504
	ds_read_b128 v[204:207], v145 offset:22528
	ds_read_b128 v[208:211], v145 offset:23552
	s_mov_b32 s71, m0
	s_mov_b32 m0, s35
	s_nop 0
	global_load_lds_dwordx4 v139, s[20:21]
	s_mov_b32 m0, s71
	s_add_u32 s74, s20, 0x80000
	s_mov_b32 s71, m0
	s_mov_b32 m0, s36
	s_nop 0
	global_load_lds_dwordx4 v141, s[20:21]
	s_mov_b32 m0, s71
	s_addc_u32 s75, s21, 0
	s_mov_b32 s71, m0
	s_mov_b32 m0, s37
	s_nop 0
	global_load_lds_dwordx4 v139, s[74:75]
	s_mov_b32 m0, s71
	s_nop 0
	s_mov_b32 s71, m0
	s_mov_b32 m0, s40
	s_nop 0
	global_load_lds_dwordx4 v141, s[74:75]
	s_mov_b32 m0, s71
	s_setprio 0
	s_waitcnt vmcnt(4)
	s_waitcnt lgkmcnt(0)
	s_barrier
	s_setprio 1
	s_waitcnt lgkmcnt(7)
	v_mfma_f32_16x16x32_bf16 v[62:65], v[148:151], v[180:183], 0
	v_mfma_f32_16x16x32_bf16 v[62:65], v[152:155], v[184:187], v[62:65]
	s_waitcnt lgkmcnt(5)
	v_mfma_f32_16x16x32_bf16 v[58:61], v[156:159], v[180:183], 0
	v_mfma_f32_16x16x32_bf16 v[58:61], v[160:163], v[184:187], v[58:61]
	s_waitcnt lgkmcnt(3)
	v_mfma_f32_16x16x32_bf16 v[42:45], v[156:159], v[188:191], 0
	v_mfma_f32_16x16x32_bf16 v[42:45], v[160:163], v[192:195], v[42:45]
	s_waitcnt lgkmcnt(1)
	v_mfma_f32_16x16x32_bf16 v[46:49], v[148:151], v[188:191], 0
	v_mfma_f32_16x16x32_bf16 v[46:49], v[152:155], v[192:195], v[46:49]
	v_mfma_f32_16x16x32_bf16 v[30:33], v[148:151], v[196:199], 0
	v_mfma_f32_16x16x32_bf16 v[30:33], v[152:155], v[200:203], v[30:33]
	v_mfma_f32_16x16x32_bf16 v[26:29], v[156:159], v[196:199], 0
	v_mfma_f32_16x16x32_bf16 v[26:29], v[160:163], v[200:203], v[26:29]
	v_mfma_f32_16x16x32_bf16 v[10:13], v[156:159], v[204:207], 0
	v_mfma_f32_16x16x32_bf16 v[10:13], v[160:163], v[208:211], v[10:13]
	s_waitcnt lgkmcnt(0)
	v_mfma_f32_16x16x32_bf16 v[14:17], v[148:151], v[204:207], 0
	v_mfma_f32_16x16x32_bf16 v[14:17], v[152:155], v[208:211], v[14:17]
	s_setprio 0
	s_setprio 1
	v_mfma_f32_16x16x32_bf16 v[54:57], v[164:167], v[180:183], 0
	v_mfma_f32_16x16x32_bf16 v[54:57], v[168:171], v[184:187], v[54:57]
	v_mfma_f32_16x16x32_bf16 v[50:53], v[172:175], v[180:183], 0
	v_mfma_f32_16x16x32_bf16 v[50:53], v[176:179], v[184:187], v[50:53]
	v_mfma_f32_16x16x32_bf16 v[34:37], v[172:175], v[188:191], 0
	v_mfma_f32_16x16x32_bf16 v[34:37], v[176:179], v[192:195], v[34:37]
	v_mfma_f32_16x16x32_bf16 v[38:41], v[164:167], v[188:191], 0
	v_mfma_f32_16x16x32_bf16 v[38:41], v[168:171], v[192:195], v[38:41]
	v_mfma_f32_16x16x32_bf16 v[22:25], v[164:167], v[196:199], 0
	v_mfma_f32_16x16x32_bf16 v[22:25], v[168:171], v[200:203], v[22:25]
	v_mfma_f32_16x16x32_bf16 v[18:21], v[172:175], v[196:199], 0
	v_mfma_f32_16x16x32_bf16 v[18:21], v[176:179], v[200:203], v[18:21]
	v_mfma_f32_16x16x32_bf16 v[2:5], v[172:175], v[204:207], 0
	v_mfma_f32_16x16x32_bf16 v[2:5], v[176:179], v[208:211], v[2:5]
	s_setprio 2
	s_barrier
	v_mfma_f32_16x16x32_bf16 v[6:9], v[164:167], v[204:207], 0
	v_mfma_f32_16x16x32_bf16 v[6:9], v[168:171], v[208:211], v[6:9]
	s_setprio 0
	s_setprio 3
	ds_read_b128 v[148:151], v146
	ds_read_b128 v[152:155], v146 offset:1024
	ds_read_b128 v[156:159], v146 offset:2048
	ds_read_b128 v[160:163], v146 offset:3072
	ds_read_b128 v[164:167], v147
	ds_read_b128 v[168:171], v147 offset:1024
	ds_read_b128 v[172:175], v147 offset:2048
	ds_read_b128 v[176:179], v147 offset:3072
	ds_read_b128 v[180:183], v145 offset:32768
	ds_read_b128 v[184:187], v145 offset:33792
	ds_read_b128 v[188:191], v145 offset:34816
	ds_read_b128 v[192:195], v145 offset:35840
	ds_read_b128 v[196:199], v145 offset:36864
	ds_read_b128 v[200:203], v145 offset:37888
	ds_read_b128 v[204:207], v145 offset:38912
	ds_read_b128 v[208:211], v145 offset:39936
	s_mov_b32 s71, m0
	s_mov_b32 m0, s31
	s_nop 0
	global_load_lds_dwordx4 v138, s[22:23]
	s_mov_b32 m0, s71
	s_nop 0
	s_mov_b32 s71, m0
	s_mov_b32 m0, s41
	s_nop 0
	global_load_lds_dwordx4 v140, s[22:23]
	s_mov_b32 m0, s71
	s_add_u32 s22, s22, 0x80000
	s_addc_u32 s23, s23, 0
	s_mov_b32 s71, m0
	s_mov_b32 m0, s42
	s_nop 0
	global_load_lds_dwordx4 v138, s[22:23]
	s_mov_b32 m0, s71
	s_nop 0
	s_mov_b32 s71, m0
	s_mov_b32 m0, s43
	s_nop 0
	global_load_lds_dwordx4 v140, s[22:23]
	s_mov_b32 m0, s71
	s_setprio 0
	s_waitcnt vmcnt(8)
	s_waitcnt lgkmcnt(0)
	s_barrier
	s_setprio 1
	s_waitcnt lgkmcnt(7)
	v_mfma_f32_16x16x32_bf16 v[126:129], v[148:151], v[180:183], v[126:129]
	v_mfma_f32_16x16x32_bf16 v[126:129], v[152:155], v[184:187], v[126:129]
	s_waitcnt lgkmcnt(5)
	v_mfma_f32_16x16x32_bf16 v[122:125], v[156:159], v[180:183], v[122:125]
	v_mfma_f32_16x16x32_bf16 v[122:125], v[160:163], v[184:187], v[122:125]
	s_waitcnt lgkmcnt(3)
	v_mfma_f32_16x16x32_bf16 v[106:109], v[156:159], v[188:191], v[106:109]
	v_mfma_f32_16x16x32_bf16 v[106:109], v[160:163], v[192:195], v[106:109]
	s_waitcnt lgkmcnt(1)
	v_mfma_f32_16x16x32_bf16 v[110:113], v[148:151], v[188:191], v[110:113]
	v_mfma_f32_16x16x32_bf16 v[110:113], v[152:155], v[192:195], v[110:113]
	v_mfma_f32_16x16x32_bf16 v[94:97], v[148:151], v[196:199], v[94:97]
	v_mfma_f32_16x16x32_bf16 v[94:97], v[152:155], v[200:203], v[94:97]
	v_mfma_f32_16x16x32_bf16 v[90:93], v[156:159], v[196:199], v[90:93]
	v_mfma_f32_16x16x32_bf16 v[90:93], v[160:163], v[200:203], v[90:93]
	v_mfma_f32_16x16x32_bf16 v[74:77], v[156:159], v[204:207], v[74:77]
	v_mfma_f32_16x16x32_bf16 v[74:77], v[160:163], v[208:211], v[74:77]
	s_waitcnt lgkmcnt(0)
	v_mfma_f32_16x16x32_bf16 v[78:81], v[148:151], v[204:207], v[78:81]
	v_mfma_f32_16x16x32_bf16 v[78:81], v[152:155], v[208:211], v[78:81]
	s_setprio 0
	s_setprio 1
	v_mfma_f32_16x16x32_bf16 v[118:121], v[164:167], v[180:183], v[118:121]
	v_mfma_f32_16x16x32_bf16 v[118:121], v[168:171], v[184:187], v[118:121]
	v_mfma_f32_16x16x32_bf16 v[114:117], v[172:175], v[180:183], v[114:117]
	v_mfma_f32_16x16x32_bf16 v[114:117], v[176:179], v[184:187], v[114:117]
	v_mfma_f32_16x16x32_bf16 v[98:101], v[172:175], v[188:191], v[98:101]
	v_mfma_f32_16x16x32_bf16 v[98:101], v[176:179], v[192:195], v[98:101]
	v_mfma_f32_16x16x32_bf16 v[102:105], v[164:167], v[188:191], v[102:105]
	v_mfma_f32_16x16x32_bf16 v[102:105], v[168:171], v[192:195], v[102:105]
	v_mfma_f32_16x16x32_bf16 v[86:89], v[164:167], v[196:199], v[86:89]
	v_mfma_f32_16x16x32_bf16 v[86:89], v[168:171], v[200:203], v[86:89]
	v_mfma_f32_16x16x32_bf16 v[82:85], v[172:175], v[196:199], v[82:85]
	v_mfma_f32_16x16x32_bf16 v[82:85], v[176:179], v[200:203], v[82:85]
	v_mfma_f32_16x16x32_bf16 v[66:69], v[172:175], v[204:207], v[66:69]
	v_mfma_f32_16x16x32_bf16 v[66:69], v[176:179], v[208:211], v[66:69]
	s_setprio 2
	s_barrier
	v_mfma_f32_16x16x32_bf16 v[70:73], v[164:167], v[204:207], v[70:73]
	v_mfma_f32_16x16x32_bf16 v[70:73], v[168:171], v[208:211], v[70:73]
	s_setprio 0
	s_setprio 3
	ds_read_b128 v[180:183], v145 offset:49152
	ds_read_b128 v[184:187], v145 offset:50176
	ds_read_b128 v[188:191], v145 offset:51200
	ds_read_b128 v[192:195], v145 offset:52224
	ds_read_b128 v[196:199], v145 offset:53248
	ds_read_b128 v[200:203], v145 offset:54272
	ds_read_b128 v[204:207], v145 offset:55296
	ds_read_b128 v[208:211], v145 offset:56320
	s_add_u32 s22, s20, 0x80
	s_addc_u32 s23, s21, 0
	s_mov_b32 s71, m0
	s_mov_b32 m0, s44
	s_nop 0
	global_load_lds_dwordx4 v139, s[22:23]
	s_mov_b32 m0, s71
	s_add_u32 s20, s20, 0x80080
	s_mov_b32 s71, m0
	s_mov_b32 m0, s45
	s_nop 0
	global_load_lds_dwordx4 v141, s[22:23]
	s_mov_b32 m0, s71
	s_addc_u32 s21, s21, 0
	s_mov_b32 s22, m0
	s_mov_b32 m0, s46
	s_nop 0
	global_load_lds_dwordx4 v139, s[20:21]
	s_mov_b32 m0, s22
	s_nop 0
	s_mov_b32 s22, m0
	s_mov_b32 m0, s47
	s_nop 0
	global_load_lds_dwordx4 v141, s[20:21]
	s_mov_b32 m0, s22
	s_setprio 0
	s_waitcnt vmcnt(4)
	s_waitcnt lgkmcnt(0)
	s_barrier
	s_setprio 1
	s_waitcnt lgkmcnt(7)
	v_mfma_f32_16x16x32_bf16 v[62:65], v[148:151], v[180:183], v[62:65]
	v_mfma_f32_16x16x32_bf16 v[62:65], v[152:155], v[184:187], v[62:65]
	s_waitcnt lgkmcnt(5)
	v_mfma_f32_16x16x32_bf16 v[58:61], v[156:159], v[180:183], v[58:61]
	v_mfma_f32_16x16x32_bf16 v[58:61], v[160:163], v[184:187], v[58:61]
	s_waitcnt lgkmcnt(3)
	v_mfma_f32_16x16x32_bf16 v[42:45], v[156:159], v[188:191], v[42:45]
	v_mfma_f32_16x16x32_bf16 v[42:45], v[160:163], v[192:195], v[42:45]
	s_waitcnt lgkmcnt(1)
	v_mfma_f32_16x16x32_bf16 v[46:49], v[148:151], v[188:191], v[46:49]
	v_mfma_f32_16x16x32_bf16 v[46:49], v[152:155], v[192:195], v[46:49]
	v_mfma_f32_16x16x32_bf16 v[30:33], v[148:151], v[196:199], v[30:33]
	v_mfma_f32_16x16x32_bf16 v[30:33], v[152:155], v[200:203], v[30:33]
	v_mfma_f32_16x16x32_bf16 v[26:29], v[156:159], v[196:199], v[26:29]
	v_mfma_f32_16x16x32_bf16 v[26:29], v[160:163], v[200:203], v[26:29]
	v_mfma_f32_16x16x32_bf16 v[10:13], v[156:159], v[204:207], v[10:13]
	v_mfma_f32_16x16x32_bf16 v[10:13], v[160:163], v[208:211], v[10:13]
	s_waitcnt lgkmcnt(0)
	v_mfma_f32_16x16x32_bf16 v[14:17], v[148:151], v[204:207], v[14:17]
	v_mfma_f32_16x16x32_bf16 v[14:17], v[152:155], v[208:211], v[14:17]
	s_setprio 0
	s_setprio 1
	v_mfma_f32_16x16x32_bf16 v[54:57], v[164:167], v[180:183], v[54:57]
	v_mfma_f32_16x16x32_bf16 v[54:57], v[168:171], v[184:187], v[54:57]
	v_mfma_f32_16x16x32_bf16 v[50:53], v[172:175], v[180:183], v[50:53]
	v_mfma_f32_16x16x32_bf16 v[50:53], v[176:179], v[184:187], v[50:53]
	v_mfma_f32_16x16x32_bf16 v[34:37], v[172:175], v[188:191], v[34:37]
	v_mfma_f32_16x16x32_bf16 v[34:37], v[176:179], v[192:195], v[34:37]
	v_mfma_f32_16x16x32_bf16 v[38:41], v[164:167], v[188:191], v[38:41]
	v_mfma_f32_16x16x32_bf16 v[38:41], v[168:171], v[192:195], v[38:41]
	v_mfma_f32_16x16x32_bf16 v[22:25], v[164:167], v[196:199], v[22:25]
	v_mfma_f32_16x16x32_bf16 v[22:25], v[168:171], v[200:203], v[22:25]
	v_mfma_f32_16x16x32_bf16 v[18:21], v[172:175], v[196:199], v[18:21]
	v_mfma_f32_16x16x32_bf16 v[18:21], v[176:179], v[200:203], v[18:21]
	v_mfma_f32_16x16x32_bf16 v[2:5], v[172:175], v[204:207], v[2:5]
	v_mfma_f32_16x16x32_bf16 v[2:5], v[176:179], v[208:211], v[2:5]
	s_setprio 2
	s_barrier
	v_mfma_f32_16x16x32_bf16 v[6:9], v[164:167], v[204:207], v[6:9]
	v_mfma_f32_16x16x32_bf16 v[6:9], v[168:171], v[208:211], v[6:9]
	s_setprio 0
	s_add_i32 s70, s70, 2
	s_add_u32 s64, s64, 0x100
	s_addc_u32 s65, s65, 0
	s_add_u32 s18, s18, 0x100
	s_addc_u32 s19, s19, 0
	s_add_u32 s66, s66, 0x100
	s_addc_u32 s67, s67, 0
	s_cmp_gt_u32 s70, 29
	.p2align 6
.LBB0_2594:
	s_setprio 3
	ds_read_b128 v[148:151], v143
	ds_read_b128 v[152:155], v143 offset:1024
	ds_read_b128 v[156:159], v143 offset:2048
	ds_read_b128 v[160:163], v143 offset:3072
	ds_read_b128 v[164:167], v144
	ds_read_b128 v[168:171], v144 offset:1024
	ds_read_b128 v[172:175], v144 offset:2048
	ds_read_b128 v[176:179], v144 offset:3072
	s_cmp_eq_u32 s70, 28
	s_cselect_b32 s21, s9, s65
	s_cselect_b32 s20, s63, s64
	s_cselect_b32 s23, s11, s67
	s_cselect_b32 s22, s62, s66
	ds_read_b128 v[180:183], v145
	ds_read_b128 v[184:187], v145 offset:1024
	ds_read_b128 v[188:191], v145 offset:2048
	ds_read_b128 v[192:195], v145 offset:3072
	ds_read_b128 v[196:199], v145 offset:4096
	ds_read_b128 v[200:203], v145 offset:5120
	ds_read_b128 v[204:207], v145 offset:6144
	ds_read_b128 v[208:211], v145 offset:7168
	s_add_u32 s74, s18, 0xfff80000
	s_addc_u32 s75, s19, -1
	s_mov_b32 s71, m0
	s_mov_b32 m0, s48
	s_nop 0
	global_load_lds_dwordx4 v138, s[74:75]
	s_mov_b32 m0, s71
	s_nop 0
	s_mov_b32 s71, m0
	s_mov_b32 m0, s57
	s_nop 0
	global_load_lds_dwordx4 v140, s[74:75]
	s_mov_b32 m0, s71
	s_nop 0
	s_mov_b32 s71, m0
	s_mov_b32 m0, s49
	s_nop 0
	global_load_lds_dwordx4 v138, s[18:19]
	s_mov_b32 m0, s71
	s_nop 0
	s_mov_b32 s71, m0
	s_mov_b32 m0, s58
	s_nop 0
	global_load_lds_dwordx4 v140, s[18:19]
	s_mov_b32 m0, s71
	s_setprio 0
	s_waitcnt vmcnt(8)
	s_waitcnt lgkmcnt(0)
	s_barrier
	s_setprio 1
	s_waitcnt lgkmcnt(7)
	v_mfma_f32_16x16x32_bf16 v[126:129], v[148:151], v[180:183], v[126:129]
	v_mfma_f32_16x16x32_bf16 v[126:129], v[152:155], v[184:187], v[126:129]
	s_waitcnt lgkmcnt(5)
	v_mfma_f32_16x16x32_bf16 v[122:125], v[156:159], v[180:183], v[122:125]
	v_mfma_f32_16x16x32_bf16 v[122:125], v[160:163], v[184:187], v[122:125]
	s_waitcnt lgkmcnt(3)
	v_mfma_f32_16x16x32_bf16 v[106:109], v[156:159], v[188:191], v[106:109]
	v_mfma_f32_16x16x32_bf16 v[106:109], v[160:163], v[192:195], v[106:109]
	s_waitcnt lgkmcnt(1)
	v_mfma_f32_16x16x32_bf16 v[110:113], v[148:151], v[188:191], v[110:113]
	v_mfma_f32_16x16x32_bf16 v[110:113], v[152:155], v[192:195], v[110:113]
	v_mfma_f32_16x16x32_bf16 v[94:97], v[148:151], v[196:199], v[94:97]
	v_mfma_f32_16x16x32_bf16 v[94:97], v[152:155], v[200:203], v[94:97]
	v_mfma_f32_16x16x32_bf16 v[90:93], v[156:159], v[196:199], v[90:93]
	v_mfma_f32_16x16x32_bf16 v[90:93], v[160:163], v[200:203], v[90:93]
	v_mfma_f32_16x16x32_bf16 v[74:77], v[156:159], v[204:207], v[74:77]
	v_mfma_f32_16x16x32_bf16 v[74:77], v[160:163], v[208:211], v[74:77]
	s_waitcnt lgkmcnt(0)
	v_mfma_f32_16x16x32_bf16 v[78:81], v[148:151], v[204:207], v[78:81]
	v_mfma_f32_16x16x32_bf16 v[78:81], v[152:155], v[208:211], v[78:81]
	s_setprio 0
	s_setprio 1
	v_mfma_f32_16x16x32_bf16 v[118:121], v[164:167], v[180:183], v[118:121]
	v_mfma_f32_16x16x32_bf16 v[118:121], v[168:171], v[184:187], v[118:121]
	v_mfma_f32_16x16x32_bf16 v[114:117], v[172:175], v[180:183], v[114:117]
	v_mfma_f32_16x16x32_bf16 v[114:117], v[176:179], v[184:187], v[114:117]
	v_mfma_f32_16x16x32_bf16 v[98:101], v[172:175], v[188:191], v[98:101]
	v_mfma_f32_16x16x32_bf16 v[98:101], v[176:179], v[192:195], v[98:101]
	v_mfma_f32_16x16x32_bf16 v[102:105], v[164:167], v[188:191], v[102:105]
	v_mfma_f32_16x16x32_bf16 v[102:105], v[168:171], v[192:195], v[102:105]
	v_mfma_f32_16x16x32_bf16 v[86:89], v[164:167], v[196:199], v[86:89]
	v_mfma_f32_16x16x32_bf16 v[86:89], v[168:171], v[200:203], v[86:89]
	v_mfma_f32_16x16x32_bf16 v[82:85], v[172:175], v[196:199], v[82:85]
	v_mfma_f32_16x16x32_bf16 v[82:85], v[176:179], v[200:203], v[82:85]
	v_mfma_f32_16x16x32_bf16 v[66:69], v[172:175], v[204:207], v[66:69]
	v_mfma_f32_16x16x32_bf16 v[66:69], v[176:179], v[208:211], v[66:69]
	s_setprio 2
	s_barrier
	v_mfma_f32_16x16x32_bf16 v[70:73], v[164:167], v[204:207], v[70:73]
	v_mfma_f32_16x16x32_bf16 v[70:73], v[168:171], v[208:211], v[70:73]
	s_setprio 0
	s_setprio 3
	ds_read_b128 v[180:183], v145 offset:16384
	ds_read_b128 v[184:187], v145 offset:17408
	ds_read_b128 v[188:191], v145 offset:18432
	ds_read_b128 v[192:195], v145 offset:19456
	ds_read_b128 v[196:199], v145 offset:20480
	ds_read_b128 v[200:203], v145 offset:21504
	ds_read_b128 v[204:207], v145 offset:22528
	ds_read_b128 v[208:211], v145 offset:23552
	s_mov_b32 s71, m0
	s_mov_b32 m0, s35
	s_nop 0
	global_load_lds_dwordx4 v139, s[20:21]
	s_mov_b32 m0, s71
	s_add_u32 s74, s20, 0x80000
	s_mov_b32 s71, m0
	s_mov_b32 m0, s36
	s_nop 0
	global_load_lds_dwordx4 v141, s[20:21]
	s_mov_b32 m0, s71
	s_addc_u32 s75, s21, 0
	s_mov_b32 s71, m0
	s_mov_b32 m0, s37
	s_nop 0
	global_load_lds_dwordx4 v139, s[74:75]
	s_mov_b32 m0, s71
	s_nop 0
	s_mov_b32 s71, m0
	s_mov_b32 m0, s40
	s_nop 0
	global_load_lds_dwordx4 v141, s[74:75]
	s_mov_b32 m0, s71
	s_setprio 0
	s_waitcnt vmcnt(4)
	s_waitcnt lgkmcnt(0)
	s_barrier
	s_setprio 1
	s_waitcnt lgkmcnt(7)
	v_mfma_f32_16x16x32_bf16 v[62:65], v[148:151], v[180:183], v[62:65]
	v_mfma_f32_16x16x32_bf16 v[62:65], v[152:155], v[184:187], v[62:65]
	s_waitcnt lgkmcnt(5)
	v_mfma_f32_16x16x32_bf16 v[58:61], v[156:159], v[180:183], v[58:61]
	v_mfma_f32_16x16x32_bf16 v[58:61], v[160:163], v[184:187], v[58:61]
	s_waitcnt lgkmcnt(3)
	v_mfma_f32_16x16x32_bf16 v[42:45], v[156:159], v[188:191], v[42:45]
	v_mfma_f32_16x16x32_bf16 v[42:45], v[160:163], v[192:195], v[42:45]
	s_waitcnt lgkmcnt(1)
	v_mfma_f32_16x16x32_bf16 v[46:49], v[148:151], v[188:191], v[46:49]
	v_mfma_f32_16x16x32_bf16 v[46:49], v[152:155], v[192:195], v[46:49]
	v_mfma_f32_16x16x32_bf16 v[30:33], v[148:151], v[196:199], v[30:33]
	v_mfma_f32_16x16x32_bf16 v[30:33], v[152:155], v[200:203], v[30:33]
	v_mfma_f32_16x16x32_bf16 v[26:29], v[156:159], v[196:199], v[26:29]
	v_mfma_f32_16x16x32_bf16 v[26:29], v[160:163], v[200:203], v[26:29]
	v_mfma_f32_16x16x32_bf16 v[10:13], v[156:159], v[204:207], v[10:13]
	v_mfma_f32_16x16x32_bf16 v[10:13], v[160:163], v[208:211], v[10:13]
	s_waitcnt lgkmcnt(0)
	v_mfma_f32_16x16x32_bf16 v[14:17], v[148:151], v[204:207], v[14:17]
	v_mfma_f32_16x16x32_bf16 v[14:17], v[152:155], v[208:211], v[14:17]
	s_setprio 0
	s_setprio 1
	v_mfma_f32_16x16x32_bf16 v[54:57], v[164:167], v[180:183], v[54:57]
	v_mfma_f32_16x16x32_bf16 v[54:57], v[168:171], v[184:187], v[54:57]
	v_mfma_f32_16x16x32_bf16 v[50:53], v[172:175], v[180:183], v[50:53]
	v_mfma_f32_16x16x32_bf16 v[50:53], v[176:179], v[184:187], v[50:53]
	v_mfma_f32_16x16x32_bf16 v[34:37], v[172:175], v[188:191], v[34:37]
	v_mfma_f32_16x16x32_bf16 v[34:37], v[176:179], v[192:195], v[34:37]
	v_mfma_f32_16x16x32_bf16 v[38:41], v[164:167], v[188:191], v[38:41]
	v_mfma_f32_16x16x32_bf16 v[38:41], v[168:171], v[192:195], v[38:41]
	v_mfma_f32_16x16x32_bf16 v[22:25], v[164:167], v[196:199], v[22:25]
	v_mfma_f32_16x16x32_bf16 v[22:25], v[168:171], v[200:203], v[22:25]
	v_mfma_f32_16x16x32_bf16 v[18:21], v[172:175], v[196:199], v[18:21]
	v_mfma_f32_16x16x32_bf16 v[18:21], v[176:179], v[200:203], v[18:21]
	v_mfma_f32_16x16x32_bf16 v[2:5], v[172:175], v[204:207], v[2:5]
	v_mfma_f32_16x16x32_bf16 v[2:5], v[176:179], v[208:211], v[2:5]
	s_setprio 2
	s_barrier
	v_mfma_f32_16x16x32_bf16 v[6:9], v[164:167], v[204:207], v[6:9]
	v_mfma_f32_16x16x32_bf16 v[6:9], v[168:171], v[208:211], v[6:9]
	s_setprio 0
	s_setprio 3
	ds_read_b128 v[148:151], v146
	ds_read_b128 v[152:155], v146 offset:1024
	ds_read_b128 v[156:159], v146 offset:2048
	ds_read_b128 v[160:163], v146 offset:3072
	ds_read_b128 v[164:167], v147
	ds_read_b128 v[168:171], v147 offset:1024
	ds_read_b128 v[172:175], v147 offset:2048
	ds_read_b128 v[176:179], v147 offset:3072
	ds_read_b128 v[180:183], v145 offset:32768
	ds_read_b128 v[184:187], v145 offset:33792
	ds_read_b128 v[188:191], v145 offset:34816
	ds_read_b128 v[192:195], v145 offset:35840
	ds_read_b128 v[196:199], v145 offset:36864
	ds_read_b128 v[200:203], v145 offset:37888
	ds_read_b128 v[204:207], v145 offset:38912
	ds_read_b128 v[208:211], v145 offset:39936
	s_mov_b32 s71, m0
	s_mov_b32 m0, s31
	s_nop 0
	global_load_lds_dwordx4 v138, s[22:23]
	s_mov_b32 m0, s71
	s_nop 0
	s_mov_b32 s71, m0
	s_mov_b32 m0, s41
	s_nop 0
	global_load_lds_dwordx4 v140, s[22:23]
	s_mov_b32 m0, s71
	s_add_u32 s22, s22, 0x80000
	s_addc_u32 s23, s23, 0
	s_mov_b32 s71, m0
	s_mov_b32 m0, s42
	s_nop 0
	global_load_lds_dwordx4 v138, s[22:23]
	s_mov_b32 m0, s71
	s_nop 0
	s_mov_b32 s71, m0
	s_mov_b32 m0, s43
	s_nop 0
	global_load_lds_dwordx4 v140, s[22:23]
	s_mov_b32 m0, s71
	s_setprio 0
	s_waitcnt vmcnt(8)
	s_waitcnt lgkmcnt(0)
	s_barrier
	s_setprio 1
	s_waitcnt lgkmcnt(7)
	v_mfma_f32_16x16x32_bf16 v[126:129], v[148:151], v[180:183], v[126:129]
	v_mfma_f32_16x16x32_bf16 v[126:129], v[152:155], v[184:187], v[126:129]
	s_waitcnt lgkmcnt(5)
	v_mfma_f32_16x16x32_bf16 v[122:125], v[156:159], v[180:183], v[122:125]
	v_mfma_f32_16x16x32_bf16 v[122:125], v[160:163], v[184:187], v[122:125]
	s_waitcnt lgkmcnt(3)
	v_mfma_f32_16x16x32_bf16 v[106:109], v[156:159], v[188:191], v[106:109]
	v_mfma_f32_16x16x32_bf16 v[106:109], v[160:163], v[192:195], v[106:109]
	s_waitcnt lgkmcnt(1)
	v_mfma_f32_16x16x32_bf16 v[110:113], v[148:151], v[188:191], v[110:113]
	v_mfma_f32_16x16x32_bf16 v[110:113], v[152:155], v[192:195], v[110:113]
	v_mfma_f32_16x16x32_bf16 v[94:97], v[148:151], v[196:199], v[94:97]
	v_mfma_f32_16x16x32_bf16 v[94:97], v[152:155], v[200:203], v[94:97]
	v_mfma_f32_16x16x32_bf16 v[90:93], v[156:159], v[196:199], v[90:93]
	v_mfma_f32_16x16x32_bf16 v[90:93], v[160:163], v[200:203], v[90:93]
	v_mfma_f32_16x16x32_bf16 v[74:77], v[156:159], v[204:207], v[74:77]
	v_mfma_f32_16x16x32_bf16 v[74:77], v[160:163], v[208:211], v[74:77]
	s_waitcnt lgkmcnt(0)
	v_mfma_f32_16x16x32_bf16 v[78:81], v[148:151], v[204:207], v[78:81]
	v_mfma_f32_16x16x32_bf16 v[78:81], v[152:155], v[208:211], v[78:81]
	s_setprio 0
	s_setprio 1
	v_mfma_f32_16x16x32_bf16 v[118:121], v[164:167], v[180:183], v[118:121]
	v_mfma_f32_16x16x32_bf16 v[118:121], v[168:171], v[184:187], v[118:121]
	v_mfma_f32_16x16x32_bf16 v[114:117], v[172:175], v[180:183], v[114:117]
	v_mfma_f32_16x16x32_bf16 v[114:117], v[176:179], v[184:187], v[114:117]
	v_mfma_f32_16x16x32_bf16 v[98:101], v[172:175], v[188:191], v[98:101]
	v_mfma_f32_16x16x32_bf16 v[98:101], v[176:179], v[192:195], v[98:101]
	v_mfma_f32_16x16x32_bf16 v[102:105], v[164:167], v[188:191], v[102:105]
	v_mfma_f32_16x16x32_bf16 v[102:105], v[168:171], v[192:195], v[102:105]
	v_mfma_f32_16x16x32_bf16 v[86:89], v[164:167], v[196:199], v[86:89]
	v_mfma_f32_16x16x32_bf16 v[86:89], v[168:171], v[200:203], v[86:89]
	v_mfma_f32_16x16x32_bf16 v[82:85], v[172:175], v[196:199], v[82:85]
	v_mfma_f32_16x16x32_bf16 v[82:85], v[176:179], v[200:203], v[82:85]
	v_mfma_f32_16x16x32_bf16 v[66:69], v[172:175], v[204:207], v[66:69]
	v_mfma_f32_16x16x32_bf16 v[66:69], v[176:179], v[208:211], v[66:69]
	s_setprio 2
	s_barrier
	v_mfma_f32_16x16x32_bf16 v[70:73], v[164:167], v[204:207], v[70:73]
	v_mfma_f32_16x16x32_bf16 v[70:73], v[168:171], v[208:211], v[70:73]
	s_setprio 0
	s_setprio 3
	ds_read_b128 v[180:183], v145 offset:49152
	ds_read_b128 v[184:187], v145 offset:50176
	ds_read_b128 v[188:191], v145 offset:51200
	ds_read_b128 v[192:195], v145 offset:52224
	ds_read_b128 v[196:199], v145 offset:53248
	ds_read_b128 v[200:203], v145 offset:54272
	ds_read_b128 v[204:207], v145 offset:55296
	ds_read_b128 v[208:211], v145 offset:56320
	s_add_u32 s22, s20, 0x80
	s_addc_u32 s23, s21, 0
	s_mov_b32 s71, m0
	s_mov_b32 m0, s44
	s_nop 0
	global_load_lds_dwordx4 v139, s[22:23]
	s_mov_b32 m0, s71
	s_add_u32 s20, s20, 0x80080
	s_mov_b32 s71, m0
	s_mov_b32 m0, s45
	s_nop 0
	global_load_lds_dwordx4 v141, s[22:23]
	s_mov_b32 m0, s71
	s_addc_u32 s21, s21, 0
	s_mov_b32 s22, m0
	s_mov_b32 m0, s46
	s_nop 0
	global_load_lds_dwordx4 v139, s[20:21]
	s_mov_b32 m0, s22
	s_nop 0
	s_mov_b32 s22, m0
	s_mov_b32 m0, s47
	s_nop 0
	global_load_lds_dwordx4 v141, s[20:21]
	s_mov_b32 m0, s22
	s_setprio 0
	s_waitcnt vmcnt(4)
	s_waitcnt lgkmcnt(0)
	s_barrier
	s_setprio 1
	s_waitcnt lgkmcnt(7)
	v_mfma_f32_16x16x32_bf16 v[62:65], v[148:151], v[180:183], v[62:65]
	v_mfma_f32_16x16x32_bf16 v[62:65], v[152:155], v[184:187], v[62:65]
	s_waitcnt lgkmcnt(5)
	v_mfma_f32_16x16x32_bf16 v[58:61], v[156:159], v[180:183], v[58:61]
	v_mfma_f32_16x16x32_bf16 v[58:61], v[160:163], v[184:187], v[58:61]
	s_waitcnt lgkmcnt(3)
	v_mfma_f32_16x16x32_bf16 v[42:45], v[156:159], v[188:191], v[42:45]
	v_mfma_f32_16x16x32_bf16 v[42:45], v[160:163], v[192:195], v[42:45]
	s_waitcnt lgkmcnt(1)
	v_mfma_f32_16x16x32_bf16 v[46:49], v[148:151], v[188:191], v[46:49]
	v_mfma_f32_16x16x32_bf16 v[46:49], v[152:155], v[192:195], v[46:49]
	v_mfma_f32_16x16x32_bf16 v[30:33], v[148:151], v[196:199], v[30:33]
	v_mfma_f32_16x16x32_bf16 v[30:33], v[152:155], v[200:203], v[30:33]
	v_mfma_f32_16x16x32_bf16 v[26:29], v[156:159], v[196:199], v[26:29]
	v_mfma_f32_16x16x32_bf16 v[26:29], v[160:163], v[200:203], v[26:29]
	v_mfma_f32_16x16x32_bf16 v[10:13], v[156:159], v[204:207], v[10:13]
	v_mfma_f32_16x16x32_bf16 v[10:13], v[160:163], v[208:211], v[10:13]
	s_waitcnt lgkmcnt(0)
	v_mfma_f32_16x16x32_bf16 v[14:17], v[148:151], v[204:207], v[14:17]
	v_mfma_f32_16x16x32_bf16 v[14:17], v[152:155], v[208:211], v[14:17]
	s_setprio 0
	s_setprio 1
	v_mfma_f32_16x16x32_bf16 v[54:57], v[164:167], v[180:183], v[54:57]
	v_mfma_f32_16x16x32_bf16 v[54:57], v[168:171], v[184:187], v[54:57]
	v_mfma_f32_16x16x32_bf16 v[50:53], v[172:175], v[180:183], v[50:53]
	v_mfma_f32_16x16x32_bf16 v[50:53], v[176:179], v[184:187], v[50:53]
	v_mfma_f32_16x16x32_bf16 v[34:37], v[172:175], v[188:191], v[34:37]
	v_mfma_f32_16x16x32_bf16 v[34:37], v[176:179], v[192:195], v[34:37]
	v_mfma_f32_16x16x32_bf16 v[38:41], v[164:167], v[188:191], v[38:41]
	v_mfma_f32_16x16x32_bf16 v[38:41], v[168:171], v[192:195], v[38:41]
	v_mfma_f32_16x16x32_bf16 v[22:25], v[164:167], v[196:199], v[22:25]
	v_mfma_f32_16x16x32_bf16 v[22:25], v[168:171], v[200:203], v[22:25]
	v_mfma_f32_16x16x32_bf16 v[18:21], v[172:175], v[196:199], v[18:21]
	v_mfma_f32_16x16x32_bf16 v[18:21], v[176:179], v[200:203], v[18:21]
	v_mfma_f32_16x16x32_bf16 v[2:5], v[172:175], v[204:207], v[2:5]
	v_mfma_f32_16x16x32_bf16 v[2:5], v[176:179], v[208:211], v[2:5]
	s_setprio 2
	s_barrier
	v_mfma_f32_16x16x32_bf16 v[6:9], v[164:167], v[204:207], v[6:9]
	v_mfma_f32_16x16x32_bf16 v[6:9], v[168:171], v[208:211], v[6:9]
	s_setprio 0
	s_add_i32 s70, s70, 2
	s_add_u32 s64, s64, 0x100
	s_addc_u32 s65, s65, 0
	s_add_u32 s18, s18, 0x100
	s_addc_u32 s19, s19, 0
	s_add_u32 s66, s66, 0x100
	s_addc_u32 s67, s67, 0
	s_cmp_gt_u32 s70, 29
	s_cbranch_scc0 .LBB0_2594
	s_and_b64 vcc, exec, s[6:7]
	s_cbranch_vccz .LBB0_2597
	s_barrier

.LBB0_2791:
	s_ashr_i32 s21, s20, 31
	s_lshl_b64 s[22:23], s[20:21], 15
	s_add_u32 s22, s37, s22
	s_addc_u32 s23, s40, s23
	s_and_b64 s[24:25], s[2:3], exec
	s_cselect_b32 s21, s23, s31
	s_cselect_b32 s63, s22, s30
	s_ashr_i32 s19, s18, 31
	s_lshl_b64 s[24:25], s[18:19], 15
	s_add_u32 s24, s41, s24
	s_addc_u32 s25, s42, s25
	s_and_b64 s[34:35], s[2:3], exec
	s_cselect_b32 s19, s25, s29
	s_cselect_b32 s64, s24, s28
	s_add_u32 s65, s28, 0x80000
	s_addc_u32 s66, s29, 0
	s_add_u32 s28, s30, 0x204000
	s_addc_u32 s29, s31, 0
	s_add_u32 s67, s30, 0x400000
	s_addc_u32 s68, s31, 0
	s_mov_b32 s69, -2
	s_waitcnt vmcnt(25)
	s_waitcnt vmcnt(24)
	s_waitcnt vmcnt(4)
	s_waitcnt vmcnt(2)
	s_waitcnt vmcnt(1)
	s_waitcnt vmcnt(0)
	s_setprio 3
	ds_read_b128 v[130:133], v181
	ds_read_b128 v[134:137], v181 offset:1024
	ds_read_b128 v[138:141], v181 offset:2048
	ds_read_b128 v[142:145], v181 offset:3072
	ds_read_b128 v[150:153], v182
	ds_read_b128 v[154:157], v182 offset:1024
	ds_read_b128 v[158:161], v182 offset:2048
	ds_read_b128 v[162:165], v182 offset:3072
	s_cmpk_eq_i32 s69, 0x52
	s_cselect_b32 s31, s19, s66
	s_cselect_b32 s30, s64, s65
	s_cselect_b32 s35, s21, s68
	s_cselect_b32 s34, s63, s67
	ds_read_b128 v[166:169], v183
	ds_read_b128 v[170:173], v183 offset:1024
	ds_read_b128 v[186:189], v183 offset:2048
	ds_read_b128 v[190:193], v183 offset:3072
	ds_read_b128 v[194:197], v183 offset:4096
	ds_read_b128 v[198:201], v183 offset:5120
	ds_read_b128 v[202:205], v183 offset:6144
	ds_read_b128 v[206:209], v183 offset:7168
	s_add_u32 s70, s28, 0xffffc000
	s_addc_u32 s71, s29, -1
	s_mov_b32 s73, m0
	s_mov_b32 m0, s57
	s_nop 0
	global_load_lds_dwordx4 v1, s[70:71]
	s_mov_b32 m0, s73
	s_nop 0
	s_mov_b32 s73, m0
	s_mov_b32 m0, s59
	s_nop 0
	global_load_lds_dwordx4 v177, s[70:71]
	s_mov_b32 m0, s73
	s_mov_b32 s70, m0
	s_mov_b32 m0, s58
	s_nop 0
	global_load_lds_dwordx4 v1, s[28:29]
	s_mov_b32 m0, s70
	s_nop 0
	s_mov_b32 s70, m0
	s_mov_b32 m0, s60
	s_nop 0
	global_load_lds_dwordx4 v177, s[28:29]
	s_mov_b32 m0, s70
	s_setprio 0
	s_waitcnt vmcnt(8)
	s_waitcnt lgkmcnt(0)
	s_barrier
	s_setprio 1
	s_waitcnt lgkmcnt(7)
	v_mfma_f32_16x16x32_bf16 v[126:129], v[130:133], v[166:169], 0
	v_mfma_f32_16x16x32_bf16 v[126:129], v[134:137], v[170:173], v[126:129]
	s_waitcnt lgkmcnt(5)
	v_mfma_f32_16x16x32_bf16 v[122:125], v[138:141], v[166:169], 0
	v_mfma_f32_16x16x32_bf16 v[122:125], v[142:145], v[170:173], v[122:125]
	s_waitcnt lgkmcnt(3)
	v_mfma_f32_16x16x32_bf16 v[110:113], v[138:141], v[186:189], 0
	v_mfma_f32_16x16x32_bf16 v[110:113], v[142:145], v[190:193], v[110:113]
	s_waitcnt lgkmcnt(1)
	v_mfma_f32_16x16x32_bf16 v[118:121], v[130:133], v[186:189], 0
	v_mfma_f32_16x16x32_bf16 v[118:121], v[134:137], v[190:193], v[118:121]
	v_mfma_f32_16x16x32_bf16 v[94:97], v[130:133], v[194:197], 0
	v_mfma_f32_16x16x32_bf16 v[94:97], v[134:137], v[198:201], v[94:97]
	v_mfma_f32_16x16x32_bf16 v[90:93], v[138:141], v[194:197], 0
	v_mfma_f32_16x16x32_bf16 v[90:93], v[142:145], v[198:201], v[90:93]
	v_mfma_f32_16x16x32_bf16 v[78:81], v[138:141], v[202:205], 0
	v_mfma_f32_16x16x32_bf16 v[78:81], v[142:145], v[206:209], v[78:81]
	s_waitcnt lgkmcnt(0)
	v_mfma_f32_16x16x32_bf16 v[86:89], v[130:133], v[202:205], 0
	v_mfma_f32_16x16x32_bf16 v[86:89], v[134:137], v[206:209], v[86:89]
	s_setprio 0
	s_setprio 1
	v_mfma_f32_16x16x32_bf16 v[114:117], v[150:153], v[166:169], 0
	v_mfma_f32_16x16x32_bf16 v[114:117], v[154:157], v[170:173], v[114:117]
	v_mfma_f32_16x16x32_bf16 v[106:109], v[158:161], v[166:169], 0
	v_mfma_f32_16x16x32_bf16 v[106:109], v[162:165], v[170:173], v[106:109]
	v_mfma_f32_16x16x32_bf16 v[98:101], v[158:161], v[186:189], 0
	v_mfma_f32_16x16x32_bf16 v[98:101], v[162:165], v[190:193], v[98:101]
	v_mfma_f32_16x16x32_bf16 v[102:105], v[150:153], v[186:189], 0
	v_mfma_f32_16x16x32_bf16 v[102:105], v[154:157], v[190:193], v[102:105]
	v_mfma_f32_16x16x32_bf16 v[82:85], v[150:153], v[194:197], 0
	v_mfma_f32_16x16x32_bf16 v[82:85], v[154:157], v[198:201], v[82:85]
	v_mfma_f32_16x16x32_bf16 v[74:77], v[158:161], v[194:197], 0
	v_mfma_f32_16x16x32_bf16 v[74:77], v[162:165], v[198:201], v[74:77]
	v_mfma_f32_16x16x32_bf16 v[66:69], v[158:161], v[202:205], 0
	v_mfma_f32_16x16x32_bf16 v[66:69], v[162:165], v[206:209], v[66:69]
	s_setprio 2
	s_barrier
	v_mfma_f32_16x16x32_bf16 v[70:73], v[150:153], v[202:205], 0
	v_mfma_f32_16x16x32_bf16 v[70:73], v[154:157], v[206:209], v[70:73]
	s_setprio 0
	s_setprio 3
	ds_read_b128 v[166:169], v183 offset:16384
	ds_read_b128 v[170:173], v183 offset:17408
	ds_read_b128 v[186:189], v183 offset:18432
	ds_read_b128 v[190:193], v183 offset:19456
	ds_read_b128 v[194:197], v183 offset:20480
	ds_read_b128 v[198:201], v183 offset:21504
	ds_read_b128 v[202:205], v183 offset:22528
	ds_read_b128 v[206:209], v183 offset:23552
	s_mov_b32 s70, m0
	s_mov_b32 m0, s27
	s_nop 0
	global_load_lds_dwordx4 v176, s[30:31]
	s_mov_b32 m0, s70
	s_nop 0
	s_mov_b32 s70, m0
	s_mov_b32 m0, s45
	s_nop 0
	global_load_lds_dwordx4 v178, s[30:31]
	s_mov_b32 m0, s70
	s_add_u32 s70, s30, 0x4000
	s_addc_u32 s71, s31, 0
	s_mov_b32 s73, m0
	s_mov_b32 m0, s46
	s_nop 0
	global_load_lds_dwordx4 v176, s[70:71]
	s_mov_b32 m0, s73
	s_nop 0
	s_mov_b32 s73, m0
	s_mov_b32 m0, s47
	s_nop 0
	global_load_lds_dwordx4 v178, s[70:71]
	s_mov_b32 m0, s73
	s_setprio 0
	s_waitcnt vmcnt(4)
	s_waitcnt lgkmcnt(0)
	s_barrier
	s_setprio 1
	s_waitcnt lgkmcnt(7)
	v_mfma_f32_16x16x32_bf16 v[62:65], v[130:133], v[166:169], 0
	v_mfma_f32_16x16x32_bf16 v[62:65], v[134:137], v[170:173], v[62:65]
	s_waitcnt lgkmcnt(5)
	v_mfma_f32_16x16x32_bf16 v[58:61], v[138:141], v[166:169], 0
	v_mfma_f32_16x16x32_bf16 v[58:61], v[142:145], v[170:173], v[58:61]
	s_waitcnt lgkmcnt(3)
	v_mfma_f32_16x16x32_bf16 v[42:45], v[138:141], v[186:189], 0
	v_mfma_f32_16x16x32_bf16 v[42:45], v[142:145], v[190:193], v[42:45]
	s_waitcnt lgkmcnt(1)
	v_mfma_f32_16x16x32_bf16 v[46:49], v[130:133], v[186:189], 0
	v_mfma_f32_16x16x32_bf16 v[46:49], v[134:137], v[190:193], v[46:49]
	v_mfma_f32_16x16x32_bf16 v[30:33], v[130:133], v[194:197], 0
	v_mfma_f32_16x16x32_bf16 v[30:33], v[134:137], v[198:201], v[30:33]
	v_mfma_f32_16x16x32_bf16 v[26:29], v[138:141], v[194:197], 0
	v_mfma_f32_16x16x32_bf16 v[26:29], v[142:145], v[198:201], v[26:29]
	v_mfma_f32_16x16x32_bf16 v[10:13], v[138:141], v[202:205], 0
	v_mfma_f32_16x16x32_bf16 v[10:13], v[142:145], v[206:209], v[10:13]
	s_waitcnt lgkmcnt(0)
	v_mfma_f32_16x16x32_bf16 v[14:17], v[130:133], v[202:205], 0
	v_mfma_f32_16x16x32_bf16 v[14:17], v[134:137], v[206:209], v[14:17]
	s_setprio 0
	s_setprio 1
	v_mfma_f32_16x16x32_bf16 v[54:57], v[150:153], v[166:169], 0
	v_mfma_f32_16x16x32_bf16 v[54:57], v[154:157], v[170:173], v[54:57]
	v_mfma_f32_16x16x32_bf16 v[50:53], v[158:161], v[166:169], 0
	v_mfma_f32_16x16x32_bf16 v[50:53], v[162:165], v[170:173], v[50:53]
	v_mfma_f32_16x16x32_bf16 v[34:37], v[158:161], v[186:189], 0
	v_mfma_f32_16x16x32_bf16 v[34:37], v[162:165], v[190:193], v[34:37]
	v_mfma_f32_16x16x32_bf16 v[38:41], v[150:153], v[186:189], 0
	v_mfma_f32_16x16x32_bf16 v[38:41], v[154:157], v[190:193], v[38:41]
	v_mfma_f32_16x16x32_bf16 v[22:25], v[150:153], v[194:197], 0
	v_mfma_f32_16x16x32_bf16 v[22:25], v[154:157], v[198:201], v[22:25]
	v_mfma_f32_16x16x32_bf16 v[18:21], v[158:161], v[194:197], 0
	v_mfma_f32_16x16x32_bf16 v[18:21], v[162:165], v[198:201], v[18:21]
	v_mfma_f32_16x16x32_bf16 v[2:5], v[158:161], v[202:205], 0
	v_mfma_f32_16x16x32_bf16 v[2:5], v[162:165], v[206:209], v[2:5]
	s_setprio 2
	s_barrier
	v_mfma_f32_16x16x32_bf16 v[6:9], v[150:153], v[202:205], 0
	v_mfma_f32_16x16x32_bf16 v[6:9], v[154:157], v[206:209], v[6:9]
	s_setprio 0
	s_setprio 3
	ds_read_b128 v[130:133], v184
	ds_read_b128 v[134:137], v184 offset:1024
	ds_read_b128 v[138:141], v184 offset:2048
	ds_read_b128 v[142:145], v184 offset:3072
	ds_read_b128 v[150:153], v185
	ds_read_b128 v[154:157], v185 offset:1024
	ds_read_b128 v[158:161], v185 offset:2048
	ds_read_b128 v[162:165], v185 offset:3072
	ds_read_b128 v[166:169], v183 offset:32768
	ds_read_b128 v[170:173], v183 offset:33792
	ds_read_b128 v[186:189], v183 offset:34816
	ds_read_b128 v[190:193], v183 offset:35840
	ds_read_b128 v[194:197], v183 offset:36864
	ds_read_b128 v[198:201], v183 offset:37888
	ds_read_b128 v[202:205], v183 offset:38912
	ds_read_b128 v[206:209], v183 offset:39936
	s_mov_b32 s70, m0
	s_mov_b32 m0, s44
	s_nop 0
	global_load_lds_dwordx4 v1, s[34:35]
	s_mov_b32 m0, s70
	s_nop 0
	s_mov_b32 s70, m0
	s_mov_b32 m0, s48
	s_nop 0
	global_load_lds_dwordx4 v177, s[34:35]
	s_mov_b32 m0, s70
	s_add_u32 s34, s34, 0x4000
	s_addc_u32 s35, s35, 0
	s_mov_b32 s70, m0
	s_mov_b32 m0, s49
	s_nop 0
	global_load_lds_dwordx4 v1, s[34:35]
	s_mov_b32 m0, s70
	s_nop 0
	s_mov_b32 s70, m0
	s_mov_b32 m0, s50
	s_nop 0
	global_load_lds_dwordx4 v177, s[34:35]
	s_mov_b32 m0, s70
	s_setprio 0
	s_waitcnt vmcnt(8)
	s_waitcnt lgkmcnt(0)
	s_barrier
	s_setprio 1
	s_waitcnt lgkmcnt(7)
	v_mfma_f32_16x16x32_bf16 v[126:129], v[130:133], v[166:169], v[126:129]
	v_mfma_f32_16x16x32_bf16 v[126:129], v[134:137], v[170:173], v[126:129]
	s_waitcnt lgkmcnt(5)
	v_mfma_f32_16x16x32_bf16 v[122:125], v[138:141], v[166:169], v[122:125]
	v_mfma_f32_16x16x32_bf16 v[122:125], v[142:145], v[170:173], v[122:125]
	s_waitcnt lgkmcnt(3)
	v_mfma_f32_16x16x32_bf16 v[110:113], v[138:141], v[186:189], v[110:113]
	v_mfma_f32_16x16x32_bf16 v[110:113], v[142:145], v[190:193], v[110:113]
	s_waitcnt lgkmcnt(1)
	v_mfma_f32_16x16x32_bf16 v[118:121], v[130:133], v[186:189], v[118:121]
	v_mfma_f32_16x16x32_bf16 v[118:121], v[134:137], v[190:193], v[118:121]
	v_mfma_f32_16x16x32_bf16 v[94:97], v[130:133], v[194:197], v[94:97]
	v_mfma_f32_16x16x32_bf16 v[94:97], v[134:137], v[198:201], v[94:97]
	v_mfma_f32_16x16x32_bf16 v[90:93], v[138:141], v[194:197], v[90:93]
	v_mfma_f32_16x16x32_bf16 v[90:93], v[142:145], v[198:201], v[90:93]
	v_mfma_f32_16x16x32_bf16 v[78:81], v[138:141], v[202:205], v[78:81]
	v_mfma_f32_16x16x32_bf16 v[78:81], v[142:145], v[206:209], v[78:81]
	s_waitcnt lgkmcnt(0)
	v_mfma_f32_16x16x32_bf16 v[86:89], v[130:133], v[202:205], v[86:89]
	v_mfma_f32_16x16x32_bf16 v[86:89], v[134:137], v[206:209], v[86:89]
	s_setprio 0
	s_setprio 1
	v_mfma_f32_16x16x32_bf16 v[114:117], v[150:153], v[166:169], v[114:117]
	v_mfma_f32_16x16x32_bf16 v[114:117], v[154:157], v[170:173], v[114:117]
	v_mfma_f32_16x16x32_bf16 v[106:109], v[158:161], v[166:169], v[106:109]
	v_mfma_f32_16x16x32_bf16 v[106:109], v[162:165], v[170:173], v[106:109]
	v_mfma_f32_16x16x32_bf16 v[98:101], v[158:161], v[186:189], v[98:101]
	v_mfma_f32_16x16x32_bf16 v[98:101], v[162:165], v[190:193], v[98:101]
	v_mfma_f32_16x16x32_bf16 v[102:105], v[150:153], v[186:189], v[102:105]
	v_mfma_f32_16x16x32_bf16 v[102:105], v[154:157], v[190:193], v[102:105]
	v_mfma_f32_16x16x32_bf16 v[82:85], v[150:153], v[194:197], v[82:85]
	v_mfma_f32_16x16x32_bf16 v[82:85], v[154:157], v[198:201], v[82:85]
	v_mfma_f32_16x16x32_bf16 v[74:77], v[158:161], v[194:197], v[74:77]
	v_mfma_f32_16x16x32_bf16 v[74:77], v[162:165], v[198:201], v[74:77]
	v_mfma_f32_16x16x32_bf16 v[66:69], v[158:161], v[202:205], v[66:69]
	v_mfma_f32_16x16x32_bf16 v[66:69], v[162:165], v[206:209], v[66:69]
	s_setprio 2
	s_barrier
	v_mfma_f32_16x16x32_bf16 v[70:73], v[150:153], v[202:205], v[70:73]
	v_mfma_f32_16x16x32_bf16 v[70:73], v[154:157], v[206:209], v[70:73]
	s_setprio 0
	s_setprio 3
	ds_read_b128 v[166:169], v183 offset:49152
	ds_read_b128 v[170:173], v183 offset:50176
	ds_read_b128 v[186:189], v183 offset:51200
	ds_read_b128 v[190:193], v183 offset:52224
	ds_read_b128 v[194:197], v183 offset:53248
	ds_read_b128 v[198:201], v183 offset:54272
	ds_read_b128 v[202:205], v183 offset:55296
	ds_read_b128 v[206:209], v183 offset:56320
	s_add_u32 s34, s30, 0x40000
	s_addc_u32 s35, s31, 0
	s_mov_b32 s70, m0
	s_mov_b32 m0, s51
	s_nop 0
	global_load_lds_dwordx4 v176, s[34:35]
	s_mov_b32 m0, s70
	s_add_u32 s30, s30, 0x44000
	s_mov_b32 s70, m0
	s_mov_b32 m0, s52
	s_nop 0
	global_load_lds_dwordx4 v178, s[34:35]
	s_mov_b32 m0, s70
	s_addc_u32 s31, s31, 0
	s_mov_b32 s34, m0
	s_mov_b32 m0, s53
	s_nop 0
	global_load_lds_dwordx4 v176, s[30:31]
	s_mov_b32 m0, s34
	s_nop 0
	s_mov_b32 s34, m0
	s_mov_b32 m0, s54
	s_nop 0
	global_load_lds_dwordx4 v178, s[30:31]
	s_mov_b32 m0, s34
	s_setprio 0
	s_waitcnt vmcnt(4)
	s_waitcnt lgkmcnt(0)
	s_barrier
	s_setprio 1
	s_waitcnt lgkmcnt(7)
	v_mfma_f32_16x16x32_bf16 v[62:65], v[130:133], v[166:169], v[62:65]
	v_mfma_f32_16x16x32_bf16 v[62:65], v[134:137], v[170:173], v[62:65]
	s_waitcnt lgkmcnt(5)
	v_mfma_f32_16x16x32_bf16 v[58:61], v[138:141], v[166:169], v[58:61]
	v_mfma_f32_16x16x32_bf16 v[58:61], v[142:145], v[170:173], v[58:61]
	s_waitcnt lgkmcnt(3)
	v_mfma_f32_16x16x32_bf16 v[42:45], v[138:141], v[186:189], v[42:45]
	v_mfma_f32_16x16x32_bf16 v[42:45], v[142:145], v[190:193], v[42:45]
	s_waitcnt lgkmcnt(1)
	v_mfma_f32_16x16x32_bf16 v[46:49], v[130:133], v[186:189], v[46:49]
	v_mfma_f32_16x16x32_bf16 v[46:49], v[134:137], v[190:193], v[46:49]
	v_mfma_f32_16x16x32_bf16 v[30:33], v[130:133], v[194:197], v[30:33]
	v_mfma_f32_16x16x32_bf16 v[30:33], v[134:137], v[198:201], v[30:33]
	v_mfma_f32_16x16x32_bf16 v[26:29], v[138:141], v[194:197], v[26:29]
	v_mfma_f32_16x16x32_bf16 v[26:29], v[142:145], v[198:201], v[26:29]
	v_mfma_f32_16x16x32_bf16 v[10:13], v[138:141], v[202:205], v[10:13]
	v_mfma_f32_16x16x32_bf16 v[10:13], v[142:145], v[206:209], v[10:13]
	s_waitcnt lgkmcnt(0)
	v_mfma_f32_16x16x32_bf16 v[14:17], v[130:133], v[202:205], v[14:17]
	v_mfma_f32_16x16x32_bf16 v[14:17], v[134:137], v[206:209], v[14:17]
	s_setprio 0
	s_setprio 1
	v_mfma_f32_16x16x32_bf16 v[54:57], v[150:153], v[166:169], v[54:57]
	v_mfma_f32_16x16x32_bf16 v[54:57], v[154:157], v[170:173], v[54:57]
	v_mfma_f32_16x16x32_bf16 v[50:53], v[158:161], v[166:169], v[50:53]
	v_mfma_f32_16x16x32_bf16 v[50:53], v[162:165], v[170:173], v[50:53]
	v_mfma_f32_16x16x32_bf16 v[34:37], v[158:161], v[186:189], v[34:37]
	v_mfma_f32_16x16x32_bf16 v[34:37], v[162:165], v[190:193], v[34:37]
	v_mfma_f32_16x16x32_bf16 v[38:41], v[150:153], v[186:189], v[38:41]
	v_mfma_f32_16x16x32_bf16 v[38:41], v[154:157], v[190:193], v[38:41]
	v_mfma_f32_16x16x32_bf16 v[22:25], v[150:153], v[194:197], v[22:25]
	v_mfma_f32_16x16x32_bf16 v[22:25], v[154:157], v[198:201], v[22:25]
	v_mfma_f32_16x16x32_bf16 v[18:21], v[158:161], v[194:197], v[18:21]
	v_mfma_f32_16x16x32_bf16 v[18:21], v[162:165], v[198:201], v[18:21]
	v_mfma_f32_16x16x32_bf16 v[2:5], v[158:161], v[202:205], v[2:5]
	v_mfma_f32_16x16x32_bf16 v[2:5], v[162:165], v[206:209], v[2:5]
	s_setprio 2
	s_barrier
	v_mfma_f32_16x16x32_bf16 v[6:9], v[150:153], v[202:205], v[6:9]
	v_mfma_f32_16x16x32_bf16 v[6:9], v[154:157], v[206:209], v[6:9]
	s_setprio 0
	s_add_i32 s69, s69, 2
	s_add_u32 s65, s65, 0x80000
	s_addc_u32 s66, s66, 0
	s_add_u32 s28, s28, 0x400000
	s_addc_u32 s29, s29, 0
	s_add_u32 s67, s67, 0x400000
	s_addc_u32 s68, s68, 0
	s_cmpk_gt_u32 s69, 0x53
	.p2align 6
.LBB0_2792:
	s_setprio 3
	ds_read_b128 v[130:133], v181
	ds_read_b128 v[134:137], v181 offset:1024
	ds_read_b128 v[138:141], v181 offset:2048
	ds_read_b128 v[142:145], v181 offset:3072
	ds_read_b128 v[150:153], v182
	ds_read_b128 v[154:157], v182 offset:1024
	ds_read_b128 v[158:161], v182 offset:2048
	ds_read_b128 v[162:165], v182 offset:3072
	s_cmpk_eq_i32 s69, 0x52
	s_cselect_b32 s31, s19, s66
	s_cselect_b32 s30, s64, s65
	s_cselect_b32 s35, s21, s68
	s_cselect_b32 s34, s63, s67
	ds_read_b128 v[166:169], v183
	ds_read_b128 v[170:173], v183 offset:1024
	ds_read_b128 v[186:189], v183 offset:2048
	ds_read_b128 v[190:193], v183 offset:3072
	ds_read_b128 v[194:197], v183 offset:4096
	ds_read_b128 v[198:201], v183 offset:5120
	ds_read_b128 v[202:205], v183 offset:6144
	ds_read_b128 v[206:209], v183 offset:7168
	s_add_u32 s70, s28, 0xffffc000
	s_addc_u32 s71, s29, -1
	s_mov_b32 s73, m0
	s_mov_b32 m0, s57
	s_nop 0
	global_load_lds_dwordx4 v1, s[70:71]
	s_mov_b32 m0, s73
	s_nop 0
	s_mov_b32 s73, m0
	s_mov_b32 m0, s59
	s_nop 0
	global_load_lds_dwordx4 v177, s[70:71]
	s_mov_b32 m0, s73
	s_mov_b32 s70, m0
	s_mov_b32 m0, s58
	s_nop 0
	global_load_lds_dwordx4 v1, s[28:29]
	s_mov_b32 m0, s70
	s_nop 0
	s_mov_b32 s70, m0
	s_mov_b32 m0, s60
	s_nop 0
	global_load_lds_dwordx4 v177, s[28:29]
	s_mov_b32 m0, s70
	s_setprio 0
	s_waitcnt vmcnt(8)
	s_waitcnt lgkmcnt(0)
	s_barrier
	s_setprio 1
	s_waitcnt lgkmcnt(7)
	v_mfma_f32_16x16x32_bf16 v[126:129], v[130:133], v[166:169], v[126:129]
	v_mfma_f32_16x16x32_bf16 v[126:129], v[134:137], v[170:173], v[126:129]
	s_waitcnt lgkmcnt(5)
	v_mfma_f32_16x16x32_bf16 v[122:125], v[138:141], v[166:169], v[122:125]
	v_mfma_f32_16x16x32_bf16 v[122:125], v[142:145], v[170:173], v[122:125]
	s_waitcnt lgkmcnt(3)
	v_mfma_f32_16x16x32_bf16 v[110:113], v[138:141], v[186:189], v[110:113]
	v_mfma_f32_16x16x32_bf16 v[110:113], v[142:145], v[190:193], v[110:113]
	s_waitcnt lgkmcnt(1)
	v_mfma_f32_16x16x32_bf16 v[118:121], v[130:133], v[186:189], v[118:121]
	v_mfma_f32_16x16x32_bf16 v[118:121], v[134:137], v[190:193], v[118:121]
	v_mfma_f32_16x16x32_bf16 v[94:97], v[130:133], v[194:197], v[94:97]
	v_mfma_f32_16x16x32_bf16 v[94:97], v[134:137], v[198:201], v[94:97]
	v_mfma_f32_16x16x32_bf16 v[90:93], v[138:141], v[194:197], v[90:93]
	v_mfma_f32_16x16x32_bf16 v[90:93], v[142:145], v[198:201], v[90:93]
	v_mfma_f32_16x16x32_bf16 v[78:81], v[138:141], v[202:205], v[78:81]
	v_mfma_f32_16x16x32_bf16 v[78:81], v[142:145], v[206:209], v[78:81]
	s_waitcnt lgkmcnt(0)
	v_mfma_f32_16x16x32_bf16 v[86:89], v[130:133], v[202:205], v[86:89]
	v_mfma_f32_16x16x32_bf16 v[86:89], v[134:137], v[206:209], v[86:89]
	s_setprio 0
	s_setprio 1
	v_mfma_f32_16x16x32_bf16 v[114:117], v[150:153], v[166:169], v[114:117]
	v_mfma_f32_16x16x32_bf16 v[114:117], v[154:157], v[170:173], v[114:117]
	v_mfma_f32_16x16x32_bf16 v[106:109], v[158:161], v[166:169], v[106:109]
	v_mfma_f32_16x16x32_bf16 v[106:109], v[162:165], v[170:173], v[106:109]
	v_mfma_f32_16x16x32_bf16 v[98:101], v[158:161], v[186:189], v[98:101]
	v_mfma_f32_16x16x32_bf16 v[98:101], v[162:165], v[190:193], v[98:101]
	v_mfma_f32_16x16x32_bf16 v[102:105], v[150:153], v[186:189], v[102:105]
	v_mfma_f32_16x16x32_bf16 v[102:105], v[154:157], v[190:193], v[102:105]
	v_mfma_f32_16x16x32_bf16 v[82:85], v[150:153], v[194:197], v[82:85]
	v_mfma_f32_16x16x32_bf16 v[82:85], v[154:157], v[198:201], v[82:85]
	v_mfma_f32_16x16x32_bf16 v[74:77], v[158:161], v[194:197], v[74:77]
	v_mfma_f32_16x16x32_bf16 v[74:77], v[162:165], v[198:201], v[74:77]
	v_mfma_f32_16x16x32_bf16 v[66:69], v[158:161], v[202:205], v[66:69]
	v_mfma_f32_16x16x32_bf16 v[66:69], v[162:165], v[206:209], v[66:69]
	s_setprio 2
	s_barrier
	v_mfma_f32_16x16x32_bf16 v[70:73], v[150:153], v[202:205], v[70:73]
	v_mfma_f32_16x16x32_bf16 v[70:73], v[154:157], v[206:209], v[70:73]
	s_setprio 0
	s_setprio 3
	ds_read_b128 v[166:169], v183 offset:16384
	ds_read_b128 v[170:173], v183 offset:17408
	ds_read_b128 v[186:189], v183 offset:18432
	ds_read_b128 v[190:193], v183 offset:19456
	ds_read_b128 v[194:197], v183 offset:20480
	ds_read_b128 v[198:201], v183 offset:21504
	ds_read_b128 v[202:205], v183 offset:22528
	ds_read_b128 v[206:209], v183 offset:23552
	s_mov_b32 s70, m0
	s_mov_b32 m0, s27
	s_nop 0
	global_load_lds_dwordx4 v176, s[30:31]
	s_mov_b32 m0, s70
	s_nop 0
	s_mov_b32 s70, m0
	s_mov_b32 m0, s45
	s_nop 0
	global_load_lds_dwordx4 v178, s[30:31]
	s_mov_b32 m0, s70
	s_add_u32 s70, s30, 0x4000
	s_addc_u32 s71, s31, 0
	s_mov_b32 s73, m0
	s_mov_b32 m0, s46
	s_nop 0
	global_load_lds_dwordx4 v176, s[70:71]
	s_mov_b32 m0, s73
	s_nop 0
	s_mov_b32 s73, m0
	s_mov_b32 m0, s47
	s_nop 0
	global_load_lds_dwordx4 v178, s[70:71]
	s_mov_b32 m0, s73
	s_setprio 0
	s_waitcnt vmcnt(4)
	s_waitcnt lgkmcnt(0)
	s_barrier
	s_setprio 1
	s_waitcnt lgkmcnt(7)
	v_mfma_f32_16x16x32_bf16 v[62:65], v[130:133], v[166:169], v[62:65]
	v_mfma_f32_16x16x32_bf16 v[62:65], v[134:137], v[170:173], v[62:65]
	s_waitcnt lgkmcnt(5)
	v_mfma_f32_16x16x32_bf16 v[58:61], v[138:141], v[166:169], v[58:61]
	v_mfma_f32_16x16x32_bf16 v[58:61], v[142:145], v[170:173], v[58:61]
	s_waitcnt lgkmcnt(3)
	v_mfma_f32_16x16x32_bf16 v[42:45], v[138:141], v[186:189], v[42:45]
	v_mfma_f32_16x16x32_bf16 v[42:45], v[142:145], v[190:193], v[42:45]
	s_waitcnt lgkmcnt(1)
	v_mfma_f32_16x16x32_bf16 v[46:49], v[130:133], v[186:189], v[46:49]
	v_mfma_f32_16x16x32_bf16 v[46:49], v[134:137], v[190:193], v[46:49]
	v_mfma_f32_16x16x32_bf16 v[30:33], v[130:133], v[194:197], v[30:33]
	v_mfma_f32_16x16x32_bf16 v[30:33], v[134:137], v[198:201], v[30:33]
	v_mfma_f32_16x16x32_bf16 v[26:29], v[138:141], v[194:197], v[26:29]
	v_mfma_f32_16x16x32_bf16 v[26:29], v[142:145], v[198:201], v[26:29]
	v_mfma_f32_16x16x32_bf16 v[10:13], v[138:141], v[202:205], v[10:13]
	v_mfma_f32_16x16x32_bf16 v[10:13], v[142:145], v[206:209], v[10:13]
	s_waitcnt lgkmcnt(0)
	v_mfma_f32_16x16x32_bf16 v[14:17], v[130:133], v[202:205], v[14:17]
	v_mfma_f32_16x16x32_bf16 v[14:17], v[134:137], v[206:209], v[14:17]
	s_setprio 0
	s_setprio 1
	v_mfma_f32_16x16x32_bf16 v[54:57], v[150:153], v[166:169], v[54:57]
	v_mfma_f32_16x16x32_bf16 v[54:57], v[154:157], v[170:173], v[54:57]
	v_mfma_f32_16x16x32_bf16 v[50:53], v[158:161], v[166:169], v[50:53]
	v_mfma_f32_16x16x32_bf16 v[50:53], v[162:165], v[170:173], v[50:53]
	v_mfma_f32_16x16x32_bf16 v[34:37], v[158:161], v[186:189], v[34:37]
	v_mfma_f32_16x16x32_bf16 v[34:37], v[162:165], v[190:193], v[34:37]
	v_mfma_f32_16x16x32_bf16 v[38:41], v[150:153], v[186:189], v[38:41]
	v_mfma_f32_16x16x32_bf16 v[38:41], v[154:157], v[190:193], v[38:41]
	v_mfma_f32_16x16x32_bf16 v[22:25], v[150:153], v[194:197], v[22:25]
	v_mfma_f32_16x16x32_bf16 v[22:25], v[154:157], v[198:201], v[22:25]
	v_mfma_f32_16x16x32_bf16 v[18:21], v[158:161], v[194:197], v[18:21]
	v_mfma_f32_16x16x32_bf16 v[18:21], v[162:165], v[198:201], v[18:21]
	v_mfma_f32_16x16x32_bf16 v[2:5], v[158:161], v[202:205], v[2:5]
	v_mfma_f32_16x16x32_bf16 v[2:5], v[162:165], v[206:209], v[2:5]
	s_setprio 2
	s_barrier
	v_mfma_f32_16x16x32_bf16 v[6:9], v[150:153], v[202:205], v[6:9]
	v_mfma_f32_16x16x32_bf16 v[6:9], v[154:157], v[206:209], v[6:9]
	s_setprio 0
	s_setprio 3
	ds_read_b128 v[130:133], v184
	ds_read_b128 v[134:137], v184 offset:1024
	ds_read_b128 v[138:141], v184 offset:2048
	ds_read_b128 v[142:145], v184 offset:3072
	ds_read_b128 v[150:153], v185
	ds_read_b128 v[154:157], v185 offset:1024
	ds_read_b128 v[158:161], v185 offset:2048
	ds_read_b128 v[162:165], v185 offset:3072
	ds_read_b128 v[166:169], v183 offset:32768
	ds_read_b128 v[170:173], v183 offset:33792
	ds_read_b128 v[186:189], v183 offset:34816
	ds_read_b128 v[190:193], v183 offset:35840
	ds_read_b128 v[194:197], v183 offset:36864
	ds_read_b128 v[198:201], v183 offset:37888
	ds_read_b128 v[202:205], v183 offset:38912
	ds_read_b128 v[206:209], v183 offset:39936
	s_mov_b32 s70, m0
	s_mov_b32 m0, s44
	s_nop 0
	global_load_lds_dwordx4 v1, s[34:35]
	s_mov_b32 m0, s70
	s_nop 0
	s_mov_b32 s70, m0
	s_mov_b32 m0, s48
	s_nop 0
	global_load_lds_dwordx4 v177, s[34:35]
	s_mov_b32 m0, s70
	s_add_u32 s34, s34, 0x4000
	s_addc_u32 s35, s35, 0
	s_mov_b32 s70, m0
	s_mov_b32 m0, s49
	s_nop 0
	global_load_lds_dwordx4 v1, s[34:35]
	s_mov_b32 m0, s70
	s_nop 0
	s_mov_b32 s70, m0
	s_mov_b32 m0, s50
	s_nop 0
	global_load_lds_dwordx4 v177, s[34:35]
	s_mov_b32 m0, s70
	s_setprio 0
	s_waitcnt vmcnt(8)
	s_waitcnt lgkmcnt(0)
	s_barrier
	s_setprio 1
	s_waitcnt lgkmcnt(7)
	v_mfma_f32_16x16x32_bf16 v[126:129], v[130:133], v[166:169], v[126:129]
	v_mfma_f32_16x16x32_bf16 v[126:129], v[134:137], v[170:173], v[126:129]
	s_waitcnt lgkmcnt(5)
	v_mfma_f32_16x16x32_bf16 v[122:125], v[138:141], v[166:169], v[122:125]
	v_mfma_f32_16x16x32_bf16 v[122:125], v[142:145], v[170:173], v[122:125]
	s_waitcnt lgkmcnt(3)
	v_mfma_f32_16x16x32_bf16 v[110:113], v[138:141], v[186:189], v[110:113]
	v_mfma_f32_16x16x32_bf16 v[110:113], v[142:145], v[190:193], v[110:113]
	s_waitcnt lgkmcnt(1)
	v_mfma_f32_16x16x32_bf16 v[118:121], v[130:133], v[186:189], v[118:121]
	v_mfma_f32_16x16x32_bf16 v[118:121], v[134:137], v[190:193], v[118:121]
	v_mfma_f32_16x16x32_bf16 v[94:97], v[130:133], v[194:197], v[94:97]
	v_mfma_f32_16x16x32_bf16 v[94:97], v[134:137], v[198:201], v[94:97]
	v_mfma_f32_16x16x32_bf16 v[90:93], v[138:141], v[194:197], v[90:93]
	v_mfma_f32_16x16x32_bf16 v[90:93], v[142:145], v[198:201], v[90:93]
	v_mfma_f32_16x16x32_bf16 v[78:81], v[138:141], v[202:205], v[78:81]
	v_mfma_f32_16x16x32_bf16 v[78:81], v[142:145], v[206:209], v[78:81]
	s_waitcnt lgkmcnt(0)
	v_mfma_f32_16x16x32_bf16 v[86:89], v[130:133], v[202:205], v[86:89]
	v_mfma_f32_16x16x32_bf16 v[86:89], v[134:137], v[206:209], v[86:89]
	s_setprio 0
	s_setprio 1
	v_mfma_f32_16x16x32_bf16 v[114:117], v[150:153], v[166:169], v[114:117]
	v_mfma_f32_16x16x32_bf16 v[114:117], v[154:157], v[170:173], v[114:117]
	v_mfma_f32_16x16x32_bf16 v[106:109], v[158:161], v[166:169], v[106:109]
	v_mfma_f32_16x16x32_bf16 v[106:109], v[162:165], v[170:173], v[106:109]
	v_mfma_f32_16x16x32_bf16 v[98:101], v[158:161], v[186:189], v[98:101]
	v_mfma_f32_16x16x32_bf16 v[98:101], v[162:165], v[190:193], v[98:101]
	v_mfma_f32_16x16x32_bf16 v[102:105], v[150:153], v[186:189], v[102:105]
	v_mfma_f32_16x16x32_bf16 v[102:105], v[154:157], v[190:193], v[102:105]
	v_mfma_f32_16x16x32_bf16 v[82:85], v[150:153], v[194:197], v[82:85]
	v_mfma_f32_16x16x32_bf16 v[82:85], v[154:157], v[198:201], v[82:85]
	v_mfma_f32_16x16x32_bf16 v[74:77], v[158:161], v[194:197], v[74:77]
	v_mfma_f32_16x16x32_bf16 v[74:77], v[162:165], v[198:201], v[74:77]
	v_mfma_f32_16x16x32_bf16 v[66:69], v[158:161], v[202:205], v[66:69]
	v_mfma_f32_16x16x32_bf16 v[66:69], v[162:165], v[206:209], v[66:69]
	s_setprio 2
	s_barrier
	v_mfma_f32_16x16x32_bf16 v[70:73], v[150:153], v[202:205], v[70:73]
	v_mfma_f32_16x16x32_bf16 v[70:73], v[154:157], v[206:209], v[70:73]
	s_setprio 0
	s_setprio 3
	ds_read_b128 v[166:169], v183 offset:49152
	ds_read_b128 v[170:173], v183 offset:50176
	ds_read_b128 v[186:189], v183 offset:51200
	ds_read_b128 v[190:193], v183 offset:52224
	ds_read_b128 v[194:197], v183 offset:53248
	ds_read_b128 v[198:201], v183 offset:54272
	ds_read_b128 v[202:205], v183 offset:55296
	ds_read_b128 v[206:209], v183 offset:56320
	s_add_u32 s34, s30, 0x40000
	s_addc_u32 s35, s31, 0
	s_mov_b32 s70, m0
	s_mov_b32 m0, s51
	s_nop 0
	global_load_lds_dwordx4 v176, s[34:35]
	s_mov_b32 m0, s70
	s_add_u32 s30, s30, 0x44000
	s_mov_b32 s70, m0
	s_mov_b32 m0, s52
	s_nop 0
	global_load_lds_dwordx4 v178, s[34:35]
	s_mov_b32 m0, s70
	s_addc_u32 s31, s31, 0
	s_mov_b32 s34, m0
	s_mov_b32 m0, s53
	s_nop 0
	global_load_lds_dwordx4 v176, s[30:31]
	s_mov_b32 m0, s34
	s_nop 0
	s_mov_b32 s34, m0
	s_mov_b32 m0, s54
	s_nop 0
	global_load_lds_dwordx4 v178, s[30:31]
	s_mov_b32 m0, s34
	s_setprio 0
	s_waitcnt vmcnt(4)
	s_waitcnt lgkmcnt(0)
	s_barrier
	s_setprio 1
	s_waitcnt lgkmcnt(7)
	v_mfma_f32_16x16x32_bf16 v[62:65], v[130:133], v[166:169], v[62:65]
	v_mfma_f32_16x16x32_bf16 v[62:65], v[134:137], v[170:173], v[62:65]
	s_waitcnt lgkmcnt(5)
	v_mfma_f32_16x16x32_bf16 v[58:61], v[138:141], v[166:169], v[58:61]
	v_mfma_f32_16x16x32_bf16 v[58:61], v[142:145], v[170:173], v[58:61]
	s_waitcnt lgkmcnt(3)
	v_mfma_f32_16x16x32_bf16 v[42:45], v[138:141], v[186:189], v[42:45]
	v_mfma_f32_16x16x32_bf16 v[42:45], v[142:145], v[190:193], v[42:45]
	s_waitcnt lgkmcnt(1)
	v_mfma_f32_16x16x32_bf16 v[46:49], v[130:133], v[186:189], v[46:49]
	v_mfma_f32_16x16x32_bf16 v[46:49], v[134:137], v[190:193], v[46:49]
	v_mfma_f32_16x16x32_bf16 v[30:33], v[130:133], v[194:197], v[30:33]
	v_mfma_f32_16x16x32_bf16 v[30:33], v[134:137], v[198:201], v[30:33]
	v_mfma_f32_16x16x32_bf16 v[26:29], v[138:141], v[194:197], v[26:29]
	v_mfma_f32_16x16x32_bf16 v[26:29], v[142:145], v[198:201], v[26:29]
	v_mfma_f32_16x16x32_bf16 v[10:13], v[138:141], v[202:205], v[10:13]
	v_mfma_f32_16x16x32_bf16 v[10:13], v[142:145], v[206:209], v[10:13]
	s_waitcnt lgkmcnt(0)
	v_mfma_f32_16x16x32_bf16 v[14:17], v[130:133], v[202:205], v[14:17]
	v_mfma_f32_16x16x32_bf16 v[14:17], v[134:137], v[206:209], v[14:17]
	s_setprio 0
	s_setprio 1
	v_mfma_f32_16x16x32_bf16 v[54:57], v[150:153], v[166:169], v[54:57]
	v_mfma_f32_16x16x32_bf16 v[54:57], v[154:157], v[170:173], v[54:57]
	v_mfma_f32_16x16x32_bf16 v[50:53], v[158:161], v[166:169], v[50:53]
	v_mfma_f32_16x16x32_bf16 v[50:53], v[162:165], v[170:173], v[50:53]
	v_mfma_f32_16x16x32_bf16 v[34:37], v[158:161], v[186:189], v[34:37]
	v_mfma_f32_16x16x32_bf16 v[34:37], v[162:165], v[190:193], v[34:37]
	v_mfma_f32_16x16x32_bf16 v[38:41], v[150:153], v[186:189], v[38:41]
	v_mfma_f32_16x16x32_bf16 v[38:41], v[154:157], v[190:193], v[38:41]
	v_mfma_f32_16x16x32_bf16 v[22:25], v[150:153], v[194:197], v[22:25]
	v_mfma_f32_16x16x32_bf16 v[22:25], v[154:157], v[198:201], v[22:25]
	v_mfma_f32_16x16x32_bf16 v[18:21], v[158:161], v[194:197], v[18:21]
	v_mfma_f32_16x16x32_bf16 v[18:21], v[162:165], v[198:201], v[18:21]
	v_mfma_f32_16x16x32_bf16 v[2:5], v[158:161], v[202:205], v[2:5]
	v_mfma_f32_16x16x32_bf16 v[2:5], v[162:165], v[206:209], v[2:5]
	s_setprio 2
	s_barrier
	v_mfma_f32_16x16x32_bf16 v[6:9], v[150:153], v[202:205], v[6:9]
	v_mfma_f32_16x16x32_bf16 v[6:9], v[154:157], v[206:209], v[6:9]
	s_setprio 0
	s_add_i32 s69, s69, 2
	s_add_u32 s65, s65, 0x80000
	s_addc_u32 s66, s66, 0
	s_add_u32 s28, s28, 0x400000
	s_addc_u32 s29, s29, 0
	s_add_u32 s67, s67, 0x400000
	s_addc_u32 s68, s68, 0
	s_cmpk_gt_u32 s69, 0x53
	s_cbranch_scc0 .LBB0_2792
	s_and_b64 vcc, exec, s[8:9]
	s_cbranch_vccz .LBB0_2795
	s_barrier
